# e15 stack plus zero-by-MFMA: the 128 v_mov clearing the accumulator tile before every unit are removed; the first K-loop trip is peeled and its first MFMA per accumulator takes C=0 (13 of 14 GEMM loop
# speedup vs baseline: 1.0059x; 1.0059x over previous
;     __device__ bool next(int i, Unit& u) const { if (!s.next(i, u)) return false; const int p = u.pn; u.pn = p < 56 ? (p % 7) * 8 + p / 7 : p; return true; }
;     __device__ bool next(int i, Unit& u) const { Unit t; if (!s.next(i >> 1, t)) return false; const int pass = i & 1; u.pm = t.pm + pass * (M / BM); u.pn = t.pn + pass * (D / BM); u.kt0 = 0; return true; }
; #define PG8_STAGE(bufoff, gbase, voff) do { _Pragma("unroll") for (int _i = 0; _i < 2; ++_i) \
;         __builtin_amdgcn_global_load_lds((const unsigned*)((const char*)(gbase) + (voff)[_i]), (PG8_LAS unsigned*)(lds + (bufoff) + ldsw + _i * 8192), 16, 0, 0); } while (0)
; #define PG8_WAIT_V(n) asm volatile("s_waitcnt vmcnt(" #n ")" ::: "memory")
; #define PG8_WAIT_L(n) asm volatile("s_waitcnt lgkmcnt(" #n ")" ::: "memory")
; #define PG8_BAR __builtin_amdgcn_s_barrier()
; template <class Epi, class Sched, bool ALIGN_EPI = false, bool SP2 = false>
; __device__ __forceinline__ void gemm_phase(PG8_LAS unsigned char* lds, const Gemm g, const Sched& S, const Epi& E) {
;     ...
;     for (;;) {
;         const bool has_next = S.next(ui + 1, nxt);
;         const char* nA = has_next ? (const char*)g.A + (size_t)nxt.pm * tstep + (size_t)nxt.kt0 * kstep : cA; const char* nB = has_next ? (const char*)g.Bt + (size_t)nxt.pn * tstep + (size_t)nxt.kt0 * kstep : cB;
;         for (int t = 0; t < nt; t += 2) {
;             if constexpr (Epi::MIDHOOK) { if (t == (nt >> 1)) E.mid(acc, cur, wr, wc, fr, fq); }
;             const bool last = (t == nt - 2);
;             const char* a1 = cA + (size_t)(t + 1) * kstep;
;             const char* a2 = last ? nA : cA + (size_t)(t + 2) * kstep; const char* b2 = last ? nB : cB + (size_t)(t + 2) * kstep;
;             const char* a3 = a2 + kstep; const char* b3 = b2 + kstep;
;             if (last && has_next) S.a_ready(nxt);
;             if constexpr (SP2) {
;             PG8_LDB(B0, 0, 0); PG8_LDB(B1, 0, 1); PG8_SCHED; PG8_LDA(At, 0, 0); PG8_STAGE(PG8_SA(1, 1), a1 + hstep, voffA);
;             PG8_WAIT_V(8); PG8_WAIT_L(0); PG8_BAR; PG8_MMA(0, 0, At, B0); PG8_MMA(0, 1, At, B1); PG8_BAR; PG8_SCHED;
;             PG8_LDA(At, 0, 1); PG8_STAGE(PG8_SB(0, 0), b2, voffB); PG8_STAGE(PG8_SB(0, 1), b2 + hstep, voffB); PG8_STAGE(PG8_SA(0, 0), a2, voffA);
;             PG8_WAIT_V(8); PG8_WAIT_L(0); PG8_BAR; PG8_MMA(1, 0, At, B0); PG8_MMA(1, 1, At, B1); PG8_BAR; PG8_SCHED;
.LBB0_87:
	s_ashr_i32 s21, s20, 31
	s_lshl_b64 s[22:23], s[20:21], 20
	s_add_u32 s22, s94, s22
	s_addc_u32 s23, s95, s23
	s_and_b64 s[36:37], s[6:7], exec
	s_cselect_b32 s21, s23, s41
	s_cselect_b32 s48, s22, s40
	s_ashr_i32 s15, s14, 31
	s_lshl_b64 s[36:37], s[14:15], 20
	s_add_u32 s36, s3, s36
	s_addc_u32 s37, s33, s37
	s_and_b64 s[44:45], s[6:7], exec
	s_cselect_b32 s15, s37, s43
	s_cselect_b32 s49, s36, s42
	s_add_u32 s40, s40, 0x80080
	s_addc_u32 s41, s41, 0
	s_add_u32 s50, s42, 0x100
	s_addc_u32 s51, s43, 0
	s_mov_b32 s52, -2
	ds_read_b128 v[146:149], v153
	ds_read_b128 v[156:159], v153 offset:1024
	ds_read_b128 v[160:163], v153 offset:2048
	ds_read_b128 v[164:167], v153 offset:3072
	ds_read_b128 v[168:171], v154
	ds_read_b128 v[172:175], v154 offset:1024
	ds_read_b128 v[176:179], v154 offset:2048
	ds_read_b128 v[180:183], v154 offset:3072
	s_add_u32 s42, s40, 0xfff80080
	s_addc_u32 s43, s41, -1
	s_cmp_eq_u32 s52, 28
	s_cselect_b32 s45, s21, s43
	s_cselect_b32 s44, s48, s42
	s_cselect_b32 s43, s15, s51
	s_cselect_b32 s42, s49, s50
	v_lshl_add_u64 v[216:217], s[40:41], 0, v[138:139]
	s_add_i32 m0, s19, 0xc000
	ds_read_b128 v[184:187], v155
	ds_read_b128 v[188:191], v155 offset:1024
	ds_read_b128 v[192:195], v155 offset:2048
	ds_read_b128 v[196:199], v155 offset:3072
	ds_read_b128 v[200:203], v155 offset:4096
	ds_read_b128 v[204:207], v155 offset:5120
	ds_read_b128 v[208:211], v155 offset:6144
	ds_read_b128 v[212:215], v155 offset:7168
	global_load_lds_dwordx4 v[216:217], off
	v_lshl_add_u64 v[216:217], s[40:41], 0, v[140:141]
	s_add_i32 m0, s19, 0xe000
	s_nop 0
	global_load_lds_dwordx4 v[216:217], off
	s_waitcnt vmcnt(8)
	s_waitcnt lgkmcnt(0)
	s_barrier
	s_setprio 1
	s_waitcnt lgkmcnt(0)
	v_mfma_f32_16x16x32_bf16 v[126:129], v[146:149], v[184:187], 0
	v_mfma_f32_16x16x32_bf16 v[122:125], v[160:163], v[184:187], 0
	v_mfma_f32_16x16x32_bf16 v[110:113], v[146:149], v[192:195], 0
	v_mfma_f32_16x16x32_bf16 v[106:109], v[160:163], v[192:195], 0
	v_mfma_f32_16x16x32_bf16 v[94:97], v[146:149], v[200:203], 0
	v_mfma_f32_16x16x32_bf16 v[90:93], v[160:163], v[200:203], 0
	v_mfma_f32_16x16x32_bf16 v[78:81], v[146:149], v[208:211], 0
	v_mfma_f32_16x16x32_bf16 v[74:77], v[160:163], v[208:211], 0
	v_mfma_f32_16x16x32_bf16 v[126:129], v[156:159], v[188:191], v[126:129]
	v_mfma_f32_16x16x32_bf16 v[122:125], v[164:167], v[188:191], v[122:125]
	v_mfma_f32_16x16x32_bf16 v[110:113], v[156:159], v[196:199], v[110:113]
	v_mfma_f32_16x16x32_bf16 v[106:109], v[164:167], v[196:199], v[106:109]
	v_mfma_f32_16x16x32_bf16 v[94:97], v[156:159], v[204:207], v[94:97]
	v_mfma_f32_16x16x32_bf16 v[90:93], v[164:167], v[204:207], v[90:93]
	v_mfma_f32_16x16x32_bf16 v[78:81], v[156:159], v[212:215], v[78:81]
	v_mfma_f32_16x16x32_bf16 v[74:77], v[164:167], v[212:215], v[74:77]
	s_setprio 0
	s_setprio 1
	v_mfma_f32_16x16x32_bf16 v[118:121], v[168:171], v[184:187], 0
	v_mfma_f32_16x16x32_bf16 v[114:117], v[176:179], v[184:187], 0
	v_mfma_f32_16x16x32_bf16 v[102:105], v[168:171], v[192:195], 0
	v_mfma_f32_16x16x32_bf16 v[98:101], v[176:179], v[192:195], 0
	v_mfma_f32_16x16x32_bf16 v[86:89], v[168:171], v[200:203], 0
	v_mfma_f32_16x16x32_bf16 v[82:85], v[176:179], v[200:203], 0
	v_mfma_f32_16x16x32_bf16 v[70:73], v[168:171], v[208:211], 0
	v_mfma_f32_16x16x32_bf16 v[66:69], v[176:179], v[208:211], 0
	v_mfma_f32_16x16x32_bf16 v[118:121], v[172:175], v[188:191], v[118:121]
	v_mfma_f32_16x16x32_bf16 v[114:117], v[180:183], v[188:191], v[114:117]
	v_mfma_f32_16x16x32_bf16 v[102:105], v[172:175], v[196:199], v[102:105]
	v_mfma_f32_16x16x32_bf16 v[98:101], v[180:183], v[196:199], v[98:101]
	v_mfma_f32_16x16x32_bf16 v[86:89], v[172:175], v[204:207], v[86:89]
	v_mfma_f32_16x16x32_bf16 v[82:85], v[180:183], v[204:207], v[82:85]
	v_mfma_f32_16x16x32_bf16 v[70:73], v[172:175], v[212:215], v[70:73]
	v_mfma_f32_16x16x32_bf16 v[66:69], v[180:183], v[212:215], v[66:69]
	s_setprio 0
	s_barrier
	s_add_i32 s53, s31, s16
	v_lshl_add_u64 v[216:217], s[42:43], 0, v[134:135]
	s_mov_b32 m0, s53
	ds_read_b128 v[184:187], v155 offset:16384
	ds_read_b128 v[188:191], v155 offset:17408
	ds_read_b128 v[192:195], v155 offset:18432
	ds_read_b128 v[196:199], v155 offset:19456
	ds_read_b128 v[200:203], v155 offset:20480
	ds_read_b128 v[204:207], v155 offset:21504
	ds_read_b128 v[208:211], v155 offset:22528
	ds_read_b128 v[212:215], v155 offset:23552
	global_load_lds_dwordx4 v[216:217], off
	s_add_i32 m0, s53, 0x2000
	s_add_u32 s54, s42, 0x80000
	v_lshl_add_u64 v[218:219], s[42:43], 0, v[130:131]
	s_addc_u32 s55, s43, 0
	s_add_i32 s53, s39, s16
	global_load_lds_dwordx4 v[218:219], off
	v_lshl_add_u64 v[220:221], s[54:55], 0, v[134:135]
	s_mov_b32 m0, s53
	v_lshl_add_u64 v[222:223], s[44:45], 0, v[132:133]
	global_load_lds_dwordx4 v[220:221], off
	v_lshl_add_u64 v[220:221], s[54:55], 0, v[130:131]
	s_add_i32 m0, s53, 0x2000
	s_nop 0
	global_load_lds_dwordx4 v[220:221], off
	v_lshl_add_u64 v[220:221], s[44:45], 0, v[136:137]
	s_mov_b32 m0, s19
	s_nop 0
	global_load_lds_dwordx4 v[220:221], off
	s_mov_b32 m0, s24
	s_nop 0
	global_load_lds_dwordx4 v[222:223], off
	s_waitcnt vmcnt(8)
	s_waitcnt lgkmcnt(0)
	s_barrier
; #define PG8_STAGE(bufoff, gbase, voff) do { _Pragma("unroll") for (int _i = 0; _i < 2; ++_i) \
;         __builtin_amdgcn_global_load_lds((const unsigned*)((const char*)(gbase) + (voff)[_i]), (PG8_LAS unsigned*)(lds + (bufoff) + ldsw + _i * 8192), 16, 0, 0); } while (0)
; #define PG8_LDA(dst, b, h) do { _Pragma("unroll") for (int m = 0; m < 4; ++m) _Pragma("unroll") for (int k = 0; k < 2; ++k) dst[m][k] = *(const PG8_LAS bf16x8*)(lds + PG8_SA(b, h) + aoff + m * 2048 + k * 1024); } while (0)
; #define PG8_LDB(dst, b, h) do { _Pragma("unroll") for (int n = 0; n < 2; ++n) _Pragma("unroll") for (int k = 0; k < 2; ++k) dst[n][k] = *(const PG8_LAS bf16x8*)(lds + PG8_SB(b, h) + boff + n * 2048 + k * 1024); } while (0)
; #define PG8_MMA(ai, bj, At, Bt) do { __builtin_amdgcn_s_setprio(1); _Pragma("unroll") for (int m = 0; m < 4; ++m) _Pragma("unroll") for (int n = 0; n < 2; ++n) _Pragma("unroll") for (int k = 0; k < 2; ++k) \
;         acc[ai][bj][m][n] = __builtin_amdgcn_mfma_f32_16x16x32_bf16(Bt[n][k], At[m][k], acc[ai][bj][m][n], 0, 0, 0); __builtin_amdgcn_s_setprio(0); } while (0)
; #define PG8_WAIT_V(n) asm volatile("s_waitcnt vmcnt(" #n ")" ::: "memory")
; #define PG8_WAIT_L(n) asm volatile("s_waitcnt lgkmcnt(" #n ")" ::: "memory")
; #define PG8_BAR __builtin_amdgcn_s_barrier()
; #define PG8_SCHED __builtin_amdgcn_sched_barrier(0)
; template <class Epi, class Sched, bool ALIGN_EPI = false, bool SP2 = false>
; __device__ __forceinline__ void gemm_phase(PG8_LAS unsigned char* lds, const Gemm g, const Sched& S, const Epi& E) {
;     ...
;             PG8_WAIT_V(8); PG8_WAIT_L(0); PG8_BAR; PG8_MMA(1, 0, At, B0); PG8_MMA(1, 1, At, B1); PG8_BAR; PG8_SCHED;
;             PG8_LDB(B0, 1, 0); PG8_LDB(B1, 1, 1); PG8_SCHED; PG8_LDA(At, 1, 0); PG8_STAGE(PG8_SA(0, 1), a2 + hstep, voffA);
;             PG8_WAIT_V(8); PG8_WAIT_L(0); PG8_BAR; PG8_MMA(0, 0, At, B0); PG8_MMA(0, 1, At, B1); PG8_BAR; PG8_SCHED;
;             PG8_LDA(At, 1, 1); PG8_STAGE(PG8_SB(1, 0), b3, voffB); PG8_STAGE(PG8_SB(1, 1), b3 + hstep, voffB); PG8_STAGE(PG8_SA(1, 0), a3, voffA);
	s_setprio 1
	s_waitcnt lgkmcnt(0)
	v_mfma_f32_16x16x32_bf16 v[62:65], v[146:149], v[184:187], 0
	v_mfma_f32_16x16x32_bf16 v[58:61], v[160:163], v[184:187], 0
	v_mfma_f32_16x16x32_bf16 v[46:49], v[146:149], v[192:195], 0
	v_mfma_f32_16x16x32_bf16 v[42:45], v[160:163], v[192:195], 0
	v_mfma_f32_16x16x32_bf16 v[30:33], v[146:149], v[200:203], 0
	v_mfma_f32_16x16x32_bf16 v[26:29], v[160:163], v[200:203], 0
	v_mfma_f32_16x16x32_bf16 v[14:17], v[146:149], v[208:211], 0
	v_mfma_f32_16x16x32_bf16 v[10:13], v[160:163], v[208:211], 0
	v_mfma_f32_16x16x32_bf16 v[62:65], v[156:159], v[188:191], v[62:65]
	v_mfma_f32_16x16x32_bf16 v[58:61], v[164:167], v[188:191], v[58:61]
	v_mfma_f32_16x16x32_bf16 v[46:49], v[156:159], v[196:199], v[46:49]
	v_mfma_f32_16x16x32_bf16 v[42:45], v[164:167], v[196:199], v[42:45]
	v_mfma_f32_16x16x32_bf16 v[30:33], v[156:159], v[204:207], v[30:33]
	v_mfma_f32_16x16x32_bf16 v[26:29], v[164:167], v[204:207], v[26:29]
	v_mfma_f32_16x16x32_bf16 v[14:17], v[156:159], v[212:215], v[14:17]
	v_mfma_f32_16x16x32_bf16 v[10:13], v[164:167], v[212:215], v[10:13]
	s_setprio 0
	s_setprio 1
	v_mfma_f32_16x16x32_bf16 v[54:57], v[168:171], v[184:187], 0
	v_mfma_f32_16x16x32_bf16 v[50:53], v[176:179], v[184:187], 0
	v_mfma_f32_16x16x32_bf16 v[38:41], v[168:171], v[192:195], 0
	v_mfma_f32_16x16x32_bf16 v[34:37], v[176:179], v[192:195], 0
	v_mfma_f32_16x16x32_bf16 v[22:25], v[168:171], v[200:203], 0
	v_mfma_f32_16x16x32_bf16 v[18:21], v[176:179], v[200:203], 0
	v_mfma_f32_16x16x32_bf16 v[6:9], v[168:171], v[208:211], 0
	v_mfma_f32_16x16x32_bf16 v[2:5], v[176:179], v[208:211], 0
	v_mfma_f32_16x16x32_bf16 v[54:57], v[172:175], v[188:191], v[54:57]
	v_mfma_f32_16x16x32_bf16 v[50:53], v[180:183], v[188:191], v[50:53]
	v_mfma_f32_16x16x32_bf16 v[38:41], v[172:175], v[196:199], v[38:41]
	v_mfma_f32_16x16x32_bf16 v[34:37], v[180:183], v[196:199], v[34:37]
	v_mfma_f32_16x16x32_bf16 v[22:25], v[172:175], v[204:207], v[22:25]
	v_mfma_f32_16x16x32_bf16 v[18:21], v[180:183], v[204:207], v[18:21]
	v_mfma_f32_16x16x32_bf16 v[6:9], v[172:175], v[212:215], v[6:9]
	v_mfma_f32_16x16x32_bf16 v[2:5], v[180:183], v[212:215], v[2:5]
	s_setprio 0
	s_barrier
	s_add_i32 s53, 0, 0x18000
	s_add_i32 s54, 0, 0x1c000
	v_add_u32_e32 v164, s53, v151
	v_add_u32_e32 v180, s54, v151
	ds_read_b128 v[146:149], v164
	ds_read_b128 v[156:159], v164 offset:1024
	ds_read_b128 v[160:163], v164 offset:2048
	ds_read_b128 v[164:167], v164 offset:3072
	ds_read_b128 v[168:171], v180
	ds_read_b128 v[172:175], v180 offset:1024
	ds_read_b128 v[176:179], v180 offset:2048
	ds_read_b128 v[180:183], v180 offset:3072
	s_add_u32 s44, s44, 0x80000
	s_addc_u32 s45, s45, 0
	s_mov_b32 m0, s25
	v_lshl_add_u64 v[224:225], s[44:45], 0, v[136:137]
	ds_read_b128 v[184:187], v155 offset:32768
	ds_read_b128 v[188:191], v155 offset:33792
	ds_read_b128 v[192:195], v155 offset:34816
	ds_read_b128 v[196:199], v155 offset:35840
	ds_read_b128 v[200:203], v155 offset:36864
	ds_read_b128 v[204:207], v155 offset:37888
	ds_read_b128 v[208:211], v155 offset:38912
	ds_read_b128 v[212:215], v155 offset:39936
	global_load_lds_dwordx4 v[224:225], off
	v_lshl_add_u64 v[224:225], s[44:45], 0, v[132:133]
	s_mov_b32 m0, s26
	s_nop 0
	global_load_lds_dwordx4 v[224:225], off
	s_waitcnt vmcnt(8)
	s_waitcnt lgkmcnt(0)
	s_barrier
	s_setprio 1
	s_waitcnt lgkmcnt(0)
	v_mfma_f32_16x16x32_bf16 v[126:129], v[146:149], v[184:187], v[126:129]
	v_mfma_f32_16x16x32_bf16 v[122:125], v[160:163], v[184:187], v[122:125]
	v_mfma_f32_16x16x32_bf16 v[110:113], v[146:149], v[192:195], v[110:113]
	v_mfma_f32_16x16x32_bf16 v[106:109], v[160:163], v[192:195], v[106:109]
	v_mfma_f32_16x16x32_bf16 v[94:97], v[146:149], v[200:203], v[94:97]
	v_mfma_f32_16x16x32_bf16 v[90:93], v[160:163], v[200:203], v[90:93]
	v_mfma_f32_16x16x32_bf16 v[78:81], v[146:149], v[208:211], v[78:81]
	v_mfma_f32_16x16x32_bf16 v[74:77], v[160:163], v[208:211], v[74:77]
	v_mfma_f32_16x16x32_bf16 v[126:129], v[156:159], v[188:191], v[126:129]
	v_mfma_f32_16x16x32_bf16 v[122:125], v[164:167], v[188:191], v[122:125]
	v_mfma_f32_16x16x32_bf16 v[110:113], v[156:159], v[196:199], v[110:113]
	v_mfma_f32_16x16x32_bf16 v[106:109], v[164:167], v[196:199], v[106:109]
	v_mfma_f32_16x16x32_bf16 v[94:97], v[156:159], v[204:207], v[94:97]
	v_mfma_f32_16x16x32_bf16 v[90:93], v[164:167], v[204:207], v[90:93]
	v_mfma_f32_16x16x32_bf16 v[78:81], v[156:159], v[212:215], v[78:81]
	v_mfma_f32_16x16x32_bf16 v[74:77], v[164:167], v[212:215], v[74:77]
	s_setprio 0
	s_setprio 1
	v_mfma_f32_16x16x32_bf16 v[118:121], v[168:171], v[184:187], v[118:121]
	v_mfma_f32_16x16x32_bf16 v[114:117], v[176:179], v[184:187], v[114:117]
	v_mfma_f32_16x16x32_bf16 v[102:105], v[168:171], v[192:195], v[102:105]
	v_mfma_f32_16x16x32_bf16 v[98:101], v[176:179], v[192:195], v[98:101]
	v_mfma_f32_16x16x32_bf16 v[86:89], v[168:171], v[200:203], v[86:89]
	v_mfma_f32_16x16x32_bf16 v[82:85], v[176:179], v[200:203], v[82:85]
	v_mfma_f32_16x16x32_bf16 v[70:73], v[168:171], v[208:211], v[70:73]
	v_mfma_f32_16x16x32_bf16 v[66:69], v[176:179], v[208:211], v[66:69]
	v_mfma_f32_16x16x32_bf16 v[118:121], v[172:175], v[188:191], v[118:121]
	v_mfma_f32_16x16x32_bf16 v[114:117], v[180:183], v[188:191], v[114:117]
	v_mfma_f32_16x16x32_bf16 v[102:105], v[172:175], v[196:199], v[102:105]
	v_mfma_f32_16x16x32_bf16 v[98:101], v[180:183], v[196:199], v[98:101]
	v_mfma_f32_16x16x32_bf16 v[86:89], v[172:175], v[204:207], v[86:89]
	v_mfma_f32_16x16x32_bf16 v[82:85], v[180:183], v[204:207], v[82:85]
	v_mfma_f32_16x16x32_bf16 v[70:73], v[172:175], v[212:215], v[70:73]
	v_mfma_f32_16x16x32_bf16 v[66:69], v[180:183], v[212:215], v[66:69]
	s_setprio 0
	s_barrier
; #define PG8_STAGE(bufoff, gbase, voff) do { _Pragma("unroll") for (int _i = 0; _i < 2; ++_i) \
;         __builtin_amdgcn_global_load_lds((const unsigned*)((const char*)(gbase) + (voff)[_i]), (PG8_LAS unsigned*)(lds + (bufoff) + ldsw + _i * 8192), 16, 0, 0); } while (0)
; #define PG8_LDA(dst, b, h) do { _Pragma("unroll") for (int m = 0; m < 4; ++m) _Pragma("unroll") for (int k = 0; k < 2; ++k) dst[m][k] = *(const PG8_LAS bf16x8*)(lds + PG8_SA(b, h) + aoff + m * 2048 + k * 1024); } while (0)
; #define PG8_LDB(dst, b, h) do { _Pragma("unroll") for (int n = 0; n < 2; ++n) _Pragma("unroll") for (int k = 0; k < 2; ++k) dst[n][k] = *(const PG8_LAS bf16x8*)(lds + PG8_SB(b, h) + boff + n * 2048 + k * 1024); } while (0)
; #define PG8_MMA(ai, bj, At, Bt) do { __builtin_amdgcn_s_setprio(1); _Pragma("unroll") for (int m = 0; m < 4; ++m) _Pragma("unroll") for (int n = 0; n < 2; ++n) _Pragma("unroll") for (int k = 0; k < 2; ++k) \
;         acc[ai][bj][m][n] = __builtin_amdgcn_mfma_f32_16x16x32_bf16(Bt[n][k], At[m][k], acc[ai][bj][m][n], 0, 0, 0); __builtin_amdgcn_s_setprio(0); } while (0)
; #define PG8_WAIT_V(n) asm volatile("s_waitcnt vmcnt(" #n ")" ::: "memory")
; template <class Epi, class Sched, bool ALIGN_EPI = false, bool SP2 = false>
; __device__ __forceinline__ void gemm_phase(PG8_LAS unsigned char* lds, const Gemm g, const Sched& S, const Epi& E) {
;     ...
;             PG8_LDB(B0, 0, 0); PG8_LDB(B1, 0, 1); PG8_SCHED; PG8_LDA(At, 0, 0); PG8_STAGE(PG8_SA(1, 1), a1 + hstep, voffA);
;             PG8_WAIT_V(8); PG8_WAIT_L(0); PG8_BAR; PG8_MMA(0, 0, At, B0); PG8_MMA(0, 1, At, B1); PG8_BAR; PG8_SCHED;
;             PG8_LDA(At, 0, 1); PG8_STAGE(PG8_SB(0, 0), b2, voffB); PG8_STAGE(PG8_SB(0, 1), b2 + hstep, voffB); PG8_STAGE(PG8_SA(0, 0), a2, voffA);
;             PG8_WAIT_V(8); PG8_WAIT_L(0); PG8_BAR; PG8_MMA(1, 0, At, B0); PG8_MMA(1, 1, At, B1); PG8_BAR; PG8_SCHED;
;             PG8_LDB(B0, 1, 0); PG8_LDB(B1, 1, 1); PG8_SCHED; PG8_LDA(At, 1, 0); PG8_STAGE(PG8_SA(0, 1), a2 + hstep, voffA);
;             PG8_WAIT_V(8); PG8_WAIT_L(0); PG8_BAR; PG8_MMA(0, 0, At, B0); PG8_MMA(0, 1, At, B1); PG8_BAR; PG8_SCHED;
;             PG8_LDA(At, 1, 1); PG8_STAGE(PG8_SB(1, 0), b3, voffB); PG8_STAGE(PG8_SB(1, 1), b3 + hstep, voffB); PG8_STAGE(PG8_SA(1, 0), a3, voffA);
;             PG8_WAIT_V(8); PG8_WAIT_L(0); PG8_BAR; PG8_MMA(1, 0, At, B0); PG8_MMA(1, 1, At, B1); PG8_BAR; PG8_SCHED;
	s_add_i32 s44, s53, s16
	v_lshl_add_u64 v[216:217], v[216:217], 0, s[10:11]
	s_mov_b32 m0, s44
	ds_read_b128 v[184:187], v155 offset:49152
	ds_read_b128 v[188:191], v155 offset:50176
	ds_read_b128 v[192:195], v155 offset:51200
	ds_read_b128 v[196:199], v155 offset:52224
	ds_read_b128 v[200:203], v155 offset:53248
	ds_read_b128 v[204:207], v155 offset:54272
	ds_read_b128 v[208:211], v155 offset:55296
	ds_read_b128 v[212:215], v155 offset:56320
	global_load_lds_dwordx4 v[216:217], off
	s_add_i32 m0, s44, 0x2000
	s_add_u32 s42, s42, 0x80080
	v_lshl_add_u64 v[216:217], v[218:219], 0, s[10:11]
	s_addc_u32 s43, s43, 0
	s_add_i32 s44, s54, s16
	global_load_lds_dwordx4 v[216:217], off
	v_lshl_add_u64 v[216:217], s[42:43], 0, v[134:135]
	s_mov_b32 m0, s44
	s_nop 0
	global_load_lds_dwordx4 v[216:217], off
	v_lshl_add_u64 v[216:217], s[42:43], 0, v[130:131]
	s_add_i32 m0, s44, 0x2000
	s_nop 0
	global_load_lds_dwordx4 v[216:217], off
	v_lshl_add_u64 v[216:217], v[220:221], 0, s[10:11]
	s_mov_b32 m0, s29
	s_nop 0
	global_load_lds_dwordx4 v[216:217], off
	v_lshl_add_u64 v[216:217], v[222:223], 0, s[10:11]
	s_mov_b32 m0, s30
	s_nop 0
	global_load_lds_dwordx4 v[216:217], off
	s_waitcnt vmcnt(8)
	s_waitcnt lgkmcnt(0)
	s_barrier
	s_setprio 1
	s_waitcnt lgkmcnt(0)
	v_mfma_f32_16x16x32_bf16 v[62:65], v[146:149], v[184:187], v[62:65]
	v_mfma_f32_16x16x32_bf16 v[58:61], v[160:163], v[184:187], v[58:61]
	v_mfma_f32_16x16x32_bf16 v[46:49], v[146:149], v[192:195], v[46:49]
	v_mfma_f32_16x16x32_bf16 v[42:45], v[160:163], v[192:195], v[42:45]
	v_mfma_f32_16x16x32_bf16 v[30:33], v[146:149], v[200:203], v[30:33]
	v_mfma_f32_16x16x32_bf16 v[26:29], v[160:163], v[200:203], v[26:29]
	v_mfma_f32_16x16x32_bf16 v[14:17], v[146:149], v[208:211], v[14:17]
	v_mfma_f32_16x16x32_bf16 v[10:13], v[160:163], v[208:211], v[10:13]
	v_mfma_f32_16x16x32_bf16 v[62:65], v[156:159], v[188:191], v[62:65]
	v_mfma_f32_16x16x32_bf16 v[58:61], v[164:167], v[188:191], v[58:61]
	v_mfma_f32_16x16x32_bf16 v[46:49], v[156:159], v[196:199], v[46:49]
	v_mfma_f32_16x16x32_bf16 v[42:45], v[164:167], v[196:199], v[42:45]
	v_mfma_f32_16x16x32_bf16 v[30:33], v[156:159], v[204:207], v[30:33]
	v_mfma_f32_16x16x32_bf16 v[26:29], v[164:167], v[204:207], v[26:29]
	v_mfma_f32_16x16x32_bf16 v[14:17], v[156:159], v[212:215], v[14:17]
	v_mfma_f32_16x16x32_bf16 v[10:13], v[164:167], v[212:215], v[10:13]
	s_setprio 0
	s_setprio 1
	v_mfma_f32_16x16x32_bf16 v[54:57], v[168:171], v[184:187], v[54:57]
	v_mfma_f32_16x16x32_bf16 v[50:53], v[176:179], v[184:187], v[50:53]
	v_mfma_f32_16x16x32_bf16 v[38:41], v[168:171], v[192:195], v[38:41]
	v_mfma_f32_16x16x32_bf16 v[34:37], v[176:179], v[192:195], v[34:37]
	v_mfma_f32_16x16x32_bf16 v[22:25], v[168:171], v[200:203], v[22:25]
	v_mfma_f32_16x16x32_bf16 v[18:21], v[176:179], v[200:203], v[18:21]
	v_mfma_f32_16x16x32_bf16 v[6:9], v[168:171], v[208:211], v[6:9]
	v_mfma_f32_16x16x32_bf16 v[2:5], v[176:179], v[208:211], v[2:5]
	v_mfma_f32_16x16x32_bf16 v[54:57], v[172:175], v[188:191], v[54:57]
	v_mfma_f32_16x16x32_bf16 v[50:53], v[180:183], v[188:191], v[50:53]
	v_mfma_f32_16x16x32_bf16 v[38:41], v[172:175], v[196:199], v[38:41]
	v_mfma_f32_16x16x32_bf16 v[34:37], v[180:183], v[196:199], v[34:37]
	v_mfma_f32_16x16x32_bf16 v[22:25], v[172:175], v[204:207], v[22:25]
	v_mfma_f32_16x16x32_bf16 v[18:21], v[180:183], v[204:207], v[18:21]
	v_mfma_f32_16x16x32_bf16 v[6:9], v[172:175], v[212:215], v[6:9]
	v_mfma_f32_16x16x32_bf16 v[2:5], v[180:183], v[212:215], v[2:5]
	s_setprio 0
	s_barrier
	s_add_i32 s52, s52, 2
	s_add_u32 s40, s40, 0x100
	s_addc_u32 s41, s41, 0
	s_add_u32 s50, s50, 0x100
	s_addc_u32 s51, s51, 0
	s_cmp_gt_u32 s52, 29
	s_cbranch_scc1 .Lkx_88
.LBB0_88:
	ds_read_b128 v[146:149], v153
	ds_read_b128 v[156:159], v153 offset:1024
	ds_read_b128 v[160:163], v153 offset:2048
	ds_read_b128 v[164:167], v153 offset:3072
	ds_read_b128 v[168:171], v154
	ds_read_b128 v[172:175], v154 offset:1024
	ds_read_b128 v[176:179], v154 offset:2048
	ds_read_b128 v[180:183], v154 offset:3072
	s_add_u32 s42, s40, 0xfff80080
	s_addc_u32 s43, s41, -1
	s_cmp_eq_u32 s52, 28
	s_cselect_b32 s45, s21, s43
	s_cselect_b32 s44, s48, s42
	s_cselect_b32 s43, s15, s51
	s_cselect_b32 s42, s49, s50
	v_lshl_add_u64 v[216:217], s[40:41], 0, v[138:139]
	s_add_i32 m0, s19, 0xc000
	ds_read_b128 v[184:187], v155
	ds_read_b128 v[188:191], v155 offset:1024
	ds_read_b128 v[192:195], v155 offset:2048
	ds_read_b128 v[196:199], v155 offset:3072
	ds_read_b128 v[200:203], v155 offset:4096
	ds_read_b128 v[204:207], v155 offset:5120
	ds_read_b128 v[208:211], v155 offset:6144
	ds_read_b128 v[212:215], v155 offset:7168
	global_load_lds_dwordx4 v[216:217], off
	v_lshl_add_u64 v[216:217], s[40:41], 0, v[140:141]
	s_add_i32 m0, s19, 0xe000
	s_nop 0
	global_load_lds_dwordx4 v[216:217], off
	s_waitcnt vmcnt(8)
	s_waitcnt lgkmcnt(0)
	s_barrier
; #define PG8_STAGE(bufoff, gbase, voff) do { _Pragma("unroll") for (int _i = 0; _i < 2; ++_i) \
;         __builtin_amdgcn_global_load_lds((const unsigned*)((const char*)(gbase) + (voff)[_i]), (PG8_LAS unsigned*)(lds + (bufoff) + ldsw + _i * 8192), 16, 0, 0); } while (0)
; #define PG8_LDA(dst, b, h) do { _Pragma("unroll") for (int m = 0; m < 4; ++m) _Pragma("unroll") for (int k = 0; k < 2; ++k) dst[m][k] = *(const PG8_LAS bf16x8*)(lds + PG8_SA(b, h) + aoff + m * 2048 + k * 1024); } while (0)
; #define PG8_LDB(dst, b, h) do { _Pragma("unroll") for (int n = 0; n < 2; ++n) _Pragma("unroll") for (int k = 0; k < 2; ++k) dst[n][k] = *(const PG8_LAS bf16x8*)(lds + PG8_SB(b, h) + boff + n * 2048 + k * 1024); } while (0)
; #define PG8_MMA(ai, bj, At, Bt) do { __builtin_amdgcn_s_setprio(1); _Pragma("unroll") for (int m = 0; m < 4; ++m) _Pragma("unroll") for (int n = 0; n < 2; ++n) _Pragma("unroll") for (int k = 0; k < 2; ++k) \
;         acc[ai][bj][m][n] = __builtin_amdgcn_mfma_f32_16x16x32_bf16(Bt[n][k], At[m][k], acc[ai][bj][m][n], 0, 0, 0); __builtin_amdgcn_s_setprio(0); } while (0)
; #define PG8_WAIT_V(n) asm volatile("s_waitcnt vmcnt(" #n ")" ::: "memory")
; #define PG8_WAIT_L(n) asm volatile("s_waitcnt lgkmcnt(" #n ")" ::: "memory")
; #define PG8_BAR __builtin_amdgcn_s_barrier()
; #define PG8_SCHED __builtin_amdgcn_sched_barrier(0)
; template <class Epi, class Sched, bool ALIGN_EPI = false, bool SP2 = false>
; __device__ __forceinline__ void gemm_phase(PG8_LAS unsigned char* lds, const Gemm g, const Sched& S, const Epi& E) {
;     ...
;             PG8_WAIT_V(8); PG8_WAIT_L(0); PG8_BAR; PG8_MMA(0, 0, At, B0); PG8_MMA(0, 1, At, B1); PG8_BAR; PG8_SCHED;
;             PG8_LDA(At, 0, 1); PG8_STAGE(PG8_SB(0, 0), b2, voffB); PG8_STAGE(PG8_SB(0, 1), b2 + hstep, voffB); PG8_STAGE(PG8_SA(0, 0), a2, voffA);
;             PG8_WAIT_V(8); PG8_WAIT_L(0); PG8_BAR; PG8_MMA(1, 0, At, B0); PG8_MMA(1, 1, At, B1); PG8_BAR; PG8_SCHED;
;             PG8_LDB(B0, 1, 0); PG8_LDB(B1, 1, 1); PG8_SCHED; PG8_LDA(At, 1, 0); PG8_STAGE(PG8_SA(0, 1), a2 + hstep, voffA);
	s_setprio 1
	s_waitcnt lgkmcnt(0)
	v_mfma_f32_16x16x32_bf16 v[126:129], v[146:149], v[184:187], v[126:129]
	v_mfma_f32_16x16x32_bf16 v[122:125], v[160:163], v[184:187], v[122:125]
	v_mfma_f32_16x16x32_bf16 v[110:113], v[146:149], v[192:195], v[110:113]
	v_mfma_f32_16x16x32_bf16 v[106:109], v[160:163], v[192:195], v[106:109]
	v_mfma_f32_16x16x32_bf16 v[94:97], v[146:149], v[200:203], v[94:97]
	v_mfma_f32_16x16x32_bf16 v[90:93], v[160:163], v[200:203], v[90:93]
	v_mfma_f32_16x16x32_bf16 v[78:81], v[146:149], v[208:211], v[78:81]
	v_mfma_f32_16x16x32_bf16 v[74:77], v[160:163], v[208:211], v[74:77]
	v_mfma_f32_16x16x32_bf16 v[126:129], v[156:159], v[188:191], v[126:129]
	v_mfma_f32_16x16x32_bf16 v[122:125], v[164:167], v[188:191], v[122:125]
	v_mfma_f32_16x16x32_bf16 v[110:113], v[156:159], v[196:199], v[110:113]
	v_mfma_f32_16x16x32_bf16 v[106:109], v[164:167], v[196:199], v[106:109]
	v_mfma_f32_16x16x32_bf16 v[94:97], v[156:159], v[204:207], v[94:97]
	v_mfma_f32_16x16x32_bf16 v[90:93], v[164:167], v[204:207], v[90:93]
	v_mfma_f32_16x16x32_bf16 v[78:81], v[156:159], v[212:215], v[78:81]
	v_mfma_f32_16x16x32_bf16 v[74:77], v[164:167], v[212:215], v[74:77]
	s_setprio 0
	s_setprio 1
	v_mfma_f32_16x16x32_bf16 v[118:121], v[168:171], v[184:187], v[118:121]
	v_mfma_f32_16x16x32_bf16 v[114:117], v[176:179], v[184:187], v[114:117]
	v_mfma_f32_16x16x32_bf16 v[102:105], v[168:171], v[192:195], v[102:105]
	v_mfma_f32_16x16x32_bf16 v[98:101], v[176:179], v[192:195], v[98:101]
	v_mfma_f32_16x16x32_bf16 v[86:89], v[168:171], v[200:203], v[86:89]
	v_mfma_f32_16x16x32_bf16 v[82:85], v[176:179], v[200:203], v[82:85]
	v_mfma_f32_16x16x32_bf16 v[70:73], v[168:171], v[208:211], v[70:73]
	v_mfma_f32_16x16x32_bf16 v[66:69], v[176:179], v[208:211], v[66:69]
	v_mfma_f32_16x16x32_bf16 v[118:121], v[172:175], v[188:191], v[118:121]
	v_mfma_f32_16x16x32_bf16 v[114:117], v[180:183], v[188:191], v[114:117]
	v_mfma_f32_16x16x32_bf16 v[102:105], v[172:175], v[196:199], v[102:105]
	v_mfma_f32_16x16x32_bf16 v[98:101], v[180:183], v[196:199], v[98:101]
	v_mfma_f32_16x16x32_bf16 v[86:89], v[172:175], v[204:207], v[86:89]
	v_mfma_f32_16x16x32_bf16 v[82:85], v[180:183], v[204:207], v[82:85]
	v_mfma_f32_16x16x32_bf16 v[70:73], v[172:175], v[212:215], v[70:73]
	v_mfma_f32_16x16x32_bf16 v[66:69], v[180:183], v[212:215], v[66:69]
	s_setprio 0
	s_barrier
	s_add_i32 s53, s31, s16
	v_lshl_add_u64 v[216:217], s[42:43], 0, v[134:135]
	s_mov_b32 m0, s53
	ds_read_b128 v[184:187], v155 offset:16384
	ds_read_b128 v[188:191], v155 offset:17408
	ds_read_b128 v[192:195], v155 offset:18432
	ds_read_b128 v[196:199], v155 offset:19456
	ds_read_b128 v[200:203], v155 offset:20480
	ds_read_b128 v[204:207], v155 offset:21504
	ds_read_b128 v[208:211], v155 offset:22528
	ds_read_b128 v[212:215], v155 offset:23552
	global_load_lds_dwordx4 v[216:217], off
	s_add_i32 m0, s53, 0x2000
	s_add_u32 s54, s42, 0x80000
	v_lshl_add_u64 v[218:219], s[42:43], 0, v[130:131]
	s_addc_u32 s55, s43, 0
	s_add_i32 s53, s39, s16
	global_load_lds_dwordx4 v[218:219], off
	v_lshl_add_u64 v[220:221], s[54:55], 0, v[134:135]
	s_mov_b32 m0, s53
	v_lshl_add_u64 v[222:223], s[44:45], 0, v[132:133]
	global_load_lds_dwordx4 v[220:221], off
	v_lshl_add_u64 v[220:221], s[54:55], 0, v[130:131]
	s_add_i32 m0, s53, 0x2000
	s_nop 0
	global_load_lds_dwordx4 v[220:221], off
	v_lshl_add_u64 v[220:221], s[44:45], 0, v[136:137]
	s_mov_b32 m0, s19
	s_nop 0
	global_load_lds_dwordx4 v[220:221], off
	s_mov_b32 m0, s24
	s_nop 0
	global_load_lds_dwordx4 v[222:223], off
	s_waitcnt vmcnt(8)
	s_waitcnt lgkmcnt(0)
	s_barrier
	s_setprio 1
	s_waitcnt lgkmcnt(0)
	v_mfma_f32_16x16x32_bf16 v[62:65], v[146:149], v[184:187], v[62:65]
	v_mfma_f32_16x16x32_bf16 v[58:61], v[160:163], v[184:187], v[58:61]
	v_mfma_f32_16x16x32_bf16 v[46:49], v[146:149], v[192:195], v[46:49]
	v_mfma_f32_16x16x32_bf16 v[42:45], v[160:163], v[192:195], v[42:45]
	v_mfma_f32_16x16x32_bf16 v[30:33], v[146:149], v[200:203], v[30:33]
	v_mfma_f32_16x16x32_bf16 v[26:29], v[160:163], v[200:203], v[26:29]
	v_mfma_f32_16x16x32_bf16 v[14:17], v[146:149], v[208:211], v[14:17]
	v_mfma_f32_16x16x32_bf16 v[10:13], v[160:163], v[208:211], v[10:13]
	v_mfma_f32_16x16x32_bf16 v[62:65], v[156:159], v[188:191], v[62:65]
	v_mfma_f32_16x16x32_bf16 v[58:61], v[164:167], v[188:191], v[58:61]
	v_mfma_f32_16x16x32_bf16 v[46:49], v[156:159], v[196:199], v[46:49]
	v_mfma_f32_16x16x32_bf16 v[42:45], v[164:167], v[196:199], v[42:45]
	v_mfma_f32_16x16x32_bf16 v[30:33], v[156:159], v[204:207], v[30:33]
	v_mfma_f32_16x16x32_bf16 v[26:29], v[164:167], v[204:207], v[26:29]
	v_mfma_f32_16x16x32_bf16 v[14:17], v[156:159], v[212:215], v[14:17]
	v_mfma_f32_16x16x32_bf16 v[10:13], v[164:167], v[212:215], v[10:13]
	s_setprio 0
	s_setprio 1
	v_mfma_f32_16x16x32_bf16 v[54:57], v[168:171], v[184:187], v[54:57]
	v_mfma_f32_16x16x32_bf16 v[50:53], v[176:179], v[184:187], v[50:53]
	v_mfma_f32_16x16x32_bf16 v[38:41], v[168:171], v[192:195], v[38:41]
	v_mfma_f32_16x16x32_bf16 v[34:37], v[176:179], v[192:195], v[34:37]
	v_mfma_f32_16x16x32_bf16 v[22:25], v[168:171], v[200:203], v[22:25]
	v_mfma_f32_16x16x32_bf16 v[18:21], v[176:179], v[200:203], v[18:21]
	v_mfma_f32_16x16x32_bf16 v[6:9], v[168:171], v[208:211], v[6:9]
	v_mfma_f32_16x16x32_bf16 v[2:5], v[176:179], v[208:211], v[2:5]
	v_mfma_f32_16x16x32_bf16 v[54:57], v[172:175], v[188:191], v[54:57]
	v_mfma_f32_16x16x32_bf16 v[50:53], v[180:183], v[188:191], v[50:53]
	v_mfma_f32_16x16x32_bf16 v[38:41], v[172:175], v[196:199], v[38:41]
	v_mfma_f32_16x16x32_bf16 v[34:37], v[180:183], v[196:199], v[34:37]
	v_mfma_f32_16x16x32_bf16 v[22:25], v[172:175], v[204:207], v[22:25]
	v_mfma_f32_16x16x32_bf16 v[18:21], v[180:183], v[204:207], v[18:21]
	v_mfma_f32_16x16x32_bf16 v[6:9], v[172:175], v[212:215], v[6:9]
	v_mfma_f32_16x16x32_bf16 v[2:5], v[180:183], v[212:215], v[2:5]
	s_setprio 0
	s_barrier
; #define PG8_STAGE(bufoff, gbase, voff) do { _Pragma("unroll") for (int _i = 0; _i < 2; ++_i) \
;         __builtin_amdgcn_global_load_lds((const unsigned*)((const char*)(gbase) + (voff)[_i]), (PG8_LAS unsigned*)(lds + (bufoff) + ldsw + _i * 8192), 16, 0, 0); } while (0)
; #define PG8_LDA(dst, b, h) do { _Pragma("unroll") for (int m = 0; m < 4; ++m) _Pragma("unroll") for (int k = 0; k < 2; ++k) dst[m][k] = *(const PG8_LAS bf16x8*)(lds + PG8_SA(b, h) + aoff + m * 2048 + k * 1024); } while (0)
; #define PG8_LDB(dst, b, h) do { _Pragma("unroll") for (int n = 0; n < 2; ++n) _Pragma("unroll") for (int k = 0; k < 2; ++k) dst[n][k] = *(const PG8_LAS bf16x8*)(lds + PG8_SB(b, h) + boff + n * 2048 + k * 1024); } while (0)
; #define PG8_MMA(ai, bj, At, Bt) do { __builtin_amdgcn_s_setprio(1); _Pragma("unroll") for (int m = 0; m < 4; ++m) _Pragma("unroll") for (int n = 0; n < 2; ++n) _Pragma("unroll") for (int k = 0; k < 2; ++k) \
;         acc[ai][bj][m][n] = __builtin_amdgcn_mfma_f32_16x16x32_bf16(Bt[n][k], At[m][k], acc[ai][bj][m][n], 0, 0, 0); __builtin_amdgcn_s_setprio(0); } while (0)
; #define PG8_WAIT_V(n) asm volatile("s_waitcnt vmcnt(" #n ")" ::: "memory")
; #define PG8_WAIT_L(n) asm volatile("s_waitcnt lgkmcnt(" #n ")" ::: "memory")
; #define PG8_BAR __builtin_amdgcn_s_barrier()
; #define PG8_SCHED __builtin_amdgcn_sched_barrier(0)
; template <class Epi, class Sched, bool ALIGN_EPI = false, bool SP2 = false>
; __device__ __forceinline__ void gemm_phase(PG8_LAS unsigned char* lds, const Gemm g, const Sched& S, const Epi& E) {
;     ...
;             PG8_LDB(B0, 1, 0); PG8_LDB(B1, 1, 1); PG8_SCHED; PG8_LDA(At, 1, 0); PG8_STAGE(PG8_SA(0, 1), a2 + hstep, voffA);
;             PG8_WAIT_V(8); PG8_WAIT_L(0); PG8_BAR; PG8_MMA(0, 0, At, B0); PG8_MMA(0, 1, At, B1); PG8_BAR; PG8_SCHED;
	s_add_i32 s53, 0, 0x18000
	s_add_i32 s54, 0, 0x1c000
	v_add_u32_e32 v164, s53, v151
	v_add_u32_e32 v180, s54, v151
	ds_read_b128 v[146:149], v164
	ds_read_b128 v[156:159], v164 offset:1024
	ds_read_b128 v[160:163], v164 offset:2048
	ds_read_b128 v[164:167], v164 offset:3072
	ds_read_b128 v[168:171], v180
	ds_read_b128 v[172:175], v180 offset:1024
	ds_read_b128 v[176:179], v180 offset:2048
	ds_read_b128 v[180:183], v180 offset:3072
	s_add_u32 s44, s44, 0x80000
	s_addc_u32 s45, s45, 0
	s_mov_b32 m0, s25
	v_lshl_add_u64 v[224:225], s[44:45], 0, v[136:137]
	ds_read_b128 v[184:187], v155 offset:32768
	ds_read_b128 v[188:191], v155 offset:33792
	ds_read_b128 v[192:195], v155 offset:34816
	ds_read_b128 v[196:199], v155 offset:35840
	ds_read_b128 v[200:203], v155 offset:36864
	ds_read_b128 v[204:207], v155 offset:37888
	ds_read_b128 v[208:211], v155 offset:38912
	ds_read_b128 v[212:215], v155 offset:39936
	global_load_lds_dwordx4 v[224:225], off
	v_lshl_add_u64 v[224:225], s[44:45], 0, v[132:133]
	s_mov_b32 m0, s26
	s_nop 0
	global_load_lds_dwordx4 v[224:225], off
	s_waitcnt vmcnt(8)
	s_waitcnt lgkmcnt(0)
	s_barrier
	s_setprio 1
	s_waitcnt lgkmcnt(0)
	v_mfma_f32_16x16x32_bf16 v[126:129], v[146:149], v[184:187], v[126:129]
	v_mfma_f32_16x16x32_bf16 v[122:125], v[160:163], v[184:187], v[122:125]
	v_mfma_f32_16x16x32_bf16 v[110:113], v[146:149], v[192:195], v[110:113]
	v_mfma_f32_16x16x32_bf16 v[106:109], v[160:163], v[192:195], v[106:109]
	v_mfma_f32_16x16x32_bf16 v[94:97], v[146:149], v[200:203], v[94:97]
	v_mfma_f32_16x16x32_bf16 v[90:93], v[160:163], v[200:203], v[90:93]
	v_mfma_f32_16x16x32_bf16 v[78:81], v[146:149], v[208:211], v[78:81]
	v_mfma_f32_16x16x32_bf16 v[74:77], v[160:163], v[208:211], v[74:77]
	v_mfma_f32_16x16x32_bf16 v[126:129], v[156:159], v[188:191], v[126:129]
	v_mfma_f32_16x16x32_bf16 v[122:125], v[164:167], v[188:191], v[122:125]
	v_mfma_f32_16x16x32_bf16 v[110:113], v[156:159], v[196:199], v[110:113]
	v_mfma_f32_16x16x32_bf16 v[106:109], v[164:167], v[196:199], v[106:109]
	v_mfma_f32_16x16x32_bf16 v[94:97], v[156:159], v[204:207], v[94:97]
	v_mfma_f32_16x16x32_bf16 v[90:93], v[164:167], v[204:207], v[90:93]
	v_mfma_f32_16x16x32_bf16 v[78:81], v[156:159], v[212:215], v[78:81]
	v_mfma_f32_16x16x32_bf16 v[74:77], v[164:167], v[212:215], v[74:77]
	s_setprio 0
	s_setprio 1
	v_mfma_f32_16x16x32_bf16 v[118:121], v[168:171], v[184:187], v[118:121]
	v_mfma_f32_16x16x32_bf16 v[114:117], v[176:179], v[184:187], v[114:117]
	v_mfma_f32_16x16x32_bf16 v[102:105], v[168:171], v[192:195], v[102:105]
	v_mfma_f32_16x16x32_bf16 v[98:101], v[176:179], v[192:195], v[98:101]
	v_mfma_f32_16x16x32_bf16 v[86:89], v[168:171], v[200:203], v[86:89]
	v_mfma_f32_16x16x32_bf16 v[82:85], v[176:179], v[200:203], v[82:85]
	v_mfma_f32_16x16x32_bf16 v[70:73], v[168:171], v[208:211], v[70:73]
	v_mfma_f32_16x16x32_bf16 v[66:69], v[176:179], v[208:211], v[66:69]
	v_mfma_f32_16x16x32_bf16 v[118:121], v[172:175], v[188:191], v[118:121]
	v_mfma_f32_16x16x32_bf16 v[114:117], v[180:183], v[188:191], v[114:117]
	v_mfma_f32_16x16x32_bf16 v[102:105], v[172:175], v[196:199], v[102:105]
	v_mfma_f32_16x16x32_bf16 v[98:101], v[180:183], v[196:199], v[98:101]
	v_mfma_f32_16x16x32_bf16 v[86:89], v[172:175], v[204:207], v[86:89]
	v_mfma_f32_16x16x32_bf16 v[82:85], v[180:183], v[204:207], v[82:85]
	v_mfma_f32_16x16x32_bf16 v[70:73], v[172:175], v[212:215], v[70:73]
	v_mfma_f32_16x16x32_bf16 v[66:69], v[180:183], v[212:215], v[66:69]
	s_setprio 0
	s_barrier
; #define PG8_STAGE(bufoff, gbase, voff) do { _Pragma("unroll") for (int _i = 0; _i < 2; ++_i) \
;         __builtin_amdgcn_global_load_lds((const unsigned*)((const char*)(gbase) + (voff)[_i]), (PG8_LAS unsigned*)(lds + (bufoff) + ldsw + _i * 8192), 16, 0, 0); } while (0)
; #define PG8_LDA(dst, b, h) do { _Pragma("unroll") for (int m = 0; m < 4; ++m) _Pragma("unroll") for (int k = 0; k < 2; ++k) dst[m][k] = *(const PG8_LAS bf16x8*)(lds + PG8_SA(b, h) + aoff + m * 2048 + k * 1024); } while (0)
; #define PG8_MMA(ai, bj, At, Bt) do { __builtin_amdgcn_s_setprio(1); _Pragma("unroll") for (int m = 0; m < 4; ++m) _Pragma("unroll") for (int n = 0; n < 2; ++n) _Pragma("unroll") for (int k = 0; k < 2; ++k) \
;         acc[ai][bj][m][n] = __builtin_amdgcn_mfma_f32_16x16x32_bf16(Bt[n][k], At[m][k], acc[ai][bj][m][n], 0, 0, 0); __builtin_amdgcn_s_setprio(0); } while (0)
; #define PG8_WAIT_V(n) asm volatile("s_waitcnt vmcnt(" #n ")" ::: "memory")
; #define PG8_WAIT_L(n) asm volatile("s_waitcnt lgkmcnt(" #n ")" ::: "memory")
; #define PG8_BAR __builtin_amdgcn_s_barrier()
; #define PG8_SCHED __builtin_amdgcn_sched_barrier(0)
; template <class Epi, class Sched, bool ALIGN_EPI = false, bool SP2 = false>
; __device__ __forceinline__ void gemm_phase(PG8_LAS unsigned char* lds, const Gemm g, const Sched& S, const Epi& E) {
;     ...
;         for (int t = 0; t < nt; t += 2) {
;     ...
;             PG8_LDA(At, 1, 1); PG8_STAGE(PG8_SB(1, 0), b3, voffB); PG8_STAGE(PG8_SB(1, 1), b3 + hstep, voffB); PG8_STAGE(PG8_SA(1, 0), a3, voffA);
;             PG8_WAIT_V(8); PG8_WAIT_L(0); PG8_BAR; PG8_MMA(1, 0, At, B0); PG8_MMA(1, 1, At, B1); PG8_BAR; PG8_SCHED;
	s_add_i32 s44, s53, s16
	v_lshl_add_u64 v[216:217], v[216:217], 0, s[10:11]
	s_mov_b32 m0, s44
	ds_read_b128 v[184:187], v155 offset:49152
	ds_read_b128 v[188:191], v155 offset:50176
	ds_read_b128 v[192:195], v155 offset:51200
	ds_read_b128 v[196:199], v155 offset:52224
	ds_read_b128 v[200:203], v155 offset:53248
	ds_read_b128 v[204:207], v155 offset:54272
	ds_read_b128 v[208:211], v155 offset:55296
	ds_read_b128 v[212:215], v155 offset:56320
	global_load_lds_dwordx4 v[216:217], off
	s_add_i32 m0, s44, 0x2000
	s_add_u32 s42, s42, 0x80080
	v_lshl_add_u64 v[216:217], v[218:219], 0, s[10:11]
	s_addc_u32 s43, s43, 0
	s_add_i32 s44, s54, s16
	global_load_lds_dwordx4 v[216:217], off
	v_lshl_add_u64 v[216:217], s[42:43], 0, v[134:135]
	s_mov_b32 m0, s44
	s_nop 0
	global_load_lds_dwordx4 v[216:217], off
	v_lshl_add_u64 v[216:217], s[42:43], 0, v[130:131]
	s_add_i32 m0, s44, 0x2000
	s_nop 0
	global_load_lds_dwordx4 v[216:217], off
	v_lshl_add_u64 v[216:217], v[220:221], 0, s[10:11]
	s_mov_b32 m0, s29
	s_nop 0
	global_load_lds_dwordx4 v[216:217], off
	v_lshl_add_u64 v[216:217], v[222:223], 0, s[10:11]
	s_mov_b32 m0, s30
	s_nop 0
	global_load_lds_dwordx4 v[216:217], off
	s_waitcnt vmcnt(8)
	s_waitcnt lgkmcnt(0)
	s_barrier
	s_setprio 1
	s_waitcnt lgkmcnt(0)
	v_mfma_f32_16x16x32_bf16 v[62:65], v[146:149], v[184:187], v[62:65]
	v_mfma_f32_16x16x32_bf16 v[58:61], v[160:163], v[184:187], v[58:61]
	v_mfma_f32_16x16x32_bf16 v[46:49], v[146:149], v[192:195], v[46:49]
	v_mfma_f32_16x16x32_bf16 v[42:45], v[160:163], v[192:195], v[42:45]
	v_mfma_f32_16x16x32_bf16 v[30:33], v[146:149], v[200:203], v[30:33]
	v_mfma_f32_16x16x32_bf16 v[26:29], v[160:163], v[200:203], v[26:29]
	v_mfma_f32_16x16x32_bf16 v[14:17], v[146:149], v[208:211], v[14:17]
	v_mfma_f32_16x16x32_bf16 v[10:13], v[160:163], v[208:211], v[10:13]
	v_mfma_f32_16x16x32_bf16 v[62:65], v[156:159], v[188:191], v[62:65]
	v_mfma_f32_16x16x32_bf16 v[58:61], v[164:167], v[188:191], v[58:61]
	v_mfma_f32_16x16x32_bf16 v[46:49], v[156:159], v[196:199], v[46:49]
	v_mfma_f32_16x16x32_bf16 v[42:45], v[164:167], v[196:199], v[42:45]
	v_mfma_f32_16x16x32_bf16 v[30:33], v[156:159], v[204:207], v[30:33]
	v_mfma_f32_16x16x32_bf16 v[26:29], v[164:167], v[204:207], v[26:29]
	v_mfma_f32_16x16x32_bf16 v[14:17], v[156:159], v[212:215], v[14:17]
	v_mfma_f32_16x16x32_bf16 v[10:13], v[164:167], v[212:215], v[10:13]
	s_setprio 0
	s_setprio 1
	v_mfma_f32_16x16x32_bf16 v[54:57], v[168:171], v[184:187], v[54:57]
	v_mfma_f32_16x16x32_bf16 v[50:53], v[176:179], v[184:187], v[50:53]
	v_mfma_f32_16x16x32_bf16 v[38:41], v[168:171], v[192:195], v[38:41]
	v_mfma_f32_16x16x32_bf16 v[34:37], v[176:179], v[192:195], v[34:37]
	v_mfma_f32_16x16x32_bf16 v[22:25], v[168:171], v[200:203], v[22:25]
	v_mfma_f32_16x16x32_bf16 v[18:21], v[176:179], v[200:203], v[18:21]
	v_mfma_f32_16x16x32_bf16 v[6:9], v[168:171], v[208:211], v[6:9]
	v_mfma_f32_16x16x32_bf16 v[2:5], v[176:179], v[208:211], v[2:5]
	v_mfma_f32_16x16x32_bf16 v[54:57], v[172:175], v[188:191], v[54:57]
	v_mfma_f32_16x16x32_bf16 v[50:53], v[180:183], v[188:191], v[50:53]
	v_mfma_f32_16x16x32_bf16 v[38:41], v[172:175], v[196:199], v[38:41]
	v_mfma_f32_16x16x32_bf16 v[34:37], v[180:183], v[196:199], v[34:37]
	v_mfma_f32_16x16x32_bf16 v[22:25], v[172:175], v[204:207], v[22:25]
	v_mfma_f32_16x16x32_bf16 v[18:21], v[180:183], v[204:207], v[18:21]
	v_mfma_f32_16x16x32_bf16 v[6:9], v[172:175], v[212:215], v[6:9]
	v_mfma_f32_16x16x32_bf16 v[2:5], v[180:183], v[212:215], v[2:5]
	s_setprio 0
	s_barrier
	s_add_i32 s52, s52, 2
	s_add_u32 s40, s40, 0x100
	s_addc_u32 s41, s41, 0
	s_add_u32 s50, s50, 0x100
	s_addc_u32 s51, s51, 0
	s_cmp_gt_u32 s52, 29
	s_cbranch_scc0 .LBB0_88
.Lkx_88:
	s_and_b64 vcc, exec, s[12:13]
	s_cbranch_vccz .LBB0_91
	s_barrier

; #define PG8_STAGE(bufoff, gbase, voff) do { _Pragma("unroll") for (int _i = 0; _i < 2; ++_i) \
;         __builtin_amdgcn_global_load_lds((const unsigned*)((const char*)(gbase) + (voff)[_i]), (PG8_LAS unsigned*)(lds + (bufoff) + ldsw + _i * 8192), 16, 0, 0); } while (0)
; #define PG8_LDA(dst, b, h) do { _Pragma("unroll") for (int m = 0; m < 4; ++m) _Pragma("unroll") for (int k = 0; k < 2; ++k) dst[m][k] = *(const PG8_LAS bf16x8*)(lds + PG8_SA(b, h) + aoff + m * 2048 + k * 1024); } while (0)
; #define PG8_LDB(dst, b, h) do { _Pragma("unroll") for (int n = 0; n < 2; ++n) _Pragma("unroll") for (int k = 0; k < 2; ++k) dst[n][k] = *(const PG8_LAS bf16x8*)(lds + PG8_SB(b, h) + boff + n * 2048 + k * 1024); } while (0)
; #define PG8_WAIT_V(n) asm volatile("s_waitcnt vmcnt(" #n ")" ::: "memory")
; #define PG8_BAR __builtin_amdgcn_s_barrier()
; template <class Epi, class Sched, bool ALIGN_EPI = false, bool SP2 = false>
; __device__ __forceinline__ void gemm_phase(PG8_LAS unsigned char* lds, const Gemm g, const Sched& S, const Epi& E) {
;     ...
;         for (int t = 0; t < nt; t += 2) {
;             if constexpr (Epi::MIDHOOK) { if (t == (nt >> 1)) E.mid(acc, cur, wr, wc, fr, fq); }
;             const bool last = (t == nt - 2);
;             const char* a1 = cA + (size_t)(t + 1) * kstep;
;             const char* a2 = last ? nA : cA + (size_t)(t + 2) * kstep; const char* b2 = last ? nB : cB + (size_t)(t + 2) * kstep;
;             const char* a3 = a2 + kstep; const char* b3 = b2 + kstep;
;             if (last && has_next) S.a_ready(nxt);
;             if constexpr (SP2) {
;             PG8_LDB(B0, 0, 0); PG8_LDB(B1, 0, 1); PG8_SCHED; PG8_LDA(At, 0, 0); PG8_STAGE(PG8_SA(1, 1), a1 + hstep, voffA);
;             PG8_WAIT_V(8); PG8_WAIT_L(0); PG8_BAR; PG8_MMA(0, 0, At, B0); PG8_MMA(0, 1, At, B1); PG8_BAR; PG8_SCHED;
;             PG8_LDA(At, 0, 1); PG8_STAGE(PG8_SB(0, 0), b2, voffB); PG8_STAGE(PG8_SB(0, 1), b2 + hstep, voffB); PG8_STAGE(PG8_SA(0, 0), a2, voffA);
;             PG8_WAIT_V(8); PG8_WAIT_L(0); PG8_BAR; PG8_MMA(1, 0, At, B0); PG8_MMA(1, 1, At, B1); PG8_BAR; PG8_SCHED;
;     ...
;         for (int a = 0; a < 2; ++a)
; #pragma unroll
;             for (int b = 0; b < 2; ++b)
; #pragma unroll
;                 for (int m = 0; m < 4; ++m)
; #pragma unroll
;                     for (int n = 0; n < 2; ++n) acc[a][b][m][n] = (f32x4){0.f, 0.f, 0.f, 0.f};
.LBB0_172:
	s_add_u32 s46, s36, 0x100
	s_addc_u32 s47, s37, 0
	s_mov_b32 s48, -2
	ds_read_b128 v[154:157], v151
	ds_read_b128 v[158:161], v151 offset:1024
	ds_read_b128 v[162:165], v151 offset:2048
	ds_read_b128 v[166:169], v151 offset:3072
	ds_read_b128 v[170:173], v152
	ds_read_b128 v[174:177], v152 offset:1024
	ds_read_b128 v[178:181], v152 offset:2048
	ds_read_b128 v[182:185], v152 offset:3072
	s_add_u32 s36, s22, 0x100
	s_addc_u32 s37, s23, 0
	s_cmpk_eq_i32 s48, 0x54
	s_cselect_b32 s41, s7, s37
	s_cselect_b32 s40, s6, s36
	s_cselect_b32 s39, s21, s47
	s_cselect_b32 s38, s20, s46
	v_lshl_add_u64 v[146:147], s[22:23], 0, v[138:139]
	s_add_i32 m0, s18, 0xc000
	ds_read_b128 v[186:189], v153
	ds_read_b128 v[190:193], v153 offset:1024
	ds_read_b128 v[194:197], v153 offset:2048
	ds_read_b128 v[198:201], v153 offset:3072
	ds_read_b128 v[202:205], v153 offset:4096
	ds_read_b128 v[206:209], v153 offset:5120
	ds_read_b128 v[210:213], v153 offset:6144
	ds_read_b128 v[214:217], v153 offset:7168
	global_load_lds_dwordx4 v[146:147], off
	v_lshl_add_u64 v[146:147], s[22:23], 0, v[140:141]
	s_add_i32 m0, s18, 0xe000
	s_nop 0
	global_load_lds_dwordx4 v[146:147], off
	s_waitcnt vmcnt(8)
	s_waitcnt lgkmcnt(0)
	s_barrier
	s_setprio 1
	s_waitcnt lgkmcnt(0)
	v_mfma_f32_16x16x32_bf16 v[126:129], v[154:157], v[186:189], 0
	v_mfma_f32_16x16x32_bf16 v[122:125], v[162:165], v[186:189], 0
	v_mfma_f32_16x16x32_bf16 v[118:121], v[154:157], v[194:197], 0
	v_mfma_f32_16x16x32_bf16 v[110:113], v[162:165], v[194:197], 0
	v_mfma_f32_16x16x32_bf16 v[102:105], v[154:157], v[202:205], 0
	v_mfma_f32_16x16x32_bf16 v[94:97], v[162:165], v[202:205], 0
	v_mfma_f32_16x16x32_bf16 v[86:89], v[154:157], v[210:213], 0
	v_mfma_f32_16x16x32_bf16 v[78:81], v[162:165], v[210:213], 0
	v_mfma_f32_16x16x32_bf16 v[126:129], v[158:161], v[190:193], v[126:129]
	v_mfma_f32_16x16x32_bf16 v[122:125], v[166:169], v[190:193], v[122:125]
	v_mfma_f32_16x16x32_bf16 v[118:121], v[158:161], v[198:201], v[118:121]
	v_mfma_f32_16x16x32_bf16 v[110:113], v[166:169], v[198:201], v[110:113]
	v_mfma_f32_16x16x32_bf16 v[102:105], v[158:161], v[206:209], v[102:105]
	v_mfma_f32_16x16x32_bf16 v[94:97], v[166:169], v[206:209], v[94:97]
	v_mfma_f32_16x16x32_bf16 v[86:89], v[158:161], v[214:217], v[86:89]
	v_mfma_f32_16x16x32_bf16 v[78:81], v[166:169], v[214:217], v[78:81]
	s_setprio 0
	s_setprio 1
	v_mfma_f32_16x16x32_bf16 v[114:117], v[170:173], v[186:189], 0
	v_mfma_f32_16x16x32_bf16 v[106:109], v[178:181], v[186:189], 0
	v_mfma_f32_16x16x32_bf16 v[98:101], v[170:173], v[194:197], 0
	v_mfma_f32_16x16x32_bf16 v[90:93], v[178:181], v[194:197], 0
	v_mfma_f32_16x16x32_bf16 v[82:85], v[170:173], v[202:205], 0
	v_mfma_f32_16x16x32_bf16 v[74:77], v[178:181], v[202:205], 0
	v_mfma_f32_16x16x32_bf16 v[70:73], v[170:173], v[210:213], 0
	v_mfma_f32_16x16x32_bf16 v[66:69], v[178:181], v[210:213], 0
	v_mfma_f32_16x16x32_bf16 v[114:117], v[174:177], v[190:193], v[114:117]
	v_mfma_f32_16x16x32_bf16 v[106:109], v[182:185], v[190:193], v[106:109]
	v_mfma_f32_16x16x32_bf16 v[98:101], v[174:177], v[198:201], v[98:101]
	v_mfma_f32_16x16x32_bf16 v[90:93], v[182:185], v[198:201], v[90:93]
	v_mfma_f32_16x16x32_bf16 v[82:85], v[174:177], v[206:209], v[82:85]
	v_mfma_f32_16x16x32_bf16 v[74:77], v[182:185], v[206:209], v[74:77]
	v_mfma_f32_16x16x32_bf16 v[70:73], v[174:177], v[214:217], v[70:73]
	v_mfma_f32_16x16x32_bf16 v[66:69], v[182:185], v[214:217], v[66:69]
	s_setprio 0
	s_barrier
	s_add_i32 s22, s30, s16
	v_lshl_add_u64 v[146:147], s[38:39], 0, v[134:135]
	s_mov_b32 m0, s22
	ds_read_b128 v[186:189], v153 offset:16384
	ds_read_b128 v[190:193], v153 offset:17408
	ds_read_b128 v[194:197], v153 offset:18432
	ds_read_b128 v[198:201], v153 offset:19456
	ds_read_b128 v[202:205], v153 offset:20480
	ds_read_b128 v[206:209], v153 offset:21504
	ds_read_b128 v[210:213], v153 offset:22528
	ds_read_b128 v[214:217], v153 offset:23552
	global_load_lds_dwordx4 v[146:147], off
	s_add_i32 m0, s22, 0x2000
	s_add_u32 s22, s38, 0x160000
	v_lshl_add_u64 v[218:219], s[38:39], 0, v[130:131]
	s_addc_u32 s23, s39, 0
	s_add_i32 s49, s31, s16
	global_load_lds_dwordx4 v[218:219], off
	v_lshl_add_u64 v[220:221], s[22:23], 0, v[134:135]
	s_mov_b32 m0, s49
	v_lshl_add_u64 v[222:223], s[40:41], 0, v[132:133]
	global_load_lds_dwordx4 v[220:221], off
	v_lshl_add_u64 v[220:221], s[22:23], 0, v[130:131]
	s_add_i32 m0, s49, 0x2000
	s_nop 0
	global_load_lds_dwordx4 v[220:221], off
	v_lshl_add_u64 v[220:221], s[40:41], 0, v[136:137]
	s_mov_b32 m0, s18
	s_nop 0
	global_load_lds_dwordx4 v[220:221], off
	s_mov_b32 m0, s19
	s_nop 0
	global_load_lds_dwordx4 v[222:223], off
	s_waitcnt vmcnt(8)
	s_waitcnt lgkmcnt(0)
	s_barrier
; #define PG8_STAGE(bufoff, gbase, voff) do { _Pragma("unroll") for (int _i = 0; _i < 2; ++_i) \
;         __builtin_amdgcn_global_load_lds((const unsigned*)((const char*)(gbase) + (voff)[_i]), (PG8_LAS unsigned*)(lds + (bufoff) + ldsw + _i * 8192), 16, 0, 0); } while (0)
; #define PG8_LDA(dst, b, h) do { _Pragma("unroll") for (int m = 0; m < 4; ++m) _Pragma("unroll") for (int k = 0; k < 2; ++k) dst[m][k] = *(const PG8_LAS bf16x8*)(lds + PG8_SA(b, h) + aoff + m * 2048 + k * 1024); } while (0)
; #define PG8_LDB(dst, b, h) do { _Pragma("unroll") for (int n = 0; n < 2; ++n) _Pragma("unroll") for (int k = 0; k < 2; ++k) dst[n][k] = *(const PG8_LAS bf16x8*)(lds + PG8_SB(b, h) + boff + n * 2048 + k * 1024); } while (0)
; #define PG8_MMA(ai, bj, At, Bt) do { __builtin_amdgcn_s_setprio(1); _Pragma("unroll") for (int m = 0; m < 4; ++m) _Pragma("unroll") for (int n = 0; n < 2; ++n) _Pragma("unroll") for (int k = 0; k < 2; ++k) \
;         acc[ai][bj][m][n] = __builtin_amdgcn_mfma_f32_16x16x32_bf16(Bt[n][k], At[m][k], acc[ai][bj][m][n], 0, 0, 0); __builtin_amdgcn_s_setprio(0); } while (0)
; #define PG8_WAIT_V(n) asm volatile("s_waitcnt vmcnt(" #n ")" ::: "memory")
; #define PG8_WAIT_L(n) asm volatile("s_waitcnt lgkmcnt(" #n ")" ::: "memory")
; #define PG8_BAR __builtin_amdgcn_s_barrier()
; #define PG8_SCHED __builtin_amdgcn_sched_barrier(0)
; template <class Epi, class Sched, bool ALIGN_EPI = false, bool SP2 = false>
; __device__ __forceinline__ void gemm_phase(PG8_LAS unsigned char* lds, const Gemm g, const Sched& S, const Epi& E) {
;     ...
;             PG8_WAIT_V(8); PG8_WAIT_L(0); PG8_BAR; PG8_MMA(1, 0, At, B0); PG8_MMA(1, 1, At, B1); PG8_BAR; PG8_SCHED;
;             PG8_LDB(B0, 1, 0); PG8_LDB(B1, 1, 1); PG8_SCHED; PG8_LDA(At, 1, 0); PG8_STAGE(PG8_SA(0, 1), a2 + hstep, voffA);
;             PG8_WAIT_V(8); PG8_WAIT_L(0); PG8_BAR; PG8_MMA(0, 0, At, B0); PG8_MMA(0, 1, At, B1); PG8_BAR; PG8_SCHED;
;             PG8_LDA(At, 1, 1); PG8_STAGE(PG8_SB(1, 0), b3, voffB); PG8_STAGE(PG8_SB(1, 1), b3 + hstep, voffB); PG8_STAGE(PG8_SA(1, 0), a3, voffA);
;             PG8_WAIT_V(8); PG8_WAIT_L(0); PG8_BAR; PG8_MMA(1, 0, At, B0); PG8_MMA(1, 1, At, B1); PG8_BAR; PG8_SCHED;
	s_setprio 1
	s_waitcnt lgkmcnt(0)
	v_mfma_f32_16x16x32_bf16 v[62:65], v[154:157], v[186:189], 0
	v_mfma_f32_16x16x32_bf16 v[58:61], v[162:165], v[186:189], 0
	v_mfma_f32_16x16x32_bf16 v[54:57], v[154:157], v[194:197], 0
	v_mfma_f32_16x16x32_bf16 v[46:49], v[162:165], v[194:197], 0
	v_mfma_f32_16x16x32_bf16 v[38:41], v[154:157], v[202:205], 0
	v_mfma_f32_16x16x32_bf16 v[30:33], v[162:165], v[202:205], 0
	v_mfma_f32_16x16x32_bf16 v[22:25], v[154:157], v[210:213], 0
	v_mfma_f32_16x16x32_bf16 v[14:17], v[162:165], v[210:213], 0
	v_mfma_f32_16x16x32_bf16 v[62:65], v[158:161], v[190:193], v[62:65]
	v_mfma_f32_16x16x32_bf16 v[58:61], v[166:169], v[190:193], v[58:61]
	v_mfma_f32_16x16x32_bf16 v[54:57], v[158:161], v[198:201], v[54:57]
	v_mfma_f32_16x16x32_bf16 v[46:49], v[166:169], v[198:201], v[46:49]
	v_mfma_f32_16x16x32_bf16 v[38:41], v[158:161], v[206:209], v[38:41]
	v_mfma_f32_16x16x32_bf16 v[30:33], v[166:169], v[206:209], v[30:33]
	v_mfma_f32_16x16x32_bf16 v[22:25], v[158:161], v[214:217], v[22:25]
	v_mfma_f32_16x16x32_bf16 v[14:17], v[166:169], v[214:217], v[14:17]
	s_setprio 0
	s_setprio 1
	v_mfma_f32_16x16x32_bf16 v[50:53], v[170:173], v[186:189], 0
	v_mfma_f32_16x16x32_bf16 v[42:45], v[178:181], v[186:189], 0
	v_mfma_f32_16x16x32_bf16 v[34:37], v[170:173], v[194:197], 0
	v_mfma_f32_16x16x32_bf16 v[26:29], v[178:181], v[194:197], 0
	v_mfma_f32_16x16x32_bf16 v[18:21], v[170:173], v[202:205], 0
	v_mfma_f32_16x16x32_bf16 v[10:13], v[178:181], v[202:205], 0
	v_mfma_f32_16x16x32_bf16 v[6:9], v[170:173], v[210:213], 0
	v_mfma_f32_16x16x32_bf16 v[2:5], v[178:181], v[210:213], 0
	v_mfma_f32_16x16x32_bf16 v[50:53], v[174:177], v[190:193], v[50:53]
	v_mfma_f32_16x16x32_bf16 v[42:45], v[182:185], v[190:193], v[42:45]
	v_mfma_f32_16x16x32_bf16 v[34:37], v[174:177], v[198:201], v[34:37]
	v_mfma_f32_16x16x32_bf16 v[26:29], v[182:185], v[198:201], v[26:29]
	v_mfma_f32_16x16x32_bf16 v[18:21], v[174:177], v[206:209], v[18:21]
	v_mfma_f32_16x16x32_bf16 v[10:13], v[182:185], v[206:209], v[10:13]
	v_mfma_f32_16x16x32_bf16 v[6:9], v[174:177], v[214:217], v[6:9]
	v_mfma_f32_16x16x32_bf16 v[2:5], v[182:185], v[214:217], v[2:5]
	s_setprio 0
	s_barrier
	s_add_i32 s49, 0, 0x18000
	s_add_i32 s50, 0, 0x1c000
	v_add_u32_e32 v166, s49, v149
	v_add_u32_e32 v182, s50, v149
	ds_read_b128 v[154:157], v166
	ds_read_b128 v[158:161], v166 offset:1024
	ds_read_b128 v[162:165], v166 offset:2048
	ds_read_b128 v[166:169], v166 offset:3072
	ds_read_b128 v[170:173], v182
	ds_read_b128 v[174:177], v182 offset:1024
	ds_read_b128 v[178:181], v182 offset:2048
	ds_read_b128 v[182:185], v182 offset:3072
	s_add_u32 s22, s40, 0x160000
	s_addc_u32 s23, s41, 0
	s_mov_b32 m0, s24
	v_lshl_add_u64 v[224:225], s[22:23], 0, v[136:137]
	ds_read_b128 v[186:189], v153 offset:32768
	ds_read_b128 v[190:193], v153 offset:33792
	ds_read_b128 v[194:197], v153 offset:34816
	ds_read_b128 v[198:201], v153 offset:35840
	ds_read_b128 v[202:205], v153 offset:36864
	ds_read_b128 v[206:209], v153 offset:37888
	ds_read_b128 v[210:213], v153 offset:38912
	ds_read_b128 v[214:217], v153 offset:39936
	global_load_lds_dwordx4 v[224:225], off
	v_lshl_add_u64 v[224:225], s[22:23], 0, v[132:133]
	s_mov_b32 m0, s25
	s_nop 0
	global_load_lds_dwordx4 v[224:225], off
	s_waitcnt vmcnt(8)
	s_waitcnt lgkmcnt(0)
	s_barrier
	s_setprio 1
	s_waitcnt lgkmcnt(0)
	v_mfma_f32_16x16x32_bf16 v[126:129], v[154:157], v[186:189], v[126:129]
	v_mfma_f32_16x16x32_bf16 v[122:125], v[162:165], v[186:189], v[122:125]
	v_mfma_f32_16x16x32_bf16 v[118:121], v[154:157], v[194:197], v[118:121]
	v_mfma_f32_16x16x32_bf16 v[110:113], v[162:165], v[194:197], v[110:113]
	v_mfma_f32_16x16x32_bf16 v[102:105], v[154:157], v[202:205], v[102:105]
	v_mfma_f32_16x16x32_bf16 v[94:97], v[162:165], v[202:205], v[94:97]
	v_mfma_f32_16x16x32_bf16 v[86:89], v[154:157], v[210:213], v[86:89]
	v_mfma_f32_16x16x32_bf16 v[78:81], v[162:165], v[210:213], v[78:81]
	v_mfma_f32_16x16x32_bf16 v[126:129], v[158:161], v[190:193], v[126:129]
	v_mfma_f32_16x16x32_bf16 v[122:125], v[166:169], v[190:193], v[122:125]
	v_mfma_f32_16x16x32_bf16 v[118:121], v[158:161], v[198:201], v[118:121]
	v_mfma_f32_16x16x32_bf16 v[110:113], v[166:169], v[198:201], v[110:113]
	v_mfma_f32_16x16x32_bf16 v[102:105], v[158:161], v[206:209], v[102:105]
	v_mfma_f32_16x16x32_bf16 v[94:97], v[166:169], v[206:209], v[94:97]
	v_mfma_f32_16x16x32_bf16 v[86:89], v[158:161], v[214:217], v[86:89]
	v_mfma_f32_16x16x32_bf16 v[78:81], v[166:169], v[214:217], v[78:81]
	s_setprio 0
	s_setprio 1
	v_mfma_f32_16x16x32_bf16 v[114:117], v[170:173], v[186:189], v[114:117]
	v_mfma_f32_16x16x32_bf16 v[106:109], v[178:181], v[186:189], v[106:109]
	v_mfma_f32_16x16x32_bf16 v[98:101], v[170:173], v[194:197], v[98:101]
	v_mfma_f32_16x16x32_bf16 v[90:93], v[178:181], v[194:197], v[90:93]
	v_mfma_f32_16x16x32_bf16 v[82:85], v[170:173], v[202:205], v[82:85]
	v_mfma_f32_16x16x32_bf16 v[74:77], v[178:181], v[202:205], v[74:77]
	v_mfma_f32_16x16x32_bf16 v[70:73], v[170:173], v[210:213], v[70:73]
	v_mfma_f32_16x16x32_bf16 v[66:69], v[178:181], v[210:213], v[66:69]
	v_mfma_f32_16x16x32_bf16 v[114:117], v[174:177], v[190:193], v[114:117]
	v_mfma_f32_16x16x32_bf16 v[106:109], v[182:185], v[190:193], v[106:109]
	v_mfma_f32_16x16x32_bf16 v[98:101], v[174:177], v[198:201], v[98:101]
	v_mfma_f32_16x16x32_bf16 v[90:93], v[182:185], v[198:201], v[90:93]
	v_mfma_f32_16x16x32_bf16 v[82:85], v[174:177], v[206:209], v[82:85]
	v_mfma_f32_16x16x32_bf16 v[74:77], v[182:185], v[206:209], v[74:77]
	v_mfma_f32_16x16x32_bf16 v[70:73], v[174:177], v[214:217], v[70:73]
	v_mfma_f32_16x16x32_bf16 v[66:69], v[182:185], v[214:217], v[66:69]
	s_setprio 0
	s_barrier
; #define PG8_STAGE(bufoff, gbase, voff) do { _Pragma("unroll") for (int _i = 0; _i < 2; ++_i) \
;         __builtin_amdgcn_global_load_lds((const unsigned*)((const char*)(gbase) + (voff)[_i]), (PG8_LAS unsigned*)(lds + (bufoff) + ldsw + _i * 8192), 16, 0, 0); } while (0)
; #define PG8_LDA(dst, b, h) do { _Pragma("unroll") for (int m = 0; m < 4; ++m) _Pragma("unroll") for (int k = 0; k < 2; ++k) dst[m][k] = *(const PG8_LAS bf16x8*)(lds + PG8_SA(b, h) + aoff + m * 2048 + k * 1024); } while (0)
; #define PG8_LDB(dst, b, h) do { _Pragma("unroll") for (int n = 0; n < 2; ++n) _Pragma("unroll") for (int k = 0; k < 2; ++k) dst[n][k] = *(const PG8_LAS bf16x8*)(lds + PG8_SB(b, h) + boff + n * 2048 + k * 1024); } while (0)
; #define PG8_MMA(ai, bj, At, Bt) do { __builtin_amdgcn_s_setprio(1); _Pragma("unroll") for (int m = 0; m < 4; ++m) _Pragma("unroll") for (int n = 0; n < 2; ++n) _Pragma("unroll") for (int k = 0; k < 2; ++k) \
;         acc[ai][bj][m][n] = __builtin_amdgcn_mfma_f32_16x16x32_bf16(Bt[n][k], At[m][k], acc[ai][bj][m][n], 0, 0, 0); __builtin_amdgcn_s_setprio(0); } while (0)
; #define PG8_WAIT_V(n) asm volatile("s_waitcnt vmcnt(" #n ")" ::: "memory")
; #define PG8_WAIT_L(n) asm volatile("s_waitcnt lgkmcnt(" #n ")" ::: "memory")
; template <class Epi, class Sched, bool ALIGN_EPI = false, bool SP2 = false>
; __device__ __forceinline__ void gemm_phase(PG8_LAS unsigned char* lds, const Gemm g, const Sched& S, const Epi& E) {
;     ...
;         for (int t = 0; t < nt; t += 2) {
;             if constexpr (Epi::MIDHOOK) { if (t == (nt >> 1)) E.mid(acc, cur, wr, wc, fr, fq); }
;             const bool last = (t == nt - 2);
;             const char* a1 = cA + (size_t)(t + 1) * kstep;
;             const char* a2 = last ? nA : cA + (size_t)(t + 2) * kstep; const char* b2 = last ? nB : cB + (size_t)(t + 2) * kstep;
;             const char* a3 = a2 + kstep; const char* b3 = b2 + kstep;
;             if (last && has_next) S.a_ready(nxt);
;             if constexpr (SP2) {
;             PG8_LDB(B0, 0, 0); PG8_LDB(B1, 0, 1); PG8_SCHED; PG8_LDA(At, 0, 0); PG8_STAGE(PG8_SA(1, 1), a1 + hstep, voffA);
;     ...
;             PG8_LDA(At, 1, 1); PG8_STAGE(PG8_SB(1, 0), b3, voffB); PG8_STAGE(PG8_SB(1, 1), b3 + hstep, voffB); PG8_STAGE(PG8_SA(1, 0), a3, voffA);
;             PG8_WAIT_V(8); PG8_WAIT_L(0); PG8_BAR; PG8_MMA(1, 0, At, B0); PG8_MMA(1, 1, At, B1); PG8_BAR; PG8_SCHED;
	s_add_i32 s22, s49, s16
	v_lshl_add_u64 v[146:147], v[146:147], 0, s[12:13]
	s_mov_b32 m0, s22
	ds_read_b128 v[186:189], v153 offset:49152
	ds_read_b128 v[190:193], v153 offset:50176
	ds_read_b128 v[194:197], v153 offset:51200
	ds_read_b128 v[198:201], v153 offset:52224
	ds_read_b128 v[202:205], v153 offset:53248
	ds_read_b128 v[206:209], v153 offset:54272
	ds_read_b128 v[210:213], v153 offset:55296
	ds_read_b128 v[214:217], v153 offset:56320
	global_load_lds_dwordx4 v[146:147], off
	s_add_i32 m0, s22, 0x2000
	s_add_u32 s22, s38, 0x160080
	v_lshl_add_u64 v[146:147], v[218:219], 0, s[12:13]
	s_addc_u32 s23, s39, 0
	s_add_i32 s38, s50, s16
	global_load_lds_dwordx4 v[146:147], off
	v_lshl_add_u64 v[146:147], s[22:23], 0, v[134:135]
	s_mov_b32 m0, s38
	s_nop 0
	global_load_lds_dwordx4 v[146:147], off
	v_lshl_add_u64 v[146:147], s[22:23], 0, v[130:131]
	s_add_i32 m0, s38, 0x2000
	s_nop 0
	global_load_lds_dwordx4 v[146:147], off
	v_lshl_add_u64 v[146:147], v[220:221], 0, s[12:13]
	s_mov_b32 m0, s28
	s_nop 0
	global_load_lds_dwordx4 v[146:147], off
	v_lshl_add_u64 v[146:147], v[222:223], 0, s[12:13]
	s_mov_b32 m0, s29
	s_nop 0
	global_load_lds_dwordx4 v[146:147], off
	s_waitcnt vmcnt(8)
	s_waitcnt lgkmcnt(0)
	s_barrier
	s_setprio 1
	s_waitcnt lgkmcnt(0)
	v_mfma_f32_16x16x32_bf16 v[62:65], v[154:157], v[186:189], v[62:65]
	v_mfma_f32_16x16x32_bf16 v[58:61], v[162:165], v[186:189], v[58:61]
	v_mfma_f32_16x16x32_bf16 v[54:57], v[154:157], v[194:197], v[54:57]
	v_mfma_f32_16x16x32_bf16 v[46:49], v[162:165], v[194:197], v[46:49]
	v_mfma_f32_16x16x32_bf16 v[38:41], v[154:157], v[202:205], v[38:41]
	v_mfma_f32_16x16x32_bf16 v[30:33], v[162:165], v[202:205], v[30:33]
	v_mfma_f32_16x16x32_bf16 v[22:25], v[154:157], v[210:213], v[22:25]
	v_mfma_f32_16x16x32_bf16 v[14:17], v[162:165], v[210:213], v[14:17]
	v_mfma_f32_16x16x32_bf16 v[62:65], v[158:161], v[190:193], v[62:65]
	v_mfma_f32_16x16x32_bf16 v[58:61], v[166:169], v[190:193], v[58:61]
	v_mfma_f32_16x16x32_bf16 v[54:57], v[158:161], v[198:201], v[54:57]
	v_mfma_f32_16x16x32_bf16 v[46:49], v[166:169], v[198:201], v[46:49]
	v_mfma_f32_16x16x32_bf16 v[38:41], v[158:161], v[206:209], v[38:41]
	v_mfma_f32_16x16x32_bf16 v[30:33], v[166:169], v[206:209], v[30:33]
	v_mfma_f32_16x16x32_bf16 v[22:25], v[158:161], v[214:217], v[22:25]
	v_mfma_f32_16x16x32_bf16 v[14:17], v[166:169], v[214:217], v[14:17]
	s_setprio 0
	s_setprio 1
	v_mfma_f32_16x16x32_bf16 v[50:53], v[170:173], v[186:189], v[50:53]
	v_mfma_f32_16x16x32_bf16 v[42:45], v[178:181], v[186:189], v[42:45]
	v_mfma_f32_16x16x32_bf16 v[34:37], v[170:173], v[194:197], v[34:37]
	v_mfma_f32_16x16x32_bf16 v[26:29], v[178:181], v[194:197], v[26:29]
	v_mfma_f32_16x16x32_bf16 v[18:21], v[170:173], v[202:205], v[18:21]
	v_mfma_f32_16x16x32_bf16 v[10:13], v[178:181], v[202:205], v[10:13]
	v_mfma_f32_16x16x32_bf16 v[6:9], v[170:173], v[210:213], v[6:9]
	v_mfma_f32_16x16x32_bf16 v[2:5], v[178:181], v[210:213], v[2:5]
	v_mfma_f32_16x16x32_bf16 v[50:53], v[174:177], v[190:193], v[50:53]
	v_mfma_f32_16x16x32_bf16 v[42:45], v[182:185], v[190:193], v[42:45]
	v_mfma_f32_16x16x32_bf16 v[34:37], v[174:177], v[198:201], v[34:37]
	v_mfma_f32_16x16x32_bf16 v[26:29], v[182:185], v[198:201], v[26:29]
	v_mfma_f32_16x16x32_bf16 v[18:21], v[174:177], v[206:209], v[18:21]
	v_mfma_f32_16x16x32_bf16 v[10:13], v[182:185], v[206:209], v[10:13]
	v_mfma_f32_16x16x32_bf16 v[6:9], v[174:177], v[214:217], v[6:9]
	v_mfma_f32_16x16x32_bf16 v[2:5], v[182:185], v[214:217], v[2:5]
	s_setprio 0
	s_barrier
	s_add_i32 s48, s48, 2
	s_add_u32 s46, s46, 0x100
	s_addc_u32 s47, s47, 0
	s_cmpk_gt_u32 s48, 0x55
	s_mov_b64 s[22:23], s[36:37]
	s_cbranch_scc1 .Lkx_173
.LBB0_173:
	ds_read_b128 v[154:157], v151
	ds_read_b128 v[158:161], v151 offset:1024
	ds_read_b128 v[162:165], v151 offset:2048
	ds_read_b128 v[166:169], v151 offset:3072
	ds_read_b128 v[170:173], v152
	ds_read_b128 v[174:177], v152 offset:1024
	ds_read_b128 v[178:181], v152 offset:2048
	ds_read_b128 v[182:185], v152 offset:3072
	s_add_u32 s36, s22, 0x100
	s_addc_u32 s37, s23, 0
	s_cmpk_eq_i32 s48, 0x54
	s_cselect_b32 s41, s7, s37
	s_cselect_b32 s40, s6, s36
	s_cselect_b32 s39, s21, s47
	s_cselect_b32 s38, s20, s46
	v_lshl_add_u64 v[146:147], s[22:23], 0, v[138:139]
	s_add_i32 m0, s18, 0xc000
	ds_read_b128 v[186:189], v153
	ds_read_b128 v[190:193], v153 offset:1024
	ds_read_b128 v[194:197], v153 offset:2048
	ds_read_b128 v[198:201], v153 offset:3072
	ds_read_b128 v[202:205], v153 offset:4096
	ds_read_b128 v[206:209], v153 offset:5120
	ds_read_b128 v[210:213], v153 offset:6144
	ds_read_b128 v[214:217], v153 offset:7168
	global_load_lds_dwordx4 v[146:147], off
	v_lshl_add_u64 v[146:147], s[22:23], 0, v[140:141]
	s_add_i32 m0, s18, 0xe000
	s_nop 0
	global_load_lds_dwordx4 v[146:147], off
	s_waitcnt vmcnt(8)
	s_waitcnt lgkmcnt(0)
	s_barrier
; #define PG8_STAGE(bufoff, gbase, voff) do { _Pragma("unroll") for (int _i = 0; _i < 2; ++_i) \
;         __builtin_amdgcn_global_load_lds((const unsigned*)((const char*)(gbase) + (voff)[_i]), (PG8_LAS unsigned*)(lds + (bufoff) + ldsw + _i * 8192), 16, 0, 0); } while (0)
; #define PG8_LDA(dst, b, h) do { _Pragma("unroll") for (int m = 0; m < 4; ++m) _Pragma("unroll") for (int k = 0; k < 2; ++k) dst[m][k] = *(const PG8_LAS bf16x8*)(lds + PG8_SA(b, h) + aoff + m * 2048 + k * 1024); } while (0)
; #define PG8_LDB(dst, b, h) do { _Pragma("unroll") for (int n = 0; n < 2; ++n) _Pragma("unroll") for (int k = 0; k < 2; ++k) dst[n][k] = *(const PG8_LAS bf16x8*)(lds + PG8_SB(b, h) + boff + n * 2048 + k * 1024); } while (0)
; #define PG8_MMA(ai, bj, At, Bt) do { __builtin_amdgcn_s_setprio(1); _Pragma("unroll") for (int m = 0; m < 4; ++m) _Pragma("unroll") for (int n = 0; n < 2; ++n) _Pragma("unroll") for (int k = 0; k < 2; ++k) \
;         acc[ai][bj][m][n] = __builtin_amdgcn_mfma_f32_16x16x32_bf16(Bt[n][k], At[m][k], acc[ai][bj][m][n], 0, 0, 0); __builtin_amdgcn_s_setprio(0); } while (0)
; #define PG8_WAIT_V(n) asm volatile("s_waitcnt vmcnt(" #n ")" ::: "memory")
; #define PG8_WAIT_L(n) asm volatile("s_waitcnt lgkmcnt(" #n ")" ::: "memory")
; #define PG8_BAR __builtin_amdgcn_s_barrier()
; #define PG8_SCHED __builtin_amdgcn_sched_barrier(0)
; template <class Epi, class Sched, bool ALIGN_EPI = false, bool SP2 = false>
; __device__ __forceinline__ void gemm_phase(PG8_LAS unsigned char* lds, const Gemm g, const Sched& S, const Epi& E) {
;     ...
;             PG8_LDB(B0, 0, 0); PG8_LDB(B1, 0, 1); PG8_SCHED; PG8_LDA(At, 0, 0); PG8_STAGE(PG8_SA(1, 1), a1 + hstep, voffA);
;             PG8_WAIT_V(8); PG8_WAIT_L(0); PG8_BAR; PG8_MMA(0, 0, At, B0); PG8_MMA(0, 1, At, B1); PG8_BAR; PG8_SCHED;
;             PG8_LDA(At, 0, 1); PG8_STAGE(PG8_SB(0, 0), b2, voffB); PG8_STAGE(PG8_SB(0, 1), b2 + hstep, voffB); PG8_STAGE(PG8_SA(0, 0), a2, voffA);
;             PG8_WAIT_V(8); PG8_WAIT_L(0); PG8_BAR; PG8_MMA(1, 0, At, B0); PG8_MMA(1, 1, At, B1); PG8_BAR; PG8_SCHED;
;             PG8_LDB(B0, 1, 0); PG8_LDB(B1, 1, 1); PG8_SCHED; PG8_LDA(At, 1, 0); PG8_STAGE(PG8_SA(0, 1), a2 + hstep, voffA);
;             PG8_WAIT_V(8); PG8_WAIT_L(0); PG8_BAR; PG8_MMA(0, 0, At, B0); PG8_MMA(0, 1, At, B1); PG8_BAR; PG8_SCHED;
	s_setprio 1
	s_waitcnt lgkmcnt(0)
	v_mfma_f32_16x16x32_bf16 v[126:129], v[154:157], v[186:189], v[126:129]
	v_mfma_f32_16x16x32_bf16 v[122:125], v[162:165], v[186:189], v[122:125]
	v_mfma_f32_16x16x32_bf16 v[118:121], v[154:157], v[194:197], v[118:121]
	v_mfma_f32_16x16x32_bf16 v[110:113], v[162:165], v[194:197], v[110:113]
	v_mfma_f32_16x16x32_bf16 v[102:105], v[154:157], v[202:205], v[102:105]
	v_mfma_f32_16x16x32_bf16 v[94:97], v[162:165], v[202:205], v[94:97]
	v_mfma_f32_16x16x32_bf16 v[86:89], v[154:157], v[210:213], v[86:89]
	v_mfma_f32_16x16x32_bf16 v[78:81], v[162:165], v[210:213], v[78:81]
	v_mfma_f32_16x16x32_bf16 v[126:129], v[158:161], v[190:193], v[126:129]
	v_mfma_f32_16x16x32_bf16 v[122:125], v[166:169], v[190:193], v[122:125]
	v_mfma_f32_16x16x32_bf16 v[118:121], v[158:161], v[198:201], v[118:121]
	v_mfma_f32_16x16x32_bf16 v[110:113], v[166:169], v[198:201], v[110:113]
	v_mfma_f32_16x16x32_bf16 v[102:105], v[158:161], v[206:209], v[102:105]
	v_mfma_f32_16x16x32_bf16 v[94:97], v[166:169], v[206:209], v[94:97]
	v_mfma_f32_16x16x32_bf16 v[86:89], v[158:161], v[214:217], v[86:89]
	v_mfma_f32_16x16x32_bf16 v[78:81], v[166:169], v[214:217], v[78:81]
	s_setprio 0
	s_setprio 1
	v_mfma_f32_16x16x32_bf16 v[114:117], v[170:173], v[186:189], v[114:117]
	v_mfma_f32_16x16x32_bf16 v[106:109], v[178:181], v[186:189], v[106:109]
	v_mfma_f32_16x16x32_bf16 v[98:101], v[170:173], v[194:197], v[98:101]
	v_mfma_f32_16x16x32_bf16 v[90:93], v[178:181], v[194:197], v[90:93]
	v_mfma_f32_16x16x32_bf16 v[82:85], v[170:173], v[202:205], v[82:85]
	v_mfma_f32_16x16x32_bf16 v[74:77], v[178:181], v[202:205], v[74:77]
	v_mfma_f32_16x16x32_bf16 v[70:73], v[170:173], v[210:213], v[70:73]
	v_mfma_f32_16x16x32_bf16 v[66:69], v[178:181], v[210:213], v[66:69]
	v_mfma_f32_16x16x32_bf16 v[114:117], v[174:177], v[190:193], v[114:117]
	v_mfma_f32_16x16x32_bf16 v[106:109], v[182:185], v[190:193], v[106:109]
	v_mfma_f32_16x16x32_bf16 v[98:101], v[174:177], v[198:201], v[98:101]
	v_mfma_f32_16x16x32_bf16 v[90:93], v[182:185], v[198:201], v[90:93]
	v_mfma_f32_16x16x32_bf16 v[82:85], v[174:177], v[206:209], v[82:85]
	v_mfma_f32_16x16x32_bf16 v[74:77], v[182:185], v[206:209], v[74:77]
	v_mfma_f32_16x16x32_bf16 v[70:73], v[174:177], v[214:217], v[70:73]
	v_mfma_f32_16x16x32_bf16 v[66:69], v[182:185], v[214:217], v[66:69]
	s_setprio 0
	s_barrier
	s_add_i32 s22, s30, s16
	v_lshl_add_u64 v[146:147], s[38:39], 0, v[134:135]
	s_mov_b32 m0, s22
	ds_read_b128 v[186:189], v153 offset:16384
	ds_read_b128 v[190:193], v153 offset:17408
	ds_read_b128 v[194:197], v153 offset:18432
	ds_read_b128 v[198:201], v153 offset:19456
	ds_read_b128 v[202:205], v153 offset:20480
	ds_read_b128 v[206:209], v153 offset:21504
	ds_read_b128 v[210:213], v153 offset:22528
	ds_read_b128 v[214:217], v153 offset:23552
	global_load_lds_dwordx4 v[146:147], off
	s_add_i32 m0, s22, 0x2000
	s_add_u32 s22, s38, 0x160000
	v_lshl_add_u64 v[218:219], s[38:39], 0, v[130:131]
	s_addc_u32 s23, s39, 0
	s_add_i32 s49, s31, s16
	global_load_lds_dwordx4 v[218:219], off
	v_lshl_add_u64 v[220:221], s[22:23], 0, v[134:135]
	s_mov_b32 m0, s49
	v_lshl_add_u64 v[222:223], s[40:41], 0, v[132:133]
	global_load_lds_dwordx4 v[220:221], off
	v_lshl_add_u64 v[220:221], s[22:23], 0, v[130:131]
	s_add_i32 m0, s49, 0x2000
	s_nop 0
	global_load_lds_dwordx4 v[220:221], off
	v_lshl_add_u64 v[220:221], s[40:41], 0, v[136:137]
	s_mov_b32 m0, s18
	s_nop 0
	global_load_lds_dwordx4 v[220:221], off
	s_mov_b32 m0, s19
	s_nop 0
	global_load_lds_dwordx4 v[222:223], off
	s_waitcnt vmcnt(8)
	s_waitcnt lgkmcnt(0)
	s_barrier
	s_setprio 1
	s_waitcnt lgkmcnt(0)
	v_mfma_f32_16x16x32_bf16 v[62:65], v[154:157], v[186:189], v[62:65]
	v_mfma_f32_16x16x32_bf16 v[58:61], v[162:165], v[186:189], v[58:61]
	v_mfma_f32_16x16x32_bf16 v[54:57], v[154:157], v[194:197], v[54:57]
	v_mfma_f32_16x16x32_bf16 v[46:49], v[162:165], v[194:197], v[46:49]
	v_mfma_f32_16x16x32_bf16 v[38:41], v[154:157], v[202:205], v[38:41]
	v_mfma_f32_16x16x32_bf16 v[30:33], v[162:165], v[202:205], v[30:33]
	v_mfma_f32_16x16x32_bf16 v[22:25], v[154:157], v[210:213], v[22:25]
	v_mfma_f32_16x16x32_bf16 v[14:17], v[162:165], v[210:213], v[14:17]
	v_mfma_f32_16x16x32_bf16 v[62:65], v[158:161], v[190:193], v[62:65]
	v_mfma_f32_16x16x32_bf16 v[58:61], v[166:169], v[190:193], v[58:61]
	v_mfma_f32_16x16x32_bf16 v[54:57], v[158:161], v[198:201], v[54:57]
	v_mfma_f32_16x16x32_bf16 v[46:49], v[166:169], v[198:201], v[46:49]
	v_mfma_f32_16x16x32_bf16 v[38:41], v[158:161], v[206:209], v[38:41]
	v_mfma_f32_16x16x32_bf16 v[30:33], v[166:169], v[206:209], v[30:33]
	v_mfma_f32_16x16x32_bf16 v[22:25], v[158:161], v[214:217], v[22:25]
	v_mfma_f32_16x16x32_bf16 v[14:17], v[166:169], v[214:217], v[14:17]
	s_setprio 0
	s_setprio 1
	v_mfma_f32_16x16x32_bf16 v[50:53], v[170:173], v[186:189], v[50:53]
	v_mfma_f32_16x16x32_bf16 v[42:45], v[178:181], v[186:189], v[42:45]
	v_mfma_f32_16x16x32_bf16 v[34:37], v[170:173], v[194:197], v[34:37]
	v_mfma_f32_16x16x32_bf16 v[26:29], v[178:181], v[194:197], v[26:29]
	v_mfma_f32_16x16x32_bf16 v[18:21], v[170:173], v[202:205], v[18:21]
	v_mfma_f32_16x16x32_bf16 v[10:13], v[178:181], v[202:205], v[10:13]
	v_mfma_f32_16x16x32_bf16 v[6:9], v[170:173], v[210:213], v[6:9]
	v_mfma_f32_16x16x32_bf16 v[2:5], v[178:181], v[210:213], v[2:5]
	v_mfma_f32_16x16x32_bf16 v[50:53], v[174:177], v[190:193], v[50:53]
	v_mfma_f32_16x16x32_bf16 v[42:45], v[182:185], v[190:193], v[42:45]
	v_mfma_f32_16x16x32_bf16 v[34:37], v[174:177], v[198:201], v[34:37]
	v_mfma_f32_16x16x32_bf16 v[26:29], v[182:185], v[198:201], v[26:29]
	v_mfma_f32_16x16x32_bf16 v[18:21], v[174:177], v[206:209], v[18:21]
	v_mfma_f32_16x16x32_bf16 v[10:13], v[182:185], v[206:209], v[10:13]
	v_mfma_f32_16x16x32_bf16 v[6:9], v[174:177], v[214:217], v[6:9]
	v_mfma_f32_16x16x32_bf16 v[2:5], v[182:185], v[214:217], v[2:5]
	s_setprio 0
	s_barrier
; #define PG8_STAGE(bufoff, gbase, voff) do { _Pragma("unroll") for (int _i = 0; _i < 2; ++_i) \
;         __builtin_amdgcn_global_load_lds((const unsigned*)((const char*)(gbase) + (voff)[_i]), (PG8_LAS unsigned*)(lds + (bufoff) + ldsw + _i * 8192), 16, 0, 0); } while (0)
; #define PG8_LDA(dst, b, h) do { _Pragma("unroll") for (int m = 0; m < 4; ++m) _Pragma("unroll") for (int k = 0; k < 2; ++k) dst[m][k] = *(const PG8_LAS bf16x8*)(lds + PG8_SA(b, h) + aoff + m * 2048 + k * 1024); } while (0)
; #define PG8_LDB(dst, b, h) do { _Pragma("unroll") for (int n = 0; n < 2; ++n) _Pragma("unroll") for (int k = 0; k < 2; ++k) dst[n][k] = *(const PG8_LAS bf16x8*)(lds + PG8_SB(b, h) + boff + n * 2048 + k * 1024); } while (0)
; #define PG8_MMA(ai, bj, At, Bt) do { __builtin_amdgcn_s_setprio(1); _Pragma("unroll") for (int m = 0; m < 4; ++m) _Pragma("unroll") for (int n = 0; n < 2; ++n) _Pragma("unroll") for (int k = 0; k < 2; ++k) \
;         acc[ai][bj][m][n] = __builtin_amdgcn_mfma_f32_16x16x32_bf16(Bt[n][k], At[m][k], acc[ai][bj][m][n], 0, 0, 0); __builtin_amdgcn_s_setprio(0); } while (0)
; #define PG8_WAIT_V(n) asm volatile("s_waitcnt vmcnt(" #n ")" ::: "memory")
; #define PG8_WAIT_L(n) asm volatile("s_waitcnt lgkmcnt(" #n ")" ::: "memory")
; #define PG8_BAR __builtin_amdgcn_s_barrier()
; #define PG8_SCHED __builtin_amdgcn_sched_barrier(0)
; template <class Epi, class Sched, bool ALIGN_EPI = false, bool SP2 = false>
; __device__ __forceinline__ void gemm_phase(PG8_LAS unsigned char* lds, const Gemm g, const Sched& S, const Epi& E) {
;     ...
;             PG8_LDB(B0, 1, 0); PG8_LDB(B1, 1, 1); PG8_SCHED; PG8_LDA(At, 1, 0); PG8_STAGE(PG8_SA(0, 1), a2 + hstep, voffA);
;             PG8_WAIT_V(8); PG8_WAIT_L(0); PG8_BAR; PG8_MMA(0, 0, At, B0); PG8_MMA(0, 1, At, B1); PG8_BAR; PG8_SCHED;
	s_add_i32 s49, 0, 0x18000
	s_add_i32 s50, 0, 0x1c000
	v_add_u32_e32 v166, s49, v149
	v_add_u32_e32 v182, s50, v149
	ds_read_b128 v[154:157], v166
	ds_read_b128 v[158:161], v166 offset:1024
	ds_read_b128 v[162:165], v166 offset:2048
	ds_read_b128 v[166:169], v166 offset:3072
	ds_read_b128 v[170:173], v182
	ds_read_b128 v[174:177], v182 offset:1024
	ds_read_b128 v[178:181], v182 offset:2048
	ds_read_b128 v[182:185], v182 offset:3072
	s_add_u32 s22, s40, 0x160000
	s_addc_u32 s23, s41, 0
	s_mov_b32 m0, s24
	v_lshl_add_u64 v[224:225], s[22:23], 0, v[136:137]
	ds_read_b128 v[186:189], v153 offset:32768
	ds_read_b128 v[190:193], v153 offset:33792
	ds_read_b128 v[194:197], v153 offset:34816
	ds_read_b128 v[198:201], v153 offset:35840
	ds_read_b128 v[202:205], v153 offset:36864
	ds_read_b128 v[206:209], v153 offset:37888
	ds_read_b128 v[210:213], v153 offset:38912
	ds_read_b128 v[214:217], v153 offset:39936
	global_load_lds_dwordx4 v[224:225], off
	v_lshl_add_u64 v[224:225], s[22:23], 0, v[132:133]
	s_mov_b32 m0, s25
	s_nop 0
	global_load_lds_dwordx4 v[224:225], off
	s_waitcnt vmcnt(8)
	s_waitcnt lgkmcnt(0)
	s_barrier
	s_setprio 1
	s_waitcnt lgkmcnt(0)
	v_mfma_f32_16x16x32_bf16 v[126:129], v[154:157], v[186:189], v[126:129]
	v_mfma_f32_16x16x32_bf16 v[122:125], v[162:165], v[186:189], v[122:125]
	v_mfma_f32_16x16x32_bf16 v[118:121], v[154:157], v[194:197], v[118:121]
	v_mfma_f32_16x16x32_bf16 v[110:113], v[162:165], v[194:197], v[110:113]
	v_mfma_f32_16x16x32_bf16 v[102:105], v[154:157], v[202:205], v[102:105]
	v_mfma_f32_16x16x32_bf16 v[94:97], v[162:165], v[202:205], v[94:97]
	v_mfma_f32_16x16x32_bf16 v[86:89], v[154:157], v[210:213], v[86:89]
	v_mfma_f32_16x16x32_bf16 v[78:81], v[162:165], v[210:213], v[78:81]
	v_mfma_f32_16x16x32_bf16 v[126:129], v[158:161], v[190:193], v[126:129]
	v_mfma_f32_16x16x32_bf16 v[122:125], v[166:169], v[190:193], v[122:125]
	v_mfma_f32_16x16x32_bf16 v[118:121], v[158:161], v[198:201], v[118:121]
	v_mfma_f32_16x16x32_bf16 v[110:113], v[166:169], v[198:201], v[110:113]
	v_mfma_f32_16x16x32_bf16 v[102:105], v[158:161], v[206:209], v[102:105]
	v_mfma_f32_16x16x32_bf16 v[94:97], v[166:169], v[206:209], v[94:97]
	v_mfma_f32_16x16x32_bf16 v[86:89], v[158:161], v[214:217], v[86:89]
	v_mfma_f32_16x16x32_bf16 v[78:81], v[166:169], v[214:217], v[78:81]
	s_setprio 0
	s_setprio 1
	v_mfma_f32_16x16x32_bf16 v[114:117], v[170:173], v[186:189], v[114:117]
	v_mfma_f32_16x16x32_bf16 v[106:109], v[178:181], v[186:189], v[106:109]
	v_mfma_f32_16x16x32_bf16 v[98:101], v[170:173], v[194:197], v[98:101]
	v_mfma_f32_16x16x32_bf16 v[90:93], v[178:181], v[194:197], v[90:93]
	v_mfma_f32_16x16x32_bf16 v[82:85], v[170:173], v[202:205], v[82:85]
	v_mfma_f32_16x16x32_bf16 v[74:77], v[178:181], v[202:205], v[74:77]
	v_mfma_f32_16x16x32_bf16 v[70:73], v[170:173], v[210:213], v[70:73]
	v_mfma_f32_16x16x32_bf16 v[66:69], v[178:181], v[210:213], v[66:69]
	v_mfma_f32_16x16x32_bf16 v[114:117], v[174:177], v[190:193], v[114:117]
	v_mfma_f32_16x16x32_bf16 v[106:109], v[182:185], v[190:193], v[106:109]
	v_mfma_f32_16x16x32_bf16 v[98:101], v[174:177], v[198:201], v[98:101]
	v_mfma_f32_16x16x32_bf16 v[90:93], v[182:185], v[198:201], v[90:93]
	v_mfma_f32_16x16x32_bf16 v[82:85], v[174:177], v[206:209], v[82:85]
	v_mfma_f32_16x16x32_bf16 v[74:77], v[182:185], v[206:209], v[74:77]
	v_mfma_f32_16x16x32_bf16 v[70:73], v[174:177], v[214:217], v[70:73]
	v_mfma_f32_16x16x32_bf16 v[66:69], v[182:185], v[214:217], v[66:69]
	s_setprio 0
	s_barrier
; #define PG8_STAGE(bufoff, gbase, voff) do { _Pragma("unroll") for (int _i = 0; _i < 2; ++_i) \
;         __builtin_amdgcn_global_load_lds((const unsigned*)((const char*)(gbase) + (voff)[_i]), (PG8_LAS unsigned*)(lds + (bufoff) + ldsw + _i * 8192), 16, 0, 0); } while (0)
; #define PG8_LDA(dst, b, h) do { _Pragma("unroll") for (int m = 0; m < 4; ++m) _Pragma("unroll") for (int k = 0; k < 2; ++k) dst[m][k] = *(const PG8_LAS bf16x8*)(lds + PG8_SA(b, h) + aoff + m * 2048 + k * 1024); } while (0)
; #define PG8_MMA(ai, bj, At, Bt) do { __builtin_amdgcn_s_setprio(1); _Pragma("unroll") for (int m = 0; m < 4; ++m) _Pragma("unroll") for (int n = 0; n < 2; ++n) _Pragma("unroll") for (int k = 0; k < 2; ++k) \
;         acc[ai][bj][m][n] = __builtin_amdgcn_mfma_f32_16x16x32_bf16(Bt[n][k], At[m][k], acc[ai][bj][m][n], 0, 0, 0); __builtin_amdgcn_s_setprio(0); } while (0)
; #define PG8_WAIT_V(n) asm volatile("s_waitcnt vmcnt(" #n ")" ::: "memory")
; #define PG8_WAIT_L(n) asm volatile("s_waitcnt lgkmcnt(" #n ")" ::: "memory")
; #define PG8_BAR __builtin_amdgcn_s_barrier()
; #define PG8_SCHED __builtin_amdgcn_sched_barrier(0)
; template <class Epi, class Sched, bool ALIGN_EPI = false, bool SP2 = false>
; __device__ __forceinline__ void gemm_phase(PG8_LAS unsigned char* lds, const Gemm g, const Sched& S, const Epi& E) {
;     ...
;         for (int t = 0; t < nt; t += 2) {
;     ...
;             PG8_LDA(At, 1, 1); PG8_STAGE(PG8_SB(1, 0), b3, voffB); PG8_STAGE(PG8_SB(1, 1), b3 + hstep, voffB); PG8_STAGE(PG8_SA(1, 0), a3, voffA);
;             PG8_WAIT_V(8); PG8_WAIT_L(0); PG8_BAR; PG8_MMA(1, 0, At, B0); PG8_MMA(1, 1, At, B1); PG8_BAR; PG8_SCHED;
	s_add_i32 s22, s49, s16
	v_lshl_add_u64 v[146:147], v[146:147], 0, s[12:13]
	s_mov_b32 m0, s22
	ds_read_b128 v[186:189], v153 offset:49152
	ds_read_b128 v[190:193], v153 offset:50176
	ds_read_b128 v[194:197], v153 offset:51200
	ds_read_b128 v[198:201], v153 offset:52224
	ds_read_b128 v[202:205], v153 offset:53248
	ds_read_b128 v[206:209], v153 offset:54272
	ds_read_b128 v[210:213], v153 offset:55296
	ds_read_b128 v[214:217], v153 offset:56320
	global_load_lds_dwordx4 v[146:147], off
	s_add_i32 m0, s22, 0x2000
	s_add_u32 s22, s38, 0x160080
	v_lshl_add_u64 v[146:147], v[218:219], 0, s[12:13]
	s_addc_u32 s23, s39, 0
	s_add_i32 s38, s50, s16
	global_load_lds_dwordx4 v[146:147], off
	v_lshl_add_u64 v[146:147], s[22:23], 0, v[134:135]
	s_mov_b32 m0, s38
	s_nop 0
	global_load_lds_dwordx4 v[146:147], off
	v_lshl_add_u64 v[146:147], s[22:23], 0, v[130:131]
	s_add_i32 m0, s38, 0x2000
	s_nop 0
	global_load_lds_dwordx4 v[146:147], off
	v_lshl_add_u64 v[146:147], v[220:221], 0, s[12:13]
	s_mov_b32 m0, s28
	s_nop 0
	global_load_lds_dwordx4 v[146:147], off
	v_lshl_add_u64 v[146:147], v[222:223], 0, s[12:13]
	s_mov_b32 m0, s29
	s_nop 0
	global_load_lds_dwordx4 v[146:147], off
	s_waitcnt vmcnt(8)
	s_waitcnt lgkmcnt(0)
	s_barrier
	s_setprio 1
	s_waitcnt lgkmcnt(0)
	v_mfma_f32_16x16x32_bf16 v[62:65], v[154:157], v[186:189], v[62:65]
	v_mfma_f32_16x16x32_bf16 v[58:61], v[162:165], v[186:189], v[58:61]
	v_mfma_f32_16x16x32_bf16 v[54:57], v[154:157], v[194:197], v[54:57]
	v_mfma_f32_16x16x32_bf16 v[46:49], v[162:165], v[194:197], v[46:49]
	v_mfma_f32_16x16x32_bf16 v[38:41], v[154:157], v[202:205], v[38:41]
	v_mfma_f32_16x16x32_bf16 v[30:33], v[162:165], v[202:205], v[30:33]
	v_mfma_f32_16x16x32_bf16 v[22:25], v[154:157], v[210:213], v[22:25]
	v_mfma_f32_16x16x32_bf16 v[14:17], v[162:165], v[210:213], v[14:17]
	v_mfma_f32_16x16x32_bf16 v[62:65], v[158:161], v[190:193], v[62:65]
	v_mfma_f32_16x16x32_bf16 v[58:61], v[166:169], v[190:193], v[58:61]
	v_mfma_f32_16x16x32_bf16 v[54:57], v[158:161], v[198:201], v[54:57]
	v_mfma_f32_16x16x32_bf16 v[46:49], v[166:169], v[198:201], v[46:49]
	v_mfma_f32_16x16x32_bf16 v[38:41], v[158:161], v[206:209], v[38:41]
	v_mfma_f32_16x16x32_bf16 v[30:33], v[166:169], v[206:209], v[30:33]
	v_mfma_f32_16x16x32_bf16 v[22:25], v[158:161], v[214:217], v[22:25]
	v_mfma_f32_16x16x32_bf16 v[14:17], v[166:169], v[214:217], v[14:17]
	s_setprio 0
	s_setprio 1
	v_mfma_f32_16x16x32_bf16 v[50:53], v[170:173], v[186:189], v[50:53]
	v_mfma_f32_16x16x32_bf16 v[42:45], v[178:181], v[186:189], v[42:45]
	v_mfma_f32_16x16x32_bf16 v[34:37], v[170:173], v[194:197], v[34:37]
	v_mfma_f32_16x16x32_bf16 v[26:29], v[178:181], v[194:197], v[26:29]
	v_mfma_f32_16x16x32_bf16 v[18:21], v[170:173], v[202:205], v[18:21]
	v_mfma_f32_16x16x32_bf16 v[10:13], v[178:181], v[202:205], v[10:13]
	v_mfma_f32_16x16x32_bf16 v[6:9], v[170:173], v[210:213], v[6:9]
	v_mfma_f32_16x16x32_bf16 v[2:5], v[178:181], v[210:213], v[2:5]
	v_mfma_f32_16x16x32_bf16 v[50:53], v[174:177], v[190:193], v[50:53]
	v_mfma_f32_16x16x32_bf16 v[42:45], v[182:185], v[190:193], v[42:45]
	v_mfma_f32_16x16x32_bf16 v[34:37], v[174:177], v[198:201], v[34:37]
	v_mfma_f32_16x16x32_bf16 v[26:29], v[182:185], v[198:201], v[26:29]
	v_mfma_f32_16x16x32_bf16 v[18:21], v[174:177], v[206:209], v[18:21]
	v_mfma_f32_16x16x32_bf16 v[10:13], v[182:185], v[206:209], v[10:13]
	v_mfma_f32_16x16x32_bf16 v[6:9], v[174:177], v[214:217], v[6:9]
	v_mfma_f32_16x16x32_bf16 v[2:5], v[182:185], v[214:217], v[2:5]
	s_setprio 0
	s_barrier
	s_add_i32 s48, s48, 2
	s_add_u32 s46, s46, 0x100
	s_addc_u32 s47, s47, 0
	s_cmpk_gt_u32 s48, 0x55
	s_mov_b64 s[22:23], s[36:37]
	s_cbranch_scc0 .LBB0_173
.Lkx_173:
	s_and_b64 vcc, exec, s[14:15]
	s_cbranch_vccz .LBB0_176
	s_barrier

; #define PG8_STAGE(bufoff, gbase, voff) do { _Pragma("unroll") for (int _i = 0; _i < 2; ++_i) \
;         __builtin_amdgcn_global_load_lds((const unsigned*)((const char*)(gbase) + (voff)[_i]), (PG8_LAS unsigned*)(lds + (bufoff) + ldsw + _i * 8192), 16, 0, 0); } while (0)
; #define PG8_LDA(dst, b, h) do { _Pragma("unroll") for (int m = 0; m < 4; ++m) _Pragma("unroll") for (int k = 0; k < 2; ++k) dst[m][k] = *(const PG8_LAS bf16x8*)(lds + PG8_SA(b, h) + aoff + m * 2048 + k * 1024); } while (0)
; #define PG8_LDB(dst, b, h) do { _Pragma("unroll") for (int n = 0; n < 2; ++n) _Pragma("unroll") for (int k = 0; k < 2; ++k) dst[n][k] = *(const PG8_LAS bf16x8*)(lds + PG8_SB(b, h) + boff + n * 2048 + k * 1024); } while (0)
; #define PG8_WAIT_V(n) asm volatile("s_waitcnt vmcnt(" #n ")" ::: "memory")
; #define PG8_BAR __builtin_amdgcn_s_barrier()
; template <class Epi, class Sched, bool ALIGN_EPI = false, bool SP2 = false>
; __device__ __forceinline__ void gemm_phase(PG8_LAS unsigned char* lds, const Gemm g, const Sched& S, const Epi& E) {
;     ...
;         for (int t = 0; t < nt; t += 2) {
;             if constexpr (Epi::MIDHOOK) { if (t == (nt >> 1)) E.mid(acc, cur, wr, wc, fr, fq); }
;             const bool last = (t == nt - 2);
;             const char* a1 = cA + (size_t)(t + 1) * kstep;
;             const char* a2 = last ? nA : cA + (size_t)(t + 2) * kstep; const char* b2 = last ? nB : cB + (size_t)(t + 2) * kstep;
;             const char* a3 = a2 + kstep; const char* b3 = b2 + kstep;
;             if (last && has_next) S.a_ready(nxt);
;             if constexpr (SP2) {
;             PG8_LDB(B0, 0, 0); PG8_LDB(B1, 0, 1); PG8_SCHED; PG8_LDA(At, 0, 0); PG8_STAGE(PG8_SA(1, 1), a1 + hstep, voffA);
;             PG8_WAIT_V(8); PG8_WAIT_L(0); PG8_BAR; PG8_MMA(0, 0, At, B0); PG8_MMA(0, 1, At, B1); PG8_BAR; PG8_SCHED;
;             PG8_LDA(At, 0, 1); PG8_STAGE(PG8_SB(0, 0), b2, voffB); PG8_STAGE(PG8_SB(0, 1), b2 + hstep, voffB); PG8_STAGE(PG8_SA(0, 0), a2, voffA);
;             PG8_WAIT_V(8); PG8_WAIT_L(0); PG8_BAR; PG8_MMA(1, 0, At, B0); PG8_MMA(1, 1, At, B1); PG8_BAR; PG8_SCHED;
;     ...
;         for (int a = 0; a < 2; ++a)
; #pragma unroll
;             for (int b = 0; b < 2; ++b)
; #pragma unroll
;                 for (int m = 0; m < 4; ++m)
; #pragma unroll
;                     for (int n = 0; n < 2; ++n) acc[a][b][m][n] = (f32x4){0.f, 0.f, 0.f, 0.f};
.LBB0_192:
	s_add_u32 s11, s40, 0x100
	s_addc_u32 s52, s41, 0
	s_mov_b32 s53, -2
	ds_read_b128 v[144:147], v141
	ds_read_b128 v[148:151], v141 offset:1024
	ds_read_b128 v[152:155], v141 offset:2048
	ds_read_b128 v[156:159], v141 offset:3072
	ds_read_b128 v[160:163], v142
	ds_read_b128 v[164:167], v142 offset:1024
	ds_read_b128 v[168:171], v142 offset:2048
	ds_read_b128 v[172:175], v142 offset:3072
	s_add_u32 s40, s38, 0x100
	s_addc_u32 s41, s39, 0
	s_cmp_eq_u32 s53, 18
	s_cselect_b32 s45, s23, s41
	s_cselect_b32 s44, s22, s40
	s_cselect_b32 s43, s37, s52
	s_cselect_b32 s42, s36, s11
	v_lshl_add_u64 v[208:209], s[38:39], 0, v[134:135]
	s_add_i32 m0, s19, 0xc000
	ds_read_b128 v[176:179], v143
	ds_read_b128 v[180:183], v143 offset:1024
	ds_read_b128 v[184:187], v143 offset:2048
	ds_read_b128 v[188:191], v143 offset:3072
	ds_read_b128 v[192:195], v143 offset:4096
	ds_read_b128 v[196:199], v143 offset:5120
	ds_read_b128 v[200:203], v143 offset:6144
	ds_read_b128 v[204:207], v143 offset:7168
	global_load_lds_dwordx4 v[208:209], off
	v_lshl_add_u64 v[208:209], s[38:39], 0, v[136:137]
	s_add_i32 m0, s19, 0xe000
	s_nop 0
	global_load_lds_dwordx4 v[208:209], off
	s_waitcnt vmcnt(8)
	s_waitcnt lgkmcnt(0)
	s_barrier
	s_setprio 1
	s_waitcnt lgkmcnt(0)
	v_mfma_f32_16x16x32_bf16 v[126:129], v[144:147], v[176:179], 0
	v_mfma_f32_16x16x32_bf16 v[122:125], v[152:155], v[176:179], 0
	v_mfma_f32_16x16x32_bf16 v[118:121], v[144:147], v[184:187], 0
	v_mfma_f32_16x16x32_bf16 v[114:117], v[152:155], v[184:187], 0
	v_mfma_f32_16x16x32_bf16 v[106:109], v[144:147], v[192:195], 0
	v_mfma_f32_16x16x32_bf16 v[98:101], v[152:155], v[192:195], 0
	v_mfma_f32_16x16x32_bf16 v[90:93], v[144:147], v[200:203], 0
	v_mfma_f32_16x16x32_bf16 v[82:85], v[152:155], v[200:203], 0
	v_mfma_f32_16x16x32_bf16 v[126:129], v[148:151], v[180:183], v[126:129]
	v_mfma_f32_16x16x32_bf16 v[122:125], v[156:159], v[180:183], v[122:125]
	v_mfma_f32_16x16x32_bf16 v[118:121], v[148:151], v[188:191], v[118:121]
	v_mfma_f32_16x16x32_bf16 v[114:117], v[156:159], v[188:191], v[114:117]
	v_mfma_f32_16x16x32_bf16 v[106:109], v[148:151], v[196:199], v[106:109]
	v_mfma_f32_16x16x32_bf16 v[98:101], v[156:159], v[196:199], v[98:101]
	v_mfma_f32_16x16x32_bf16 v[90:93], v[148:151], v[204:207], v[90:93]
	v_mfma_f32_16x16x32_bf16 v[82:85], v[156:159], v[204:207], v[82:85]
	s_setprio 0
	s_setprio 1
	v_mfma_f32_16x16x32_bf16 v[110:113], v[160:163], v[176:179], 0
	v_mfma_f32_16x16x32_bf16 v[102:105], v[168:171], v[176:179], 0
	v_mfma_f32_16x16x32_bf16 v[94:97], v[160:163], v[184:187], 0
	v_mfma_f32_16x16x32_bf16 v[86:89], v[168:171], v[184:187], 0
	v_mfma_f32_16x16x32_bf16 v[78:81], v[160:163], v[192:195], 0
	v_mfma_f32_16x16x32_bf16 v[74:77], v[168:171], v[192:195], 0
	v_mfma_f32_16x16x32_bf16 v[70:73], v[160:163], v[200:203], 0
	v_mfma_f32_16x16x32_bf16 v[66:69], v[168:171], v[200:203], 0
	v_mfma_f32_16x16x32_bf16 v[110:113], v[164:167], v[180:183], v[110:113]
	v_mfma_f32_16x16x32_bf16 v[102:105], v[172:175], v[180:183], v[102:105]
	v_mfma_f32_16x16x32_bf16 v[94:97], v[164:167], v[188:191], v[94:97]
	v_mfma_f32_16x16x32_bf16 v[86:89], v[172:175], v[188:191], v[86:89]
	v_mfma_f32_16x16x32_bf16 v[78:81], v[164:167], v[196:199], v[78:81]
	v_mfma_f32_16x16x32_bf16 v[74:77], v[172:175], v[196:199], v[74:77]
	v_mfma_f32_16x16x32_bf16 v[70:73], v[164:167], v[204:207], v[70:73]
	v_mfma_f32_16x16x32_bf16 v[66:69], v[172:175], v[204:207], v[66:69]
	s_setprio 0
	s_barrier
	s_add_i32 s38, s46, s16
	v_lshl_add_u64 v[208:209], s[42:43], 0, v[132:133]
	s_mov_b32 m0, s38
	ds_read_b128 v[176:179], v143 offset:16384
	ds_read_b128 v[180:183], v143 offset:17408
	ds_read_b128 v[184:187], v143 offset:18432
	ds_read_b128 v[188:191], v143 offset:19456
	ds_read_b128 v[192:195], v143 offset:20480
	ds_read_b128 v[196:199], v143 offset:21504
	ds_read_b128 v[200:203], v143 offset:22528
	ds_read_b128 v[204:207], v143 offset:23552
	global_load_lds_dwordx4 v[208:209], off
	s_add_i32 m0, s38, 0x2000
	s_add_u32 s38, s42, 0x160000
	v_lshl_add_u64 v[210:211], s[42:43], 0, v[130:131]
	s_addc_u32 s39, s43, 0
	s_add_i32 s54, s47, s16
	global_load_lds_dwordx4 v[210:211], off
	v_lshl_add_u64 v[212:213], s[38:39], 0, v[132:133]
	s_mov_b32 m0, s54
	v_lshl_add_u64 v[214:215], s[44:45], 0, v[130:131]
	global_load_lds_dwordx4 v[212:213], off
	v_lshl_add_u64 v[212:213], s[38:39], 0, v[130:131]
	s_add_i32 m0, s54, 0x2000
	s_nop 0
	global_load_lds_dwordx4 v[212:213], off
	v_lshl_add_u64 v[212:213], s[44:45], 0, v[132:133]
	s_mov_b32 m0, s19
	s_nop 0
	global_load_lds_dwordx4 v[212:213], off
	s_mov_b32 m0, s24
	s_nop 0
	global_load_lds_dwordx4 v[214:215], off
	s_waitcnt vmcnt(8)
	s_waitcnt lgkmcnt(0)
	s_barrier
; #define PG8_STAGE(bufoff, gbase, voff) do { _Pragma("unroll") for (int _i = 0; _i < 2; ++_i) \
;         __builtin_amdgcn_global_load_lds((const unsigned*)((const char*)(gbase) + (voff)[_i]), (PG8_LAS unsigned*)(lds + (bufoff) + ldsw + _i * 8192), 16, 0, 0); } while (0)
; #define PG8_LDA(dst, b, h) do { _Pragma("unroll") for (int m = 0; m < 4; ++m) _Pragma("unroll") for (int k = 0; k < 2; ++k) dst[m][k] = *(const PG8_LAS bf16x8*)(lds + PG8_SA(b, h) + aoff + m * 2048 + k * 1024); } while (0)
; #define PG8_LDB(dst, b, h) do { _Pragma("unroll") for (int n = 0; n < 2; ++n) _Pragma("unroll") for (int k = 0; k < 2; ++k) dst[n][k] = *(const PG8_LAS bf16x8*)(lds + PG8_SB(b, h) + boff + n * 2048 + k * 1024); } while (0)
; #define PG8_MMA(ai, bj, At, Bt) do { __builtin_amdgcn_s_setprio(1); _Pragma("unroll") for (int m = 0; m < 4; ++m) _Pragma("unroll") for (int n = 0; n < 2; ++n) _Pragma("unroll") for (int k = 0; k < 2; ++k) \
;         acc[ai][bj][m][n] = __builtin_amdgcn_mfma_f32_16x16x32_bf16(Bt[n][k], At[m][k], acc[ai][bj][m][n], 0, 0, 0); __builtin_amdgcn_s_setprio(0); } while (0)
; #define PG8_WAIT_V(n) asm volatile("s_waitcnt vmcnt(" #n ")" ::: "memory")
; #define PG8_WAIT_L(n) asm volatile("s_waitcnt lgkmcnt(" #n ")" ::: "memory")
; #define PG8_BAR __builtin_amdgcn_s_barrier()
; #define PG8_SCHED __builtin_amdgcn_sched_barrier(0)
; template <class Epi, class Sched, bool ALIGN_EPI = false, bool SP2 = false>
; __device__ __forceinline__ void gemm_phase(PG8_LAS unsigned char* lds, const Gemm g, const Sched& S, const Epi& E) {
;     ...
;             PG8_WAIT_V(8); PG8_WAIT_L(0); PG8_BAR; PG8_MMA(1, 0, At, B0); PG8_MMA(1, 1, At, B1); PG8_BAR; PG8_SCHED;
;             PG8_LDB(B0, 1, 0); PG8_LDB(B1, 1, 1); PG8_SCHED; PG8_LDA(At, 1, 0); PG8_STAGE(PG8_SA(0, 1), a2 + hstep, voffA);
;             PG8_WAIT_V(8); PG8_WAIT_L(0); PG8_BAR; PG8_MMA(0, 0, At, B0); PG8_MMA(0, 1, At, B1); PG8_BAR; PG8_SCHED;
;             PG8_LDA(At, 1, 1); PG8_STAGE(PG8_SB(1, 0), b3, voffB); PG8_STAGE(PG8_SB(1, 1), b3 + hstep, voffB); PG8_STAGE(PG8_SA(1, 0), a3, voffA);
;             PG8_WAIT_V(8); PG8_WAIT_L(0); PG8_BAR; PG8_MMA(1, 0, At, B0); PG8_MMA(1, 1, At, B1); PG8_BAR; PG8_SCHED;
	s_setprio 1
	s_waitcnt lgkmcnt(0)
	v_mfma_f32_16x16x32_bf16 v[62:65], v[144:147], v[176:179], 0
	v_mfma_f32_16x16x32_bf16 v[58:61], v[152:155], v[176:179], 0
	v_mfma_f32_16x16x32_bf16 v[54:57], v[144:147], v[184:187], 0
	v_mfma_f32_16x16x32_bf16 v[50:53], v[152:155], v[184:187], 0
	v_mfma_f32_16x16x32_bf16 v[38:41], v[144:147], v[192:195], 0
	v_mfma_f32_16x16x32_bf16 v[34:37], v[152:155], v[192:195], 0
	v_mfma_f32_16x16x32_bf16 v[22:25], v[144:147], v[200:203], 0
	v_mfma_f32_16x16x32_bf16 v[18:21], v[152:155], v[200:203], 0
	v_mfma_f32_16x16x32_bf16 v[62:65], v[148:151], v[180:183], v[62:65]
	v_mfma_f32_16x16x32_bf16 v[58:61], v[156:159], v[180:183], v[58:61]
	v_mfma_f32_16x16x32_bf16 v[54:57], v[148:151], v[188:191], v[54:57]
	v_mfma_f32_16x16x32_bf16 v[50:53], v[156:159], v[188:191], v[50:53]
	v_mfma_f32_16x16x32_bf16 v[38:41], v[148:151], v[196:199], v[38:41]
	v_mfma_f32_16x16x32_bf16 v[34:37], v[156:159], v[196:199], v[34:37]
	v_mfma_f32_16x16x32_bf16 v[22:25], v[148:151], v[204:207], v[22:25]
	v_mfma_f32_16x16x32_bf16 v[18:21], v[156:159], v[204:207], v[18:21]
	s_setprio 0
	s_setprio 1
	v_mfma_f32_16x16x32_bf16 v[46:49], v[160:163], v[176:179], 0
	v_mfma_f32_16x16x32_bf16 v[42:45], v[168:171], v[176:179], 0
	v_mfma_f32_16x16x32_bf16 v[30:33], v[160:163], v[184:187], 0
	v_mfma_f32_16x16x32_bf16 v[26:29], v[168:171], v[184:187], 0
	v_mfma_f32_16x16x32_bf16 v[14:17], v[160:163], v[192:195], 0
	v_mfma_f32_16x16x32_bf16 v[10:13], v[168:171], v[192:195], 0
	v_mfma_f32_16x16x32_bf16 v[6:9], v[160:163], v[200:203], 0
	v_mfma_f32_16x16x32_bf16 v[2:5], v[168:171], v[200:203], 0
	v_mfma_f32_16x16x32_bf16 v[46:49], v[164:167], v[180:183], v[46:49]
	v_mfma_f32_16x16x32_bf16 v[42:45], v[172:175], v[180:183], v[42:45]
	v_mfma_f32_16x16x32_bf16 v[30:33], v[164:167], v[188:191], v[30:33]
	v_mfma_f32_16x16x32_bf16 v[26:29], v[172:175], v[188:191], v[26:29]
	v_mfma_f32_16x16x32_bf16 v[14:17], v[164:167], v[196:199], v[14:17]
	v_mfma_f32_16x16x32_bf16 v[10:13], v[172:175], v[196:199], v[10:13]
	v_mfma_f32_16x16x32_bf16 v[6:9], v[164:167], v[204:207], v[6:9]
	v_mfma_f32_16x16x32_bf16 v[2:5], v[172:175], v[204:207], v[2:5]
	s_setprio 0
	s_barrier
	s_add_i32 s54, 0, 0x18000
	s_add_i32 s55, 0, 0x1c000
	v_add_u32_e32 v156, s54, v138
	v_add_u32_e32 v172, s55, v138
	ds_read_b128 v[144:147], v156
	ds_read_b128 v[148:151], v156 offset:1024
	ds_read_b128 v[152:155], v156 offset:2048
	ds_read_b128 v[156:159], v156 offset:3072
	ds_read_b128 v[160:163], v172
	ds_read_b128 v[164:167], v172 offset:1024
	ds_read_b128 v[168:171], v172 offset:2048
	ds_read_b128 v[172:175], v172 offset:3072
	s_add_u32 s38, s44, 0x160000
	s_addc_u32 s39, s45, 0
	s_mov_b32 m0, s25
	v_lshl_add_u64 v[216:217], s[38:39], 0, v[132:133]
	ds_read_b128 v[176:179], v143 offset:32768
	ds_read_b128 v[180:183], v143 offset:33792
	ds_read_b128 v[184:187], v143 offset:34816
	ds_read_b128 v[188:191], v143 offset:35840
	ds_read_b128 v[192:195], v143 offset:36864
	ds_read_b128 v[196:199], v143 offset:37888
	ds_read_b128 v[200:203], v143 offset:38912
	ds_read_b128 v[204:207], v143 offset:39936
	global_load_lds_dwordx4 v[216:217], off
	v_lshl_add_u64 v[216:217], s[38:39], 0, v[130:131]
	s_mov_b32 m0, s26
	s_nop 0
	global_load_lds_dwordx4 v[216:217], off
	s_waitcnt vmcnt(8)
	s_waitcnt lgkmcnt(0)
	s_barrier
	s_setprio 1
	s_waitcnt lgkmcnt(0)
	v_mfma_f32_16x16x32_bf16 v[126:129], v[144:147], v[176:179], v[126:129]
	v_mfma_f32_16x16x32_bf16 v[122:125], v[152:155], v[176:179], v[122:125]
	v_mfma_f32_16x16x32_bf16 v[118:121], v[144:147], v[184:187], v[118:121]
	v_mfma_f32_16x16x32_bf16 v[114:117], v[152:155], v[184:187], v[114:117]
	v_mfma_f32_16x16x32_bf16 v[106:109], v[144:147], v[192:195], v[106:109]
	v_mfma_f32_16x16x32_bf16 v[98:101], v[152:155], v[192:195], v[98:101]
	v_mfma_f32_16x16x32_bf16 v[90:93], v[144:147], v[200:203], v[90:93]
	v_mfma_f32_16x16x32_bf16 v[82:85], v[152:155], v[200:203], v[82:85]
	v_mfma_f32_16x16x32_bf16 v[126:129], v[148:151], v[180:183], v[126:129]
	v_mfma_f32_16x16x32_bf16 v[122:125], v[156:159], v[180:183], v[122:125]
	v_mfma_f32_16x16x32_bf16 v[118:121], v[148:151], v[188:191], v[118:121]
	v_mfma_f32_16x16x32_bf16 v[114:117], v[156:159], v[188:191], v[114:117]
	v_mfma_f32_16x16x32_bf16 v[106:109], v[148:151], v[196:199], v[106:109]
	v_mfma_f32_16x16x32_bf16 v[98:101], v[156:159], v[196:199], v[98:101]
	v_mfma_f32_16x16x32_bf16 v[90:93], v[148:151], v[204:207], v[90:93]
	v_mfma_f32_16x16x32_bf16 v[82:85], v[156:159], v[204:207], v[82:85]
	s_setprio 0
	s_setprio 1
	v_mfma_f32_16x16x32_bf16 v[110:113], v[160:163], v[176:179], v[110:113]
	v_mfma_f32_16x16x32_bf16 v[102:105], v[168:171], v[176:179], v[102:105]
	v_mfma_f32_16x16x32_bf16 v[94:97], v[160:163], v[184:187], v[94:97]
	v_mfma_f32_16x16x32_bf16 v[86:89], v[168:171], v[184:187], v[86:89]
	v_mfma_f32_16x16x32_bf16 v[78:81], v[160:163], v[192:195], v[78:81]
	v_mfma_f32_16x16x32_bf16 v[74:77], v[168:171], v[192:195], v[74:77]
	v_mfma_f32_16x16x32_bf16 v[70:73], v[160:163], v[200:203], v[70:73]
	v_mfma_f32_16x16x32_bf16 v[66:69], v[168:171], v[200:203], v[66:69]
	v_mfma_f32_16x16x32_bf16 v[110:113], v[164:167], v[180:183], v[110:113]
	v_mfma_f32_16x16x32_bf16 v[102:105], v[172:175], v[180:183], v[102:105]
	v_mfma_f32_16x16x32_bf16 v[94:97], v[164:167], v[188:191], v[94:97]
	v_mfma_f32_16x16x32_bf16 v[86:89], v[172:175], v[188:191], v[86:89]
	v_mfma_f32_16x16x32_bf16 v[78:81], v[164:167], v[196:199], v[78:81]
	v_mfma_f32_16x16x32_bf16 v[74:77], v[172:175], v[196:199], v[74:77]
	v_mfma_f32_16x16x32_bf16 v[70:73], v[164:167], v[204:207], v[70:73]
	v_mfma_f32_16x16x32_bf16 v[66:69], v[172:175], v[204:207], v[66:69]
	s_setprio 0
	s_barrier
; #define PG8_STAGE(bufoff, gbase, voff) do { _Pragma("unroll") for (int _i = 0; _i < 2; ++_i) \
;         __builtin_amdgcn_global_load_lds((const unsigned*)((const char*)(gbase) + (voff)[_i]), (PG8_LAS unsigned*)(lds + (bufoff) + ldsw + _i * 8192), 16, 0, 0); } while (0)
; #define PG8_LDA(dst, b, h) do { _Pragma("unroll") for (int m = 0; m < 4; ++m) _Pragma("unroll") for (int k = 0; k < 2; ++k) dst[m][k] = *(const PG8_LAS bf16x8*)(lds + PG8_SA(b, h) + aoff + m * 2048 + k * 1024); } while (0)
; #define PG8_LDB(dst, b, h) do { _Pragma("unroll") for (int n = 0; n < 2; ++n) _Pragma("unroll") for (int k = 0; k < 2; ++k) dst[n][k] = *(const PG8_LAS bf16x8*)(lds + PG8_SB(b, h) + boff + n * 2048 + k * 1024); } while (0)
; #define PG8_MMA(ai, bj, At, Bt) do { __builtin_amdgcn_s_setprio(1); _Pragma("unroll") for (int m = 0; m < 4; ++m) _Pragma("unroll") for (int n = 0; n < 2; ++n) _Pragma("unroll") for (int k = 0; k < 2; ++k) \
;         acc[ai][bj][m][n] = __builtin_amdgcn_mfma_f32_16x16x32_bf16(Bt[n][k], At[m][k], acc[ai][bj][m][n], 0, 0, 0); __builtin_amdgcn_s_setprio(0); } while (0)
; #define PG8_WAIT_V(n) asm volatile("s_waitcnt vmcnt(" #n ")" ::: "memory")
; #define PG8_WAIT_L(n) asm volatile("s_waitcnt lgkmcnt(" #n ")" ::: "memory")
; template <class Epi, class Sched, bool ALIGN_EPI = false, bool SP2 = false>
; __device__ __forceinline__ void gemm_phase(PG8_LAS unsigned char* lds, const Gemm g, const Sched& S, const Epi& E) {
;     ...
;         for (int t = 0; t < nt; t += 2) {
;             if constexpr (Epi::MIDHOOK) { if (t == (nt >> 1)) E.mid(acc, cur, wr, wc, fr, fq); }
;             const bool last = (t == nt - 2);
;             const char* a1 = cA + (size_t)(t + 1) * kstep;
;             const char* a2 = last ? nA : cA + (size_t)(t + 2) * kstep; const char* b2 = last ? nB : cB + (size_t)(t + 2) * kstep;
;             const char* a3 = a2 + kstep; const char* b3 = b2 + kstep;
;             if (last && has_next) S.a_ready(nxt);
;             if constexpr (SP2) {
;             PG8_LDB(B0, 0, 0); PG8_LDB(B1, 0, 1); PG8_SCHED; PG8_LDA(At, 0, 0); PG8_STAGE(PG8_SA(1, 1), a1 + hstep, voffA);
;     ...
;             PG8_LDA(At, 1, 1); PG8_STAGE(PG8_SB(1, 0), b3, voffB); PG8_STAGE(PG8_SB(1, 1), b3 + hstep, voffB); PG8_STAGE(PG8_SA(1, 0), a3, voffA);
;             PG8_WAIT_V(8); PG8_WAIT_L(0); PG8_BAR; PG8_MMA(1, 0, At, B0); PG8_MMA(1, 1, At, B1); PG8_BAR; PG8_SCHED;
	s_add_i32 s38, s54, s16
	v_lshl_add_u64 v[208:209], v[208:209], 0, s[14:15]
	s_mov_b32 m0, s38
	ds_read_b128 v[176:179], v143 offset:49152
	ds_read_b128 v[180:183], v143 offset:50176
	ds_read_b128 v[184:187], v143 offset:51200
	ds_read_b128 v[188:191], v143 offset:52224
	ds_read_b128 v[192:195], v143 offset:53248
	ds_read_b128 v[196:199], v143 offset:54272
	ds_read_b128 v[200:203], v143 offset:55296
	ds_read_b128 v[204:207], v143 offset:56320
	global_load_lds_dwordx4 v[208:209], off
	s_add_i32 m0, s38, 0x2000
	s_add_u32 s38, s42, 0x160080
	v_lshl_add_u64 v[208:209], v[210:211], 0, s[14:15]
	s_addc_u32 s39, s43, 0
	s_add_i32 s42, s55, s16
	global_load_lds_dwordx4 v[208:209], off
	v_lshl_add_u64 v[208:209], s[38:39], 0, v[132:133]
	s_mov_b32 m0, s42
	s_nop 0
	global_load_lds_dwordx4 v[208:209], off
	v_lshl_add_u64 v[208:209], s[38:39], 0, v[130:131]
	s_add_i32 m0, s42, 0x2000
	s_nop 0
	global_load_lds_dwordx4 v[208:209], off
	v_lshl_add_u64 v[208:209], v[212:213], 0, s[14:15]
	s_mov_b32 m0, s29
	s_nop 0
	global_load_lds_dwordx4 v[208:209], off
	v_lshl_add_u64 v[208:209], v[214:215], 0, s[14:15]
	s_mov_b32 m0, s30
	s_nop 0
	global_load_lds_dwordx4 v[208:209], off
	s_waitcnt vmcnt(8)
	s_waitcnt lgkmcnt(0)
	s_barrier
	s_setprio 1
	s_waitcnt lgkmcnt(0)
	v_mfma_f32_16x16x32_bf16 v[62:65], v[144:147], v[176:179], v[62:65]
	v_mfma_f32_16x16x32_bf16 v[58:61], v[152:155], v[176:179], v[58:61]
	v_mfma_f32_16x16x32_bf16 v[54:57], v[144:147], v[184:187], v[54:57]
	v_mfma_f32_16x16x32_bf16 v[50:53], v[152:155], v[184:187], v[50:53]
	v_mfma_f32_16x16x32_bf16 v[38:41], v[144:147], v[192:195], v[38:41]
	v_mfma_f32_16x16x32_bf16 v[34:37], v[152:155], v[192:195], v[34:37]
	v_mfma_f32_16x16x32_bf16 v[22:25], v[144:147], v[200:203], v[22:25]
	v_mfma_f32_16x16x32_bf16 v[18:21], v[152:155], v[200:203], v[18:21]
	v_mfma_f32_16x16x32_bf16 v[62:65], v[148:151], v[180:183], v[62:65]
	v_mfma_f32_16x16x32_bf16 v[58:61], v[156:159], v[180:183], v[58:61]
	v_mfma_f32_16x16x32_bf16 v[54:57], v[148:151], v[188:191], v[54:57]
	v_mfma_f32_16x16x32_bf16 v[50:53], v[156:159], v[188:191], v[50:53]
	v_mfma_f32_16x16x32_bf16 v[38:41], v[148:151], v[196:199], v[38:41]
	v_mfma_f32_16x16x32_bf16 v[34:37], v[156:159], v[196:199], v[34:37]
	v_mfma_f32_16x16x32_bf16 v[22:25], v[148:151], v[204:207], v[22:25]
	v_mfma_f32_16x16x32_bf16 v[18:21], v[156:159], v[204:207], v[18:21]
	s_setprio 0
	s_setprio 1
	v_mfma_f32_16x16x32_bf16 v[46:49], v[160:163], v[176:179], v[46:49]
	v_mfma_f32_16x16x32_bf16 v[42:45], v[168:171], v[176:179], v[42:45]
	v_mfma_f32_16x16x32_bf16 v[30:33], v[160:163], v[184:187], v[30:33]
	v_mfma_f32_16x16x32_bf16 v[26:29], v[168:171], v[184:187], v[26:29]
	v_mfma_f32_16x16x32_bf16 v[14:17], v[160:163], v[192:195], v[14:17]
	v_mfma_f32_16x16x32_bf16 v[10:13], v[168:171], v[192:195], v[10:13]
	v_mfma_f32_16x16x32_bf16 v[6:9], v[160:163], v[200:203], v[6:9]
	v_mfma_f32_16x16x32_bf16 v[2:5], v[168:171], v[200:203], v[2:5]
	v_mfma_f32_16x16x32_bf16 v[46:49], v[164:167], v[180:183], v[46:49]
	v_mfma_f32_16x16x32_bf16 v[42:45], v[172:175], v[180:183], v[42:45]
	v_mfma_f32_16x16x32_bf16 v[30:33], v[164:167], v[188:191], v[30:33]
	v_mfma_f32_16x16x32_bf16 v[26:29], v[172:175], v[188:191], v[26:29]
	v_mfma_f32_16x16x32_bf16 v[14:17], v[164:167], v[196:199], v[14:17]
	v_mfma_f32_16x16x32_bf16 v[10:13], v[172:175], v[196:199], v[10:13]
	v_mfma_f32_16x16x32_bf16 v[6:9], v[164:167], v[204:207], v[6:9]
	v_mfma_f32_16x16x32_bf16 v[2:5], v[172:175], v[204:207], v[2:5]
	s_setprio 0
	s_barrier
	s_add_i32 s53, s53, 2
	s_add_u32 s11, s11, 0x100
	s_addc_u32 s52, s52, 0
	s_cmp_gt_u32 s53, 19
	s_mov_b64 s[38:39], s[40:41]
	s_cbranch_scc1 .Lkx_193
.LBB0_193:
	ds_read_b128 v[144:147], v141
	ds_read_b128 v[148:151], v141 offset:1024
	ds_read_b128 v[152:155], v141 offset:2048
	ds_read_b128 v[156:159], v141 offset:3072
	ds_read_b128 v[160:163], v142
	ds_read_b128 v[164:167], v142 offset:1024
	ds_read_b128 v[168:171], v142 offset:2048
	ds_read_b128 v[172:175], v142 offset:3072
	s_add_u32 s40, s38, 0x100
	s_addc_u32 s41, s39, 0
	s_cmp_eq_u32 s53, 18
	s_cselect_b32 s45, s23, s41
	s_cselect_b32 s44, s22, s40
	s_cselect_b32 s43, s37, s52
	s_cselect_b32 s42, s36, s11
	v_lshl_add_u64 v[208:209], s[38:39], 0, v[134:135]
	s_add_i32 m0, s19, 0xc000
	ds_read_b128 v[176:179], v143
	ds_read_b128 v[180:183], v143 offset:1024
	ds_read_b128 v[184:187], v143 offset:2048
	ds_read_b128 v[188:191], v143 offset:3072
	ds_read_b128 v[192:195], v143 offset:4096
	ds_read_b128 v[196:199], v143 offset:5120
	ds_read_b128 v[200:203], v143 offset:6144
	ds_read_b128 v[204:207], v143 offset:7168
	global_load_lds_dwordx4 v[208:209], off
	v_lshl_add_u64 v[208:209], s[38:39], 0, v[136:137]
	s_add_i32 m0, s19, 0xe000
	s_nop 0
	global_load_lds_dwordx4 v[208:209], off
	s_waitcnt vmcnt(8)
	s_waitcnt lgkmcnt(0)
	s_barrier
; #define PG8_STAGE(bufoff, gbase, voff) do { _Pragma("unroll") for (int _i = 0; _i < 2; ++_i) \
;         __builtin_amdgcn_global_load_lds((const unsigned*)((const char*)(gbase) + (voff)[_i]), (PG8_LAS unsigned*)(lds + (bufoff) + ldsw + _i * 8192), 16, 0, 0); } while (0)
; #define PG8_LDA(dst, b, h) do { _Pragma("unroll") for (int m = 0; m < 4; ++m) _Pragma("unroll") for (int k = 0; k < 2; ++k) dst[m][k] = *(const PG8_LAS bf16x8*)(lds + PG8_SA(b, h) + aoff + m * 2048 + k * 1024); } while (0)
; #define PG8_LDB(dst, b, h) do { _Pragma("unroll") for (int n = 0; n < 2; ++n) _Pragma("unroll") for (int k = 0; k < 2; ++k) dst[n][k] = *(const PG8_LAS bf16x8*)(lds + PG8_SB(b, h) + boff + n * 2048 + k * 1024); } while (0)
; #define PG8_MMA(ai, bj, At, Bt) do { __builtin_amdgcn_s_setprio(1); _Pragma("unroll") for (int m = 0; m < 4; ++m) _Pragma("unroll") for (int n = 0; n < 2; ++n) _Pragma("unroll") for (int k = 0; k < 2; ++k) \
;         acc[ai][bj][m][n] = __builtin_amdgcn_mfma_f32_16x16x32_bf16(Bt[n][k], At[m][k], acc[ai][bj][m][n], 0, 0, 0); __builtin_amdgcn_s_setprio(0); } while (0)
; #define PG8_WAIT_V(n) asm volatile("s_waitcnt vmcnt(" #n ")" ::: "memory")
; #define PG8_WAIT_L(n) asm volatile("s_waitcnt lgkmcnt(" #n ")" ::: "memory")
; #define PG8_BAR __builtin_amdgcn_s_barrier()
; #define PG8_SCHED __builtin_amdgcn_sched_barrier(0)
; template <class Epi, class Sched, bool ALIGN_EPI = false, bool SP2 = false>
; __device__ __forceinline__ void gemm_phase(PG8_LAS unsigned char* lds, const Gemm g, const Sched& S, const Epi& E) {
;     ...
;             PG8_LDB(B0, 0, 0); PG8_LDB(B1, 0, 1); PG8_SCHED; PG8_LDA(At, 0, 0); PG8_STAGE(PG8_SA(1, 1), a1 + hstep, voffA);
;             PG8_WAIT_V(8); PG8_WAIT_L(0); PG8_BAR; PG8_MMA(0, 0, At, B0); PG8_MMA(0, 1, At, B1); PG8_BAR; PG8_SCHED;
;             PG8_LDA(At, 0, 1); PG8_STAGE(PG8_SB(0, 0), b2, voffB); PG8_STAGE(PG8_SB(0, 1), b2 + hstep, voffB); PG8_STAGE(PG8_SA(0, 0), a2, voffA);
;             PG8_WAIT_V(8); PG8_WAIT_L(0); PG8_BAR; PG8_MMA(1, 0, At, B0); PG8_MMA(1, 1, At, B1); PG8_BAR; PG8_SCHED;
;             PG8_LDB(B0, 1, 0); PG8_LDB(B1, 1, 1); PG8_SCHED; PG8_LDA(At, 1, 0); PG8_STAGE(PG8_SA(0, 1), a2 + hstep, voffA);
;             PG8_WAIT_V(8); PG8_WAIT_L(0); PG8_BAR; PG8_MMA(0, 0, At, B0); PG8_MMA(0, 1, At, B1); PG8_BAR; PG8_SCHED;
	s_setprio 1
	s_waitcnt lgkmcnt(0)
	v_mfma_f32_16x16x32_bf16 v[126:129], v[144:147], v[176:179], v[126:129]
	v_mfma_f32_16x16x32_bf16 v[122:125], v[152:155], v[176:179], v[122:125]
	v_mfma_f32_16x16x32_bf16 v[118:121], v[144:147], v[184:187], v[118:121]
	v_mfma_f32_16x16x32_bf16 v[114:117], v[152:155], v[184:187], v[114:117]
	v_mfma_f32_16x16x32_bf16 v[106:109], v[144:147], v[192:195], v[106:109]
	v_mfma_f32_16x16x32_bf16 v[98:101], v[152:155], v[192:195], v[98:101]
	v_mfma_f32_16x16x32_bf16 v[90:93], v[144:147], v[200:203], v[90:93]
	v_mfma_f32_16x16x32_bf16 v[82:85], v[152:155], v[200:203], v[82:85]
	v_mfma_f32_16x16x32_bf16 v[126:129], v[148:151], v[180:183], v[126:129]
	v_mfma_f32_16x16x32_bf16 v[122:125], v[156:159], v[180:183], v[122:125]
	v_mfma_f32_16x16x32_bf16 v[118:121], v[148:151], v[188:191], v[118:121]
	v_mfma_f32_16x16x32_bf16 v[114:117], v[156:159], v[188:191], v[114:117]
	v_mfma_f32_16x16x32_bf16 v[106:109], v[148:151], v[196:199], v[106:109]
	v_mfma_f32_16x16x32_bf16 v[98:101], v[156:159], v[196:199], v[98:101]
	v_mfma_f32_16x16x32_bf16 v[90:93], v[148:151], v[204:207], v[90:93]
	v_mfma_f32_16x16x32_bf16 v[82:85], v[156:159], v[204:207], v[82:85]
	s_setprio 0
	s_setprio 1
	v_mfma_f32_16x16x32_bf16 v[110:113], v[160:163], v[176:179], v[110:113]
	v_mfma_f32_16x16x32_bf16 v[102:105], v[168:171], v[176:179], v[102:105]
	v_mfma_f32_16x16x32_bf16 v[94:97], v[160:163], v[184:187], v[94:97]
	v_mfma_f32_16x16x32_bf16 v[86:89], v[168:171], v[184:187], v[86:89]
	v_mfma_f32_16x16x32_bf16 v[78:81], v[160:163], v[192:195], v[78:81]
	v_mfma_f32_16x16x32_bf16 v[74:77], v[168:171], v[192:195], v[74:77]
	v_mfma_f32_16x16x32_bf16 v[70:73], v[160:163], v[200:203], v[70:73]
	v_mfma_f32_16x16x32_bf16 v[66:69], v[168:171], v[200:203], v[66:69]
	v_mfma_f32_16x16x32_bf16 v[110:113], v[164:167], v[180:183], v[110:113]
	v_mfma_f32_16x16x32_bf16 v[102:105], v[172:175], v[180:183], v[102:105]
	v_mfma_f32_16x16x32_bf16 v[94:97], v[164:167], v[188:191], v[94:97]
	v_mfma_f32_16x16x32_bf16 v[86:89], v[172:175], v[188:191], v[86:89]
	v_mfma_f32_16x16x32_bf16 v[78:81], v[164:167], v[196:199], v[78:81]
	v_mfma_f32_16x16x32_bf16 v[74:77], v[172:175], v[196:199], v[74:77]
	v_mfma_f32_16x16x32_bf16 v[70:73], v[164:167], v[204:207], v[70:73]
	v_mfma_f32_16x16x32_bf16 v[66:69], v[172:175], v[204:207], v[66:69]
	s_setprio 0
	s_barrier
	s_add_i32 s38, s46, s16
	v_lshl_add_u64 v[208:209], s[42:43], 0, v[132:133]
	s_mov_b32 m0, s38
	ds_read_b128 v[176:179], v143 offset:16384
	ds_read_b128 v[180:183], v143 offset:17408
	ds_read_b128 v[184:187], v143 offset:18432
	ds_read_b128 v[188:191], v143 offset:19456
	ds_read_b128 v[192:195], v143 offset:20480
	ds_read_b128 v[196:199], v143 offset:21504
	ds_read_b128 v[200:203], v143 offset:22528
	ds_read_b128 v[204:207], v143 offset:23552
	global_load_lds_dwordx4 v[208:209], off
	s_add_i32 m0, s38, 0x2000
	s_add_u32 s38, s42, 0x160000
	v_lshl_add_u64 v[210:211], s[42:43], 0, v[130:131]
	s_addc_u32 s39, s43, 0
	s_add_i32 s54, s47, s16
	global_load_lds_dwordx4 v[210:211], off
	v_lshl_add_u64 v[212:213], s[38:39], 0, v[132:133]
	s_mov_b32 m0, s54
	v_lshl_add_u64 v[214:215], s[44:45], 0, v[130:131]
	global_load_lds_dwordx4 v[212:213], off
	v_lshl_add_u64 v[212:213], s[38:39], 0, v[130:131]
	s_add_i32 m0, s54, 0x2000
	s_nop 0
	global_load_lds_dwordx4 v[212:213], off
	v_lshl_add_u64 v[212:213], s[44:45], 0, v[132:133]
	s_mov_b32 m0, s19
	s_nop 0
	global_load_lds_dwordx4 v[212:213], off
	s_mov_b32 m0, s24
	s_nop 0
	global_load_lds_dwordx4 v[214:215], off
	s_waitcnt vmcnt(8)
	s_waitcnt lgkmcnt(0)
	s_barrier
	s_setprio 1
	s_waitcnt lgkmcnt(0)
	v_mfma_f32_16x16x32_bf16 v[62:65], v[144:147], v[176:179], v[62:65]
	v_mfma_f32_16x16x32_bf16 v[58:61], v[152:155], v[176:179], v[58:61]
	v_mfma_f32_16x16x32_bf16 v[54:57], v[144:147], v[184:187], v[54:57]
	v_mfma_f32_16x16x32_bf16 v[50:53], v[152:155], v[184:187], v[50:53]
	v_mfma_f32_16x16x32_bf16 v[38:41], v[144:147], v[192:195], v[38:41]
	v_mfma_f32_16x16x32_bf16 v[34:37], v[152:155], v[192:195], v[34:37]
	v_mfma_f32_16x16x32_bf16 v[22:25], v[144:147], v[200:203], v[22:25]
	v_mfma_f32_16x16x32_bf16 v[18:21], v[152:155], v[200:203], v[18:21]
	v_mfma_f32_16x16x32_bf16 v[62:65], v[148:151], v[180:183], v[62:65]
	v_mfma_f32_16x16x32_bf16 v[58:61], v[156:159], v[180:183], v[58:61]
	v_mfma_f32_16x16x32_bf16 v[54:57], v[148:151], v[188:191], v[54:57]
	v_mfma_f32_16x16x32_bf16 v[50:53], v[156:159], v[188:191], v[50:53]
	v_mfma_f32_16x16x32_bf16 v[38:41], v[148:151], v[196:199], v[38:41]
	v_mfma_f32_16x16x32_bf16 v[34:37], v[156:159], v[196:199], v[34:37]
	v_mfma_f32_16x16x32_bf16 v[22:25], v[148:151], v[204:207], v[22:25]
	v_mfma_f32_16x16x32_bf16 v[18:21], v[156:159], v[204:207], v[18:21]
	s_setprio 0
	s_setprio 1
	v_mfma_f32_16x16x32_bf16 v[46:49], v[160:163], v[176:179], v[46:49]
	v_mfma_f32_16x16x32_bf16 v[42:45], v[168:171], v[176:179], v[42:45]
	v_mfma_f32_16x16x32_bf16 v[30:33], v[160:163], v[184:187], v[30:33]
	v_mfma_f32_16x16x32_bf16 v[26:29], v[168:171], v[184:187], v[26:29]
	v_mfma_f32_16x16x32_bf16 v[14:17], v[160:163], v[192:195], v[14:17]
	v_mfma_f32_16x16x32_bf16 v[10:13], v[168:171], v[192:195], v[10:13]
	v_mfma_f32_16x16x32_bf16 v[6:9], v[160:163], v[200:203], v[6:9]
	v_mfma_f32_16x16x32_bf16 v[2:5], v[168:171], v[200:203], v[2:5]
	v_mfma_f32_16x16x32_bf16 v[46:49], v[164:167], v[180:183], v[46:49]
	v_mfma_f32_16x16x32_bf16 v[42:45], v[172:175], v[180:183], v[42:45]
	v_mfma_f32_16x16x32_bf16 v[30:33], v[164:167], v[188:191], v[30:33]
	v_mfma_f32_16x16x32_bf16 v[26:29], v[172:175], v[188:191], v[26:29]
	v_mfma_f32_16x16x32_bf16 v[14:17], v[164:167], v[196:199], v[14:17]
	v_mfma_f32_16x16x32_bf16 v[10:13], v[172:175], v[196:199], v[10:13]
	v_mfma_f32_16x16x32_bf16 v[6:9], v[164:167], v[204:207], v[6:9]
	v_mfma_f32_16x16x32_bf16 v[2:5], v[172:175], v[204:207], v[2:5]
	s_setprio 0
	s_barrier
; #define PG8_STAGE(bufoff, gbase, voff) do { _Pragma("unroll") for (int _i = 0; _i < 2; ++_i) \
;         __builtin_amdgcn_global_load_lds((const unsigned*)((const char*)(gbase) + (voff)[_i]), (PG8_LAS unsigned*)(lds + (bufoff) + ldsw + _i * 8192), 16, 0, 0); } while (0)
; #define PG8_LDA(dst, b, h) do { _Pragma("unroll") for (int m = 0; m < 4; ++m) _Pragma("unroll") for (int k = 0; k < 2; ++k) dst[m][k] = *(const PG8_LAS bf16x8*)(lds + PG8_SA(b, h) + aoff + m * 2048 + k * 1024); } while (0)
; #define PG8_LDB(dst, b, h) do { _Pragma("unroll") for (int n = 0; n < 2; ++n) _Pragma("unroll") for (int k = 0; k < 2; ++k) dst[n][k] = *(const PG8_LAS bf16x8*)(lds + PG8_SB(b, h) + boff + n * 2048 + k * 1024); } while (0)
; #define PG8_MMA(ai, bj, At, Bt) do { __builtin_amdgcn_s_setprio(1); _Pragma("unroll") for (int m = 0; m < 4; ++m) _Pragma("unroll") for (int n = 0; n < 2; ++n) _Pragma("unroll") for (int k = 0; k < 2; ++k) \
;         acc[ai][bj][m][n] = __builtin_amdgcn_mfma_f32_16x16x32_bf16(Bt[n][k], At[m][k], acc[ai][bj][m][n], 0, 0, 0); __builtin_amdgcn_s_setprio(0); } while (0)
; #define PG8_WAIT_V(n) asm volatile("s_waitcnt vmcnt(" #n ")" ::: "memory")
; #define PG8_WAIT_L(n) asm volatile("s_waitcnt lgkmcnt(" #n ")" ::: "memory")
; #define PG8_BAR __builtin_amdgcn_s_barrier()
; #define PG8_SCHED __builtin_amdgcn_sched_barrier(0)
; template <class Epi, class Sched, bool ALIGN_EPI = false, bool SP2 = false>
; __device__ __forceinline__ void gemm_phase(PG8_LAS unsigned char* lds, const Gemm g, const Sched& S, const Epi& E) {
;     ...
;             PG8_LDB(B0, 1, 0); PG8_LDB(B1, 1, 1); PG8_SCHED; PG8_LDA(At, 1, 0); PG8_STAGE(PG8_SA(0, 1), a2 + hstep, voffA);
;             PG8_WAIT_V(8); PG8_WAIT_L(0); PG8_BAR; PG8_MMA(0, 0, At, B0); PG8_MMA(0, 1, At, B1); PG8_BAR; PG8_SCHED;
	s_add_i32 s54, 0, 0x18000
	s_add_i32 s55, 0, 0x1c000
	v_add_u32_e32 v156, s54, v138
	v_add_u32_e32 v172, s55, v138
	ds_read_b128 v[144:147], v156
	ds_read_b128 v[148:151], v156 offset:1024
	ds_read_b128 v[152:155], v156 offset:2048
	ds_read_b128 v[156:159], v156 offset:3072
	ds_read_b128 v[160:163], v172
	ds_read_b128 v[164:167], v172 offset:1024
	ds_read_b128 v[168:171], v172 offset:2048
	ds_read_b128 v[172:175], v172 offset:3072
	s_add_u32 s38, s44, 0x160000
	s_addc_u32 s39, s45, 0
	s_mov_b32 m0, s25
	v_lshl_add_u64 v[216:217], s[38:39], 0, v[132:133]
	ds_read_b128 v[176:179], v143 offset:32768
	ds_read_b128 v[180:183], v143 offset:33792
	ds_read_b128 v[184:187], v143 offset:34816
	ds_read_b128 v[188:191], v143 offset:35840
	ds_read_b128 v[192:195], v143 offset:36864
	ds_read_b128 v[196:199], v143 offset:37888
	ds_read_b128 v[200:203], v143 offset:38912
	ds_read_b128 v[204:207], v143 offset:39936
	global_load_lds_dwordx4 v[216:217], off
	v_lshl_add_u64 v[216:217], s[38:39], 0, v[130:131]
	s_mov_b32 m0, s26
	s_nop 0
	global_load_lds_dwordx4 v[216:217], off
	s_waitcnt vmcnt(8)
	s_waitcnt lgkmcnt(0)
	s_barrier
	s_setprio 1
	s_waitcnt lgkmcnt(0)
	v_mfma_f32_16x16x32_bf16 v[126:129], v[144:147], v[176:179], v[126:129]
	v_mfma_f32_16x16x32_bf16 v[122:125], v[152:155], v[176:179], v[122:125]
	v_mfma_f32_16x16x32_bf16 v[118:121], v[144:147], v[184:187], v[118:121]
	v_mfma_f32_16x16x32_bf16 v[114:117], v[152:155], v[184:187], v[114:117]
	v_mfma_f32_16x16x32_bf16 v[106:109], v[144:147], v[192:195], v[106:109]
	v_mfma_f32_16x16x32_bf16 v[98:101], v[152:155], v[192:195], v[98:101]
	v_mfma_f32_16x16x32_bf16 v[90:93], v[144:147], v[200:203], v[90:93]
	v_mfma_f32_16x16x32_bf16 v[82:85], v[152:155], v[200:203], v[82:85]
	v_mfma_f32_16x16x32_bf16 v[126:129], v[148:151], v[180:183], v[126:129]
	v_mfma_f32_16x16x32_bf16 v[122:125], v[156:159], v[180:183], v[122:125]
	v_mfma_f32_16x16x32_bf16 v[118:121], v[148:151], v[188:191], v[118:121]
	v_mfma_f32_16x16x32_bf16 v[114:117], v[156:159], v[188:191], v[114:117]
	v_mfma_f32_16x16x32_bf16 v[106:109], v[148:151], v[196:199], v[106:109]
	v_mfma_f32_16x16x32_bf16 v[98:101], v[156:159], v[196:199], v[98:101]
	v_mfma_f32_16x16x32_bf16 v[90:93], v[148:151], v[204:207], v[90:93]
	v_mfma_f32_16x16x32_bf16 v[82:85], v[156:159], v[204:207], v[82:85]
	s_setprio 0
	s_setprio 1
	v_mfma_f32_16x16x32_bf16 v[110:113], v[160:163], v[176:179], v[110:113]
	v_mfma_f32_16x16x32_bf16 v[102:105], v[168:171], v[176:179], v[102:105]
	v_mfma_f32_16x16x32_bf16 v[94:97], v[160:163], v[184:187], v[94:97]
	v_mfma_f32_16x16x32_bf16 v[86:89], v[168:171], v[184:187], v[86:89]
	v_mfma_f32_16x16x32_bf16 v[78:81], v[160:163], v[192:195], v[78:81]
	v_mfma_f32_16x16x32_bf16 v[74:77], v[168:171], v[192:195], v[74:77]
	v_mfma_f32_16x16x32_bf16 v[70:73], v[160:163], v[200:203], v[70:73]
	v_mfma_f32_16x16x32_bf16 v[66:69], v[168:171], v[200:203], v[66:69]
	v_mfma_f32_16x16x32_bf16 v[110:113], v[164:167], v[180:183], v[110:113]
	v_mfma_f32_16x16x32_bf16 v[102:105], v[172:175], v[180:183], v[102:105]
	v_mfma_f32_16x16x32_bf16 v[94:97], v[164:167], v[188:191], v[94:97]
	v_mfma_f32_16x16x32_bf16 v[86:89], v[172:175], v[188:191], v[86:89]
	v_mfma_f32_16x16x32_bf16 v[78:81], v[164:167], v[196:199], v[78:81]
	v_mfma_f32_16x16x32_bf16 v[74:77], v[172:175], v[196:199], v[74:77]
	v_mfma_f32_16x16x32_bf16 v[70:73], v[164:167], v[204:207], v[70:73]
	v_mfma_f32_16x16x32_bf16 v[66:69], v[172:175], v[204:207], v[66:69]
	s_setprio 0
	s_barrier
; #define PG8_STAGE(bufoff, gbase, voff) do { _Pragma("unroll") for (int _i = 0; _i < 2; ++_i) \
;         __builtin_amdgcn_global_load_lds((const unsigned*)((const char*)(gbase) + (voff)[_i]), (PG8_LAS unsigned*)(lds + (bufoff) + ldsw + _i * 8192), 16, 0, 0); } while (0)
; #define PG8_LDA(dst, b, h) do { _Pragma("unroll") for (int m = 0; m < 4; ++m) _Pragma("unroll") for (int k = 0; k < 2; ++k) dst[m][k] = *(const PG8_LAS bf16x8*)(lds + PG8_SA(b, h) + aoff + m * 2048 + k * 1024); } while (0)
; #define PG8_MMA(ai, bj, At, Bt) do { __builtin_amdgcn_s_setprio(1); _Pragma("unroll") for (int m = 0; m < 4; ++m) _Pragma("unroll") for (int n = 0; n < 2; ++n) _Pragma("unroll") for (int k = 0; k < 2; ++k) \
;         acc[ai][bj][m][n] = __builtin_amdgcn_mfma_f32_16x16x32_bf16(Bt[n][k], At[m][k], acc[ai][bj][m][n], 0, 0, 0); __builtin_amdgcn_s_setprio(0); } while (0)
; #define PG8_WAIT_V(n) asm volatile("s_waitcnt vmcnt(" #n ")" ::: "memory")
; #define PG8_WAIT_L(n) asm volatile("s_waitcnt lgkmcnt(" #n ")" ::: "memory")
; #define PG8_BAR __builtin_amdgcn_s_barrier()
; #define PG8_SCHED __builtin_amdgcn_sched_barrier(0)
; template <class Epi, class Sched, bool ALIGN_EPI = false, bool SP2 = false>
; __device__ __forceinline__ void gemm_phase(PG8_LAS unsigned char* lds, const Gemm g, const Sched& S, const Epi& E) {
;     ...
;         for (int t = 0; t < nt; t += 2) {
;     ...
;             PG8_LDA(At, 1, 1); PG8_STAGE(PG8_SB(1, 0), b3, voffB); PG8_STAGE(PG8_SB(1, 1), b3 + hstep, voffB); PG8_STAGE(PG8_SA(1, 0), a3, voffA);
;             PG8_WAIT_V(8); PG8_WAIT_L(0); PG8_BAR; PG8_MMA(1, 0, At, B0); PG8_MMA(1, 1, At, B1); PG8_BAR; PG8_SCHED;
	s_add_i32 s38, s54, s16
	v_lshl_add_u64 v[208:209], v[208:209], 0, s[14:15]
	s_mov_b32 m0, s38
	ds_read_b128 v[176:179], v143 offset:49152
	ds_read_b128 v[180:183], v143 offset:50176
	ds_read_b128 v[184:187], v143 offset:51200
	ds_read_b128 v[188:191], v143 offset:52224
	ds_read_b128 v[192:195], v143 offset:53248
	ds_read_b128 v[196:199], v143 offset:54272
	ds_read_b128 v[200:203], v143 offset:55296
	ds_read_b128 v[204:207], v143 offset:56320
	global_load_lds_dwordx4 v[208:209], off
	s_add_i32 m0, s38, 0x2000
	s_add_u32 s38, s42, 0x160080
	v_lshl_add_u64 v[208:209], v[210:211], 0, s[14:15]
	s_addc_u32 s39, s43, 0
	s_add_i32 s42, s55, s16
	global_load_lds_dwordx4 v[208:209], off
	v_lshl_add_u64 v[208:209], s[38:39], 0, v[132:133]
	s_mov_b32 m0, s42
	s_nop 0
	global_load_lds_dwordx4 v[208:209], off
	v_lshl_add_u64 v[208:209], s[38:39], 0, v[130:131]
	s_add_i32 m0, s42, 0x2000
	s_nop 0
	global_load_lds_dwordx4 v[208:209], off
	v_lshl_add_u64 v[208:209], v[212:213], 0, s[14:15]
	s_mov_b32 m0, s29
	s_nop 0
	global_load_lds_dwordx4 v[208:209], off
	v_lshl_add_u64 v[208:209], v[214:215], 0, s[14:15]
	s_mov_b32 m0, s30
	s_nop 0
	global_load_lds_dwordx4 v[208:209], off
	s_waitcnt vmcnt(8)
	s_waitcnt lgkmcnt(0)
	s_barrier
	s_setprio 1
	s_waitcnt lgkmcnt(0)
	v_mfma_f32_16x16x32_bf16 v[62:65], v[144:147], v[176:179], v[62:65]
	v_mfma_f32_16x16x32_bf16 v[58:61], v[152:155], v[176:179], v[58:61]
	v_mfma_f32_16x16x32_bf16 v[54:57], v[144:147], v[184:187], v[54:57]
	v_mfma_f32_16x16x32_bf16 v[50:53], v[152:155], v[184:187], v[50:53]
	v_mfma_f32_16x16x32_bf16 v[38:41], v[144:147], v[192:195], v[38:41]
	v_mfma_f32_16x16x32_bf16 v[34:37], v[152:155], v[192:195], v[34:37]
	v_mfma_f32_16x16x32_bf16 v[22:25], v[144:147], v[200:203], v[22:25]
	v_mfma_f32_16x16x32_bf16 v[18:21], v[152:155], v[200:203], v[18:21]
	v_mfma_f32_16x16x32_bf16 v[62:65], v[148:151], v[180:183], v[62:65]
	v_mfma_f32_16x16x32_bf16 v[58:61], v[156:159], v[180:183], v[58:61]
	v_mfma_f32_16x16x32_bf16 v[54:57], v[148:151], v[188:191], v[54:57]
	v_mfma_f32_16x16x32_bf16 v[50:53], v[156:159], v[188:191], v[50:53]
	v_mfma_f32_16x16x32_bf16 v[38:41], v[148:151], v[196:199], v[38:41]
	v_mfma_f32_16x16x32_bf16 v[34:37], v[156:159], v[196:199], v[34:37]
	v_mfma_f32_16x16x32_bf16 v[22:25], v[148:151], v[204:207], v[22:25]
	v_mfma_f32_16x16x32_bf16 v[18:21], v[156:159], v[204:207], v[18:21]
	s_setprio 0
	s_setprio 1
	v_mfma_f32_16x16x32_bf16 v[46:49], v[160:163], v[176:179], v[46:49]
	v_mfma_f32_16x16x32_bf16 v[42:45], v[168:171], v[176:179], v[42:45]
	v_mfma_f32_16x16x32_bf16 v[30:33], v[160:163], v[184:187], v[30:33]
	v_mfma_f32_16x16x32_bf16 v[26:29], v[168:171], v[184:187], v[26:29]
	v_mfma_f32_16x16x32_bf16 v[14:17], v[160:163], v[192:195], v[14:17]
	v_mfma_f32_16x16x32_bf16 v[10:13], v[168:171], v[192:195], v[10:13]
	v_mfma_f32_16x16x32_bf16 v[6:9], v[160:163], v[200:203], v[6:9]
	v_mfma_f32_16x16x32_bf16 v[2:5], v[168:171], v[200:203], v[2:5]
	v_mfma_f32_16x16x32_bf16 v[46:49], v[164:167], v[180:183], v[46:49]
	v_mfma_f32_16x16x32_bf16 v[42:45], v[172:175], v[180:183], v[42:45]
	v_mfma_f32_16x16x32_bf16 v[30:33], v[164:167], v[188:191], v[30:33]
	v_mfma_f32_16x16x32_bf16 v[26:29], v[172:175], v[188:191], v[26:29]
	v_mfma_f32_16x16x32_bf16 v[14:17], v[164:167], v[196:199], v[14:17]
	v_mfma_f32_16x16x32_bf16 v[10:13], v[172:175], v[196:199], v[10:13]
	v_mfma_f32_16x16x32_bf16 v[6:9], v[164:167], v[204:207], v[6:9]
	v_mfma_f32_16x16x32_bf16 v[2:5], v[172:175], v[204:207], v[2:5]
	s_setprio 0
	s_barrier
	s_add_i32 s53, s53, 2
	s_add_u32 s11, s11, 0x100
	s_addc_u32 s52, s52, 0
	s_cmp_gt_u32 s53, 19
	s_mov_b64 s[38:39], s[40:41]
	s_cbranch_scc0 .LBB0_193
.Lkx_193:
	s_and_b64 vcc, exec, s[20:21]
	s_cbranch_vccz .LBB0_196
	s_barrier

;     __device__ bool next(int i, Unit& u) const { if (!s.next(i, u)) return false; const int p = u.pn; u.pn = p < 56 ? (p % 7) * 8 + p / 7 : p; return true; }
;     __device__ bool next(int i, Unit& u) const { Unit t; if (!s.next(i >> 1, t)) return false; const int pass = i & 1; u.pm = t.pm + pass * (M / BM); u.pn = t.pn + pass * (D / BM); u.kt0 = 0; return true; }
; #define PG8_LDA(dst, b, h) do { _Pragma("unroll") for (int m = 0; m < 4; ++m) _Pragma("unroll") for (int k = 0; k < 2; ++k) dst[m][k] = *(const PG8_LAS bf16x8*)(lds + PG8_SA(b, h) + aoff + m * 2048 + k * 1024); } while (0)
; template <class Epi, class Sched, bool ALIGN_EPI = false, bool SP2 = false>
; __device__ __forceinline__ void gemm_phase(PG8_LAS unsigned char* lds, const Gemm g, const Sched& S, const Epi& E) {
;     ...
;         const bool has_next = S.next(ui + 1, nxt);
;         const char* nA = has_next ? (const char*)g.A + (size_t)nxt.pm * tstep + (size_t)nxt.kt0 * kstep : cA; const char* nB = has_next ? (const char*)g.Bt + (size_t)nxt.pn * tstep + (size_t)nxt.kt0 * kstep : cB;
;         for (int t = 0; t < nt; t += 2) {
;             if constexpr (Epi::MIDHOOK) { if (t == (nt >> 1)) E.mid(acc, cur, wr, wc, fr, fq); }
;             const bool last = (t == nt - 2);
;             const char* a1 = cA + (size_t)(t + 1) * kstep;
;             const char* a2 = last ? nA : cA + (size_t)(t + 2) * kstep; const char* b2 = last ? nB : cB + (size_t)(t + 2) * kstep;
;             const char* a3 = a2 + kstep; const char* b3 = b2 + kstep;
;             if (last && has_next) S.a_ready(nxt);
;             if constexpr (SP2) {
;             PG8_LDB(B0, 0, 0); PG8_LDB(B1, 0, 1); PG8_SCHED; PG8_LDA(At, 0, 0); PG8_STAGE(PG8_SA(1, 1), a1 + hstep, voffA);
;             PG8_WAIT_V(8); PG8_WAIT_L(0); PG8_BAR; PG8_MMA(0, 0, At, B0); PG8_MMA(0, 1, At, B1); PG8_BAR; PG8_SCHED;
;             PG8_LDA(At, 0, 1); PG8_STAGE(PG8_SB(0, 0), b2, voffB); PG8_STAGE(PG8_SB(0, 1), b2 + hstep, voffB); PG8_STAGE(PG8_SA(0, 0), a2, voffA);
;             PG8_WAIT_V(8); PG8_WAIT_L(0); PG8_BAR; PG8_MMA(1, 0, At, B0); PG8_MMA(1, 1, At, B1); PG8_BAR; PG8_SCHED;
;     ...
;         for (int a = 0; a < 2; ++a)
; #pragma unroll
;             for (int b = 0; b < 2; ++b)
; #pragma unroll
;                 for (int m = 0; m < 4; ++m)
; #pragma unroll
;                     for (int n = 0; n < 2; ++n) acc[a][b][m][n] = (f32x4){0.f, 0.f, 0.f, 0.f};
.LBB0_345:
	s_ashr_i32 s57, s56, 31
	s_lshl_b64 s[6:7], s[56:57], 20
	v_readlane_b32 s16, v245, 44
	v_readlane_b32 s17, v245, 45
	s_add_u32 s82, s16, s6
	s_addc_u32 s83, s17, s7
	s_and_b64 s[6:7], s[8:9], exec
	s_cselect_b32 s6, s83, s11
	s_cselect_b32 s7, s82, s10
	s_ashr_i32 s67, s66, 31
	s_lshl_b64 s[16:17], s[66:67], 20
	s_add_u32 s88, s33, s16
	s_addc_u32 s89, s53, s17
	s_and_b64 s[16:17], s[8:9], exec
	s_cselect_b32 s13, s89, s15
	s_cselect_b32 s18, s88, s14
	s_add_u32 s10, s10, 0x80080
	s_addc_u32 s11, s11, 0
	s_add_u32 s19, s14, 0x100
	s_addc_u32 s22, s15, 0
	s_mov_b32 s23, -2
	s_waitcnt lgkmcnt(0)
	ds_read_b128 v[150:153], v177
	ds_read_b128 v[154:157], v177 offset:1024
	ds_read_b128 v[158:161], v177 offset:2048
	ds_read_b128 v[162:165], v177 offset:3072
	ds_read_b128 v[166:169], v178
	ds_read_b128 v[182:185], v178 offset:1024
	ds_read_b128 v[186:189], v178 offset:2048
	ds_read_b128 v[190:193], v178 offset:3072
	s_add_u32 s14, s10, 0xfff80080
	s_addc_u32 s15, s11, -1
	s_cmp_eq_u32 s23, 28
	s_cselect_b32 s17, s6, s15
	s_cselect_b32 s16, s7, s14
	s_cselect_b32 s15, s13, s22
	s_cselect_b32 s14, s18, s19
	v_lshl_add_u64 v[170:171], s[10:11], 0, v[142:143]
	s_add_i32 m0, s59, 0xc000
	ds_read_b128 v[194:197], v179
	ds_read_b128 v[198:201], v179 offset:1024
	ds_read_b128 v[202:205], v179 offset:2048
	ds_read_b128 v[206:209], v179 offset:3072
	ds_read_b128 v[210:213], v179 offset:4096
	ds_read_b128 v[214:217], v179 offset:5120
	ds_read_b128 v[218:221], v179 offset:6144
	ds_read_b128 v[222:225], v179 offset:7168
	global_load_lds_dwordx4 v[170:171], off
	v_lshl_add_u64 v[170:171], s[10:11], 0, v[144:145]
	s_add_i32 m0, s59, 0xe000
	s_nop 0
	global_load_lds_dwordx4 v[170:171], off
	s_waitcnt vmcnt(8)
	s_waitcnt lgkmcnt(0)
	s_barrier
	s_setprio 1
	s_waitcnt lgkmcnt(0)
	v_mfma_f32_16x16x32_bf16 v[58:61], v[150:153], v[194:197], 0
	v_mfma_f32_16x16x32_bf16 v[62:65], v[158:161], v[194:197], 0
	v_mfma_f32_16x16x32_bf16 v[50:53], v[150:153], v[202:205], 0
	v_mfma_f32_16x16x32_bf16 v[54:57], v[158:161], v[202:205], 0
	v_mfma_f32_16x16x32_bf16 v[42:45], v[150:153], v[210:213], 0
	v_mfma_f32_16x16x32_bf16 v[46:49], v[158:161], v[210:213], 0
	v_mfma_f32_16x16x32_bf16 v[34:37], v[150:153], v[218:221], 0
	v_mfma_f32_16x16x32_bf16 v[38:41], v[158:161], v[218:221], 0
	v_mfma_f32_16x16x32_bf16 v[58:61], v[154:157], v[198:201], v[58:61]
	v_mfma_f32_16x16x32_bf16 v[62:65], v[162:165], v[198:201], v[62:65]
	v_mfma_f32_16x16x32_bf16 v[50:53], v[154:157], v[206:209], v[50:53]
	v_mfma_f32_16x16x32_bf16 v[54:57], v[162:165], v[206:209], v[54:57]
	v_mfma_f32_16x16x32_bf16 v[42:45], v[154:157], v[214:217], v[42:45]
	v_mfma_f32_16x16x32_bf16 v[46:49], v[162:165], v[214:217], v[46:49]
	v_mfma_f32_16x16x32_bf16 v[34:37], v[154:157], v[222:225], v[34:37]
	v_mfma_f32_16x16x32_bf16 v[38:41], v[162:165], v[222:225], v[38:41]
	s_setprio 0
	s_setprio 1
	v_mfma_f32_16x16x32_bf16 v[126:129], v[166:169], v[194:197], 0
	v_mfma_f32_16x16x32_bf16 v[122:125], v[186:189], v[194:197], 0
	v_mfma_f32_16x16x32_bf16 v[118:121], v[166:169], v[202:205], 0
	v_mfma_f32_16x16x32_bf16 v[114:117], v[186:189], v[202:205], 0
	v_mfma_f32_16x16x32_bf16 v[110:113], v[166:169], v[210:213], 0
	v_mfma_f32_16x16x32_bf16 v[106:109], v[186:189], v[210:213], 0
	v_mfma_f32_16x16x32_bf16 v[102:105], v[166:169], v[218:221], 0
	v_mfma_f32_16x16x32_bf16 v[98:101], v[186:189], v[218:221], 0
	v_mfma_f32_16x16x32_bf16 v[126:129], v[182:185], v[198:201], v[126:129]
	v_mfma_f32_16x16x32_bf16 v[122:125], v[190:193], v[198:201], v[122:125]
	v_mfma_f32_16x16x32_bf16 v[118:121], v[182:185], v[206:209], v[118:121]
	v_mfma_f32_16x16x32_bf16 v[114:117], v[190:193], v[206:209], v[114:117]
	v_mfma_f32_16x16x32_bf16 v[110:113], v[182:185], v[214:217], v[110:113]
	v_mfma_f32_16x16x32_bf16 v[106:109], v[190:193], v[214:217], v[106:109]
	v_mfma_f32_16x16x32_bf16 v[102:105], v[182:185], v[222:225], v[102:105]
	v_mfma_f32_16x16x32_bf16 v[98:101], v[190:193], v[222:225], v[98:101]
	s_setprio 0
	s_barrier
	s_add_i32 s24, s95, s55
	v_lshl_add_u64 v[170:171], s[14:15], 0, v[132:133]
	s_mov_b32 m0, s24
	ds_read_b128 v[194:197], v179 offset:16384
	ds_read_b128 v[198:201], v179 offset:17408
	ds_read_b128 v[202:205], v179 offset:18432
	ds_read_b128 v[206:209], v179 offset:19456
	ds_read_b128 v[210:213], v179 offset:20480
	ds_read_b128 v[214:217], v179 offset:21504
	ds_read_b128 v[218:221], v179 offset:22528
	ds_read_b128 v[222:225], v179 offset:23552
	global_load_lds_dwordx4 v[170:171], off
	s_add_i32 m0, s24, 0x2000
	s_add_u32 s24, s14, 0x80000
	v_lshl_add_u64 v[226:227], s[14:15], 0, v[136:137]
	s_addc_u32 s25, s15, 0
	s_add_i32 s26, s81, s55
	global_load_lds_dwordx4 v[226:227], off
	v_lshl_add_u64 v[228:229], s[24:25], 0, v[132:133]
	s_mov_b32 m0, s26
	v_lshl_add_u64 v[230:231], s[16:17], 0, v[134:135]
	global_load_lds_dwordx4 v[228:229], off
	v_lshl_add_u64 v[228:229], s[24:25], 0, v[136:137]
	s_add_i32 m0, s26, 0x2000
	s_nop 0
	global_load_lds_dwordx4 v[228:229], off
	v_lshl_add_u64 v[228:229], s[16:17], 0, v[130:131]
	s_mov_b32 m0, s59
	s_nop 0
	global_load_lds_dwordx4 v[228:229], off
	s_mov_b32 m0, s61
	s_nop 0
	global_load_lds_dwordx4 v[230:231], off
	s_waitcnt vmcnt(8)
	s_waitcnt lgkmcnt(0)
	s_barrier
; #define PG8_STAGE(bufoff, gbase, voff) do { _Pragma("unroll") for (int _i = 0; _i < 2; ++_i) \
;         __builtin_amdgcn_global_load_lds((const unsigned*)((const char*)(gbase) + (voff)[_i]), (PG8_LAS unsigned*)(lds + (bufoff) + ldsw + _i * 8192), 16, 0, 0); } while (0)
; #define PG8_LDA(dst, b, h) do { _Pragma("unroll") for (int m = 0; m < 4; ++m) _Pragma("unroll") for (int k = 0; k < 2; ++k) dst[m][k] = *(const PG8_LAS bf16x8*)(lds + PG8_SA(b, h) + aoff + m * 2048 + k * 1024); } while (0)
; #define PG8_LDB(dst, b, h) do { _Pragma("unroll") for (int n = 0; n < 2; ++n) _Pragma("unroll") for (int k = 0; k < 2; ++k) dst[n][k] = *(const PG8_LAS bf16x8*)(lds + PG8_SB(b, h) + boff + n * 2048 + k * 1024); } while (0)
; #define PG8_MMA(ai, bj, At, Bt) do { __builtin_amdgcn_s_setprio(1); _Pragma("unroll") for (int m = 0; m < 4; ++m) _Pragma("unroll") for (int n = 0; n < 2; ++n) _Pragma("unroll") for (int k = 0; k < 2; ++k) \
;         acc[ai][bj][m][n] = __builtin_amdgcn_mfma_f32_16x16x32_bf16(Bt[n][k], At[m][k], acc[ai][bj][m][n], 0, 0, 0); __builtin_amdgcn_s_setprio(0); } while (0)
; #define PG8_WAIT_V(n) asm volatile("s_waitcnt vmcnt(" #n ")" ::: "memory")
; #define PG8_WAIT_L(n) asm volatile("s_waitcnt lgkmcnt(" #n ")" ::: "memory")
; #define PG8_BAR __builtin_amdgcn_s_barrier()
; #define PG8_SCHED __builtin_amdgcn_sched_barrier(0)
; template <class Epi, class Sched, bool ALIGN_EPI = false, bool SP2 = false>
; __device__ __forceinline__ void gemm_phase(PG8_LAS unsigned char* lds, const Gemm g, const Sched& S, const Epi& E) {
;     ...
;             PG8_WAIT_V(8); PG8_WAIT_L(0); PG8_BAR; PG8_MMA(1, 0, At, B0); PG8_MMA(1, 1, At, B1); PG8_BAR; PG8_SCHED;
;             PG8_LDB(B0, 1, 0); PG8_LDB(B1, 1, 1); PG8_SCHED; PG8_LDA(At, 1, 0); PG8_STAGE(PG8_SA(0, 1), a2 + hstep, voffA);
;             PG8_WAIT_V(8); PG8_WAIT_L(0); PG8_BAR; PG8_MMA(0, 0, At, B0); PG8_MMA(0, 1, At, B1); PG8_BAR; PG8_SCHED;
;             PG8_LDA(At, 1, 1); PG8_STAGE(PG8_SB(1, 0), b3, voffB); PG8_STAGE(PG8_SB(1, 1), b3 + hstep, voffB); PG8_STAGE(PG8_SA(1, 0), a3, voffA);
;             PG8_WAIT_V(8); PG8_WAIT_L(0); PG8_BAR; PG8_MMA(1, 0, At, B0); PG8_MMA(1, 1, At, B1); PG8_BAR; PG8_SCHED;
	s_setprio 1
	s_waitcnt lgkmcnt(0)
	v_mfma_f32_16x16x32_bf16 v[26:29], v[150:153], v[194:197], 0
	v_mfma_f32_16x16x32_bf16 v[30:33], v[158:161], v[194:197], 0
	v_mfma_f32_16x16x32_bf16 v[18:21], v[150:153], v[202:205], 0
	v_mfma_f32_16x16x32_bf16 v[22:25], v[158:161], v[202:205], 0
	v_mfma_f32_16x16x32_bf16 v[10:13], v[150:153], v[210:213], 0
	v_mfma_f32_16x16x32_bf16 v[14:17], v[158:161], v[210:213], 0
	v_mfma_f32_16x16x32_bf16 v[2:5], v[150:153], v[218:221], 0
	v_mfma_f32_16x16x32_bf16 v[6:9], v[158:161], v[218:221], 0
	v_mfma_f32_16x16x32_bf16 v[26:29], v[154:157], v[198:201], v[26:29]
	v_mfma_f32_16x16x32_bf16 v[30:33], v[162:165], v[198:201], v[30:33]
	v_mfma_f32_16x16x32_bf16 v[18:21], v[154:157], v[206:209], v[18:21]
	v_mfma_f32_16x16x32_bf16 v[22:25], v[162:165], v[206:209], v[22:25]
	v_mfma_f32_16x16x32_bf16 v[10:13], v[154:157], v[214:217], v[10:13]
	v_mfma_f32_16x16x32_bf16 v[14:17], v[162:165], v[214:217], v[14:17]
	v_mfma_f32_16x16x32_bf16 v[2:5], v[154:157], v[222:225], v[2:5]
	v_mfma_f32_16x16x32_bf16 v[6:9], v[162:165], v[222:225], v[6:9]
	s_setprio 0
	s_setprio 1
	v_mfma_f32_16x16x32_bf16 v[94:97], v[166:169], v[194:197], 0
	v_mfma_f32_16x16x32_bf16 v[90:93], v[186:189], v[194:197], 0
	v_mfma_f32_16x16x32_bf16 v[86:89], v[166:169], v[202:205], 0
	v_mfma_f32_16x16x32_bf16 v[82:85], v[186:189], v[202:205], 0
	v_mfma_f32_16x16x32_bf16 v[78:81], v[166:169], v[210:213], 0
	v_mfma_f32_16x16x32_bf16 v[74:77], v[186:189], v[210:213], 0
	v_mfma_f32_16x16x32_bf16 v[70:73], v[166:169], v[218:221], 0
	v_mfma_f32_16x16x32_bf16 v[66:69], v[186:189], v[218:221], 0
	v_mfma_f32_16x16x32_bf16 v[94:97], v[182:185], v[198:201], v[94:97]
	v_mfma_f32_16x16x32_bf16 v[90:93], v[190:193], v[198:201], v[90:93]
	v_mfma_f32_16x16x32_bf16 v[86:89], v[182:185], v[206:209], v[86:89]
	v_mfma_f32_16x16x32_bf16 v[82:85], v[190:193], v[206:209], v[82:85]
	v_mfma_f32_16x16x32_bf16 v[78:81], v[182:185], v[214:217], v[78:81]
	v_mfma_f32_16x16x32_bf16 v[74:77], v[190:193], v[214:217], v[74:77]
	v_mfma_f32_16x16x32_bf16 v[70:73], v[182:185], v[222:225], v[70:73]
	v_mfma_f32_16x16x32_bf16 v[66:69], v[190:193], v[222:225], v[66:69]
	s_setprio 0
	s_barrier
	s_add_i32 s24, 0, 0x18000
	v_add_u32_e32 v138, s24, v172
	s_add_i32 s25, 0, 0x1c000
	ds_read_b128 v[150:153], v138
	ds_read_b128 v[154:157], v138 offset:1024
	ds_read_b128 v[158:161], v138 offset:2048
	ds_read_b128 v[162:165], v138 offset:3072
	v_add_u32_e32 v138, s25, v172
	ds_read_b128 v[166:169], v138
	ds_read_b128 v[182:185], v138 offset:1024
	ds_read_b128 v[186:189], v138 offset:2048
	ds_read_b128 v[190:193], v138 offset:3072
	s_add_u32 s16, s16, 0x80000
	s_addc_u32 s17, s17, 0
	s_mov_b32 m0, s63
	v_lshl_add_u64 v[232:233], s[16:17], 0, v[130:131]
	ds_read_b128 v[194:197], v179 offset:32768
	ds_read_b128 v[198:201], v179 offset:33792
	ds_read_b128 v[202:205], v179 offset:34816
	ds_read_b128 v[206:209], v179 offset:35840
	ds_read_b128 v[210:213], v179 offset:36864
	ds_read_b128 v[214:217], v179 offset:37888
	ds_read_b128 v[218:221], v179 offset:38912
	ds_read_b128 v[222:225], v179 offset:39936
	global_load_lds_dwordx4 v[232:233], off
	v_lshl_add_u64 v[232:233], s[16:17], 0, v[134:135]
	s_mov_b32 m0, s65
	s_nop 0
	global_load_lds_dwordx4 v[232:233], off
	s_waitcnt vmcnt(8)
	s_waitcnt lgkmcnt(0)
	s_barrier
	s_setprio 1
	s_waitcnt lgkmcnt(0)
	v_mfma_f32_16x16x32_bf16 v[58:61], v[150:153], v[194:197], v[58:61]
	v_mfma_f32_16x16x32_bf16 v[62:65], v[158:161], v[194:197], v[62:65]
	v_mfma_f32_16x16x32_bf16 v[50:53], v[150:153], v[202:205], v[50:53]
	v_mfma_f32_16x16x32_bf16 v[54:57], v[158:161], v[202:205], v[54:57]
	v_mfma_f32_16x16x32_bf16 v[42:45], v[150:153], v[210:213], v[42:45]
	v_mfma_f32_16x16x32_bf16 v[46:49], v[158:161], v[210:213], v[46:49]
	v_mfma_f32_16x16x32_bf16 v[34:37], v[150:153], v[218:221], v[34:37]
	v_mfma_f32_16x16x32_bf16 v[38:41], v[158:161], v[218:221], v[38:41]
	v_mfma_f32_16x16x32_bf16 v[58:61], v[154:157], v[198:201], v[58:61]
	v_mfma_f32_16x16x32_bf16 v[62:65], v[162:165], v[198:201], v[62:65]
	v_mfma_f32_16x16x32_bf16 v[50:53], v[154:157], v[206:209], v[50:53]
	v_mfma_f32_16x16x32_bf16 v[54:57], v[162:165], v[206:209], v[54:57]
	v_mfma_f32_16x16x32_bf16 v[42:45], v[154:157], v[214:217], v[42:45]
	v_mfma_f32_16x16x32_bf16 v[46:49], v[162:165], v[214:217], v[46:49]
	v_mfma_f32_16x16x32_bf16 v[34:37], v[154:157], v[222:225], v[34:37]
	v_mfma_f32_16x16x32_bf16 v[38:41], v[162:165], v[222:225], v[38:41]
	s_setprio 0
	s_setprio 1
	v_mfma_f32_16x16x32_bf16 v[126:129], v[166:169], v[194:197], v[126:129]
	v_mfma_f32_16x16x32_bf16 v[122:125], v[186:189], v[194:197], v[122:125]
	v_mfma_f32_16x16x32_bf16 v[118:121], v[166:169], v[202:205], v[118:121]
	v_mfma_f32_16x16x32_bf16 v[114:117], v[186:189], v[202:205], v[114:117]
	v_mfma_f32_16x16x32_bf16 v[110:113], v[166:169], v[210:213], v[110:113]
	v_mfma_f32_16x16x32_bf16 v[106:109], v[186:189], v[210:213], v[106:109]
	v_mfma_f32_16x16x32_bf16 v[102:105], v[166:169], v[218:221], v[102:105]
	v_mfma_f32_16x16x32_bf16 v[98:101], v[186:189], v[218:221], v[98:101]
	v_mfma_f32_16x16x32_bf16 v[126:129], v[182:185], v[198:201], v[126:129]
	v_mfma_f32_16x16x32_bf16 v[122:125], v[190:193], v[198:201], v[122:125]
	v_mfma_f32_16x16x32_bf16 v[118:121], v[182:185], v[206:209], v[118:121]
	v_mfma_f32_16x16x32_bf16 v[114:117], v[190:193], v[206:209], v[114:117]
	v_mfma_f32_16x16x32_bf16 v[110:113], v[182:185], v[214:217], v[110:113]
	v_mfma_f32_16x16x32_bf16 v[106:109], v[190:193], v[214:217], v[106:109]
	v_mfma_f32_16x16x32_bf16 v[102:105], v[182:185], v[222:225], v[102:105]
	v_mfma_f32_16x16x32_bf16 v[98:101], v[190:193], v[222:225], v[98:101]
	s_setprio 0
	s_barrier
; #define PG8_STAGE(bufoff, gbase, voff) do { _Pragma("unroll") for (int _i = 0; _i < 2; ++_i) \
;         __builtin_amdgcn_global_load_lds((const unsigned*)((const char*)(gbase) + (voff)[_i]), (PG8_LAS unsigned*)(lds + (bufoff) + ldsw + _i * 8192), 16, 0, 0); } while (0)
; #define PG8_LDA(dst, b, h) do { _Pragma("unroll") for (int m = 0; m < 4; ++m) _Pragma("unroll") for (int k = 0; k < 2; ++k) dst[m][k] = *(const PG8_LAS bf16x8*)(lds + PG8_SA(b, h) + aoff + m * 2048 + k * 1024); } while (0)
; #define PG8_LDB(dst, b, h) do { _Pragma("unroll") for (int n = 0; n < 2; ++n) _Pragma("unroll") for (int k = 0; k < 2; ++k) dst[n][k] = *(const PG8_LAS bf16x8*)(lds + PG8_SB(b, h) + boff + n * 2048 + k * 1024); } while (0)
; #define PG8_MMA(ai, bj, At, Bt) do { __builtin_amdgcn_s_setprio(1); _Pragma("unroll") for (int m = 0; m < 4; ++m) _Pragma("unroll") for (int n = 0; n < 2; ++n) _Pragma("unroll") for (int k = 0; k < 2; ++k) \
;         acc[ai][bj][m][n] = __builtin_amdgcn_mfma_f32_16x16x32_bf16(Bt[n][k], At[m][k], acc[ai][bj][m][n], 0, 0, 0); __builtin_amdgcn_s_setprio(0); } while (0)
; #define PG8_WAIT_V(n) asm volatile("s_waitcnt vmcnt(" #n ")" ::: "memory")
; #define PG8_WAIT_L(n) asm volatile("s_waitcnt lgkmcnt(" #n ")" ::: "memory")
; template <class Epi, class Sched, bool ALIGN_EPI = false, bool SP2 = false>
; __device__ __forceinline__ void gemm_phase(PG8_LAS unsigned char* lds, const Gemm g, const Sched& S, const Epi& E) {
;     ...
;         for (int t = 0; t < nt; t += 2) {
;             if constexpr (Epi::MIDHOOK) { if (t == (nt >> 1)) E.mid(acc, cur, wr, wc, fr, fq); }
;             const bool last = (t == nt - 2);
;             const char* a1 = cA + (size_t)(t + 1) * kstep;
;             const char* a2 = last ? nA : cA + (size_t)(t + 2) * kstep; const char* b2 = last ? nB : cB + (size_t)(t + 2) * kstep;
;             const char* a3 = a2 + kstep; const char* b3 = b2 + kstep;
;             if (last && has_next) S.a_ready(nxt);
;             if constexpr (SP2) {
;             PG8_LDB(B0, 0, 0); PG8_LDB(B1, 0, 1); PG8_SCHED; PG8_LDA(At, 0, 0); PG8_STAGE(PG8_SA(1, 1), a1 + hstep, voffA);
;     ...
;             PG8_LDA(At, 1, 1); PG8_STAGE(PG8_SB(1, 0), b3, voffB); PG8_STAGE(PG8_SB(1, 1), b3 + hstep, voffB); PG8_STAGE(PG8_SA(1, 0), a3, voffA);
;             PG8_WAIT_V(8); PG8_WAIT_L(0); PG8_BAR; PG8_MMA(1, 0, At, B0); PG8_MMA(1, 1, At, B1); PG8_BAR; PG8_SCHED;
	s_add_i32 s16, s24, s55
	v_lshl_add_u64 v[170:171], v[170:171], 0, s[90:91]
	s_mov_b32 m0, s16
	ds_read_b128 v[194:197], v179 offset:49152
	ds_read_b128 v[198:201], v179 offset:50176
	ds_read_b128 v[202:205], v179 offset:51200
	ds_read_b128 v[206:209], v179 offset:52224
	ds_read_b128 v[210:213], v179 offset:53248
	ds_read_b128 v[214:217], v179 offset:54272
	ds_read_b128 v[218:221], v179 offset:55296
	ds_read_b128 v[222:225], v179 offset:56320
	global_load_lds_dwordx4 v[170:171], off
	s_add_i32 m0, s16, 0x2000
	s_add_u32 s14, s14, 0x80080
	v_lshl_add_u64 v[170:171], v[226:227], 0, s[90:91]
	s_addc_u32 s15, s15, 0
	s_add_i32 s16, s25, s55
	global_load_lds_dwordx4 v[170:171], off
	v_lshl_add_u64 v[170:171], s[14:15], 0, v[132:133]
	s_mov_b32 m0, s16
	s_nop 0
	global_load_lds_dwordx4 v[170:171], off
	v_lshl_add_u64 v[170:171], s[14:15], 0, v[136:137]
	s_add_i32 m0, s16, 0x2000
	s_nop 0
	global_load_lds_dwordx4 v[170:171], off
	v_lshl_add_u64 v[170:171], v[228:229], 0, s[90:91]
	s_mov_b32 m0, s92
	s_nop 0
	global_load_lds_dwordx4 v[170:171], off
	v_lshl_add_u64 v[170:171], v[230:231], 0, s[90:91]
	s_mov_b32 m0, s93
	s_nop 0
	global_load_lds_dwordx4 v[170:171], off
	s_waitcnt vmcnt(8)
	s_waitcnt lgkmcnt(0)
	s_barrier
	s_setprio 1
	s_waitcnt lgkmcnt(0)
	v_mfma_f32_16x16x32_bf16 v[26:29], v[150:153], v[194:197], v[26:29]
	v_mfma_f32_16x16x32_bf16 v[30:33], v[158:161], v[194:197], v[30:33]
	v_mfma_f32_16x16x32_bf16 v[18:21], v[150:153], v[202:205], v[18:21]
	v_mfma_f32_16x16x32_bf16 v[22:25], v[158:161], v[202:205], v[22:25]
	v_mfma_f32_16x16x32_bf16 v[10:13], v[150:153], v[210:213], v[10:13]
	v_mfma_f32_16x16x32_bf16 v[14:17], v[158:161], v[210:213], v[14:17]
	v_mfma_f32_16x16x32_bf16 v[2:5], v[150:153], v[218:221], v[2:5]
	v_mfma_f32_16x16x32_bf16 v[6:9], v[158:161], v[218:221], v[6:9]
	v_mfma_f32_16x16x32_bf16 v[26:29], v[154:157], v[198:201], v[26:29]
	v_mfma_f32_16x16x32_bf16 v[30:33], v[162:165], v[198:201], v[30:33]
	v_mfma_f32_16x16x32_bf16 v[18:21], v[154:157], v[206:209], v[18:21]
	v_mfma_f32_16x16x32_bf16 v[22:25], v[162:165], v[206:209], v[22:25]
	v_mfma_f32_16x16x32_bf16 v[10:13], v[154:157], v[214:217], v[10:13]
	v_mfma_f32_16x16x32_bf16 v[14:17], v[162:165], v[214:217], v[14:17]
	v_mfma_f32_16x16x32_bf16 v[2:5], v[154:157], v[222:225], v[2:5]
	v_mfma_f32_16x16x32_bf16 v[6:9], v[162:165], v[222:225], v[6:9]
	s_setprio 0
	s_setprio 1
	v_mfma_f32_16x16x32_bf16 v[94:97], v[166:169], v[194:197], v[94:97]
	v_mfma_f32_16x16x32_bf16 v[90:93], v[186:189], v[194:197], v[90:93]
	v_mfma_f32_16x16x32_bf16 v[86:89], v[166:169], v[202:205], v[86:89]
	v_mfma_f32_16x16x32_bf16 v[82:85], v[186:189], v[202:205], v[82:85]
	v_mfma_f32_16x16x32_bf16 v[78:81], v[166:169], v[210:213], v[78:81]
	v_mfma_f32_16x16x32_bf16 v[74:77], v[186:189], v[210:213], v[74:77]
	v_mfma_f32_16x16x32_bf16 v[70:73], v[166:169], v[218:221], v[70:73]
	v_mfma_f32_16x16x32_bf16 v[66:69], v[186:189], v[218:221], v[66:69]
	v_mfma_f32_16x16x32_bf16 v[94:97], v[182:185], v[198:201], v[94:97]
	v_mfma_f32_16x16x32_bf16 v[90:93], v[190:193], v[198:201], v[90:93]
	v_mfma_f32_16x16x32_bf16 v[86:89], v[182:185], v[206:209], v[86:89]
	v_mfma_f32_16x16x32_bf16 v[82:85], v[190:193], v[206:209], v[82:85]
	v_mfma_f32_16x16x32_bf16 v[78:81], v[182:185], v[214:217], v[78:81]
	v_mfma_f32_16x16x32_bf16 v[74:77], v[190:193], v[214:217], v[74:77]
	v_mfma_f32_16x16x32_bf16 v[70:73], v[182:185], v[222:225], v[70:73]
	v_mfma_f32_16x16x32_bf16 v[66:69], v[190:193], v[222:225], v[66:69]
	s_setprio 0
	s_barrier
	s_add_i32 s23, s23, 2
	s_add_u32 s10, s10, 0x100
	s_addc_u32 s11, s11, 0
	s_add_u32 s19, s19, 0x100
	s_addc_u32 s22, s22, 0
	s_cmp_gt_u32 s23, 29
	s_cbranch_scc1 .Lkx_346
.LBB0_346:
	ds_read_b128 v[150:153], v177
	ds_read_b128 v[154:157], v177 offset:1024
	ds_read_b128 v[158:161], v177 offset:2048
	ds_read_b128 v[162:165], v177 offset:3072
	ds_read_b128 v[166:169], v178
	ds_read_b128 v[182:185], v178 offset:1024
	ds_read_b128 v[186:189], v178 offset:2048
	ds_read_b128 v[190:193], v178 offset:3072
	s_add_u32 s14, s10, 0xfff80080
	s_addc_u32 s15, s11, -1
	s_cmp_eq_u32 s23, 28
	s_cselect_b32 s17, s6, s15
	s_cselect_b32 s16, s7, s14
	s_cselect_b32 s15, s13, s22
	s_cselect_b32 s14, s18, s19
	v_lshl_add_u64 v[170:171], s[10:11], 0, v[142:143]
	s_add_i32 m0, s59, 0xc000
	ds_read_b128 v[194:197], v179
	ds_read_b128 v[198:201], v179 offset:1024
	ds_read_b128 v[202:205], v179 offset:2048
	ds_read_b128 v[206:209], v179 offset:3072
	ds_read_b128 v[210:213], v179 offset:4096
	ds_read_b128 v[214:217], v179 offset:5120
	ds_read_b128 v[218:221], v179 offset:6144
	ds_read_b128 v[222:225], v179 offset:7168
	global_load_lds_dwordx4 v[170:171], off
	v_lshl_add_u64 v[170:171], s[10:11], 0, v[144:145]
	s_add_i32 m0, s59, 0xe000
	s_nop 0
	global_load_lds_dwordx4 v[170:171], off
	s_waitcnt vmcnt(8)
	s_waitcnt lgkmcnt(0)
	s_barrier
; #define PG8_STAGE(bufoff, gbase, voff) do { _Pragma("unroll") for (int _i = 0; _i < 2; ++_i) \
;         __builtin_amdgcn_global_load_lds((const unsigned*)((const char*)(gbase) + (voff)[_i]), (PG8_LAS unsigned*)(lds + (bufoff) + ldsw + _i * 8192), 16, 0, 0); } while (0)
; #define PG8_LDA(dst, b, h) do { _Pragma("unroll") for (int m = 0; m < 4; ++m) _Pragma("unroll") for (int k = 0; k < 2; ++k) dst[m][k] = *(const PG8_LAS bf16x8*)(lds + PG8_SA(b, h) + aoff + m * 2048 + k * 1024); } while (0)
; #define PG8_LDB(dst, b, h) do { _Pragma("unroll") for (int n = 0; n < 2; ++n) _Pragma("unroll") for (int k = 0; k < 2; ++k) dst[n][k] = *(const PG8_LAS bf16x8*)(lds + PG8_SB(b, h) + boff + n * 2048 + k * 1024); } while (0)
; #define PG8_MMA(ai, bj, At, Bt) do { __builtin_amdgcn_s_setprio(1); _Pragma("unroll") for (int m = 0; m < 4; ++m) _Pragma("unroll") for (int n = 0; n < 2; ++n) _Pragma("unroll") for (int k = 0; k < 2; ++k) \
;         acc[ai][bj][m][n] = __builtin_amdgcn_mfma_f32_16x16x32_bf16(Bt[n][k], At[m][k], acc[ai][bj][m][n], 0, 0, 0); __builtin_amdgcn_s_setprio(0); } while (0)
; #define PG8_WAIT_V(n) asm volatile("s_waitcnt vmcnt(" #n ")" ::: "memory")
; #define PG8_WAIT_L(n) asm volatile("s_waitcnt lgkmcnt(" #n ")" ::: "memory")
; #define PG8_BAR __builtin_amdgcn_s_barrier()
; #define PG8_SCHED __builtin_amdgcn_sched_barrier(0)
; template <class Epi, class Sched, bool ALIGN_EPI = false, bool SP2 = false>
; __device__ __forceinline__ void gemm_phase(PG8_LAS unsigned char* lds, const Gemm g, const Sched& S, const Epi& E) {
;     ...
;             PG8_LDB(B0, 0, 0); PG8_LDB(B1, 0, 1); PG8_SCHED; PG8_LDA(At, 0, 0); PG8_STAGE(PG8_SA(1, 1), a1 + hstep, voffA);
;             PG8_WAIT_V(8); PG8_WAIT_L(0); PG8_BAR; PG8_MMA(0, 0, At, B0); PG8_MMA(0, 1, At, B1); PG8_BAR; PG8_SCHED;
;             PG8_LDA(At, 0, 1); PG8_STAGE(PG8_SB(0, 0), b2, voffB); PG8_STAGE(PG8_SB(0, 1), b2 + hstep, voffB); PG8_STAGE(PG8_SA(0, 0), a2, voffA);
;             PG8_WAIT_V(8); PG8_WAIT_L(0); PG8_BAR; PG8_MMA(1, 0, At, B0); PG8_MMA(1, 1, At, B1); PG8_BAR; PG8_SCHED;
;             PG8_LDB(B0, 1, 0); PG8_LDB(B1, 1, 1); PG8_SCHED; PG8_LDA(At, 1, 0); PG8_STAGE(PG8_SA(0, 1), a2 + hstep, voffA);
;             PG8_WAIT_V(8); PG8_WAIT_L(0); PG8_BAR; PG8_MMA(0, 0, At, B0); PG8_MMA(0, 1, At, B1); PG8_BAR; PG8_SCHED;
	s_setprio 1
	s_waitcnt lgkmcnt(0)
	v_mfma_f32_16x16x32_bf16 v[58:61], v[150:153], v[194:197], v[58:61]
	v_mfma_f32_16x16x32_bf16 v[62:65], v[158:161], v[194:197], v[62:65]
	v_mfma_f32_16x16x32_bf16 v[50:53], v[150:153], v[202:205], v[50:53]
	v_mfma_f32_16x16x32_bf16 v[54:57], v[158:161], v[202:205], v[54:57]
	v_mfma_f32_16x16x32_bf16 v[42:45], v[150:153], v[210:213], v[42:45]
	v_mfma_f32_16x16x32_bf16 v[46:49], v[158:161], v[210:213], v[46:49]
	v_mfma_f32_16x16x32_bf16 v[34:37], v[150:153], v[218:221], v[34:37]
	v_mfma_f32_16x16x32_bf16 v[38:41], v[158:161], v[218:221], v[38:41]
	v_mfma_f32_16x16x32_bf16 v[58:61], v[154:157], v[198:201], v[58:61]
	v_mfma_f32_16x16x32_bf16 v[62:65], v[162:165], v[198:201], v[62:65]
	v_mfma_f32_16x16x32_bf16 v[50:53], v[154:157], v[206:209], v[50:53]
	v_mfma_f32_16x16x32_bf16 v[54:57], v[162:165], v[206:209], v[54:57]
	v_mfma_f32_16x16x32_bf16 v[42:45], v[154:157], v[214:217], v[42:45]
	v_mfma_f32_16x16x32_bf16 v[46:49], v[162:165], v[214:217], v[46:49]
	v_mfma_f32_16x16x32_bf16 v[34:37], v[154:157], v[222:225], v[34:37]
	v_mfma_f32_16x16x32_bf16 v[38:41], v[162:165], v[222:225], v[38:41]
	s_setprio 0
	s_setprio 1
	v_mfma_f32_16x16x32_bf16 v[126:129], v[166:169], v[194:197], v[126:129]
	v_mfma_f32_16x16x32_bf16 v[122:125], v[186:189], v[194:197], v[122:125]
	v_mfma_f32_16x16x32_bf16 v[118:121], v[166:169], v[202:205], v[118:121]
	v_mfma_f32_16x16x32_bf16 v[114:117], v[186:189], v[202:205], v[114:117]
	v_mfma_f32_16x16x32_bf16 v[110:113], v[166:169], v[210:213], v[110:113]
	v_mfma_f32_16x16x32_bf16 v[106:109], v[186:189], v[210:213], v[106:109]
	v_mfma_f32_16x16x32_bf16 v[102:105], v[166:169], v[218:221], v[102:105]
	v_mfma_f32_16x16x32_bf16 v[98:101], v[186:189], v[218:221], v[98:101]
	v_mfma_f32_16x16x32_bf16 v[126:129], v[182:185], v[198:201], v[126:129]
	v_mfma_f32_16x16x32_bf16 v[122:125], v[190:193], v[198:201], v[122:125]
	v_mfma_f32_16x16x32_bf16 v[118:121], v[182:185], v[206:209], v[118:121]
	v_mfma_f32_16x16x32_bf16 v[114:117], v[190:193], v[206:209], v[114:117]
	v_mfma_f32_16x16x32_bf16 v[110:113], v[182:185], v[214:217], v[110:113]
	v_mfma_f32_16x16x32_bf16 v[106:109], v[190:193], v[214:217], v[106:109]
	v_mfma_f32_16x16x32_bf16 v[102:105], v[182:185], v[222:225], v[102:105]
	v_mfma_f32_16x16x32_bf16 v[98:101], v[190:193], v[222:225], v[98:101]
	s_setprio 0
	s_barrier
	s_add_i32 s24, s95, s55
	v_lshl_add_u64 v[170:171], s[14:15], 0, v[132:133]
	s_mov_b32 m0, s24
	ds_read_b128 v[194:197], v179 offset:16384
	ds_read_b128 v[198:201], v179 offset:17408
	ds_read_b128 v[202:205], v179 offset:18432
	ds_read_b128 v[206:209], v179 offset:19456
	ds_read_b128 v[210:213], v179 offset:20480
	ds_read_b128 v[214:217], v179 offset:21504
	ds_read_b128 v[218:221], v179 offset:22528
	ds_read_b128 v[222:225], v179 offset:23552
	global_load_lds_dwordx4 v[170:171], off
	s_add_i32 m0, s24, 0x2000
	s_add_u32 s24, s14, 0x80000
	v_lshl_add_u64 v[226:227], s[14:15], 0, v[136:137]
	s_addc_u32 s25, s15, 0
	s_add_i32 s26, s81, s55
	global_load_lds_dwordx4 v[226:227], off
	v_lshl_add_u64 v[228:229], s[24:25], 0, v[132:133]
	s_mov_b32 m0, s26
	v_lshl_add_u64 v[230:231], s[16:17], 0, v[134:135]
	global_load_lds_dwordx4 v[228:229], off
	v_lshl_add_u64 v[228:229], s[24:25], 0, v[136:137]
	s_add_i32 m0, s26, 0x2000
	s_nop 0
	global_load_lds_dwordx4 v[228:229], off
	v_lshl_add_u64 v[228:229], s[16:17], 0, v[130:131]
	s_mov_b32 m0, s59
	s_nop 0
	global_load_lds_dwordx4 v[228:229], off
	s_mov_b32 m0, s61
	s_nop 0
	global_load_lds_dwordx4 v[230:231], off
	s_waitcnt vmcnt(8)
	s_waitcnt lgkmcnt(0)
	s_barrier
	s_setprio 1
	s_waitcnt lgkmcnt(0)
	v_mfma_f32_16x16x32_bf16 v[26:29], v[150:153], v[194:197], v[26:29]
	v_mfma_f32_16x16x32_bf16 v[30:33], v[158:161], v[194:197], v[30:33]
	v_mfma_f32_16x16x32_bf16 v[18:21], v[150:153], v[202:205], v[18:21]
	v_mfma_f32_16x16x32_bf16 v[22:25], v[158:161], v[202:205], v[22:25]
	v_mfma_f32_16x16x32_bf16 v[10:13], v[150:153], v[210:213], v[10:13]
	v_mfma_f32_16x16x32_bf16 v[14:17], v[158:161], v[210:213], v[14:17]
	v_mfma_f32_16x16x32_bf16 v[2:5], v[150:153], v[218:221], v[2:5]
	v_mfma_f32_16x16x32_bf16 v[6:9], v[158:161], v[218:221], v[6:9]
	v_mfma_f32_16x16x32_bf16 v[26:29], v[154:157], v[198:201], v[26:29]
	v_mfma_f32_16x16x32_bf16 v[30:33], v[162:165], v[198:201], v[30:33]
	v_mfma_f32_16x16x32_bf16 v[18:21], v[154:157], v[206:209], v[18:21]
	v_mfma_f32_16x16x32_bf16 v[22:25], v[162:165], v[206:209], v[22:25]
	v_mfma_f32_16x16x32_bf16 v[10:13], v[154:157], v[214:217], v[10:13]
	v_mfma_f32_16x16x32_bf16 v[14:17], v[162:165], v[214:217], v[14:17]
	v_mfma_f32_16x16x32_bf16 v[2:5], v[154:157], v[222:225], v[2:5]
	v_mfma_f32_16x16x32_bf16 v[6:9], v[162:165], v[222:225], v[6:9]
	s_setprio 0
	s_setprio 1
	v_mfma_f32_16x16x32_bf16 v[94:97], v[166:169], v[194:197], v[94:97]
	v_mfma_f32_16x16x32_bf16 v[90:93], v[186:189], v[194:197], v[90:93]
	v_mfma_f32_16x16x32_bf16 v[86:89], v[166:169], v[202:205], v[86:89]
	v_mfma_f32_16x16x32_bf16 v[82:85], v[186:189], v[202:205], v[82:85]
	v_mfma_f32_16x16x32_bf16 v[78:81], v[166:169], v[210:213], v[78:81]
	v_mfma_f32_16x16x32_bf16 v[74:77], v[186:189], v[210:213], v[74:77]
	v_mfma_f32_16x16x32_bf16 v[70:73], v[166:169], v[218:221], v[70:73]
	v_mfma_f32_16x16x32_bf16 v[66:69], v[186:189], v[218:221], v[66:69]
	v_mfma_f32_16x16x32_bf16 v[94:97], v[182:185], v[198:201], v[94:97]
	v_mfma_f32_16x16x32_bf16 v[90:93], v[190:193], v[198:201], v[90:93]
	v_mfma_f32_16x16x32_bf16 v[86:89], v[182:185], v[206:209], v[86:89]
	v_mfma_f32_16x16x32_bf16 v[82:85], v[190:193], v[206:209], v[82:85]
	v_mfma_f32_16x16x32_bf16 v[78:81], v[182:185], v[214:217], v[78:81]
	v_mfma_f32_16x16x32_bf16 v[74:77], v[190:193], v[214:217], v[74:77]
	v_mfma_f32_16x16x32_bf16 v[70:73], v[182:185], v[222:225], v[70:73]
	v_mfma_f32_16x16x32_bf16 v[66:69], v[190:193], v[222:225], v[66:69]
	s_setprio 0
	s_barrier
; #define PG8_STAGE(bufoff, gbase, voff) do { _Pragma("unroll") for (int _i = 0; _i < 2; ++_i) \
;         __builtin_amdgcn_global_load_lds((const unsigned*)((const char*)(gbase) + (voff)[_i]), (PG8_LAS unsigned*)(lds + (bufoff) + ldsw + _i * 8192), 16, 0, 0); } while (0)
; #define PG8_LDA(dst, b, h) do { _Pragma("unroll") for (int m = 0; m < 4; ++m) _Pragma("unroll") for (int k = 0; k < 2; ++k) dst[m][k] = *(const PG8_LAS bf16x8*)(lds + PG8_SA(b, h) + aoff + m * 2048 + k * 1024); } while (0)
; #define PG8_LDB(dst, b, h) do { _Pragma("unroll") for (int n = 0; n < 2; ++n) _Pragma("unroll") for (int k = 0; k < 2; ++k) dst[n][k] = *(const PG8_LAS bf16x8*)(lds + PG8_SB(b, h) + boff + n * 2048 + k * 1024); } while (0)
; #define PG8_MMA(ai, bj, At, Bt) do { __builtin_amdgcn_s_setprio(1); _Pragma("unroll") for (int m = 0; m < 4; ++m) _Pragma("unroll") for (int n = 0; n < 2; ++n) _Pragma("unroll") for (int k = 0; k < 2; ++k) \
;         acc[ai][bj][m][n] = __builtin_amdgcn_mfma_f32_16x16x32_bf16(Bt[n][k], At[m][k], acc[ai][bj][m][n], 0, 0, 0); __builtin_amdgcn_s_setprio(0); } while (0)
; #define PG8_WAIT_V(n) asm volatile("s_waitcnt vmcnt(" #n ")" ::: "memory")
; #define PG8_WAIT_L(n) asm volatile("s_waitcnt lgkmcnt(" #n ")" ::: "memory")
; #define PG8_BAR __builtin_amdgcn_s_barrier()
; #define PG8_SCHED __builtin_amdgcn_sched_barrier(0)
; template <class Epi, class Sched, bool ALIGN_EPI = false, bool SP2 = false>
; __device__ __forceinline__ void gemm_phase(PG8_LAS unsigned char* lds, const Gemm g, const Sched& S, const Epi& E) {
;     ...
;             PG8_LDB(B0, 1, 0); PG8_LDB(B1, 1, 1); PG8_SCHED; PG8_LDA(At, 1, 0); PG8_STAGE(PG8_SA(0, 1), a2 + hstep, voffA);
;             PG8_WAIT_V(8); PG8_WAIT_L(0); PG8_BAR; PG8_MMA(0, 0, At, B0); PG8_MMA(0, 1, At, B1); PG8_BAR; PG8_SCHED;
	s_add_i32 s24, 0, 0x18000
	v_add_u32_e32 v138, s24, v172
	s_add_i32 s25, 0, 0x1c000
	ds_read_b128 v[150:153], v138
	ds_read_b128 v[154:157], v138 offset:1024
	ds_read_b128 v[158:161], v138 offset:2048
	ds_read_b128 v[162:165], v138 offset:3072
	v_add_u32_e32 v138, s25, v172
	ds_read_b128 v[166:169], v138
	ds_read_b128 v[182:185], v138 offset:1024
	ds_read_b128 v[186:189], v138 offset:2048
	ds_read_b128 v[190:193], v138 offset:3072
	s_add_u32 s16, s16, 0x80000
	s_addc_u32 s17, s17, 0
	s_mov_b32 m0, s63
	v_lshl_add_u64 v[232:233], s[16:17], 0, v[130:131]
	ds_read_b128 v[194:197], v179 offset:32768
	ds_read_b128 v[198:201], v179 offset:33792
	ds_read_b128 v[202:205], v179 offset:34816
	ds_read_b128 v[206:209], v179 offset:35840
	ds_read_b128 v[210:213], v179 offset:36864
	ds_read_b128 v[214:217], v179 offset:37888
	ds_read_b128 v[218:221], v179 offset:38912
	ds_read_b128 v[222:225], v179 offset:39936
	global_load_lds_dwordx4 v[232:233], off
	v_lshl_add_u64 v[232:233], s[16:17], 0, v[134:135]
	s_mov_b32 m0, s65
	s_nop 0
	global_load_lds_dwordx4 v[232:233], off
	s_waitcnt vmcnt(8)
	s_waitcnt lgkmcnt(0)
	s_barrier
	s_setprio 1
	s_waitcnt lgkmcnt(0)
	v_mfma_f32_16x16x32_bf16 v[58:61], v[150:153], v[194:197], v[58:61]
	v_mfma_f32_16x16x32_bf16 v[62:65], v[158:161], v[194:197], v[62:65]
	v_mfma_f32_16x16x32_bf16 v[50:53], v[150:153], v[202:205], v[50:53]
	v_mfma_f32_16x16x32_bf16 v[54:57], v[158:161], v[202:205], v[54:57]
	v_mfma_f32_16x16x32_bf16 v[42:45], v[150:153], v[210:213], v[42:45]
	v_mfma_f32_16x16x32_bf16 v[46:49], v[158:161], v[210:213], v[46:49]
	v_mfma_f32_16x16x32_bf16 v[34:37], v[150:153], v[218:221], v[34:37]
	v_mfma_f32_16x16x32_bf16 v[38:41], v[158:161], v[218:221], v[38:41]
	v_mfma_f32_16x16x32_bf16 v[58:61], v[154:157], v[198:201], v[58:61]
	v_mfma_f32_16x16x32_bf16 v[62:65], v[162:165], v[198:201], v[62:65]
	v_mfma_f32_16x16x32_bf16 v[50:53], v[154:157], v[206:209], v[50:53]
	v_mfma_f32_16x16x32_bf16 v[54:57], v[162:165], v[206:209], v[54:57]
	v_mfma_f32_16x16x32_bf16 v[42:45], v[154:157], v[214:217], v[42:45]
	v_mfma_f32_16x16x32_bf16 v[46:49], v[162:165], v[214:217], v[46:49]
	v_mfma_f32_16x16x32_bf16 v[34:37], v[154:157], v[222:225], v[34:37]
	v_mfma_f32_16x16x32_bf16 v[38:41], v[162:165], v[222:225], v[38:41]
	s_setprio 0
	s_setprio 1
	v_mfma_f32_16x16x32_bf16 v[126:129], v[166:169], v[194:197], v[126:129]
	v_mfma_f32_16x16x32_bf16 v[122:125], v[186:189], v[194:197], v[122:125]
	v_mfma_f32_16x16x32_bf16 v[118:121], v[166:169], v[202:205], v[118:121]
	v_mfma_f32_16x16x32_bf16 v[114:117], v[186:189], v[202:205], v[114:117]
	v_mfma_f32_16x16x32_bf16 v[110:113], v[166:169], v[210:213], v[110:113]
	v_mfma_f32_16x16x32_bf16 v[106:109], v[186:189], v[210:213], v[106:109]
	v_mfma_f32_16x16x32_bf16 v[102:105], v[166:169], v[218:221], v[102:105]
	v_mfma_f32_16x16x32_bf16 v[98:101], v[186:189], v[218:221], v[98:101]
	v_mfma_f32_16x16x32_bf16 v[126:129], v[182:185], v[198:201], v[126:129]
	v_mfma_f32_16x16x32_bf16 v[122:125], v[190:193], v[198:201], v[122:125]
	v_mfma_f32_16x16x32_bf16 v[118:121], v[182:185], v[206:209], v[118:121]
	v_mfma_f32_16x16x32_bf16 v[114:117], v[190:193], v[206:209], v[114:117]
	v_mfma_f32_16x16x32_bf16 v[110:113], v[182:185], v[214:217], v[110:113]
	v_mfma_f32_16x16x32_bf16 v[106:109], v[190:193], v[214:217], v[106:109]
	v_mfma_f32_16x16x32_bf16 v[102:105], v[182:185], v[222:225], v[102:105]
	v_mfma_f32_16x16x32_bf16 v[98:101], v[190:193], v[222:225], v[98:101]
	s_setprio 0
	s_barrier
; #define PG8_STAGE(bufoff, gbase, voff) do { _Pragma("unroll") for (int _i = 0; _i < 2; ++_i) \
;         __builtin_amdgcn_global_load_lds((const unsigned*)((const char*)(gbase) + (voff)[_i]), (PG8_LAS unsigned*)(lds + (bufoff) + ldsw + _i * 8192), 16, 0, 0); } while (0)
; #define PG8_LDA(dst, b, h) do { _Pragma("unroll") for (int m = 0; m < 4; ++m) _Pragma("unroll") for (int k = 0; k < 2; ++k) dst[m][k] = *(const PG8_LAS bf16x8*)(lds + PG8_SA(b, h) + aoff + m * 2048 + k * 1024); } while (0)
; #define PG8_MMA(ai, bj, At, Bt) do { __builtin_amdgcn_s_setprio(1); _Pragma("unroll") for (int m = 0; m < 4; ++m) _Pragma("unroll") for (int n = 0; n < 2; ++n) _Pragma("unroll") for (int k = 0; k < 2; ++k) \
;         acc[ai][bj][m][n] = __builtin_amdgcn_mfma_f32_16x16x32_bf16(Bt[n][k], At[m][k], acc[ai][bj][m][n], 0, 0, 0); __builtin_amdgcn_s_setprio(0); } while (0)
; #define PG8_WAIT_V(n) asm volatile("s_waitcnt vmcnt(" #n ")" ::: "memory")
; #define PG8_WAIT_L(n) asm volatile("s_waitcnt lgkmcnt(" #n ")" ::: "memory")
; #define PG8_BAR __builtin_amdgcn_s_barrier()
; #define PG8_SCHED __builtin_amdgcn_sched_barrier(0)
; template <class Epi, class Sched, bool ALIGN_EPI = false, bool SP2 = false>
; __device__ __forceinline__ void gemm_phase(PG8_LAS unsigned char* lds, const Gemm g, const Sched& S, const Epi& E) {
;     ...
;         for (int t = 0; t < nt; t += 2) {
;     ...
;             PG8_LDA(At, 1, 1); PG8_STAGE(PG8_SB(1, 0), b3, voffB); PG8_STAGE(PG8_SB(1, 1), b3 + hstep, voffB); PG8_STAGE(PG8_SA(1, 0), a3, voffA);
;             PG8_WAIT_V(8); PG8_WAIT_L(0); PG8_BAR; PG8_MMA(1, 0, At, B0); PG8_MMA(1, 1, At, B1); PG8_BAR; PG8_SCHED;
;     ...
;         if constexpr (ALIGN_EPI) { if (wr == 0) PG8_BAR; }
;         if constexpr (!Epi::AFTER_DRAIN) { E(acc, cur, wr, wc, fr, fq); S.done(cur); } else { if (has_next) { E(acc, cur, wr, wc, fr, fq); S.done(cur); } }
;         if (!has_next) break;
	s_add_i32 s16, s24, s55
	v_lshl_add_u64 v[170:171], v[170:171], 0, s[90:91]
	s_mov_b32 m0, s16
	ds_read_b128 v[194:197], v179 offset:49152
	ds_read_b128 v[198:201], v179 offset:50176
	ds_read_b128 v[202:205], v179 offset:51200
	ds_read_b128 v[206:209], v179 offset:52224
	ds_read_b128 v[210:213], v179 offset:53248
	ds_read_b128 v[214:217], v179 offset:54272
	ds_read_b128 v[218:221], v179 offset:55296
	ds_read_b128 v[222:225], v179 offset:56320
	global_load_lds_dwordx4 v[170:171], off
	s_add_i32 m0, s16, 0x2000
	s_add_u32 s14, s14, 0x80080
	v_lshl_add_u64 v[170:171], v[226:227], 0, s[90:91]
	s_addc_u32 s15, s15, 0
	s_add_i32 s16, s25, s55
	global_load_lds_dwordx4 v[170:171], off
	v_lshl_add_u64 v[170:171], s[14:15], 0, v[132:133]
	s_mov_b32 m0, s16
	s_nop 0
	global_load_lds_dwordx4 v[170:171], off
	v_lshl_add_u64 v[170:171], s[14:15], 0, v[136:137]
	s_add_i32 m0, s16, 0x2000
	s_nop 0
	global_load_lds_dwordx4 v[170:171], off
	v_lshl_add_u64 v[170:171], v[228:229], 0, s[90:91]
	s_mov_b32 m0, s92
	s_nop 0
	global_load_lds_dwordx4 v[170:171], off
	v_lshl_add_u64 v[170:171], v[230:231], 0, s[90:91]
	s_mov_b32 m0, s93
	s_nop 0
	global_load_lds_dwordx4 v[170:171], off
	s_waitcnt vmcnt(8)
	s_waitcnt lgkmcnt(0)
	s_barrier
	s_setprio 1
	s_waitcnt lgkmcnt(0)
	v_mfma_f32_16x16x32_bf16 v[26:29], v[150:153], v[194:197], v[26:29]
	v_mfma_f32_16x16x32_bf16 v[30:33], v[158:161], v[194:197], v[30:33]
	v_mfma_f32_16x16x32_bf16 v[18:21], v[150:153], v[202:205], v[18:21]
	v_mfma_f32_16x16x32_bf16 v[22:25], v[158:161], v[202:205], v[22:25]
	v_mfma_f32_16x16x32_bf16 v[10:13], v[150:153], v[210:213], v[10:13]
	v_mfma_f32_16x16x32_bf16 v[14:17], v[158:161], v[210:213], v[14:17]
	v_mfma_f32_16x16x32_bf16 v[2:5], v[150:153], v[218:221], v[2:5]
	v_mfma_f32_16x16x32_bf16 v[6:9], v[158:161], v[218:221], v[6:9]
	v_mfma_f32_16x16x32_bf16 v[26:29], v[154:157], v[198:201], v[26:29]
	v_mfma_f32_16x16x32_bf16 v[30:33], v[162:165], v[198:201], v[30:33]
	v_mfma_f32_16x16x32_bf16 v[18:21], v[154:157], v[206:209], v[18:21]
	v_mfma_f32_16x16x32_bf16 v[22:25], v[162:165], v[206:209], v[22:25]
	v_mfma_f32_16x16x32_bf16 v[10:13], v[154:157], v[214:217], v[10:13]
	v_mfma_f32_16x16x32_bf16 v[14:17], v[162:165], v[214:217], v[14:17]
	v_mfma_f32_16x16x32_bf16 v[2:5], v[154:157], v[222:225], v[2:5]
	v_mfma_f32_16x16x32_bf16 v[6:9], v[162:165], v[222:225], v[6:9]
	s_setprio 0
	s_setprio 1
	v_mfma_f32_16x16x32_bf16 v[94:97], v[166:169], v[194:197], v[94:97]
	v_mfma_f32_16x16x32_bf16 v[90:93], v[186:189], v[194:197], v[90:93]
	v_mfma_f32_16x16x32_bf16 v[86:89], v[166:169], v[202:205], v[86:89]
	v_mfma_f32_16x16x32_bf16 v[82:85], v[186:189], v[202:205], v[82:85]
	v_mfma_f32_16x16x32_bf16 v[78:81], v[166:169], v[210:213], v[78:81]
	v_mfma_f32_16x16x32_bf16 v[74:77], v[186:189], v[210:213], v[74:77]
	v_mfma_f32_16x16x32_bf16 v[70:73], v[166:169], v[218:221], v[70:73]
	v_mfma_f32_16x16x32_bf16 v[66:69], v[186:189], v[218:221], v[66:69]
	v_mfma_f32_16x16x32_bf16 v[94:97], v[182:185], v[198:201], v[94:97]
	v_mfma_f32_16x16x32_bf16 v[90:93], v[190:193], v[198:201], v[90:93]
	v_mfma_f32_16x16x32_bf16 v[86:89], v[182:185], v[206:209], v[86:89]
	v_mfma_f32_16x16x32_bf16 v[82:85], v[190:193], v[206:209], v[82:85]
	v_mfma_f32_16x16x32_bf16 v[78:81], v[182:185], v[214:217], v[78:81]
	v_mfma_f32_16x16x32_bf16 v[74:77], v[190:193], v[214:217], v[74:77]
	v_mfma_f32_16x16x32_bf16 v[70:73], v[182:185], v[222:225], v[70:73]
	v_mfma_f32_16x16x32_bf16 v[66:69], v[190:193], v[222:225], v[66:69]
	s_setprio 0
	s_barrier
	s_add_i32 s23, s23, 2
	s_add_u32 s10, s10, 0x100
	s_addc_u32 s11, s11, 0
	s_add_u32 s19, s19, 0x100
	s_addc_u32 s22, s22, 0
	s_cmp_gt_u32 s23, 29
	s_cbranch_scc0 .LBB0_346
.Lkx_346:
	v_readlane_b32 s6, v244, 18
	v_readlane_b32 s7, v244, 19
	s_and_b64 vcc, exec, s[6:7]
	s_cbranch_vccnz .LBB0_351
	s_ashr_i32 s13, s12, 3
	s_cmp_lg_u32 s13, 7
	s_mov_b64 s[6:7], -1
	s_cbranch_scc1 .LBB0_352

;     __device__ bool next(int i, Unit& u) const { if (!s.next(i, u)) return false; const int p = u.pn; u.pn = p < 56 ? (p % 7) * 8 + p / 7 : p; return true; }
;     __device__ bool next(int i, Unit& u) const { Unit t; if (!s.next(i >> 1, t)) return false; const int pass = i & 1; u.pm = t.pm + pass * (M / BM); u.pn = t.pn + pass * (D / BM); u.kt0 = 0; return true; }
; #define PG8_LDA(dst, b, h) do { _Pragma("unroll") for (int m = 0; m < 4; ++m) _Pragma("unroll") for (int k = 0; k < 2; ++k) dst[m][k] = *(const PG8_LAS bf16x8*)(lds + PG8_SA(b, h) + aoff + m * 2048 + k * 1024); } while (0)
; template <class Epi, class Sched, bool ALIGN_EPI = false, bool SP2 = false>
; __device__ __forceinline__ void gemm_phase(PG8_LAS unsigned char* lds, const Gemm g, const Sched& S, const Epi& E) {
;     ...
;         const bool has_next = S.next(ui + 1, nxt);
;         const char* nA = has_next ? (const char*)g.A + (size_t)nxt.pm * tstep + (size_t)nxt.kt0 * kstep : cA; const char* nB = has_next ? (const char*)g.Bt + (size_t)nxt.pn * tstep + (size_t)nxt.kt0 * kstep : cB;
;         for (int t = 0; t < nt; t += 2) {
;             if constexpr (Epi::MIDHOOK) { if (t == (nt >> 1)) E.mid(acc, cur, wr, wc, fr, fq); }
;             const bool last = (t == nt - 2);
;             const char* a1 = cA + (size_t)(t + 1) * kstep;
;             const char* a2 = last ? nA : cA + (size_t)(t + 2) * kstep; const char* b2 = last ? nB : cB + (size_t)(t + 2) * kstep;
;             const char* a3 = a2 + kstep; const char* b3 = b2 + kstep;
;             if (last && has_next) S.a_ready(nxt);
;             if constexpr (SP2) {
;             PG8_LDB(B0, 0, 0); PG8_LDB(B1, 0, 1); PG8_SCHED; PG8_LDA(At, 0, 0); PG8_STAGE(PG8_SA(1, 1), a1 + hstep, voffA);
;             PG8_WAIT_V(8); PG8_WAIT_L(0); PG8_BAR; PG8_MMA(0, 0, At, B0); PG8_MMA(0, 1, At, B1); PG8_BAR; PG8_SCHED;
;             PG8_LDA(At, 0, 1); PG8_STAGE(PG8_SB(0, 0), b2, voffB); PG8_STAGE(PG8_SB(0, 1), b2 + hstep, voffB); PG8_STAGE(PG8_SA(0, 0), a2, voffA);
;             PG8_WAIT_V(8); PG8_WAIT_L(0); PG8_BAR; PG8_MMA(1, 0, At, B0); PG8_MMA(1, 1, At, B1); PG8_BAR; PG8_SCHED;
;     ...
;         for (int a = 0; a < 2; ++a)
; #pragma unroll
;             for (int b = 0; b < 2; ++b)
; #pragma unroll
;                 for (int m = 0; m < 4; ++m)
; #pragma unroll
;                     for (int n = 0; n < 2; ++n) acc[a][b][m][n] = (f32x4){0.f, 0.f, 0.f, 0.f};
.LBB0_1218:
	s_ashr_i32 s21, s20, 31
	s_lshl_b64 s[26:27], s[20:21], 21
	s_add_u32 s11, s40, s26
	s_addc_u32 s21, s41, s27
	s_add_u32 s26, s11, s28
	s_addc_u32 s27, s21, s29
	s_and_b64 s[38:39], exec, s[24:25]
	s_cselect_b32 s11, s27, s31
	s_cselect_b32 s21, s26, s30
	s_ashr_i32 s23, s22, 31
	s_lshl_b64 s[38:39], s[22:23], 21
	s_add_u32 s23, s3, s38
	s_addc_u32 s38, s33, s39
	s_add_u32 s28, s23, s28
	s_addc_u32 s29, s38, s29
	s_and_b64 s[38:39], exec, s[24:25]
	s_cselect_b32 s23, s29, s37
	s_cselect_b32 s58, s28, s36
	s_add_u32 s30, s30, 0x100080
	s_addc_u32 s31, s31, 0
	s_add_u32 s59, s36, 0x100
	s_addc_u32 s60, s37, 0
	s_mov_b32 s61, -2
	s_waitcnt lgkmcnt(0)
	ds_read_b128 v[138:141], v147
	ds_read_b128 v[150:153], v147 offset:1024
	ds_read_b128 v[154:157], v147 offset:2048
	ds_read_b128 v[158:161], v147 offset:3072
	ds_read_b128 v[162:165], v148
	ds_read_b128 v[166:169], v148 offset:1024
	ds_read_b128 v[170:173], v148 offset:2048
	ds_read_b128 v[174:177], v148 offset:3072
	s_add_u32 s36, s30, 0xfff00080
	s_addc_u32 s37, s31, -1
	s_cmp_eq_u32 s61, 4
	s_cselect_b32 s39, s11, s37
	s_cselect_b32 s38, s21, s36
	s_cselect_b32 s37, s23, s60
	s_cselect_b32 s36, s58, s59
	v_lshl_add_u64 v[142:143], s[30:31], 0, v[134:135]
	s_add_i32 m0, s45, 0xc000
	ds_read_b128 v[178:181], v149
	ds_read_b128 v[182:185], v149 offset:1024
	ds_read_b128 v[186:189], v149 offset:2048
	ds_read_b128 v[190:193], v149 offset:3072
	ds_read_b128 v[194:197], v149 offset:4096
	ds_read_b128 v[198:201], v149 offset:5120
	ds_read_b128 v[202:205], v149 offset:6144
	ds_read_b128 v[206:209], v149 offset:7168
	global_load_lds_dwordx4 v[142:143], off
	v_lshl_add_u64 v[142:143], s[30:31], 0, v[136:137]
	s_add_i32 m0, s45, 0xe000
	s_nop 0
	global_load_lds_dwordx4 v[142:143], off
	s_waitcnt vmcnt(8)
	s_waitcnt lgkmcnt(0)
	s_barrier
	s_setprio 1
	s_waitcnt lgkmcnt(0)
	v_mfma_f32_16x16x32_bf16 v[126:129], v[138:141], v[178:181], 0
	v_mfma_f32_16x16x32_bf16 v[122:125], v[154:157], v[178:181], 0
	v_mfma_f32_16x16x32_bf16 v[110:113], v[138:141], v[186:189], 0
	v_mfma_f32_16x16x32_bf16 v[106:109], v[154:157], v[186:189], 0
	v_mfma_f32_16x16x32_bf16 v[94:97], v[138:141], v[194:197], 0
	v_mfma_f32_16x16x32_bf16 v[90:93], v[154:157], v[194:197], 0
	v_mfma_f32_16x16x32_bf16 v[78:81], v[138:141], v[202:205], 0
	v_mfma_f32_16x16x32_bf16 v[74:77], v[154:157], v[202:205], 0
	v_mfma_f32_16x16x32_bf16 v[126:129], v[150:153], v[182:185], v[126:129]
	v_mfma_f32_16x16x32_bf16 v[122:125], v[158:161], v[182:185], v[122:125]
	v_mfma_f32_16x16x32_bf16 v[110:113], v[150:153], v[190:193], v[110:113]
	v_mfma_f32_16x16x32_bf16 v[106:109], v[158:161], v[190:193], v[106:109]
	v_mfma_f32_16x16x32_bf16 v[94:97], v[150:153], v[198:201], v[94:97]
	v_mfma_f32_16x16x32_bf16 v[90:93], v[158:161], v[198:201], v[90:93]
	v_mfma_f32_16x16x32_bf16 v[78:81], v[150:153], v[206:209], v[78:81]
	v_mfma_f32_16x16x32_bf16 v[74:77], v[158:161], v[206:209], v[74:77]
	s_setprio 0
	s_setprio 1
	v_mfma_f32_16x16x32_bf16 v[118:121], v[162:165], v[178:181], 0
	v_mfma_f32_16x16x32_bf16 v[114:117], v[170:173], v[178:181], 0
	v_mfma_f32_16x16x32_bf16 v[102:105], v[162:165], v[186:189], 0
	v_mfma_f32_16x16x32_bf16 v[98:101], v[170:173], v[186:189], 0
	v_mfma_f32_16x16x32_bf16 v[86:89], v[162:165], v[194:197], 0
	v_mfma_f32_16x16x32_bf16 v[82:85], v[170:173], v[194:197], 0
	v_mfma_f32_16x16x32_bf16 v[70:73], v[162:165], v[202:205], 0
	v_mfma_f32_16x16x32_bf16 v[66:69], v[170:173], v[202:205], 0
	v_mfma_f32_16x16x32_bf16 v[118:121], v[166:169], v[182:185], v[118:121]
	v_mfma_f32_16x16x32_bf16 v[114:117], v[174:177], v[182:185], v[114:117]
	v_mfma_f32_16x16x32_bf16 v[102:105], v[166:169], v[190:193], v[102:105]
	v_mfma_f32_16x16x32_bf16 v[98:101], v[174:177], v[190:193], v[98:101]
	v_mfma_f32_16x16x32_bf16 v[86:89], v[166:169], v[198:201], v[86:89]
	v_mfma_f32_16x16x32_bf16 v[82:85], v[174:177], v[198:201], v[82:85]
	v_mfma_f32_16x16x32_bf16 v[70:73], v[166:169], v[206:209], v[70:73]
	v_mfma_f32_16x16x32_bf16 v[66:69], v[174:177], v[206:209], v[66:69]
	s_setprio 0
	s_barrier
	s_add_i32 s62, s54, s42
	v_lshl_add_u64 v[142:143], s[36:37], 0, v[132:133]
	s_mov_b32 m0, s62
	ds_read_b128 v[178:181], v149 offset:16384
	ds_read_b128 v[182:185], v149 offset:17408
	ds_read_b128 v[186:189], v149 offset:18432
	ds_read_b128 v[190:193], v149 offset:19456
	ds_read_b128 v[194:197], v149 offset:20480
	ds_read_b128 v[198:201], v149 offset:21504
	ds_read_b128 v[202:205], v149 offset:22528
	ds_read_b128 v[206:209], v149 offset:23552
	global_load_lds_dwordx4 v[142:143], off
	s_add_i32 m0, s62, 0x2000
	s_add_u32 s62, s36, 0x100000
	v_lshl_add_u64 v[210:211], s[36:37], 0, v[130:131]
	s_addc_u32 s63, s37, 0
	s_add_i32 s64, s55, s42
	global_load_lds_dwordx4 v[210:211], off
	v_lshl_add_u64 v[212:213], s[62:63], 0, v[132:133]
	s_mov_b32 m0, s64
	v_lshl_add_u64 v[214:215], s[38:39], 0, v[130:131]
	global_load_lds_dwordx4 v[212:213], off
	v_lshl_add_u64 v[212:213], s[62:63], 0, v[130:131]
	s_add_i32 m0, s64, 0x2000
	s_nop 0
	global_load_lds_dwordx4 v[212:213], off
	v_lshl_add_u64 v[212:213], s[38:39], 0, v[132:133]
	s_mov_b32 m0, s45
	s_nop 0
	global_load_lds_dwordx4 v[212:213], off
	s_mov_b32 m0, s46
	s_nop 0
	global_load_lds_dwordx4 v[214:215], off
	s_waitcnt vmcnt(8)
	s_waitcnt lgkmcnt(0)
	s_barrier
; #define PG8_STAGE(bufoff, gbase, voff) do { _Pragma("unroll") for (int _i = 0; _i < 2; ++_i) \
;         __builtin_amdgcn_global_load_lds((const unsigned*)((const char*)(gbase) + (voff)[_i]), (PG8_LAS unsigned*)(lds + (bufoff) + ldsw + _i * 8192), 16, 0, 0); } while (0)
; #define PG8_LDA(dst, b, h) do { _Pragma("unroll") for (int m = 0; m < 4; ++m) _Pragma("unroll") for (int k = 0; k < 2; ++k) dst[m][k] = *(const PG8_LAS bf16x8*)(lds + PG8_SA(b, h) + aoff + m * 2048 + k * 1024); } while (0)
; #define PG8_LDB(dst, b, h) do { _Pragma("unroll") for (int n = 0; n < 2; ++n) _Pragma("unroll") for (int k = 0; k < 2; ++k) dst[n][k] = *(const PG8_LAS bf16x8*)(lds + PG8_SB(b, h) + boff + n * 2048 + k * 1024); } while (0)
; #define PG8_MMA(ai, bj, At, Bt) do { __builtin_amdgcn_s_setprio(1); _Pragma("unroll") for (int m = 0; m < 4; ++m) _Pragma("unroll") for (int n = 0; n < 2; ++n) _Pragma("unroll") for (int k = 0; k < 2; ++k) \
;         acc[ai][bj][m][n] = __builtin_amdgcn_mfma_f32_16x16x32_bf16(Bt[n][k], At[m][k], acc[ai][bj][m][n], 0, 0, 0); __builtin_amdgcn_s_setprio(0); } while (0)
; #define PG8_WAIT_V(n) asm volatile("s_waitcnt vmcnt(" #n ")" ::: "memory")
; #define PG8_WAIT_L(n) asm volatile("s_waitcnt lgkmcnt(" #n ")" ::: "memory")
; #define PG8_BAR __builtin_amdgcn_s_barrier()
; #define PG8_SCHED __builtin_amdgcn_sched_barrier(0)
; template <class Epi, class Sched, bool ALIGN_EPI = false, bool SP2 = false>
; __device__ __forceinline__ void gemm_phase(PG8_LAS unsigned char* lds, const Gemm g, const Sched& S, const Epi& E) {
;     ...
;             PG8_WAIT_V(8); PG8_WAIT_L(0); PG8_BAR; PG8_MMA(1, 0, At, B0); PG8_MMA(1, 1, At, B1); PG8_BAR; PG8_SCHED;
;             PG8_LDB(B0, 1, 0); PG8_LDB(B1, 1, 1); PG8_SCHED; PG8_LDA(At, 1, 0); PG8_STAGE(PG8_SA(0, 1), a2 + hstep, voffA);
;             PG8_WAIT_V(8); PG8_WAIT_L(0); PG8_BAR; PG8_MMA(0, 0, At, B0); PG8_MMA(0, 1, At, B1); PG8_BAR; PG8_SCHED;
;             PG8_LDA(At, 1, 1); PG8_STAGE(PG8_SB(1, 0), b3, voffB); PG8_STAGE(PG8_SB(1, 1), b3 + hstep, voffB); PG8_STAGE(PG8_SA(1, 0), a3, voffA);
;             PG8_WAIT_V(8); PG8_WAIT_L(0); PG8_BAR; PG8_MMA(1, 0, At, B0); PG8_MMA(1, 1, At, B1); PG8_BAR; PG8_SCHED;
	s_setprio 1
	s_waitcnt lgkmcnt(0)
	v_mfma_f32_16x16x32_bf16 v[62:65], v[138:141], v[178:181], 0
	v_mfma_f32_16x16x32_bf16 v[58:61], v[154:157], v[178:181], 0
	v_mfma_f32_16x16x32_bf16 v[46:49], v[138:141], v[186:189], 0
	v_mfma_f32_16x16x32_bf16 v[42:45], v[154:157], v[186:189], 0
	v_mfma_f32_16x16x32_bf16 v[30:33], v[138:141], v[194:197], 0
	v_mfma_f32_16x16x32_bf16 v[26:29], v[154:157], v[194:197], 0
	v_mfma_f32_16x16x32_bf16 v[14:17], v[138:141], v[202:205], 0
	v_mfma_f32_16x16x32_bf16 v[10:13], v[154:157], v[202:205], 0
	v_mfma_f32_16x16x32_bf16 v[62:65], v[150:153], v[182:185], v[62:65]
	v_mfma_f32_16x16x32_bf16 v[58:61], v[158:161], v[182:185], v[58:61]
	v_mfma_f32_16x16x32_bf16 v[46:49], v[150:153], v[190:193], v[46:49]
	v_mfma_f32_16x16x32_bf16 v[42:45], v[158:161], v[190:193], v[42:45]
	v_mfma_f32_16x16x32_bf16 v[30:33], v[150:153], v[198:201], v[30:33]
	v_mfma_f32_16x16x32_bf16 v[26:29], v[158:161], v[198:201], v[26:29]
	v_mfma_f32_16x16x32_bf16 v[14:17], v[150:153], v[206:209], v[14:17]
	v_mfma_f32_16x16x32_bf16 v[10:13], v[158:161], v[206:209], v[10:13]
	s_setprio 0
	s_setprio 1
	v_mfma_f32_16x16x32_bf16 v[54:57], v[162:165], v[178:181], 0
	v_mfma_f32_16x16x32_bf16 v[50:53], v[170:173], v[178:181], 0
	v_mfma_f32_16x16x32_bf16 v[38:41], v[162:165], v[186:189], 0
	v_mfma_f32_16x16x32_bf16 v[34:37], v[170:173], v[186:189], 0
	v_mfma_f32_16x16x32_bf16 v[22:25], v[162:165], v[194:197], 0
	v_mfma_f32_16x16x32_bf16 v[18:21], v[170:173], v[194:197], 0
	v_mfma_f32_16x16x32_bf16 v[6:9], v[162:165], v[202:205], 0
	v_mfma_f32_16x16x32_bf16 v[2:5], v[170:173], v[202:205], 0
	v_mfma_f32_16x16x32_bf16 v[54:57], v[166:169], v[182:185], v[54:57]
	v_mfma_f32_16x16x32_bf16 v[50:53], v[174:177], v[182:185], v[50:53]
	v_mfma_f32_16x16x32_bf16 v[38:41], v[166:169], v[190:193], v[38:41]
	v_mfma_f32_16x16x32_bf16 v[34:37], v[174:177], v[190:193], v[34:37]
	v_mfma_f32_16x16x32_bf16 v[22:25], v[166:169], v[198:201], v[22:25]
	v_mfma_f32_16x16x32_bf16 v[18:21], v[174:177], v[198:201], v[18:21]
	v_mfma_f32_16x16x32_bf16 v[6:9], v[166:169], v[206:209], v[6:9]
	v_mfma_f32_16x16x32_bf16 v[2:5], v[174:177], v[206:209], v[2:5]
	s_setprio 0
	s_barrier
	s_add_i32 s62, 0, 0x18000
	s_add_i32 s63, 0, 0x1c000
	v_add_u32_e32 v158, s62, v144
	v_add_u32_e32 v174, s63, v144
	ds_read_b128 v[138:141], v158
	ds_read_b128 v[150:153], v158 offset:1024
	ds_read_b128 v[154:157], v158 offset:2048
	ds_read_b128 v[158:161], v158 offset:3072
	ds_read_b128 v[162:165], v174
	ds_read_b128 v[166:169], v174 offset:1024
	ds_read_b128 v[170:173], v174 offset:2048
	ds_read_b128 v[174:177], v174 offset:3072
	s_add_u32 s38, s38, 0x100000
	s_addc_u32 s39, s39, 0
	s_mov_b32 m0, s47
	v_lshl_add_u64 v[216:217], s[38:39], 0, v[132:133]
	ds_read_b128 v[178:181], v149 offset:32768
	ds_read_b128 v[182:185], v149 offset:33792
	ds_read_b128 v[186:189], v149 offset:34816
	ds_read_b128 v[190:193], v149 offset:35840
	ds_read_b128 v[194:197], v149 offset:36864
	ds_read_b128 v[198:201], v149 offset:37888
	ds_read_b128 v[202:205], v149 offset:38912
	ds_read_b128 v[206:209], v149 offset:39936
	global_load_lds_dwordx4 v[216:217], off
	v_lshl_add_u64 v[216:217], s[38:39], 0, v[130:131]
	s_mov_b32 m0, s48
	s_nop 0
	global_load_lds_dwordx4 v[216:217], off
	s_waitcnt vmcnt(8)
	s_waitcnt lgkmcnt(0)
	s_barrier
	s_setprio 1
	s_waitcnt lgkmcnt(0)
	v_mfma_f32_16x16x32_bf16 v[126:129], v[138:141], v[178:181], v[126:129]
	v_mfma_f32_16x16x32_bf16 v[122:125], v[154:157], v[178:181], v[122:125]
	v_mfma_f32_16x16x32_bf16 v[110:113], v[138:141], v[186:189], v[110:113]
	v_mfma_f32_16x16x32_bf16 v[106:109], v[154:157], v[186:189], v[106:109]
	v_mfma_f32_16x16x32_bf16 v[94:97], v[138:141], v[194:197], v[94:97]
	v_mfma_f32_16x16x32_bf16 v[90:93], v[154:157], v[194:197], v[90:93]
	v_mfma_f32_16x16x32_bf16 v[78:81], v[138:141], v[202:205], v[78:81]
	v_mfma_f32_16x16x32_bf16 v[74:77], v[154:157], v[202:205], v[74:77]
	v_mfma_f32_16x16x32_bf16 v[126:129], v[150:153], v[182:185], v[126:129]
	v_mfma_f32_16x16x32_bf16 v[122:125], v[158:161], v[182:185], v[122:125]
	v_mfma_f32_16x16x32_bf16 v[110:113], v[150:153], v[190:193], v[110:113]
	v_mfma_f32_16x16x32_bf16 v[106:109], v[158:161], v[190:193], v[106:109]
	v_mfma_f32_16x16x32_bf16 v[94:97], v[150:153], v[198:201], v[94:97]
	v_mfma_f32_16x16x32_bf16 v[90:93], v[158:161], v[198:201], v[90:93]
	v_mfma_f32_16x16x32_bf16 v[78:81], v[150:153], v[206:209], v[78:81]
	v_mfma_f32_16x16x32_bf16 v[74:77], v[158:161], v[206:209], v[74:77]
	s_setprio 0
	s_setprio 1
	v_mfma_f32_16x16x32_bf16 v[118:121], v[162:165], v[178:181], v[118:121]
	v_mfma_f32_16x16x32_bf16 v[114:117], v[170:173], v[178:181], v[114:117]
	v_mfma_f32_16x16x32_bf16 v[102:105], v[162:165], v[186:189], v[102:105]
	v_mfma_f32_16x16x32_bf16 v[98:101], v[170:173], v[186:189], v[98:101]
	v_mfma_f32_16x16x32_bf16 v[86:89], v[162:165], v[194:197], v[86:89]
	v_mfma_f32_16x16x32_bf16 v[82:85], v[170:173], v[194:197], v[82:85]
	v_mfma_f32_16x16x32_bf16 v[70:73], v[162:165], v[202:205], v[70:73]
	v_mfma_f32_16x16x32_bf16 v[66:69], v[170:173], v[202:205], v[66:69]
	v_mfma_f32_16x16x32_bf16 v[118:121], v[166:169], v[182:185], v[118:121]
	v_mfma_f32_16x16x32_bf16 v[114:117], v[174:177], v[182:185], v[114:117]
	v_mfma_f32_16x16x32_bf16 v[102:105], v[166:169], v[190:193], v[102:105]
	v_mfma_f32_16x16x32_bf16 v[98:101], v[174:177], v[190:193], v[98:101]
	v_mfma_f32_16x16x32_bf16 v[86:89], v[166:169], v[198:201], v[86:89]
	v_mfma_f32_16x16x32_bf16 v[82:85], v[174:177], v[198:201], v[82:85]
	v_mfma_f32_16x16x32_bf16 v[70:73], v[166:169], v[206:209], v[70:73]
	v_mfma_f32_16x16x32_bf16 v[66:69], v[174:177], v[206:209], v[66:69]
	s_setprio 0
	s_barrier
; #define PG8_STAGE(bufoff, gbase, voff) do { _Pragma("unroll") for (int _i = 0; _i < 2; ++_i) \
;         __builtin_amdgcn_global_load_lds((const unsigned*)((const char*)(gbase) + (voff)[_i]), (PG8_LAS unsigned*)(lds + (bufoff) + ldsw + _i * 8192), 16, 0, 0); } while (0)
; #define PG8_LDA(dst, b, h) do { _Pragma("unroll") for (int m = 0; m < 4; ++m) _Pragma("unroll") for (int k = 0; k < 2; ++k) dst[m][k] = *(const PG8_LAS bf16x8*)(lds + PG8_SA(b, h) + aoff + m * 2048 + k * 1024); } while (0)
; #define PG8_LDB(dst, b, h) do { _Pragma("unroll") for (int n = 0; n < 2; ++n) _Pragma("unroll") for (int k = 0; k < 2; ++k) dst[n][k] = *(const PG8_LAS bf16x8*)(lds + PG8_SB(b, h) + boff + n * 2048 + k * 1024); } while (0)
; #define PG8_MMA(ai, bj, At, Bt) do { __builtin_amdgcn_s_setprio(1); _Pragma("unroll") for (int m = 0; m < 4; ++m) _Pragma("unroll") for (int n = 0; n < 2; ++n) _Pragma("unroll") for (int k = 0; k < 2; ++k) \
;         acc[ai][bj][m][n] = __builtin_amdgcn_mfma_f32_16x16x32_bf16(Bt[n][k], At[m][k], acc[ai][bj][m][n], 0, 0, 0); __builtin_amdgcn_s_setprio(0); } while (0)
; #define PG8_WAIT_V(n) asm volatile("s_waitcnt vmcnt(" #n ")" ::: "memory")
; #define PG8_WAIT_L(n) asm volatile("s_waitcnt lgkmcnt(" #n ")" ::: "memory")
; template <class Epi, class Sched, bool ALIGN_EPI = false, bool SP2 = false>
; __device__ __forceinline__ void gemm_phase(PG8_LAS unsigned char* lds, const Gemm g, const Sched& S, const Epi& E) {
;     ...
;         for (int t = 0; t < nt; t += 2) {
;             if constexpr (Epi::MIDHOOK) { if (t == (nt >> 1)) E.mid(acc, cur, wr, wc, fr, fq); }
;             const bool last = (t == nt - 2);
;             const char* a1 = cA + (size_t)(t + 1) * kstep;
;             const char* a2 = last ? nA : cA + (size_t)(t + 2) * kstep; const char* b2 = last ? nB : cB + (size_t)(t + 2) * kstep;
;             const char* a3 = a2 + kstep; const char* b3 = b2 + kstep;
;             if (last && has_next) S.a_ready(nxt);
;             if constexpr (SP2) {
;             PG8_LDB(B0, 0, 0); PG8_LDB(B1, 0, 1); PG8_SCHED; PG8_LDA(At, 0, 0); PG8_STAGE(PG8_SA(1, 1), a1 + hstep, voffA);
;     ...
;             PG8_LDA(At, 1, 1); PG8_STAGE(PG8_SB(1, 0), b3, voffB); PG8_STAGE(PG8_SB(1, 1), b3 + hstep, voffB); PG8_STAGE(PG8_SA(1, 0), a3, voffA);
;             PG8_WAIT_V(8); PG8_WAIT_L(0); PG8_BAR; PG8_MMA(1, 0, At, B0); PG8_MMA(1, 1, At, B1); PG8_BAR; PG8_SCHED;
	s_add_i32 s38, s62, s42
	v_lshl_add_u64 v[142:143], v[142:143], 0, s[16:17]
	s_mov_b32 m0, s38
	ds_read_b128 v[178:181], v149 offset:49152
	ds_read_b128 v[182:185], v149 offset:50176
	ds_read_b128 v[186:189], v149 offset:51200
	ds_read_b128 v[190:193], v149 offset:52224
	ds_read_b128 v[194:197], v149 offset:53248
	ds_read_b128 v[198:201], v149 offset:54272
	ds_read_b128 v[202:205], v149 offset:55296
	ds_read_b128 v[206:209], v149 offset:56320
	global_load_lds_dwordx4 v[142:143], off
	s_add_i32 m0, s38, 0x2000
	s_add_u32 s36, s36, 0x100080
	v_lshl_add_u64 v[142:143], v[210:211], 0, s[16:17]
	s_addc_u32 s37, s37, 0
	s_add_i32 s38, s63, s42
	global_load_lds_dwordx4 v[142:143], off
	v_lshl_add_u64 v[142:143], s[36:37], 0, v[132:133]
	s_mov_b32 m0, s38
	s_nop 0
	global_load_lds_dwordx4 v[142:143], off
	v_lshl_add_u64 v[142:143], s[36:37], 0, v[130:131]
	s_add_i32 m0, s38, 0x2000
	s_nop 0
	global_load_lds_dwordx4 v[142:143], off
	v_lshl_add_u64 v[142:143], v[212:213], 0, s[16:17]
	s_mov_b32 m0, s51
	s_nop 0
	global_load_lds_dwordx4 v[142:143], off
	v_lshl_add_u64 v[142:143], v[214:215], 0, s[16:17]
	s_mov_b32 m0, s52
	s_nop 0
	global_load_lds_dwordx4 v[142:143], off
	s_waitcnt vmcnt(8)
	s_waitcnt lgkmcnt(0)
	s_barrier
	s_setprio 1
	s_waitcnt lgkmcnt(0)
	v_mfma_f32_16x16x32_bf16 v[62:65], v[138:141], v[178:181], v[62:65]
	v_mfma_f32_16x16x32_bf16 v[58:61], v[154:157], v[178:181], v[58:61]
	v_mfma_f32_16x16x32_bf16 v[46:49], v[138:141], v[186:189], v[46:49]
	v_mfma_f32_16x16x32_bf16 v[42:45], v[154:157], v[186:189], v[42:45]
	v_mfma_f32_16x16x32_bf16 v[30:33], v[138:141], v[194:197], v[30:33]
	v_mfma_f32_16x16x32_bf16 v[26:29], v[154:157], v[194:197], v[26:29]
	v_mfma_f32_16x16x32_bf16 v[14:17], v[138:141], v[202:205], v[14:17]
	v_mfma_f32_16x16x32_bf16 v[10:13], v[154:157], v[202:205], v[10:13]
	v_mfma_f32_16x16x32_bf16 v[62:65], v[150:153], v[182:185], v[62:65]
	v_mfma_f32_16x16x32_bf16 v[58:61], v[158:161], v[182:185], v[58:61]
	v_mfma_f32_16x16x32_bf16 v[46:49], v[150:153], v[190:193], v[46:49]
	v_mfma_f32_16x16x32_bf16 v[42:45], v[158:161], v[190:193], v[42:45]
	v_mfma_f32_16x16x32_bf16 v[30:33], v[150:153], v[198:201], v[30:33]
	v_mfma_f32_16x16x32_bf16 v[26:29], v[158:161], v[198:201], v[26:29]
	v_mfma_f32_16x16x32_bf16 v[14:17], v[150:153], v[206:209], v[14:17]
	v_mfma_f32_16x16x32_bf16 v[10:13], v[158:161], v[206:209], v[10:13]
	s_setprio 0
	s_setprio 1
	v_mfma_f32_16x16x32_bf16 v[54:57], v[162:165], v[178:181], v[54:57]
	v_mfma_f32_16x16x32_bf16 v[50:53], v[170:173], v[178:181], v[50:53]
	v_mfma_f32_16x16x32_bf16 v[38:41], v[162:165], v[186:189], v[38:41]
	v_mfma_f32_16x16x32_bf16 v[34:37], v[170:173], v[186:189], v[34:37]
	v_mfma_f32_16x16x32_bf16 v[22:25], v[162:165], v[194:197], v[22:25]
	v_mfma_f32_16x16x32_bf16 v[18:21], v[170:173], v[194:197], v[18:21]
	v_mfma_f32_16x16x32_bf16 v[6:9], v[162:165], v[202:205], v[6:9]
	v_mfma_f32_16x16x32_bf16 v[2:5], v[170:173], v[202:205], v[2:5]
	v_mfma_f32_16x16x32_bf16 v[54:57], v[166:169], v[182:185], v[54:57]
	v_mfma_f32_16x16x32_bf16 v[50:53], v[174:177], v[182:185], v[50:53]
	v_mfma_f32_16x16x32_bf16 v[38:41], v[166:169], v[190:193], v[38:41]
	v_mfma_f32_16x16x32_bf16 v[34:37], v[174:177], v[190:193], v[34:37]
	v_mfma_f32_16x16x32_bf16 v[22:25], v[166:169], v[198:201], v[22:25]
	v_mfma_f32_16x16x32_bf16 v[18:21], v[174:177], v[198:201], v[18:21]
	v_mfma_f32_16x16x32_bf16 v[6:9], v[166:169], v[206:209], v[6:9]
	v_mfma_f32_16x16x32_bf16 v[2:5], v[174:177], v[206:209], v[2:5]
	s_setprio 0
	s_barrier
	s_add_i32 s61, s61, 2
	s_add_u32 s30, s30, 0x100
	s_addc_u32 s31, s31, 0
	s_add_u32 s59, s59, 0x100
	s_addc_u32 s60, s60, 0
	s_cmp_gt_u32 s61, 5
	s_cbranch_scc1 .Lkx_1219
.LBB0_1219:
	ds_read_b128 v[138:141], v147
	ds_read_b128 v[150:153], v147 offset:1024
	ds_read_b128 v[154:157], v147 offset:2048
	ds_read_b128 v[158:161], v147 offset:3072
	ds_read_b128 v[162:165], v148
	ds_read_b128 v[166:169], v148 offset:1024
	ds_read_b128 v[170:173], v148 offset:2048
	ds_read_b128 v[174:177], v148 offset:3072
	s_add_u32 s36, s30, 0xfff00080
	s_addc_u32 s37, s31, -1
	s_cmp_eq_u32 s61, 4
	s_cselect_b32 s39, s11, s37
	s_cselect_b32 s38, s21, s36
	s_cselect_b32 s37, s23, s60
	s_cselect_b32 s36, s58, s59
	v_lshl_add_u64 v[142:143], s[30:31], 0, v[134:135]
	s_add_i32 m0, s45, 0xc000
	ds_read_b128 v[178:181], v149
	ds_read_b128 v[182:185], v149 offset:1024
	ds_read_b128 v[186:189], v149 offset:2048
	ds_read_b128 v[190:193], v149 offset:3072
	ds_read_b128 v[194:197], v149 offset:4096
	ds_read_b128 v[198:201], v149 offset:5120
	ds_read_b128 v[202:205], v149 offset:6144
	ds_read_b128 v[206:209], v149 offset:7168
	global_load_lds_dwordx4 v[142:143], off
	v_lshl_add_u64 v[142:143], s[30:31], 0, v[136:137]
	s_add_i32 m0, s45, 0xe000
	s_nop 0
	global_load_lds_dwordx4 v[142:143], off
	s_waitcnt vmcnt(8)
	s_waitcnt lgkmcnt(0)
	s_barrier
; #define PG8_STAGE(bufoff, gbase, voff) do { _Pragma("unroll") for (int _i = 0; _i < 2; ++_i) \
;         __builtin_amdgcn_global_load_lds((const unsigned*)((const char*)(gbase) + (voff)[_i]), (PG8_LAS unsigned*)(lds + (bufoff) + ldsw + _i * 8192), 16, 0, 0); } while (0)
; #define PG8_LDA(dst, b, h) do { _Pragma("unroll") for (int m = 0; m < 4; ++m) _Pragma("unroll") for (int k = 0; k < 2; ++k) dst[m][k] = *(const PG8_LAS bf16x8*)(lds + PG8_SA(b, h) + aoff + m * 2048 + k * 1024); } while (0)
; #define PG8_LDB(dst, b, h) do { _Pragma("unroll") for (int n = 0; n < 2; ++n) _Pragma("unroll") for (int k = 0; k < 2; ++k) dst[n][k] = *(const PG8_LAS bf16x8*)(lds + PG8_SB(b, h) + boff + n * 2048 + k * 1024); } while (0)
; #define PG8_MMA(ai, bj, At, Bt) do { __builtin_amdgcn_s_setprio(1); _Pragma("unroll") for (int m = 0; m < 4; ++m) _Pragma("unroll") for (int n = 0; n < 2; ++n) _Pragma("unroll") for (int k = 0; k < 2; ++k) \
;         acc[ai][bj][m][n] = __builtin_amdgcn_mfma_f32_16x16x32_bf16(Bt[n][k], At[m][k], acc[ai][bj][m][n], 0, 0, 0); __builtin_amdgcn_s_setprio(0); } while (0)
; #define PG8_WAIT_V(n) asm volatile("s_waitcnt vmcnt(" #n ")" ::: "memory")
; #define PG8_WAIT_L(n) asm volatile("s_waitcnt lgkmcnt(" #n ")" ::: "memory")
; #define PG8_BAR __builtin_amdgcn_s_barrier()
; #define PG8_SCHED __builtin_amdgcn_sched_barrier(0)
; template <class Epi, class Sched, bool ALIGN_EPI = false, bool SP2 = false>
; __device__ __forceinline__ void gemm_phase(PG8_LAS unsigned char* lds, const Gemm g, const Sched& S, const Epi& E) {
;     ...
;             PG8_LDB(B0, 0, 0); PG8_LDB(B1, 0, 1); PG8_SCHED; PG8_LDA(At, 0, 0); PG8_STAGE(PG8_SA(1, 1), a1 + hstep, voffA);
;             PG8_WAIT_V(8); PG8_WAIT_L(0); PG8_BAR; PG8_MMA(0, 0, At, B0); PG8_MMA(0, 1, At, B1); PG8_BAR; PG8_SCHED;
;             PG8_LDA(At, 0, 1); PG8_STAGE(PG8_SB(0, 0), b2, voffB); PG8_STAGE(PG8_SB(0, 1), b2 + hstep, voffB); PG8_STAGE(PG8_SA(0, 0), a2, voffA);
;             PG8_WAIT_V(8); PG8_WAIT_L(0); PG8_BAR; PG8_MMA(1, 0, At, B0); PG8_MMA(1, 1, At, B1); PG8_BAR; PG8_SCHED;
;             PG8_LDB(B0, 1, 0); PG8_LDB(B1, 1, 1); PG8_SCHED; PG8_LDA(At, 1, 0); PG8_STAGE(PG8_SA(0, 1), a2 + hstep, voffA);
;             PG8_WAIT_V(8); PG8_WAIT_L(0); PG8_BAR; PG8_MMA(0, 0, At, B0); PG8_MMA(0, 1, At, B1); PG8_BAR; PG8_SCHED;
	s_setprio 1
	s_waitcnt lgkmcnt(0)
	v_mfma_f32_16x16x32_bf16 v[126:129], v[138:141], v[178:181], v[126:129]
	v_mfma_f32_16x16x32_bf16 v[122:125], v[154:157], v[178:181], v[122:125]
	v_mfma_f32_16x16x32_bf16 v[110:113], v[138:141], v[186:189], v[110:113]
	v_mfma_f32_16x16x32_bf16 v[106:109], v[154:157], v[186:189], v[106:109]
	v_mfma_f32_16x16x32_bf16 v[94:97], v[138:141], v[194:197], v[94:97]
	v_mfma_f32_16x16x32_bf16 v[90:93], v[154:157], v[194:197], v[90:93]
	v_mfma_f32_16x16x32_bf16 v[78:81], v[138:141], v[202:205], v[78:81]
	v_mfma_f32_16x16x32_bf16 v[74:77], v[154:157], v[202:205], v[74:77]
	v_mfma_f32_16x16x32_bf16 v[126:129], v[150:153], v[182:185], v[126:129]
	v_mfma_f32_16x16x32_bf16 v[122:125], v[158:161], v[182:185], v[122:125]
	v_mfma_f32_16x16x32_bf16 v[110:113], v[150:153], v[190:193], v[110:113]
	v_mfma_f32_16x16x32_bf16 v[106:109], v[158:161], v[190:193], v[106:109]
	v_mfma_f32_16x16x32_bf16 v[94:97], v[150:153], v[198:201], v[94:97]
	v_mfma_f32_16x16x32_bf16 v[90:93], v[158:161], v[198:201], v[90:93]
	v_mfma_f32_16x16x32_bf16 v[78:81], v[150:153], v[206:209], v[78:81]
	v_mfma_f32_16x16x32_bf16 v[74:77], v[158:161], v[206:209], v[74:77]
	s_setprio 0
	s_setprio 1
	v_mfma_f32_16x16x32_bf16 v[118:121], v[162:165], v[178:181], v[118:121]
	v_mfma_f32_16x16x32_bf16 v[114:117], v[170:173], v[178:181], v[114:117]
	v_mfma_f32_16x16x32_bf16 v[102:105], v[162:165], v[186:189], v[102:105]
	v_mfma_f32_16x16x32_bf16 v[98:101], v[170:173], v[186:189], v[98:101]
	v_mfma_f32_16x16x32_bf16 v[86:89], v[162:165], v[194:197], v[86:89]
	v_mfma_f32_16x16x32_bf16 v[82:85], v[170:173], v[194:197], v[82:85]
	v_mfma_f32_16x16x32_bf16 v[70:73], v[162:165], v[202:205], v[70:73]
	v_mfma_f32_16x16x32_bf16 v[66:69], v[170:173], v[202:205], v[66:69]
	v_mfma_f32_16x16x32_bf16 v[118:121], v[166:169], v[182:185], v[118:121]
	v_mfma_f32_16x16x32_bf16 v[114:117], v[174:177], v[182:185], v[114:117]
	v_mfma_f32_16x16x32_bf16 v[102:105], v[166:169], v[190:193], v[102:105]
	v_mfma_f32_16x16x32_bf16 v[98:101], v[174:177], v[190:193], v[98:101]
	v_mfma_f32_16x16x32_bf16 v[86:89], v[166:169], v[198:201], v[86:89]
	v_mfma_f32_16x16x32_bf16 v[82:85], v[174:177], v[198:201], v[82:85]
	v_mfma_f32_16x16x32_bf16 v[70:73], v[166:169], v[206:209], v[70:73]
	v_mfma_f32_16x16x32_bf16 v[66:69], v[174:177], v[206:209], v[66:69]
	s_setprio 0
	s_barrier
	s_add_i32 s62, s54, s42
	v_lshl_add_u64 v[142:143], s[36:37], 0, v[132:133]
	s_mov_b32 m0, s62
	ds_read_b128 v[178:181], v149 offset:16384
	ds_read_b128 v[182:185], v149 offset:17408
	ds_read_b128 v[186:189], v149 offset:18432
	ds_read_b128 v[190:193], v149 offset:19456
	ds_read_b128 v[194:197], v149 offset:20480
	ds_read_b128 v[198:201], v149 offset:21504
	ds_read_b128 v[202:205], v149 offset:22528
	ds_read_b128 v[206:209], v149 offset:23552
	global_load_lds_dwordx4 v[142:143], off
	s_add_i32 m0, s62, 0x2000
	s_add_u32 s62, s36, 0x100000
	v_lshl_add_u64 v[210:211], s[36:37], 0, v[130:131]
	s_addc_u32 s63, s37, 0
	s_add_i32 s64, s55, s42
	global_load_lds_dwordx4 v[210:211], off
	v_lshl_add_u64 v[212:213], s[62:63], 0, v[132:133]
	s_mov_b32 m0, s64
	v_lshl_add_u64 v[214:215], s[38:39], 0, v[130:131]
	global_load_lds_dwordx4 v[212:213], off
	v_lshl_add_u64 v[212:213], s[62:63], 0, v[130:131]
	s_add_i32 m0, s64, 0x2000
	s_nop 0
	global_load_lds_dwordx4 v[212:213], off
	v_lshl_add_u64 v[212:213], s[38:39], 0, v[132:133]
	s_mov_b32 m0, s45
	s_nop 0
	global_load_lds_dwordx4 v[212:213], off
	s_mov_b32 m0, s46
	s_nop 0
	global_load_lds_dwordx4 v[214:215], off
	s_waitcnt vmcnt(8)
	s_waitcnt lgkmcnt(0)
	s_barrier
	s_setprio 1
	s_waitcnt lgkmcnt(0)
	v_mfma_f32_16x16x32_bf16 v[62:65], v[138:141], v[178:181], v[62:65]
	v_mfma_f32_16x16x32_bf16 v[58:61], v[154:157], v[178:181], v[58:61]
	v_mfma_f32_16x16x32_bf16 v[46:49], v[138:141], v[186:189], v[46:49]
	v_mfma_f32_16x16x32_bf16 v[42:45], v[154:157], v[186:189], v[42:45]
	v_mfma_f32_16x16x32_bf16 v[30:33], v[138:141], v[194:197], v[30:33]
	v_mfma_f32_16x16x32_bf16 v[26:29], v[154:157], v[194:197], v[26:29]
	v_mfma_f32_16x16x32_bf16 v[14:17], v[138:141], v[202:205], v[14:17]
	v_mfma_f32_16x16x32_bf16 v[10:13], v[154:157], v[202:205], v[10:13]
	v_mfma_f32_16x16x32_bf16 v[62:65], v[150:153], v[182:185], v[62:65]
	v_mfma_f32_16x16x32_bf16 v[58:61], v[158:161], v[182:185], v[58:61]
	v_mfma_f32_16x16x32_bf16 v[46:49], v[150:153], v[190:193], v[46:49]
	v_mfma_f32_16x16x32_bf16 v[42:45], v[158:161], v[190:193], v[42:45]
	v_mfma_f32_16x16x32_bf16 v[30:33], v[150:153], v[198:201], v[30:33]
	v_mfma_f32_16x16x32_bf16 v[26:29], v[158:161], v[198:201], v[26:29]
	v_mfma_f32_16x16x32_bf16 v[14:17], v[150:153], v[206:209], v[14:17]
	v_mfma_f32_16x16x32_bf16 v[10:13], v[158:161], v[206:209], v[10:13]
	s_setprio 0
	s_setprio 1
	v_mfma_f32_16x16x32_bf16 v[54:57], v[162:165], v[178:181], v[54:57]
	v_mfma_f32_16x16x32_bf16 v[50:53], v[170:173], v[178:181], v[50:53]
	v_mfma_f32_16x16x32_bf16 v[38:41], v[162:165], v[186:189], v[38:41]
	v_mfma_f32_16x16x32_bf16 v[34:37], v[170:173], v[186:189], v[34:37]
	v_mfma_f32_16x16x32_bf16 v[22:25], v[162:165], v[194:197], v[22:25]
	v_mfma_f32_16x16x32_bf16 v[18:21], v[170:173], v[194:197], v[18:21]
	v_mfma_f32_16x16x32_bf16 v[6:9], v[162:165], v[202:205], v[6:9]
	v_mfma_f32_16x16x32_bf16 v[2:5], v[170:173], v[202:205], v[2:5]
	v_mfma_f32_16x16x32_bf16 v[54:57], v[166:169], v[182:185], v[54:57]
	v_mfma_f32_16x16x32_bf16 v[50:53], v[174:177], v[182:185], v[50:53]
	v_mfma_f32_16x16x32_bf16 v[38:41], v[166:169], v[190:193], v[38:41]
	v_mfma_f32_16x16x32_bf16 v[34:37], v[174:177], v[190:193], v[34:37]
	v_mfma_f32_16x16x32_bf16 v[22:25], v[166:169], v[198:201], v[22:25]
	v_mfma_f32_16x16x32_bf16 v[18:21], v[174:177], v[198:201], v[18:21]
	v_mfma_f32_16x16x32_bf16 v[6:9], v[166:169], v[206:209], v[6:9]
	v_mfma_f32_16x16x32_bf16 v[2:5], v[174:177], v[206:209], v[2:5]
	s_setprio 0
	s_barrier
; #define PG8_STAGE(bufoff, gbase, voff) do { _Pragma("unroll") for (int _i = 0; _i < 2; ++_i) \
;         __builtin_amdgcn_global_load_lds((const unsigned*)((const char*)(gbase) + (voff)[_i]), (PG8_LAS unsigned*)(lds + (bufoff) + ldsw + _i * 8192), 16, 0, 0); } while (0)
; #define PG8_LDA(dst, b, h) do { _Pragma("unroll") for (int m = 0; m < 4; ++m) _Pragma("unroll") for (int k = 0; k < 2; ++k) dst[m][k] = *(const PG8_LAS bf16x8*)(lds + PG8_SA(b, h) + aoff + m * 2048 + k * 1024); } while (0)
; #define PG8_LDB(dst, b, h) do { _Pragma("unroll") for (int n = 0; n < 2; ++n) _Pragma("unroll") for (int k = 0; k < 2; ++k) dst[n][k] = *(const PG8_LAS bf16x8*)(lds + PG8_SB(b, h) + boff + n * 2048 + k * 1024); } while (0)
; #define PG8_MMA(ai, bj, At, Bt) do { __builtin_amdgcn_s_setprio(1); _Pragma("unroll") for (int m = 0; m < 4; ++m) _Pragma("unroll") for (int n = 0; n < 2; ++n) _Pragma("unroll") for (int k = 0; k < 2; ++k) \
;         acc[ai][bj][m][n] = __builtin_amdgcn_mfma_f32_16x16x32_bf16(Bt[n][k], At[m][k], acc[ai][bj][m][n], 0, 0, 0); __builtin_amdgcn_s_setprio(0); } while (0)
; #define PG8_WAIT_V(n) asm volatile("s_waitcnt vmcnt(" #n ")" ::: "memory")
; #define PG8_WAIT_L(n) asm volatile("s_waitcnt lgkmcnt(" #n ")" ::: "memory")
; #define PG8_BAR __builtin_amdgcn_s_barrier()
; #define PG8_SCHED __builtin_amdgcn_sched_barrier(0)
; template <class Epi, class Sched, bool ALIGN_EPI = false, bool SP2 = false>
; __device__ __forceinline__ void gemm_phase(PG8_LAS unsigned char* lds, const Gemm g, const Sched& S, const Epi& E) {
;     ...
;             PG8_LDB(B0, 1, 0); PG8_LDB(B1, 1, 1); PG8_SCHED; PG8_LDA(At, 1, 0); PG8_STAGE(PG8_SA(0, 1), a2 + hstep, voffA);
;             PG8_WAIT_V(8); PG8_WAIT_L(0); PG8_BAR; PG8_MMA(0, 0, At, B0); PG8_MMA(0, 1, At, B1); PG8_BAR; PG8_SCHED;
	s_add_i32 s62, 0, 0x18000
	s_add_i32 s63, 0, 0x1c000
	v_add_u32_e32 v158, s62, v144
	v_add_u32_e32 v174, s63, v144
	ds_read_b128 v[138:141], v158
	ds_read_b128 v[150:153], v158 offset:1024
	ds_read_b128 v[154:157], v158 offset:2048
	ds_read_b128 v[158:161], v158 offset:3072
	ds_read_b128 v[162:165], v174
	ds_read_b128 v[166:169], v174 offset:1024
	ds_read_b128 v[170:173], v174 offset:2048
	ds_read_b128 v[174:177], v174 offset:3072
	s_add_u32 s38, s38, 0x100000
	s_addc_u32 s39, s39, 0
	s_mov_b32 m0, s47
	v_lshl_add_u64 v[216:217], s[38:39], 0, v[132:133]
	ds_read_b128 v[178:181], v149 offset:32768
	ds_read_b128 v[182:185], v149 offset:33792
	ds_read_b128 v[186:189], v149 offset:34816
	ds_read_b128 v[190:193], v149 offset:35840
	ds_read_b128 v[194:197], v149 offset:36864
	ds_read_b128 v[198:201], v149 offset:37888
	ds_read_b128 v[202:205], v149 offset:38912
	ds_read_b128 v[206:209], v149 offset:39936
	global_load_lds_dwordx4 v[216:217], off
	v_lshl_add_u64 v[216:217], s[38:39], 0, v[130:131]
	s_mov_b32 m0, s48
	s_nop 0
	global_load_lds_dwordx4 v[216:217], off
	s_waitcnt vmcnt(8)
	s_waitcnt lgkmcnt(0)
	s_barrier
	s_setprio 1
	s_waitcnt lgkmcnt(0)
	v_mfma_f32_16x16x32_bf16 v[126:129], v[138:141], v[178:181], v[126:129]
	v_mfma_f32_16x16x32_bf16 v[122:125], v[154:157], v[178:181], v[122:125]
	v_mfma_f32_16x16x32_bf16 v[110:113], v[138:141], v[186:189], v[110:113]
	v_mfma_f32_16x16x32_bf16 v[106:109], v[154:157], v[186:189], v[106:109]
	v_mfma_f32_16x16x32_bf16 v[94:97], v[138:141], v[194:197], v[94:97]
	v_mfma_f32_16x16x32_bf16 v[90:93], v[154:157], v[194:197], v[90:93]
	v_mfma_f32_16x16x32_bf16 v[78:81], v[138:141], v[202:205], v[78:81]
	v_mfma_f32_16x16x32_bf16 v[74:77], v[154:157], v[202:205], v[74:77]
	v_mfma_f32_16x16x32_bf16 v[126:129], v[150:153], v[182:185], v[126:129]
	v_mfma_f32_16x16x32_bf16 v[122:125], v[158:161], v[182:185], v[122:125]
	v_mfma_f32_16x16x32_bf16 v[110:113], v[150:153], v[190:193], v[110:113]
	v_mfma_f32_16x16x32_bf16 v[106:109], v[158:161], v[190:193], v[106:109]
	v_mfma_f32_16x16x32_bf16 v[94:97], v[150:153], v[198:201], v[94:97]
	v_mfma_f32_16x16x32_bf16 v[90:93], v[158:161], v[198:201], v[90:93]
	v_mfma_f32_16x16x32_bf16 v[78:81], v[150:153], v[206:209], v[78:81]
	v_mfma_f32_16x16x32_bf16 v[74:77], v[158:161], v[206:209], v[74:77]
	s_setprio 0
	s_setprio 1
	v_mfma_f32_16x16x32_bf16 v[118:121], v[162:165], v[178:181], v[118:121]
	v_mfma_f32_16x16x32_bf16 v[114:117], v[170:173], v[178:181], v[114:117]
	v_mfma_f32_16x16x32_bf16 v[102:105], v[162:165], v[186:189], v[102:105]
	v_mfma_f32_16x16x32_bf16 v[98:101], v[170:173], v[186:189], v[98:101]
	v_mfma_f32_16x16x32_bf16 v[86:89], v[162:165], v[194:197], v[86:89]
	v_mfma_f32_16x16x32_bf16 v[82:85], v[170:173], v[194:197], v[82:85]
	v_mfma_f32_16x16x32_bf16 v[70:73], v[162:165], v[202:205], v[70:73]
	v_mfma_f32_16x16x32_bf16 v[66:69], v[170:173], v[202:205], v[66:69]
	v_mfma_f32_16x16x32_bf16 v[118:121], v[166:169], v[182:185], v[118:121]
	v_mfma_f32_16x16x32_bf16 v[114:117], v[174:177], v[182:185], v[114:117]
	v_mfma_f32_16x16x32_bf16 v[102:105], v[166:169], v[190:193], v[102:105]
	v_mfma_f32_16x16x32_bf16 v[98:101], v[174:177], v[190:193], v[98:101]
	v_mfma_f32_16x16x32_bf16 v[86:89], v[166:169], v[198:201], v[86:89]
	v_mfma_f32_16x16x32_bf16 v[82:85], v[174:177], v[198:201], v[82:85]
	v_mfma_f32_16x16x32_bf16 v[70:73], v[166:169], v[206:209], v[70:73]
	v_mfma_f32_16x16x32_bf16 v[66:69], v[174:177], v[206:209], v[66:69]
	s_setprio 0
	s_barrier
; #define PG8_STAGE(bufoff, gbase, voff) do { _Pragma("unroll") for (int _i = 0; _i < 2; ++_i) \
;         __builtin_amdgcn_global_load_lds((const unsigned*)((const char*)(gbase) + (voff)[_i]), (PG8_LAS unsigned*)(lds + (bufoff) + ldsw + _i * 8192), 16, 0, 0); } while (0)
; #define PG8_LDA(dst, b, h) do { _Pragma("unroll") for (int m = 0; m < 4; ++m) _Pragma("unroll") for (int k = 0; k < 2; ++k) dst[m][k] = *(const PG8_LAS bf16x8*)(lds + PG8_SA(b, h) + aoff + m * 2048 + k * 1024); } while (0)
; #define PG8_WAIT_V(n) asm volatile("s_waitcnt vmcnt(" #n ")" ::: "memory")
; #define PG8_BAR __builtin_amdgcn_s_barrier()
; template <class Epi, class Sched, bool ALIGN_EPI = false, bool SP2 = false>
; __device__ __forceinline__ void gemm_phase(PG8_LAS unsigned char* lds, const Gemm g, const Sched& S, const Epi& E) {
;     ...
;         for (int t = 0; t < nt; t += 2) {
;             if constexpr (Epi::MIDHOOK) { if (t == (nt >> 1)) E.mid(acc, cur, wr, wc, fr, fq); }
;             const bool last = (t == nt - 2);
;             const char* a1 = cA + (size_t)(t + 1) * kstep;
;             const char* a2 = last ? nA : cA + (size_t)(t + 2) * kstep; const char* b2 = last ? nB : cB + (size_t)(t + 2) * kstep;
;             const char* a3 = a2 + kstep; const char* b3 = b2 + kstep;
;             if (last && has_next) S.a_ready(nxt);
;             if constexpr (SP2) {
;             PG8_LDB(B0, 0, 0); PG8_LDB(B1, 0, 1); PG8_SCHED; PG8_LDA(At, 0, 0); PG8_STAGE(PG8_SA(1, 1), a1 + hstep, voffA);
;             PG8_WAIT_V(8); PG8_WAIT_L(0); PG8_BAR; PG8_MMA(0, 0, At, B0); PG8_MMA(0, 1, At, B1); PG8_BAR; PG8_SCHED;
;             PG8_LDA(At, 0, 1); PG8_STAGE(PG8_SB(0, 0), b2, voffB); PG8_STAGE(PG8_SB(0, 1), b2 + hstep, voffB); PG8_STAGE(PG8_SA(0, 0), a2, voffA);
;             PG8_WAIT_V(8); PG8_WAIT_L(0); PG8_BAR; PG8_MMA(1, 0, At, B0); PG8_MMA(1, 1, At, B1); PG8_BAR; PG8_SCHED;
;             PG8_LDB(B0, 1, 0); PG8_LDB(B1, 1, 1); PG8_SCHED; PG8_LDA(At, 1, 0); PG8_STAGE(PG8_SA(0, 1), a2 + hstep, voffA);
;             PG8_WAIT_V(8); PG8_WAIT_L(0); PG8_BAR; PG8_MMA(0, 0, At, B0); PG8_MMA(0, 1, At, B1); PG8_BAR; PG8_SCHED;
;             PG8_LDA(At, 1, 1); PG8_STAGE(PG8_SB(1, 0), b3, voffB); PG8_STAGE(PG8_SB(1, 1), b3 + hstep, voffB); PG8_STAGE(PG8_SA(1, 0), a3, voffA);
;             PG8_WAIT_V(8); PG8_WAIT_L(0); PG8_BAR; PG8_MMA(1, 0, At, B0); PG8_MMA(1, 1, At, B1); PG8_BAR; PG8_SCHED;
	s_add_i32 s38, s62, s42
	v_lshl_add_u64 v[142:143], v[142:143], 0, s[16:17]
	s_mov_b32 m0, s38
	ds_read_b128 v[178:181], v149 offset:49152
	ds_read_b128 v[182:185], v149 offset:50176
	ds_read_b128 v[186:189], v149 offset:51200
	ds_read_b128 v[190:193], v149 offset:52224
	ds_read_b128 v[194:197], v149 offset:53248
	ds_read_b128 v[198:201], v149 offset:54272
	ds_read_b128 v[202:205], v149 offset:55296
	ds_read_b128 v[206:209], v149 offset:56320
	global_load_lds_dwordx4 v[142:143], off
	s_add_i32 m0, s38, 0x2000
	s_add_u32 s36, s36, 0x100080
	v_lshl_add_u64 v[142:143], v[210:211], 0, s[16:17]
	s_addc_u32 s37, s37, 0
	s_add_i32 s38, s63, s42
	global_load_lds_dwordx4 v[142:143], off
	v_lshl_add_u64 v[142:143], s[36:37], 0, v[132:133]
	s_mov_b32 m0, s38
	s_nop 0
	global_load_lds_dwordx4 v[142:143], off
	v_lshl_add_u64 v[142:143], s[36:37], 0, v[130:131]
	s_add_i32 m0, s38, 0x2000
	s_nop 0
	global_load_lds_dwordx4 v[142:143], off
	v_lshl_add_u64 v[142:143], v[212:213], 0, s[16:17]
	s_mov_b32 m0, s51
	s_nop 0
	global_load_lds_dwordx4 v[142:143], off
	v_lshl_add_u64 v[142:143], v[214:215], 0, s[16:17]
	s_mov_b32 m0, s52
	s_nop 0
	global_load_lds_dwordx4 v[142:143], off
	s_waitcnt vmcnt(8)
	s_waitcnt lgkmcnt(0)
	s_barrier
	s_setprio 1
	s_waitcnt lgkmcnt(0)
	v_mfma_f32_16x16x32_bf16 v[62:65], v[138:141], v[178:181], v[62:65]
	v_mfma_f32_16x16x32_bf16 v[58:61], v[154:157], v[178:181], v[58:61]
	v_mfma_f32_16x16x32_bf16 v[46:49], v[138:141], v[186:189], v[46:49]
	v_mfma_f32_16x16x32_bf16 v[42:45], v[154:157], v[186:189], v[42:45]
	v_mfma_f32_16x16x32_bf16 v[30:33], v[138:141], v[194:197], v[30:33]
	v_mfma_f32_16x16x32_bf16 v[26:29], v[154:157], v[194:197], v[26:29]
	v_mfma_f32_16x16x32_bf16 v[14:17], v[138:141], v[202:205], v[14:17]
	v_mfma_f32_16x16x32_bf16 v[10:13], v[154:157], v[202:205], v[10:13]
	v_mfma_f32_16x16x32_bf16 v[62:65], v[150:153], v[182:185], v[62:65]
	v_mfma_f32_16x16x32_bf16 v[58:61], v[158:161], v[182:185], v[58:61]
	v_mfma_f32_16x16x32_bf16 v[46:49], v[150:153], v[190:193], v[46:49]
	v_mfma_f32_16x16x32_bf16 v[42:45], v[158:161], v[190:193], v[42:45]
	v_mfma_f32_16x16x32_bf16 v[30:33], v[150:153], v[198:201], v[30:33]
	v_mfma_f32_16x16x32_bf16 v[26:29], v[158:161], v[198:201], v[26:29]
	v_mfma_f32_16x16x32_bf16 v[14:17], v[150:153], v[206:209], v[14:17]
	v_mfma_f32_16x16x32_bf16 v[10:13], v[158:161], v[206:209], v[10:13]
	s_setprio 0
	s_setprio 1
	v_mfma_f32_16x16x32_bf16 v[54:57], v[162:165], v[178:181], v[54:57]
	v_mfma_f32_16x16x32_bf16 v[50:53], v[170:173], v[178:181], v[50:53]
	v_mfma_f32_16x16x32_bf16 v[38:41], v[162:165], v[186:189], v[38:41]
	v_mfma_f32_16x16x32_bf16 v[34:37], v[170:173], v[186:189], v[34:37]
	v_mfma_f32_16x16x32_bf16 v[22:25], v[162:165], v[194:197], v[22:25]
	v_mfma_f32_16x16x32_bf16 v[18:21], v[170:173], v[194:197], v[18:21]
	v_mfma_f32_16x16x32_bf16 v[6:9], v[162:165], v[202:205], v[6:9]
	v_mfma_f32_16x16x32_bf16 v[2:5], v[170:173], v[202:205], v[2:5]
	v_mfma_f32_16x16x32_bf16 v[54:57], v[166:169], v[182:185], v[54:57]
	v_mfma_f32_16x16x32_bf16 v[50:53], v[174:177], v[182:185], v[50:53]
	v_mfma_f32_16x16x32_bf16 v[38:41], v[166:169], v[190:193], v[38:41]
	v_mfma_f32_16x16x32_bf16 v[34:37], v[174:177], v[190:193], v[34:37]
	v_mfma_f32_16x16x32_bf16 v[22:25], v[166:169], v[198:201], v[22:25]
	v_mfma_f32_16x16x32_bf16 v[18:21], v[174:177], v[198:201], v[18:21]
	v_mfma_f32_16x16x32_bf16 v[6:9], v[166:169], v[206:209], v[6:9]
	v_mfma_f32_16x16x32_bf16 v[2:5], v[174:177], v[206:209], v[2:5]
	s_setprio 0
	s_barrier
	s_add_i32 s61, s61, 2
	s_add_u32 s30, s30, 0x100
	s_addc_u32 s31, s31, 0
	s_add_u32 s59, s59, 0x100
	s_addc_u32 s60, s60, 0
	s_cmp_gt_u32 s61, 5
	s_cbranch_scc0 .LBB0_1219
.Lkx_1219:
	s_and_b64 vcc, exec, s[18:19]
	s_cbranch_vccz .LBB0_1222
	s_barrier

; #define PG8_STAGE(bufoff, gbase, voff) do { _Pragma("unroll") for (int _i = 0; _i < 2; ++_i) \
;         __builtin_amdgcn_global_load_lds((const unsigned*)((const char*)(gbase) + (voff)[_i]), (PG8_LAS unsigned*)(lds + (bufoff) + ldsw + _i * 8192), 16, 0, 0); } while (0)
; #define PG8_LDA(dst, b, h) do { _Pragma("unroll") for (int m = 0; m < 4; ++m) _Pragma("unroll") for (int k = 0; k < 2; ++k) dst[m][k] = *(const PG8_LAS bf16x8*)(lds + PG8_SA(b, h) + aoff + m * 2048 + k * 1024); } while (0)
; #define PG8_WAIT_V(n) asm volatile("s_waitcnt vmcnt(" #n ")" ::: "memory")
; #define PG8_BAR __builtin_amdgcn_s_barrier()
; template <class Epi, class Sched, bool ALIGN_EPI = false, bool SP2 = false>
; __device__ __forceinline__ void gemm_phase(PG8_LAS unsigned char* lds, const Gemm g, const Sched& S, const Epi& E) {
;     ...
;         const char* nA = has_next ? (const char*)g.A + (size_t)nxt.pm * tstep + (size_t)nxt.kt0 * kstep : cA; const char* nB = has_next ? (const char*)g.Bt + (size_t)nxt.pn * tstep + (size_t)nxt.kt0 * kstep : cB;
;         for (int t = 0; t < nt; t += 2) {
;             if constexpr (Epi::MIDHOOK) { if (t == (nt >> 1)) E.mid(acc, cur, wr, wc, fr, fq); }
;             const bool last = (t == nt - 2);
;             const char* a1 = cA + (size_t)(t + 1) * kstep;
;             const char* a2 = last ? nA : cA + (size_t)(t + 2) * kstep; const char* b2 = last ? nB : cB + (size_t)(t + 2) * kstep;
;             const char* a3 = a2 + kstep; const char* b3 = b2 + kstep;
;             if (last && has_next) S.a_ready(nxt);
;             if constexpr (SP2) {
;             PG8_LDB(B0, 0, 0); PG8_LDB(B1, 0, 1); PG8_SCHED; PG8_LDA(At, 0, 0); PG8_STAGE(PG8_SA(1, 1), a1 + hstep, voffA);
;             PG8_WAIT_V(8); PG8_WAIT_L(0); PG8_BAR; PG8_MMA(0, 0, At, B0); PG8_MMA(0, 1, At, B1); PG8_BAR; PG8_SCHED;
;             PG8_LDA(At, 0, 1); PG8_STAGE(PG8_SB(0, 0), b2, voffB); PG8_STAGE(PG8_SB(0, 1), b2 + hstep, voffB); PG8_STAGE(PG8_SA(0, 0), a2, voffA);
;             PG8_WAIT_V(8); PG8_WAIT_L(0); PG8_BAR; PG8_MMA(1, 0, At, B0); PG8_MMA(1, 1, At, B1); PG8_BAR; PG8_SCHED;
;     ...
; #pragma unroll
;         for (int a = 0; a < 2; ++a)
; #pragma unroll
;             for (int b = 0; b < 2; ++b)
; #pragma unroll
;                 for (int m = 0; m < 4; ++m)
; #pragma unroll
;                     for (int n = 0; n < 2; ++n) acc[a][b][m][n] = (f32x4){0.f, 0.f, 0.f, 0.f};
.LBB0_1392:
	s_ashr_i32 s19, s18, 31
	s_lshl_b64 s[20:21], s[18:19], 20
	s_add_u32 s20, s3, s20
	s_addc_u32 s21, s33, s21
	s_and_b64 s[22:23], s[0:1], exec
	s_cselect_b32 s19, s21, s27
	s_cselect_b32 s50, s20, s26
	s_ashr_i32 s17, s16, 31
	s_lshl_b64 s[22:23], s[16:17], 20
	s_add_u32 s22, s48, s22
	s_addc_u32 s23, s49, s23
	s_and_b64 s[30:31], s[0:1], exec
	s_cselect_b32 s17, s23, s29
	s_cselect_b32 s51, s22, s28
	s_add_u32 s26, s26, 0x80080
	s_addc_u32 s27, s27, 0
	s_add_u32 s52, s28, 0x100
	s_addc_u32 s53, s29, 0
	s_mov_b32 s54, -2
	s_waitcnt lgkmcnt(0)
	ds_read_b128 v[156:159], v152
	ds_read_b128 v[160:163], v152 offset:1024
	ds_read_b128 v[164:167], v152 offset:2048
	ds_read_b128 v[168:171], v152 offset:3072
	ds_read_b128 v[172:175], v153
	ds_read_b128 v[176:179], v153 offset:1024
	ds_read_b128 v[180:183], v153 offset:2048
	ds_read_b128 v[184:187], v153 offset:3072
	s_add_u32 s28, s26, 0xfff80080
	s_addc_u32 s29, s27, -1
	s_cmp_eq_u32 s54, 28
	s_cselect_b32 s31, s19, s29
	s_cselect_b32 s30, s50, s28
	s_cselect_b32 s29, s17, s53
	s_cselect_b32 s28, s51, s52
	v_lshl_add_u64 v[146:147], s[26:27], 0, v[138:139]
	s_add_i32 m0, s25, 0xc000
	ds_read_b128 v[188:191], v154
	ds_read_b128 v[192:195], v154 offset:1024
	ds_read_b128 v[196:199], v154 offset:2048
	ds_read_b128 v[200:203], v154 offset:3072
	ds_read_b128 v[204:207], v154 offset:4096
	ds_read_b128 v[208:211], v154 offset:5120
	ds_read_b128 v[212:215], v154 offset:6144
	ds_read_b128 v[216:219], v154 offset:7168
	global_load_lds_dwordx4 v[146:147], off
	v_lshl_add_u64 v[146:147], s[26:27], 0, v[140:141]
	s_add_i32 m0, s25, 0xe000
	s_nop 0
	global_load_lds_dwordx4 v[146:147], off
	s_waitcnt vmcnt(8)
	s_waitcnt lgkmcnt(0)
	s_barrier
	s_setprio 1
	s_waitcnt lgkmcnt(0)
	v_mfma_f32_16x16x32_bf16 v[126:129], v[156:159], v[188:191], 0
	v_mfma_f32_16x16x32_bf16 v[122:125], v[164:167], v[188:191], 0
	v_mfma_f32_16x16x32_bf16 v[118:121], v[156:159], v[196:199], 0
	v_mfma_f32_16x16x32_bf16 v[110:113], v[164:167], v[196:199], 0
	v_mfma_f32_16x16x32_bf16 v[102:105], v[156:159], v[204:207], 0
	v_mfma_f32_16x16x32_bf16 v[94:97], v[164:167], v[204:207], 0
	v_mfma_f32_16x16x32_bf16 v[86:89], v[156:159], v[212:215], 0
	v_mfma_f32_16x16x32_bf16 v[78:81], v[164:167], v[212:215], 0
	v_mfma_f32_16x16x32_bf16 v[126:129], v[160:163], v[192:195], v[126:129]
	v_mfma_f32_16x16x32_bf16 v[122:125], v[168:171], v[192:195], v[122:125]
	v_mfma_f32_16x16x32_bf16 v[118:121], v[160:163], v[200:203], v[118:121]
	v_mfma_f32_16x16x32_bf16 v[110:113], v[168:171], v[200:203], v[110:113]
	v_mfma_f32_16x16x32_bf16 v[102:105], v[160:163], v[208:211], v[102:105]
	v_mfma_f32_16x16x32_bf16 v[94:97], v[168:171], v[208:211], v[94:97]
	v_mfma_f32_16x16x32_bf16 v[86:89], v[160:163], v[216:219], v[86:89]
	v_mfma_f32_16x16x32_bf16 v[78:81], v[168:171], v[216:219], v[78:81]
	s_setprio 0
	s_setprio 1
	v_mfma_f32_16x16x32_bf16 v[114:117], v[172:175], v[188:191], 0
	v_mfma_f32_16x16x32_bf16 v[106:109], v[180:183], v[188:191], 0
	v_mfma_f32_16x16x32_bf16 v[98:101], v[172:175], v[196:199], 0
	v_mfma_f32_16x16x32_bf16 v[90:93], v[180:183], v[196:199], 0
	v_mfma_f32_16x16x32_bf16 v[82:85], v[172:175], v[204:207], 0
	v_mfma_f32_16x16x32_bf16 v[74:77], v[180:183], v[204:207], 0
	v_mfma_f32_16x16x32_bf16 v[70:73], v[172:175], v[212:215], 0
	v_mfma_f32_16x16x32_bf16 v[66:69], v[180:183], v[212:215], 0
	v_mfma_f32_16x16x32_bf16 v[114:117], v[176:179], v[192:195], v[114:117]
	v_mfma_f32_16x16x32_bf16 v[106:109], v[184:187], v[192:195], v[106:109]
	v_mfma_f32_16x16x32_bf16 v[98:101], v[176:179], v[200:203], v[98:101]
	v_mfma_f32_16x16x32_bf16 v[90:93], v[184:187], v[200:203], v[90:93]
	v_mfma_f32_16x16x32_bf16 v[82:85], v[176:179], v[208:211], v[82:85]
	v_mfma_f32_16x16x32_bf16 v[74:77], v[184:187], v[208:211], v[74:77]
	v_mfma_f32_16x16x32_bf16 v[70:73], v[176:179], v[216:219], v[70:73]
	v_mfma_f32_16x16x32_bf16 v[66:69], v[184:187], v[216:219], v[66:69]
	s_setprio 0
	s_barrier
	s_add_i32 s55, s45, s36
	v_lshl_add_u64 v[146:147], s[28:29], 0, v[134:135]
	s_mov_b32 m0, s55
	ds_read_b128 v[188:191], v154 offset:16384
	ds_read_b128 v[192:195], v154 offset:17408
	ds_read_b128 v[196:199], v154 offset:18432
	ds_read_b128 v[200:203], v154 offset:19456
	ds_read_b128 v[204:207], v154 offset:20480
	ds_read_b128 v[208:211], v154 offset:21504
	ds_read_b128 v[212:215], v154 offset:22528
	ds_read_b128 v[216:219], v154 offset:23552
	global_load_lds_dwordx4 v[146:147], off
	s_add_i32 m0, s55, 0x2000
	s_add_u32 s56, s28, 0x80000
	v_lshl_add_u64 v[220:221], s[28:29], 0, v[130:131]
	s_addc_u32 s57, s29, 0
	s_add_i32 s55, s46, s36
	global_load_lds_dwordx4 v[220:221], off
	v_lshl_add_u64 v[222:223], s[56:57], 0, v[134:135]
	s_mov_b32 m0, s55
	v_lshl_add_u64 v[224:225], s[30:31], 0, v[132:133]
	global_load_lds_dwordx4 v[222:223], off
	v_lshl_add_u64 v[222:223], s[56:57], 0, v[130:131]
	s_add_i32 m0, s55, 0x2000
	s_nop 0
	global_load_lds_dwordx4 v[222:223], off
	v_lshl_add_u64 v[222:223], s[30:31], 0, v[136:137]
	s_mov_b32 m0, s25
	s_nop 0
	global_load_lds_dwordx4 v[222:223], off
	s_mov_b32 m0, s38
	s_nop 0
	global_load_lds_dwordx4 v[224:225], off
	s_waitcnt vmcnt(8)
	s_waitcnt lgkmcnt(0)
	s_barrier
; #define PG8_STAGE(bufoff, gbase, voff) do { _Pragma("unroll") for (int _i = 0; _i < 2; ++_i) \
;         __builtin_amdgcn_global_load_lds((const unsigned*)((const char*)(gbase) + (voff)[_i]), (PG8_LAS unsigned*)(lds + (bufoff) + ldsw + _i * 8192), 16, 0, 0); } while (0)
; #define PG8_LDA(dst, b, h) do { _Pragma("unroll") for (int m = 0; m < 4; ++m) _Pragma("unroll") for (int k = 0; k < 2; ++k) dst[m][k] = *(const PG8_LAS bf16x8*)(lds + PG8_SA(b, h) + aoff + m * 2048 + k * 1024); } while (0)
; #define PG8_LDB(dst, b, h) do { _Pragma("unroll") for (int n = 0; n < 2; ++n) _Pragma("unroll") for (int k = 0; k < 2; ++k) dst[n][k] = *(const PG8_LAS bf16x8*)(lds + PG8_SB(b, h) + boff + n * 2048 + k * 1024); } while (0)
; #define PG8_MMA(ai, bj, At, Bt) do { __builtin_amdgcn_s_setprio(1); _Pragma("unroll") for (int m = 0; m < 4; ++m) _Pragma("unroll") for (int n = 0; n < 2; ++n) _Pragma("unroll") for (int k = 0; k < 2; ++k) \
;         acc[ai][bj][m][n] = __builtin_amdgcn_mfma_f32_16x16x32_bf16(Bt[n][k], At[m][k], acc[ai][bj][m][n], 0, 0, 0); __builtin_amdgcn_s_setprio(0); } while (0)
; #define PG8_WAIT_V(n) asm volatile("s_waitcnt vmcnt(" #n ")" ::: "memory")
; #define PG8_WAIT_L(n) asm volatile("s_waitcnt lgkmcnt(" #n ")" ::: "memory")
; #define PG8_BAR __builtin_amdgcn_s_barrier()
; #define PG8_SCHED __builtin_amdgcn_sched_barrier(0)
; template <class Epi, class Sched, bool ALIGN_EPI = false, bool SP2 = false>
; __device__ __forceinline__ void gemm_phase(PG8_LAS unsigned char* lds, const Gemm g, const Sched& S, const Epi& E) {
;     ...
;             PG8_LDA(At, 0, 1); PG8_STAGE(PG8_SB(0, 0), b2, voffB); PG8_STAGE(PG8_SB(0, 1), b2 + hstep, voffB); PG8_STAGE(PG8_SA(0, 0), a2, voffA);
;             PG8_WAIT_V(8); PG8_WAIT_L(0); PG8_BAR; PG8_MMA(1, 0, At, B0); PG8_MMA(1, 1, At, B1); PG8_BAR; PG8_SCHED;
;             PG8_LDB(B0, 1, 0); PG8_LDB(B1, 1, 1); PG8_SCHED; PG8_LDA(At, 1, 0); PG8_STAGE(PG8_SA(0, 1), a2 + hstep, voffA);
;             PG8_WAIT_V(8); PG8_WAIT_L(0); PG8_BAR; PG8_MMA(0, 0, At, B0); PG8_MMA(0, 1, At, B1); PG8_BAR; PG8_SCHED;
	s_setprio 1
	s_waitcnt lgkmcnt(0)
	v_mfma_f32_16x16x32_bf16 v[62:65], v[156:159], v[188:191], 0
	v_mfma_f32_16x16x32_bf16 v[58:61], v[164:167], v[188:191], 0
	v_mfma_f32_16x16x32_bf16 v[54:57], v[156:159], v[196:199], 0
	v_mfma_f32_16x16x32_bf16 v[46:49], v[164:167], v[196:199], 0
	v_mfma_f32_16x16x32_bf16 v[38:41], v[156:159], v[204:207], 0
	v_mfma_f32_16x16x32_bf16 v[30:33], v[164:167], v[204:207], 0
	v_mfma_f32_16x16x32_bf16 v[22:25], v[156:159], v[212:215], 0
	v_mfma_f32_16x16x32_bf16 v[14:17], v[164:167], v[212:215], 0
	v_mfma_f32_16x16x32_bf16 v[62:65], v[160:163], v[192:195], v[62:65]
	v_mfma_f32_16x16x32_bf16 v[58:61], v[168:171], v[192:195], v[58:61]
	v_mfma_f32_16x16x32_bf16 v[54:57], v[160:163], v[200:203], v[54:57]
	v_mfma_f32_16x16x32_bf16 v[46:49], v[168:171], v[200:203], v[46:49]
	v_mfma_f32_16x16x32_bf16 v[38:41], v[160:163], v[208:211], v[38:41]
	v_mfma_f32_16x16x32_bf16 v[30:33], v[168:171], v[208:211], v[30:33]
	v_mfma_f32_16x16x32_bf16 v[22:25], v[160:163], v[216:219], v[22:25]
	v_mfma_f32_16x16x32_bf16 v[14:17], v[168:171], v[216:219], v[14:17]
	s_setprio 0
	s_setprio 1
	v_mfma_f32_16x16x32_bf16 v[50:53], v[172:175], v[188:191], 0
	v_mfma_f32_16x16x32_bf16 v[42:45], v[180:183], v[188:191], 0
	v_mfma_f32_16x16x32_bf16 v[34:37], v[172:175], v[196:199], 0
	v_mfma_f32_16x16x32_bf16 v[26:29], v[180:183], v[196:199], 0
	v_mfma_f32_16x16x32_bf16 v[18:21], v[172:175], v[204:207], 0
	v_mfma_f32_16x16x32_bf16 v[10:13], v[180:183], v[204:207], 0
	v_mfma_f32_16x16x32_bf16 v[6:9], v[172:175], v[212:215], 0
	v_mfma_f32_16x16x32_bf16 v[2:5], v[180:183], v[212:215], 0
	v_mfma_f32_16x16x32_bf16 v[50:53], v[176:179], v[192:195], v[50:53]
	v_mfma_f32_16x16x32_bf16 v[42:45], v[184:187], v[192:195], v[42:45]
	v_mfma_f32_16x16x32_bf16 v[34:37], v[176:179], v[200:203], v[34:37]
	v_mfma_f32_16x16x32_bf16 v[26:29], v[184:187], v[200:203], v[26:29]
	v_mfma_f32_16x16x32_bf16 v[18:21], v[176:179], v[208:211], v[18:21]
	v_mfma_f32_16x16x32_bf16 v[10:13], v[184:187], v[208:211], v[10:13]
	v_mfma_f32_16x16x32_bf16 v[6:9], v[176:179], v[216:219], v[6:9]
	v_mfma_f32_16x16x32_bf16 v[2:5], v[184:187], v[216:219], v[2:5]
	s_setprio 0
	s_barrier
	s_add_i32 s55, 0, 0x18000
	v_add_u32_e32 v155, s55, v150
	s_add_i32 s56, 0, 0x1c000
	ds_read_b128 v[156:159], v155
	ds_read_b128 v[160:163], v155 offset:1024
	ds_read_b128 v[164:167], v155 offset:2048
	ds_read_b128 v[168:171], v155 offset:3072
	v_add_u32_e32 v155, s56, v150
	ds_read_b128 v[172:175], v155
	ds_read_b128 v[176:179], v155 offset:1024
	ds_read_b128 v[180:183], v155 offset:2048
	ds_read_b128 v[184:187], v155 offset:3072
	s_add_u32 s30, s30, 0x80000
	s_addc_u32 s31, s31, 0
	s_mov_b32 m0, s39
	v_lshl_add_u64 v[226:227], s[30:31], 0, v[136:137]
	ds_read_b128 v[188:191], v154 offset:32768
	ds_read_b128 v[192:195], v154 offset:33792
	ds_read_b128 v[196:199], v154 offset:34816
	ds_read_b128 v[200:203], v154 offset:35840
	ds_read_b128 v[204:207], v154 offset:36864
	ds_read_b128 v[208:211], v154 offset:37888
	ds_read_b128 v[212:215], v154 offset:38912
	ds_read_b128 v[216:219], v154 offset:39936
	global_load_lds_dwordx4 v[226:227], off
	v_lshl_add_u64 v[226:227], s[30:31], 0, v[132:133]
	s_mov_b32 m0, s40
	s_nop 0
	global_load_lds_dwordx4 v[226:227], off
	s_waitcnt vmcnt(8)
	s_waitcnt lgkmcnt(0)
	s_barrier
	s_setprio 1
	s_waitcnt lgkmcnt(0)
	v_mfma_f32_16x16x32_bf16 v[126:129], v[156:159], v[188:191], v[126:129]
	v_mfma_f32_16x16x32_bf16 v[122:125], v[164:167], v[188:191], v[122:125]
	v_mfma_f32_16x16x32_bf16 v[118:121], v[156:159], v[196:199], v[118:121]
	v_mfma_f32_16x16x32_bf16 v[110:113], v[164:167], v[196:199], v[110:113]
	v_mfma_f32_16x16x32_bf16 v[102:105], v[156:159], v[204:207], v[102:105]
	v_mfma_f32_16x16x32_bf16 v[94:97], v[164:167], v[204:207], v[94:97]
	v_mfma_f32_16x16x32_bf16 v[86:89], v[156:159], v[212:215], v[86:89]
	v_mfma_f32_16x16x32_bf16 v[78:81], v[164:167], v[212:215], v[78:81]
	v_mfma_f32_16x16x32_bf16 v[126:129], v[160:163], v[192:195], v[126:129]
	v_mfma_f32_16x16x32_bf16 v[122:125], v[168:171], v[192:195], v[122:125]
	v_mfma_f32_16x16x32_bf16 v[118:121], v[160:163], v[200:203], v[118:121]
	v_mfma_f32_16x16x32_bf16 v[110:113], v[168:171], v[200:203], v[110:113]
	v_mfma_f32_16x16x32_bf16 v[102:105], v[160:163], v[208:211], v[102:105]
	v_mfma_f32_16x16x32_bf16 v[94:97], v[168:171], v[208:211], v[94:97]
	v_mfma_f32_16x16x32_bf16 v[86:89], v[160:163], v[216:219], v[86:89]
	v_mfma_f32_16x16x32_bf16 v[78:81], v[168:171], v[216:219], v[78:81]
	s_setprio 0
	s_setprio 1
	v_mfma_f32_16x16x32_bf16 v[114:117], v[172:175], v[188:191], v[114:117]
	v_mfma_f32_16x16x32_bf16 v[106:109], v[180:183], v[188:191], v[106:109]
	v_mfma_f32_16x16x32_bf16 v[98:101], v[172:175], v[196:199], v[98:101]
	v_mfma_f32_16x16x32_bf16 v[90:93], v[180:183], v[196:199], v[90:93]
	v_mfma_f32_16x16x32_bf16 v[82:85], v[172:175], v[204:207], v[82:85]
	v_mfma_f32_16x16x32_bf16 v[74:77], v[180:183], v[204:207], v[74:77]
	v_mfma_f32_16x16x32_bf16 v[70:73], v[172:175], v[212:215], v[70:73]
	v_mfma_f32_16x16x32_bf16 v[66:69], v[180:183], v[212:215], v[66:69]
	v_mfma_f32_16x16x32_bf16 v[114:117], v[176:179], v[192:195], v[114:117]
	v_mfma_f32_16x16x32_bf16 v[106:109], v[184:187], v[192:195], v[106:109]
	v_mfma_f32_16x16x32_bf16 v[98:101], v[176:179], v[200:203], v[98:101]
	v_mfma_f32_16x16x32_bf16 v[90:93], v[184:187], v[200:203], v[90:93]
	v_mfma_f32_16x16x32_bf16 v[82:85], v[176:179], v[208:211], v[82:85]
	v_mfma_f32_16x16x32_bf16 v[74:77], v[184:187], v[208:211], v[74:77]
	v_mfma_f32_16x16x32_bf16 v[70:73], v[176:179], v[216:219], v[70:73]
	v_mfma_f32_16x16x32_bf16 v[66:69], v[184:187], v[216:219], v[66:69]
	s_setprio 0
	s_barrier
; #define PG8_STAGE(bufoff, gbase, voff) do { _Pragma("unroll") for (int _i = 0; _i < 2; ++_i) \
;         __builtin_amdgcn_global_load_lds((const unsigned*)((const char*)(gbase) + (voff)[_i]), (PG8_LAS unsigned*)(lds + (bufoff) + ldsw + _i * 8192), 16, 0, 0); } while (0)
; #define PG8_LDA(dst, b, h) do { _Pragma("unroll") for (int m = 0; m < 4; ++m) _Pragma("unroll") for (int k = 0; k < 2; ++k) dst[m][k] = *(const PG8_LAS bf16x8*)(lds + PG8_SA(b, h) + aoff + m * 2048 + k * 1024); } while (0)
; #define PG8_WAIT_V(n) asm volatile("s_waitcnt vmcnt(" #n ")" ::: "memory")
; #define PG8_BAR __builtin_amdgcn_s_barrier()
; template <class Epi, class Sched, bool ALIGN_EPI = false, bool SP2 = false>
; __device__ __forceinline__ void gemm_phase(PG8_LAS unsigned char* lds, const Gemm g, const Sched& S, const Epi& E) {
;     ...
;         for (int t = 0; t < nt; t += 2) {
;             if constexpr (Epi::MIDHOOK) { if (t == (nt >> 1)) E.mid(acc, cur, wr, wc, fr, fq); }
;             const bool last = (t == nt - 2);
;             const char* a1 = cA + (size_t)(t + 1) * kstep;
;             const char* a2 = last ? nA : cA + (size_t)(t + 2) * kstep; const char* b2 = last ? nB : cB + (size_t)(t + 2) * kstep;
;             const char* a3 = a2 + kstep; const char* b3 = b2 + kstep;
;             if (last && has_next) S.a_ready(nxt);
;             if constexpr (SP2) {
;             PG8_LDB(B0, 0, 0); PG8_LDB(B1, 0, 1); PG8_SCHED; PG8_LDA(At, 0, 0); PG8_STAGE(PG8_SA(1, 1), a1 + hstep, voffA);
;             PG8_WAIT_V(8); PG8_WAIT_L(0); PG8_BAR; PG8_MMA(0, 0, At, B0); PG8_MMA(0, 1, At, B1); PG8_BAR; PG8_SCHED;
;             PG8_LDA(At, 0, 1); PG8_STAGE(PG8_SB(0, 0), b2, voffB); PG8_STAGE(PG8_SB(0, 1), b2 + hstep, voffB); PG8_STAGE(PG8_SA(0, 0), a2, voffA);
;             PG8_WAIT_V(8); PG8_WAIT_L(0); PG8_BAR; PG8_MMA(1, 0, At, B0); PG8_MMA(1, 1, At, B1); PG8_BAR; PG8_SCHED;
;             PG8_LDB(B0, 1, 0); PG8_LDB(B1, 1, 1); PG8_SCHED; PG8_LDA(At, 1, 0); PG8_STAGE(PG8_SA(0, 1), a2 + hstep, voffA);
;             PG8_WAIT_V(8); PG8_WAIT_L(0); PG8_BAR; PG8_MMA(0, 0, At, B0); PG8_MMA(0, 1, At, B1); PG8_BAR; PG8_SCHED;
;             PG8_LDA(At, 1, 1); PG8_STAGE(PG8_SB(1, 0), b3, voffB); PG8_STAGE(PG8_SB(1, 1), b3 + hstep, voffB); PG8_STAGE(PG8_SA(1, 0), a3, voffA);
;             PG8_WAIT_V(8); PG8_WAIT_L(0); PG8_BAR; PG8_MMA(1, 0, At, B0); PG8_MMA(1, 1, At, B1); PG8_BAR; PG8_SCHED;
	s_add_i32 s30, s55, s36
	v_lshl_add_u64 v[146:147], v[146:147], 0, s[12:13]
	s_mov_b32 m0, s30
	ds_read_b128 v[188:191], v154 offset:49152
	ds_read_b128 v[192:195], v154 offset:50176
	ds_read_b128 v[196:199], v154 offset:51200
	ds_read_b128 v[200:203], v154 offset:52224
	ds_read_b128 v[204:207], v154 offset:53248
	ds_read_b128 v[208:211], v154 offset:54272
	ds_read_b128 v[212:215], v154 offset:55296
	ds_read_b128 v[216:219], v154 offset:56320
	global_load_lds_dwordx4 v[146:147], off
	s_add_i32 m0, s30, 0x2000
	s_add_u32 s28, s28, 0x80080
	v_lshl_add_u64 v[146:147], v[220:221], 0, s[12:13]
	s_addc_u32 s29, s29, 0
	s_add_i32 s30, s56, s36
	global_load_lds_dwordx4 v[146:147], off
	v_lshl_add_u64 v[146:147], s[28:29], 0, v[134:135]
	s_mov_b32 m0, s30
	s_nop 0
	global_load_lds_dwordx4 v[146:147], off
	v_lshl_add_u64 v[146:147], s[28:29], 0, v[130:131]
	s_add_i32 m0, s30, 0x2000
	s_nop 0
	global_load_lds_dwordx4 v[146:147], off
	v_lshl_add_u64 v[146:147], v[222:223], 0, s[12:13]
	s_mov_b32 m0, s43
	s_nop 0
	global_load_lds_dwordx4 v[146:147], off
	v_lshl_add_u64 v[146:147], v[224:225], 0, s[12:13]
	s_mov_b32 m0, s44
	s_nop 0
	global_load_lds_dwordx4 v[146:147], off
	s_waitcnt vmcnt(8)
	s_waitcnt lgkmcnt(0)
	s_barrier
	s_setprio 1
	s_waitcnt lgkmcnt(0)
	v_mfma_f32_16x16x32_bf16 v[62:65], v[156:159], v[188:191], v[62:65]
	v_mfma_f32_16x16x32_bf16 v[58:61], v[164:167], v[188:191], v[58:61]
	v_mfma_f32_16x16x32_bf16 v[54:57], v[156:159], v[196:199], v[54:57]
	v_mfma_f32_16x16x32_bf16 v[46:49], v[164:167], v[196:199], v[46:49]
	v_mfma_f32_16x16x32_bf16 v[38:41], v[156:159], v[204:207], v[38:41]
	v_mfma_f32_16x16x32_bf16 v[30:33], v[164:167], v[204:207], v[30:33]
	v_mfma_f32_16x16x32_bf16 v[22:25], v[156:159], v[212:215], v[22:25]
	v_mfma_f32_16x16x32_bf16 v[14:17], v[164:167], v[212:215], v[14:17]
	v_mfma_f32_16x16x32_bf16 v[62:65], v[160:163], v[192:195], v[62:65]
	v_mfma_f32_16x16x32_bf16 v[58:61], v[168:171], v[192:195], v[58:61]
	v_mfma_f32_16x16x32_bf16 v[54:57], v[160:163], v[200:203], v[54:57]
	v_mfma_f32_16x16x32_bf16 v[46:49], v[168:171], v[200:203], v[46:49]
	v_mfma_f32_16x16x32_bf16 v[38:41], v[160:163], v[208:211], v[38:41]
	v_mfma_f32_16x16x32_bf16 v[30:33], v[168:171], v[208:211], v[30:33]
	v_mfma_f32_16x16x32_bf16 v[22:25], v[160:163], v[216:219], v[22:25]
	v_mfma_f32_16x16x32_bf16 v[14:17], v[168:171], v[216:219], v[14:17]
	s_setprio 0
	s_setprio 1
	v_mfma_f32_16x16x32_bf16 v[50:53], v[172:175], v[188:191], v[50:53]
	v_mfma_f32_16x16x32_bf16 v[42:45], v[180:183], v[188:191], v[42:45]
	v_mfma_f32_16x16x32_bf16 v[34:37], v[172:175], v[196:199], v[34:37]
	v_mfma_f32_16x16x32_bf16 v[26:29], v[180:183], v[196:199], v[26:29]
	v_mfma_f32_16x16x32_bf16 v[18:21], v[172:175], v[204:207], v[18:21]
	v_mfma_f32_16x16x32_bf16 v[10:13], v[180:183], v[204:207], v[10:13]
	v_mfma_f32_16x16x32_bf16 v[6:9], v[172:175], v[212:215], v[6:9]
	v_mfma_f32_16x16x32_bf16 v[2:5], v[180:183], v[212:215], v[2:5]
	v_mfma_f32_16x16x32_bf16 v[50:53], v[176:179], v[192:195], v[50:53]
	v_mfma_f32_16x16x32_bf16 v[42:45], v[184:187], v[192:195], v[42:45]
	v_mfma_f32_16x16x32_bf16 v[34:37], v[176:179], v[200:203], v[34:37]
	v_mfma_f32_16x16x32_bf16 v[26:29], v[184:187], v[200:203], v[26:29]
	v_mfma_f32_16x16x32_bf16 v[18:21], v[176:179], v[208:211], v[18:21]
	v_mfma_f32_16x16x32_bf16 v[10:13], v[184:187], v[208:211], v[10:13]
	v_mfma_f32_16x16x32_bf16 v[6:9], v[176:179], v[216:219], v[6:9]
	v_mfma_f32_16x16x32_bf16 v[2:5], v[184:187], v[216:219], v[2:5]
	s_setprio 0
	s_barrier
	s_add_i32 s54, s54, 2
	s_add_u32 s26, s26, 0x100
	s_addc_u32 s27, s27, 0
	s_add_u32 s52, s52, 0x100
	s_addc_u32 s53, s53, 0
	s_cmp_gt_u32 s54, 29
	s_cbranch_scc1 .Lkx_1393
.LBB0_1393:
	ds_read_b128 v[156:159], v152
	ds_read_b128 v[160:163], v152 offset:1024
	ds_read_b128 v[164:167], v152 offset:2048
	ds_read_b128 v[168:171], v152 offset:3072
	ds_read_b128 v[172:175], v153
	ds_read_b128 v[176:179], v153 offset:1024
	ds_read_b128 v[180:183], v153 offset:2048
	ds_read_b128 v[184:187], v153 offset:3072
	s_add_u32 s28, s26, 0xfff80080
	s_addc_u32 s29, s27, -1
	s_cmp_eq_u32 s54, 28
	s_cselect_b32 s31, s19, s29
	s_cselect_b32 s30, s50, s28
	s_cselect_b32 s29, s17, s53
	s_cselect_b32 s28, s51, s52
	v_lshl_add_u64 v[146:147], s[26:27], 0, v[138:139]
	s_add_i32 m0, s25, 0xc000
	ds_read_b128 v[188:191], v154
	ds_read_b128 v[192:195], v154 offset:1024
	ds_read_b128 v[196:199], v154 offset:2048
	ds_read_b128 v[200:203], v154 offset:3072
	ds_read_b128 v[204:207], v154 offset:4096
	ds_read_b128 v[208:211], v154 offset:5120
	ds_read_b128 v[212:215], v154 offset:6144
	ds_read_b128 v[216:219], v154 offset:7168
	global_load_lds_dwordx4 v[146:147], off
	v_lshl_add_u64 v[146:147], s[26:27], 0, v[140:141]
	s_add_i32 m0, s25, 0xe000
	s_nop 0
	global_load_lds_dwordx4 v[146:147], off
	s_waitcnt vmcnt(8)
	s_waitcnt lgkmcnt(0)
	s_barrier
; #define PG8_STAGE(bufoff, gbase, voff) do { _Pragma("unroll") for (int _i = 0; _i < 2; ++_i) \
;         __builtin_amdgcn_global_load_lds((const unsigned*)((const char*)(gbase) + (voff)[_i]), (PG8_LAS unsigned*)(lds + (bufoff) + ldsw + _i * 8192), 16, 0, 0); } while (0)
; #define PG8_LDA(dst, b, h) do { _Pragma("unroll") for (int m = 0; m < 4; ++m) _Pragma("unroll") for (int k = 0; k < 2; ++k) dst[m][k] = *(const PG8_LAS bf16x8*)(lds + PG8_SA(b, h) + aoff + m * 2048 + k * 1024); } while (0)
; #define PG8_LDB(dst, b, h) do { _Pragma("unroll") for (int n = 0; n < 2; ++n) _Pragma("unroll") for (int k = 0; k < 2; ++k) dst[n][k] = *(const PG8_LAS bf16x8*)(lds + PG8_SB(b, h) + boff + n * 2048 + k * 1024); } while (0)
; #define PG8_MMA(ai, bj, At, Bt) do { __builtin_amdgcn_s_setprio(1); _Pragma("unroll") for (int m = 0; m < 4; ++m) _Pragma("unroll") for (int n = 0; n < 2; ++n) _Pragma("unroll") for (int k = 0; k < 2; ++k) \
;         acc[ai][bj][m][n] = __builtin_amdgcn_mfma_f32_16x16x32_bf16(Bt[n][k], At[m][k], acc[ai][bj][m][n], 0, 0, 0); __builtin_amdgcn_s_setprio(0); } while (0)
; #define PG8_WAIT_V(n) asm volatile("s_waitcnt vmcnt(" #n ")" ::: "memory")
; #define PG8_WAIT_L(n) asm volatile("s_waitcnt lgkmcnt(" #n ")" ::: "memory")
; #define PG8_BAR __builtin_amdgcn_s_barrier()
; #define PG8_SCHED __builtin_amdgcn_sched_barrier(0)
; template <class Epi, class Sched, bool ALIGN_EPI = false, bool SP2 = false>
; __device__ __forceinline__ void gemm_phase(PG8_LAS unsigned char* lds, const Gemm g, const Sched& S, const Epi& E) {
;     ...
;             PG8_LDB(B0, 0, 0); PG8_LDB(B1, 0, 1); PG8_SCHED; PG8_LDA(At, 0, 0); PG8_STAGE(PG8_SA(1, 1), a1 + hstep, voffA);
;             PG8_WAIT_V(8); PG8_WAIT_L(0); PG8_BAR; PG8_MMA(0, 0, At, B0); PG8_MMA(0, 1, At, B1); PG8_BAR; PG8_SCHED;
;             PG8_LDA(At, 0, 1); PG8_STAGE(PG8_SB(0, 0), b2, voffB); PG8_STAGE(PG8_SB(0, 1), b2 + hstep, voffB); PG8_STAGE(PG8_SA(0, 0), a2, voffA);
;             PG8_WAIT_V(8); PG8_WAIT_L(0); PG8_BAR; PG8_MMA(1, 0, At, B0); PG8_MMA(1, 1, At, B1); PG8_BAR; PG8_SCHED;
	s_setprio 1
	s_waitcnt lgkmcnt(0)
	v_mfma_f32_16x16x32_bf16 v[126:129], v[156:159], v[188:191], v[126:129]
	v_mfma_f32_16x16x32_bf16 v[122:125], v[164:167], v[188:191], v[122:125]
	v_mfma_f32_16x16x32_bf16 v[118:121], v[156:159], v[196:199], v[118:121]
	v_mfma_f32_16x16x32_bf16 v[110:113], v[164:167], v[196:199], v[110:113]
	v_mfma_f32_16x16x32_bf16 v[102:105], v[156:159], v[204:207], v[102:105]
	v_mfma_f32_16x16x32_bf16 v[94:97], v[164:167], v[204:207], v[94:97]
	v_mfma_f32_16x16x32_bf16 v[86:89], v[156:159], v[212:215], v[86:89]
	v_mfma_f32_16x16x32_bf16 v[78:81], v[164:167], v[212:215], v[78:81]
	v_mfma_f32_16x16x32_bf16 v[126:129], v[160:163], v[192:195], v[126:129]
	v_mfma_f32_16x16x32_bf16 v[122:125], v[168:171], v[192:195], v[122:125]
	v_mfma_f32_16x16x32_bf16 v[118:121], v[160:163], v[200:203], v[118:121]
	v_mfma_f32_16x16x32_bf16 v[110:113], v[168:171], v[200:203], v[110:113]
	v_mfma_f32_16x16x32_bf16 v[102:105], v[160:163], v[208:211], v[102:105]
	v_mfma_f32_16x16x32_bf16 v[94:97], v[168:171], v[208:211], v[94:97]
	v_mfma_f32_16x16x32_bf16 v[86:89], v[160:163], v[216:219], v[86:89]
	v_mfma_f32_16x16x32_bf16 v[78:81], v[168:171], v[216:219], v[78:81]
	s_setprio 0
	s_setprio 1
	v_mfma_f32_16x16x32_bf16 v[114:117], v[172:175], v[188:191], v[114:117]
	v_mfma_f32_16x16x32_bf16 v[106:109], v[180:183], v[188:191], v[106:109]
	v_mfma_f32_16x16x32_bf16 v[98:101], v[172:175], v[196:199], v[98:101]
	v_mfma_f32_16x16x32_bf16 v[90:93], v[180:183], v[196:199], v[90:93]
	v_mfma_f32_16x16x32_bf16 v[82:85], v[172:175], v[204:207], v[82:85]
	v_mfma_f32_16x16x32_bf16 v[74:77], v[180:183], v[204:207], v[74:77]
	v_mfma_f32_16x16x32_bf16 v[70:73], v[172:175], v[212:215], v[70:73]
	v_mfma_f32_16x16x32_bf16 v[66:69], v[180:183], v[212:215], v[66:69]
	v_mfma_f32_16x16x32_bf16 v[114:117], v[176:179], v[192:195], v[114:117]
	v_mfma_f32_16x16x32_bf16 v[106:109], v[184:187], v[192:195], v[106:109]
	v_mfma_f32_16x16x32_bf16 v[98:101], v[176:179], v[200:203], v[98:101]
	v_mfma_f32_16x16x32_bf16 v[90:93], v[184:187], v[200:203], v[90:93]
	v_mfma_f32_16x16x32_bf16 v[82:85], v[176:179], v[208:211], v[82:85]
	v_mfma_f32_16x16x32_bf16 v[74:77], v[184:187], v[208:211], v[74:77]
	v_mfma_f32_16x16x32_bf16 v[70:73], v[176:179], v[216:219], v[70:73]
	v_mfma_f32_16x16x32_bf16 v[66:69], v[184:187], v[216:219], v[66:69]
	s_setprio 0
	s_barrier
	s_add_i32 s55, s45, s36
	v_lshl_add_u64 v[146:147], s[28:29], 0, v[134:135]
	s_mov_b32 m0, s55
	ds_read_b128 v[188:191], v154 offset:16384
	ds_read_b128 v[192:195], v154 offset:17408
	ds_read_b128 v[196:199], v154 offset:18432
	ds_read_b128 v[200:203], v154 offset:19456
	ds_read_b128 v[204:207], v154 offset:20480
	ds_read_b128 v[208:211], v154 offset:21504
	ds_read_b128 v[212:215], v154 offset:22528
	ds_read_b128 v[216:219], v154 offset:23552
	global_load_lds_dwordx4 v[146:147], off
	s_add_i32 m0, s55, 0x2000
	s_add_u32 s56, s28, 0x80000
	v_lshl_add_u64 v[220:221], s[28:29], 0, v[130:131]
	s_addc_u32 s57, s29, 0
	s_add_i32 s55, s46, s36
	global_load_lds_dwordx4 v[220:221], off
	v_lshl_add_u64 v[222:223], s[56:57], 0, v[134:135]
	s_mov_b32 m0, s55
	v_lshl_add_u64 v[224:225], s[30:31], 0, v[132:133]
	global_load_lds_dwordx4 v[222:223], off
	v_lshl_add_u64 v[222:223], s[56:57], 0, v[130:131]
	s_add_i32 m0, s55, 0x2000
	s_nop 0
	global_load_lds_dwordx4 v[222:223], off
	v_lshl_add_u64 v[222:223], s[30:31], 0, v[136:137]
	s_mov_b32 m0, s25
	s_nop 0
	global_load_lds_dwordx4 v[222:223], off
	s_mov_b32 m0, s38
	s_nop 0
	global_load_lds_dwordx4 v[224:225], off
	s_waitcnt vmcnt(8)
	s_waitcnt lgkmcnt(0)
	s_barrier
	s_setprio 1
	s_waitcnt lgkmcnt(0)
	v_mfma_f32_16x16x32_bf16 v[62:65], v[156:159], v[188:191], v[62:65]
	v_mfma_f32_16x16x32_bf16 v[58:61], v[164:167], v[188:191], v[58:61]
	v_mfma_f32_16x16x32_bf16 v[54:57], v[156:159], v[196:199], v[54:57]
	v_mfma_f32_16x16x32_bf16 v[46:49], v[164:167], v[196:199], v[46:49]
	v_mfma_f32_16x16x32_bf16 v[38:41], v[156:159], v[204:207], v[38:41]
	v_mfma_f32_16x16x32_bf16 v[30:33], v[164:167], v[204:207], v[30:33]
	v_mfma_f32_16x16x32_bf16 v[22:25], v[156:159], v[212:215], v[22:25]
	v_mfma_f32_16x16x32_bf16 v[14:17], v[164:167], v[212:215], v[14:17]
	v_mfma_f32_16x16x32_bf16 v[62:65], v[160:163], v[192:195], v[62:65]
	v_mfma_f32_16x16x32_bf16 v[58:61], v[168:171], v[192:195], v[58:61]
	v_mfma_f32_16x16x32_bf16 v[54:57], v[160:163], v[200:203], v[54:57]
	v_mfma_f32_16x16x32_bf16 v[46:49], v[168:171], v[200:203], v[46:49]
	v_mfma_f32_16x16x32_bf16 v[38:41], v[160:163], v[208:211], v[38:41]
	v_mfma_f32_16x16x32_bf16 v[30:33], v[168:171], v[208:211], v[30:33]
	v_mfma_f32_16x16x32_bf16 v[22:25], v[160:163], v[216:219], v[22:25]
	v_mfma_f32_16x16x32_bf16 v[14:17], v[168:171], v[216:219], v[14:17]
	s_setprio 0
	s_setprio 1
	v_mfma_f32_16x16x32_bf16 v[50:53], v[172:175], v[188:191], v[50:53]
	v_mfma_f32_16x16x32_bf16 v[42:45], v[180:183], v[188:191], v[42:45]
	v_mfma_f32_16x16x32_bf16 v[34:37], v[172:175], v[196:199], v[34:37]
	v_mfma_f32_16x16x32_bf16 v[26:29], v[180:183], v[196:199], v[26:29]
	v_mfma_f32_16x16x32_bf16 v[18:21], v[172:175], v[204:207], v[18:21]
	v_mfma_f32_16x16x32_bf16 v[10:13], v[180:183], v[204:207], v[10:13]
	v_mfma_f32_16x16x32_bf16 v[6:9], v[172:175], v[212:215], v[6:9]
	v_mfma_f32_16x16x32_bf16 v[2:5], v[180:183], v[212:215], v[2:5]
	v_mfma_f32_16x16x32_bf16 v[50:53], v[176:179], v[192:195], v[50:53]
	v_mfma_f32_16x16x32_bf16 v[42:45], v[184:187], v[192:195], v[42:45]
	v_mfma_f32_16x16x32_bf16 v[34:37], v[176:179], v[200:203], v[34:37]
	v_mfma_f32_16x16x32_bf16 v[26:29], v[184:187], v[200:203], v[26:29]
	v_mfma_f32_16x16x32_bf16 v[18:21], v[176:179], v[208:211], v[18:21]
	v_mfma_f32_16x16x32_bf16 v[10:13], v[184:187], v[208:211], v[10:13]
	v_mfma_f32_16x16x32_bf16 v[6:9], v[176:179], v[216:219], v[6:9]
	v_mfma_f32_16x16x32_bf16 v[2:5], v[184:187], v[216:219], v[2:5]
	s_setprio 0
	s_barrier
; #define PG8_STAGE(bufoff, gbase, voff) do { _Pragma("unroll") for (int _i = 0; _i < 2; ++_i) \
;         __builtin_amdgcn_global_load_lds((const unsigned*)((const char*)(gbase) + (voff)[_i]), (PG8_LAS unsigned*)(lds + (bufoff) + ldsw + _i * 8192), 16, 0, 0); } while (0)
; #define PG8_LDA(dst, b, h) do { _Pragma("unroll") for (int m = 0; m < 4; ++m) _Pragma("unroll") for (int k = 0; k < 2; ++k) dst[m][k] = *(const PG8_LAS bf16x8*)(lds + PG8_SA(b, h) + aoff + m * 2048 + k * 1024); } while (0)
; #define PG8_LDB(dst, b, h) do { _Pragma("unroll") for (int n = 0; n < 2; ++n) _Pragma("unroll") for (int k = 0; k < 2; ++k) dst[n][k] = *(const PG8_LAS bf16x8*)(lds + PG8_SB(b, h) + boff + n * 2048 + k * 1024); } while (0)
; #define PG8_MMA(ai, bj, At, Bt) do { __builtin_amdgcn_s_setprio(1); _Pragma("unroll") for (int m = 0; m < 4; ++m) _Pragma("unroll") for (int n = 0; n < 2; ++n) _Pragma("unroll") for (int k = 0; k < 2; ++k) \
;         acc[ai][bj][m][n] = __builtin_amdgcn_mfma_f32_16x16x32_bf16(Bt[n][k], At[m][k], acc[ai][bj][m][n], 0, 0, 0); __builtin_amdgcn_s_setprio(0); } while (0)
; #define PG8_WAIT_V(n) asm volatile("s_waitcnt vmcnt(" #n ")" ::: "memory")
; #define PG8_WAIT_L(n) asm volatile("s_waitcnt lgkmcnt(" #n ")" ::: "memory")
; #define PG8_BAR __builtin_amdgcn_s_barrier()
; #define PG8_SCHED __builtin_amdgcn_sched_barrier(0)
; template <class Epi, class Sched, bool ALIGN_EPI = false, bool SP2 = false>
; __device__ __forceinline__ void gemm_phase(PG8_LAS unsigned char* lds, const Gemm g, const Sched& S, const Epi& E) {
;     ...
;             PG8_LDB(B0, 1, 0); PG8_LDB(B1, 1, 1); PG8_SCHED; PG8_LDA(At, 1, 0); PG8_STAGE(PG8_SA(0, 1), a2 + hstep, voffA);
;             PG8_WAIT_V(8); PG8_WAIT_L(0); PG8_BAR; PG8_MMA(0, 0, At, B0); PG8_MMA(0, 1, At, B1); PG8_BAR; PG8_SCHED;
	s_add_i32 s55, 0, 0x18000
	v_add_u32_e32 v155, s55, v150
	s_add_i32 s56, 0, 0x1c000
	ds_read_b128 v[156:159], v155
	ds_read_b128 v[160:163], v155 offset:1024
	ds_read_b128 v[164:167], v155 offset:2048
	ds_read_b128 v[168:171], v155 offset:3072
	v_add_u32_e32 v155, s56, v150
	ds_read_b128 v[172:175], v155
	ds_read_b128 v[176:179], v155 offset:1024
	ds_read_b128 v[180:183], v155 offset:2048
	ds_read_b128 v[184:187], v155 offset:3072
	s_add_u32 s30, s30, 0x80000
	s_addc_u32 s31, s31, 0
	s_mov_b32 m0, s39
	v_lshl_add_u64 v[226:227], s[30:31], 0, v[136:137]
	ds_read_b128 v[188:191], v154 offset:32768
	ds_read_b128 v[192:195], v154 offset:33792
	ds_read_b128 v[196:199], v154 offset:34816
	ds_read_b128 v[200:203], v154 offset:35840
	ds_read_b128 v[204:207], v154 offset:36864
	ds_read_b128 v[208:211], v154 offset:37888
	ds_read_b128 v[212:215], v154 offset:38912
	ds_read_b128 v[216:219], v154 offset:39936
	global_load_lds_dwordx4 v[226:227], off
	v_lshl_add_u64 v[226:227], s[30:31], 0, v[132:133]
	s_mov_b32 m0, s40
	s_nop 0
	global_load_lds_dwordx4 v[226:227], off
	s_waitcnt vmcnt(8)
	s_waitcnt lgkmcnt(0)
	s_barrier
	s_setprio 1
	s_waitcnt lgkmcnt(0)
	v_mfma_f32_16x16x32_bf16 v[126:129], v[156:159], v[188:191], v[126:129]
	v_mfma_f32_16x16x32_bf16 v[122:125], v[164:167], v[188:191], v[122:125]
	v_mfma_f32_16x16x32_bf16 v[118:121], v[156:159], v[196:199], v[118:121]
	v_mfma_f32_16x16x32_bf16 v[110:113], v[164:167], v[196:199], v[110:113]
	v_mfma_f32_16x16x32_bf16 v[102:105], v[156:159], v[204:207], v[102:105]
	v_mfma_f32_16x16x32_bf16 v[94:97], v[164:167], v[204:207], v[94:97]
	v_mfma_f32_16x16x32_bf16 v[86:89], v[156:159], v[212:215], v[86:89]
	v_mfma_f32_16x16x32_bf16 v[78:81], v[164:167], v[212:215], v[78:81]
	v_mfma_f32_16x16x32_bf16 v[126:129], v[160:163], v[192:195], v[126:129]
	v_mfma_f32_16x16x32_bf16 v[122:125], v[168:171], v[192:195], v[122:125]
	v_mfma_f32_16x16x32_bf16 v[118:121], v[160:163], v[200:203], v[118:121]
	v_mfma_f32_16x16x32_bf16 v[110:113], v[168:171], v[200:203], v[110:113]
	v_mfma_f32_16x16x32_bf16 v[102:105], v[160:163], v[208:211], v[102:105]
	v_mfma_f32_16x16x32_bf16 v[94:97], v[168:171], v[208:211], v[94:97]
	v_mfma_f32_16x16x32_bf16 v[86:89], v[160:163], v[216:219], v[86:89]
	v_mfma_f32_16x16x32_bf16 v[78:81], v[168:171], v[216:219], v[78:81]
	s_setprio 0
	s_setprio 1
	v_mfma_f32_16x16x32_bf16 v[114:117], v[172:175], v[188:191], v[114:117]
	v_mfma_f32_16x16x32_bf16 v[106:109], v[180:183], v[188:191], v[106:109]
	v_mfma_f32_16x16x32_bf16 v[98:101], v[172:175], v[196:199], v[98:101]
	v_mfma_f32_16x16x32_bf16 v[90:93], v[180:183], v[196:199], v[90:93]
	v_mfma_f32_16x16x32_bf16 v[82:85], v[172:175], v[204:207], v[82:85]
	v_mfma_f32_16x16x32_bf16 v[74:77], v[180:183], v[204:207], v[74:77]
	v_mfma_f32_16x16x32_bf16 v[70:73], v[172:175], v[212:215], v[70:73]
	v_mfma_f32_16x16x32_bf16 v[66:69], v[180:183], v[212:215], v[66:69]
	v_mfma_f32_16x16x32_bf16 v[114:117], v[176:179], v[192:195], v[114:117]
	v_mfma_f32_16x16x32_bf16 v[106:109], v[184:187], v[192:195], v[106:109]
	v_mfma_f32_16x16x32_bf16 v[98:101], v[176:179], v[200:203], v[98:101]
	v_mfma_f32_16x16x32_bf16 v[90:93], v[184:187], v[200:203], v[90:93]
	v_mfma_f32_16x16x32_bf16 v[82:85], v[176:179], v[208:211], v[82:85]
	v_mfma_f32_16x16x32_bf16 v[74:77], v[184:187], v[208:211], v[74:77]
	v_mfma_f32_16x16x32_bf16 v[70:73], v[176:179], v[216:219], v[70:73]
	v_mfma_f32_16x16x32_bf16 v[66:69], v[184:187], v[216:219], v[66:69]
	s_setprio 0
	s_barrier
; #define PG8_STAGE(bufoff, gbase, voff) do { _Pragma("unroll") for (int _i = 0; _i < 2; ++_i) \
;         __builtin_amdgcn_global_load_lds((const unsigned*)((const char*)(gbase) + (voff)[_i]), (PG8_LAS unsigned*)(lds + (bufoff) + ldsw + _i * 8192), 16, 0, 0); } while (0)
; #define PG8_LDA(dst, b, h) do { _Pragma("unroll") for (int m = 0; m < 4; ++m) _Pragma("unroll") for (int k = 0; k < 2; ++k) dst[m][k] = *(const PG8_LAS bf16x8*)(lds + PG8_SA(b, h) + aoff + m * 2048 + k * 1024); } while (0)
; #define PG8_WAIT_V(n) asm volatile("s_waitcnt vmcnt(" #n ")" ::: "memory")
; #define PG8_BAR __builtin_amdgcn_s_barrier()
; template <class Epi, class Sched, bool ALIGN_EPI = false, bool SP2 = false>
; __device__ __forceinline__ void gemm_phase(PG8_LAS unsigned char* lds, const Gemm g, const Sched& S, const Epi& E) {
;     ...
;         for (int t = 0; t < nt; t += 2) {
;             if constexpr (Epi::MIDHOOK) { if (t == (nt >> 1)) E.mid(acc, cur, wr, wc, fr, fq); }
;             const bool last = (t == nt - 2);
;             const char* a1 = cA + (size_t)(t + 1) * kstep;
;             const char* a2 = last ? nA : cA + (size_t)(t + 2) * kstep; const char* b2 = last ? nB : cB + (size_t)(t + 2) * kstep;
;             const char* a3 = a2 + kstep; const char* b3 = b2 + kstep;
;             if (last && has_next) S.a_ready(nxt);
;             if constexpr (SP2) {
;             PG8_LDB(B0, 0, 0); PG8_LDB(B1, 0, 1); PG8_SCHED; PG8_LDA(At, 0, 0); PG8_STAGE(PG8_SA(1, 1), a1 + hstep, voffA);
;             PG8_WAIT_V(8); PG8_WAIT_L(0); PG8_BAR; PG8_MMA(0, 0, At, B0); PG8_MMA(0, 1, At, B1); PG8_BAR; PG8_SCHED;
;             PG8_LDA(At, 0, 1); PG8_STAGE(PG8_SB(0, 0), b2, voffB); PG8_STAGE(PG8_SB(0, 1), b2 + hstep, voffB); PG8_STAGE(PG8_SA(0, 0), a2, voffA);
;             PG8_WAIT_V(8); PG8_WAIT_L(0); PG8_BAR; PG8_MMA(1, 0, At, B0); PG8_MMA(1, 1, At, B1); PG8_BAR; PG8_SCHED;
;             PG8_LDB(B0, 1, 0); PG8_LDB(B1, 1, 1); PG8_SCHED; PG8_LDA(At, 1, 0); PG8_STAGE(PG8_SA(0, 1), a2 + hstep, voffA);
;             PG8_WAIT_V(8); PG8_WAIT_L(0); PG8_BAR; PG8_MMA(0, 0, At, B0); PG8_MMA(0, 1, At, B1); PG8_BAR; PG8_SCHED;
;             PG8_LDA(At, 1, 1); PG8_STAGE(PG8_SB(1, 0), b3, voffB); PG8_STAGE(PG8_SB(1, 1), b3 + hstep, voffB); PG8_STAGE(PG8_SA(1, 0), a3, voffA);
;             PG8_WAIT_V(8); PG8_WAIT_L(0); PG8_BAR; PG8_MMA(1, 0, At, B0); PG8_MMA(1, 1, At, B1); PG8_BAR; PG8_SCHED;
	s_add_i32 s30, s55, s36
	v_lshl_add_u64 v[146:147], v[146:147], 0, s[12:13]
	s_mov_b32 m0, s30
	ds_read_b128 v[188:191], v154 offset:49152
	ds_read_b128 v[192:195], v154 offset:50176
	ds_read_b128 v[196:199], v154 offset:51200
	ds_read_b128 v[200:203], v154 offset:52224
	ds_read_b128 v[204:207], v154 offset:53248
	ds_read_b128 v[208:211], v154 offset:54272
	ds_read_b128 v[212:215], v154 offset:55296
	ds_read_b128 v[216:219], v154 offset:56320
	global_load_lds_dwordx4 v[146:147], off
	s_add_i32 m0, s30, 0x2000
	s_add_u32 s28, s28, 0x80080
	v_lshl_add_u64 v[146:147], v[220:221], 0, s[12:13]
	s_addc_u32 s29, s29, 0
	s_add_i32 s30, s56, s36
	global_load_lds_dwordx4 v[146:147], off
	v_lshl_add_u64 v[146:147], s[28:29], 0, v[134:135]
	s_mov_b32 m0, s30
	s_nop 0
	global_load_lds_dwordx4 v[146:147], off
	v_lshl_add_u64 v[146:147], s[28:29], 0, v[130:131]
	s_add_i32 m0, s30, 0x2000
	s_nop 0
	global_load_lds_dwordx4 v[146:147], off
	v_lshl_add_u64 v[146:147], v[222:223], 0, s[12:13]
	s_mov_b32 m0, s43
	s_nop 0
	global_load_lds_dwordx4 v[146:147], off
	v_lshl_add_u64 v[146:147], v[224:225], 0, s[12:13]
	s_mov_b32 m0, s44
	s_nop 0
	global_load_lds_dwordx4 v[146:147], off
	s_waitcnt vmcnt(8)
	s_waitcnt lgkmcnt(0)
	s_barrier
	s_setprio 1
	s_waitcnt lgkmcnt(0)
	v_mfma_f32_16x16x32_bf16 v[62:65], v[156:159], v[188:191], v[62:65]
	v_mfma_f32_16x16x32_bf16 v[58:61], v[164:167], v[188:191], v[58:61]
	v_mfma_f32_16x16x32_bf16 v[54:57], v[156:159], v[196:199], v[54:57]
	v_mfma_f32_16x16x32_bf16 v[46:49], v[164:167], v[196:199], v[46:49]
	v_mfma_f32_16x16x32_bf16 v[38:41], v[156:159], v[204:207], v[38:41]
	v_mfma_f32_16x16x32_bf16 v[30:33], v[164:167], v[204:207], v[30:33]
	v_mfma_f32_16x16x32_bf16 v[22:25], v[156:159], v[212:215], v[22:25]
	v_mfma_f32_16x16x32_bf16 v[14:17], v[164:167], v[212:215], v[14:17]
	v_mfma_f32_16x16x32_bf16 v[62:65], v[160:163], v[192:195], v[62:65]
	v_mfma_f32_16x16x32_bf16 v[58:61], v[168:171], v[192:195], v[58:61]
	v_mfma_f32_16x16x32_bf16 v[54:57], v[160:163], v[200:203], v[54:57]
	v_mfma_f32_16x16x32_bf16 v[46:49], v[168:171], v[200:203], v[46:49]
	v_mfma_f32_16x16x32_bf16 v[38:41], v[160:163], v[208:211], v[38:41]
	v_mfma_f32_16x16x32_bf16 v[30:33], v[168:171], v[208:211], v[30:33]
	v_mfma_f32_16x16x32_bf16 v[22:25], v[160:163], v[216:219], v[22:25]
	v_mfma_f32_16x16x32_bf16 v[14:17], v[168:171], v[216:219], v[14:17]
	s_setprio 0
	s_setprio 1
	v_mfma_f32_16x16x32_bf16 v[50:53], v[172:175], v[188:191], v[50:53]
	v_mfma_f32_16x16x32_bf16 v[42:45], v[180:183], v[188:191], v[42:45]
	v_mfma_f32_16x16x32_bf16 v[34:37], v[172:175], v[196:199], v[34:37]
	v_mfma_f32_16x16x32_bf16 v[26:29], v[180:183], v[196:199], v[26:29]
	v_mfma_f32_16x16x32_bf16 v[18:21], v[172:175], v[204:207], v[18:21]
	v_mfma_f32_16x16x32_bf16 v[10:13], v[180:183], v[204:207], v[10:13]
	v_mfma_f32_16x16x32_bf16 v[6:9], v[172:175], v[212:215], v[6:9]
	v_mfma_f32_16x16x32_bf16 v[2:5], v[180:183], v[212:215], v[2:5]
	v_mfma_f32_16x16x32_bf16 v[50:53], v[176:179], v[192:195], v[50:53]
	v_mfma_f32_16x16x32_bf16 v[42:45], v[184:187], v[192:195], v[42:45]
	v_mfma_f32_16x16x32_bf16 v[34:37], v[176:179], v[200:203], v[34:37]
	v_mfma_f32_16x16x32_bf16 v[26:29], v[184:187], v[200:203], v[26:29]
	v_mfma_f32_16x16x32_bf16 v[18:21], v[176:179], v[208:211], v[18:21]
	v_mfma_f32_16x16x32_bf16 v[10:13], v[184:187], v[208:211], v[10:13]
	v_mfma_f32_16x16x32_bf16 v[6:9], v[176:179], v[216:219], v[6:9]
	v_mfma_f32_16x16x32_bf16 v[2:5], v[184:187], v[216:219], v[2:5]
	s_setprio 0
	s_barrier
	s_add_i32 s54, s54, 2
	s_add_u32 s26, s26, 0x100
	s_addc_u32 s27, s27, 0
	s_add_u32 s52, s52, 0x100
	s_addc_u32 s53, s53, 0
	s_cmp_gt_u32 s54, 29
	s_cbranch_scc0 .LBB0_1393

; #define PG8_STAGE(bufoff, gbase, voff) do { _Pragma("unroll") for (int _i = 0; _i < 2; ++_i) \
;         __builtin_amdgcn_global_load_lds((const unsigned*)((const char*)(gbase) + (voff)[_i]), (PG8_LAS unsigned*)(lds + (bufoff) + ldsw + _i * 8192), 16, 0, 0); } while (0)
; #define PG8_LDA(dst, b, h) do { _Pragma("unroll") for (int m = 0; m < 4; ++m) _Pragma("unroll") for (int k = 0; k < 2; ++k) dst[m][k] = *(const PG8_LAS bf16x8*)(lds + PG8_SA(b, h) + aoff + m * 2048 + k * 1024); } while (0)
; #define PG8_WAIT_V(n) asm volatile("s_waitcnt vmcnt(" #n ")" ::: "memory")
; #define PG8_BAR __builtin_amdgcn_s_barrier()
; template <class Epi, class Sched, bool ALIGN_EPI = false, bool SP2 = false>
; __device__ __forceinline__ void gemm_phase(PG8_LAS unsigned char* lds, const Gemm g, const Sched& S, const Epi& E) {
;     ...
;         const char* nA = has_next ? (const char*)g.A + (size_t)nxt.pm * tstep + (size_t)nxt.kt0 * kstep : cA; const char* nB = has_next ? (const char*)g.Bt + (size_t)nxt.pn * tstep + (size_t)nxt.kt0 * kstep : cB;
;         for (int t = 0; t < nt; t += 2) {
;             if constexpr (Epi::MIDHOOK) { if (t == (nt >> 1)) E.mid(acc, cur, wr, wc, fr, fq); }
;             const bool last = (t == nt - 2);
;             const char* a1 = cA + (size_t)(t + 1) * kstep;
;             const char* a2 = last ? nA : cA + (size_t)(t + 2) * kstep; const char* b2 = last ? nB : cB + (size_t)(t + 2) * kstep;
;             const char* a3 = a2 + kstep; const char* b3 = b2 + kstep;
;             if (last && has_next) S.a_ready(nxt);
;             if constexpr (SP2) {
;             PG8_LDB(B0, 0, 0); PG8_LDB(B1, 0, 1); PG8_SCHED; PG8_LDA(At, 0, 0); PG8_STAGE(PG8_SA(1, 1), a1 + hstep, voffA);
;             PG8_WAIT_V(8); PG8_WAIT_L(0); PG8_BAR; PG8_MMA(0, 0, At, B0); PG8_MMA(0, 1, At, B1); PG8_BAR; PG8_SCHED;
;             PG8_LDA(At, 0, 1); PG8_STAGE(PG8_SB(0, 0), b2, voffB); PG8_STAGE(PG8_SB(0, 1), b2 + hstep, voffB); PG8_STAGE(PG8_SA(0, 0), a2, voffA);
;             PG8_WAIT_V(8); PG8_WAIT_L(0); PG8_BAR; PG8_MMA(1, 0, At, B0); PG8_MMA(1, 1, At, B1); PG8_BAR; PG8_SCHED;
;     ...
; #pragma unroll
;         for (int a = 0; a < 2; ++a)
; #pragma unroll
;             for (int b = 0; b < 2; ++b)
; #pragma unroll
;                 for (int m = 0; m < 4; ++m)
; #pragma unroll
;                     for (int n = 0; n < 2; ++n) acc[a][b][m][n] = (f32x4){0.f, 0.f, 0.f, 0.f};
.LBB0_1427:
	s_mov_b32 s7, 0
	s_mov_b64 s[28:29], -1
	s_mov_b64 s[30:31], 0
	s_waitcnt lgkmcnt(0)
	s_add_u32 s21, s16, s7
	s_addc_u32 s23, s17, 0
	s_add_u32 s38, s21, 0x100
	s_addc_u32 s39, s23, 0
	s_and_b64 s[36:37], s[30:31], exec
	s_cselect_b32 s39, s25, s39
	s_cselect_b32 s38, s24, s38
	s_add_u32 s7, s14, s7
	s_addc_u32 s36, s15, 0
	s_add_u32 s7, s7, 0x100
	s_addc_u32 s36, s36, 0
	s_and_b64 s[30:31], s[30:31], exec
	s_cselect_b32 s41, s27, s36
	s_cselect_b32 s40, s26, s7
	s_add_u32 s46, s21, 0x80080
	s_addc_u32 s47, s23, 0
	s_add_i32 s70, s60, s44
	ds_read_b128 v[140:143], v137
	ds_read_b128 v[144:147], v137 offset:1024
	ds_read_b128 v[148:151], v137 offset:2048
	ds_read_b128 v[152:155], v137 offset:3072
	ds_read_b128 v[156:159], v138
	ds_read_b128 v[160:163], v138 offset:1024
	ds_read_b128 v[164:167], v138 offset:2048
	ds_read_b128 v[168:171], v138 offset:3072
	s_add_i32 m0, s51, 0xc000
	s_add_i32 s71, s51, 0xe000
	s_add_i32 s67, s70, 0x2000
	s_add_u32 s42, s40, 0x80000
	s_addc_u32 s43, s41, 0
	s_add_i32 s69, s61, s44
	s_add_i32 s68, s69, 0x2000
	s_add_i32 s66, 0, 0x18000
	s_add_i32 s65, 0, 0x1c000
	s_add_u32 s36, s38, 0x80000
	s_addc_u32 s37, s39, 0
	s_add_i32 s64, s66, s44
	s_add_i32 s21, s64, 0x2000
	s_add_u32 s30, s40, 0x80080
	s_addc_u32 s31, s41, 0
	s_add_i32 s23, s65, s44
	s_add_i32 s7, s23, 0x2000
	v_lshl_add_u64 v[204:205], s[46:47], 0, v[132:133]
	ds_read_b128 v[172:175], v139
	ds_read_b128 v[176:179], v139 offset:1024
	ds_read_b128 v[180:183], v139 offset:2048
	ds_read_b128 v[184:187], v139 offset:3072
	ds_read_b128 v[188:191], v139 offset:4096
	ds_read_b128 v[192:195], v139 offset:5120
	ds_read_b128 v[196:199], v139 offset:6144
	ds_read_b128 v[200:203], v139 offset:7168
	global_load_lds_dwordx4 v[204:205], off
	v_lshl_add_u64 v[204:205], s[46:47], 0, v[130:131]
	s_mov_b32 m0, s71
	s_nop 0
	global_load_lds_dwordx4 v[204:205], off
	s_waitcnt vmcnt(8)
	s_waitcnt lgkmcnt(0)
	s_barrier
	s_setprio 1
	s_waitcnt lgkmcnt(0)
	v_mfma_f32_16x16x32_bf16 v[126:129], v[140:143], v[172:175], 0
	v_mfma_f32_16x16x32_bf16 v[122:125], v[148:151], v[172:175], 0
	v_mfma_f32_16x16x32_bf16 v[118:121], v[140:143], v[180:183], 0
	v_mfma_f32_16x16x32_bf16 v[114:117], v[148:151], v[180:183], 0
	v_mfma_f32_16x16x32_bf16 v[106:109], v[140:143], v[188:191], 0
	v_mfma_f32_16x16x32_bf16 v[98:101], v[148:151], v[188:191], 0
	v_mfma_f32_16x16x32_bf16 v[90:93], v[140:143], v[196:199], 0
	v_mfma_f32_16x16x32_bf16 v[82:85], v[148:151], v[196:199], 0
	v_mfma_f32_16x16x32_bf16 v[126:129], v[144:147], v[176:179], v[126:129]
	v_mfma_f32_16x16x32_bf16 v[122:125], v[152:155], v[176:179], v[122:125]
	v_mfma_f32_16x16x32_bf16 v[118:121], v[144:147], v[184:187], v[118:121]
	v_mfma_f32_16x16x32_bf16 v[114:117], v[152:155], v[184:187], v[114:117]
	v_mfma_f32_16x16x32_bf16 v[106:109], v[144:147], v[192:195], v[106:109]
	v_mfma_f32_16x16x32_bf16 v[98:101], v[152:155], v[192:195], v[98:101]
	v_mfma_f32_16x16x32_bf16 v[90:93], v[144:147], v[200:203], v[90:93]
	v_mfma_f32_16x16x32_bf16 v[82:85], v[152:155], v[200:203], v[82:85]
	s_setprio 0
	s_setprio 1
	v_mfma_f32_16x16x32_bf16 v[110:113], v[156:159], v[172:175], 0
	v_mfma_f32_16x16x32_bf16 v[102:105], v[164:167], v[172:175], 0
	v_mfma_f32_16x16x32_bf16 v[94:97], v[156:159], v[180:183], 0
	v_mfma_f32_16x16x32_bf16 v[86:89], v[164:167], v[180:183], 0
	v_mfma_f32_16x16x32_bf16 v[78:81], v[156:159], v[188:191], 0
	v_mfma_f32_16x16x32_bf16 v[74:77], v[164:167], v[188:191], 0
	v_mfma_f32_16x16x32_bf16 v[70:73], v[156:159], v[196:199], 0
	v_mfma_f32_16x16x32_bf16 v[66:69], v[164:167], v[196:199], 0
	v_mfma_f32_16x16x32_bf16 v[110:113], v[160:163], v[176:179], v[110:113]
	v_mfma_f32_16x16x32_bf16 v[102:105], v[168:171], v[176:179], v[102:105]
	v_mfma_f32_16x16x32_bf16 v[94:97], v[160:163], v[184:187], v[94:97]
	v_mfma_f32_16x16x32_bf16 v[86:89], v[168:171], v[184:187], v[86:89]
	v_mfma_f32_16x16x32_bf16 v[78:81], v[160:163], v[192:195], v[78:81]
	v_mfma_f32_16x16x32_bf16 v[74:77], v[168:171], v[192:195], v[74:77]
	v_mfma_f32_16x16x32_bf16 v[70:73], v[160:163], v[200:203], v[70:73]
	v_mfma_f32_16x16x32_bf16 v[66:69], v[168:171], v[200:203], v[66:69]
	s_setprio 0
	s_barrier
	s_mov_b32 m0, s70
	v_lshl_add_u64 v[204:205], s[40:41], 0, v[132:133]
	ds_read_b128 v[172:175], v139 offset:16384
	ds_read_b128 v[176:179], v139 offset:17408
	ds_read_b128 v[180:183], v139 offset:18432
	ds_read_b128 v[184:187], v139 offset:19456
	ds_read_b128 v[188:191], v139 offset:20480
	ds_read_b128 v[192:195], v139 offset:21504
	ds_read_b128 v[196:199], v139 offset:22528
	ds_read_b128 v[200:203], v139 offset:23552
	global_load_lds_dwordx4 v[204:205], off
	v_lshl_add_u64 v[206:207], s[40:41], 0, v[130:131]
	s_mov_b32 m0, s67
	v_lshl_add_u64 v[208:209], s[42:43], 0, v[132:133]
	global_load_lds_dwordx4 v[206:207], off
	s_mov_b32 m0, s69
	v_lshl_add_u64 v[210:211], s[38:39], 0, v[130:131]
	global_load_lds_dwordx4 v[208:209], off
	v_lshl_add_u64 v[208:209], s[42:43], 0, v[130:131]
	s_mov_b32 m0, s68
	s_nop 0
	global_load_lds_dwordx4 v[208:209], off
	v_lshl_add_u64 v[208:209], s[38:39], 0, v[132:133]
	s_mov_b32 m0, s51
	s_nop 0
	global_load_lds_dwordx4 v[208:209], off
	s_mov_b32 m0, s52
	s_nop 0
	global_load_lds_dwordx4 v[210:211], off
	s_waitcnt vmcnt(8)
	s_waitcnt lgkmcnt(0)
	s_barrier
; #define PG8_STAGE(bufoff, gbase, voff) do { _Pragma("unroll") for (int _i = 0; _i < 2; ++_i) \
;         __builtin_amdgcn_global_load_lds((const unsigned*)((const char*)(gbase) + (voff)[_i]), (PG8_LAS unsigned*)(lds + (bufoff) + ldsw + _i * 8192), 16, 0, 0); } while (0)
; #define PG8_LDA(dst, b, h) do { _Pragma("unroll") for (int m = 0; m < 4; ++m) _Pragma("unroll") for (int k = 0; k < 2; ++k) dst[m][k] = *(const PG8_LAS bf16x8*)(lds + PG8_SA(b, h) + aoff + m * 2048 + k * 1024); } while (0)
; #define PG8_LDB(dst, b, h) do { _Pragma("unroll") for (int n = 0; n < 2; ++n) _Pragma("unroll") for (int k = 0; k < 2; ++k) dst[n][k] = *(const PG8_LAS bf16x8*)(lds + PG8_SB(b, h) + boff + n * 2048 + k * 1024); } while (0)
; #define PG8_MMA(ai, bj, At, Bt) do { __builtin_amdgcn_s_setprio(1); _Pragma("unroll") for (int m = 0; m < 4; ++m) _Pragma("unroll") for (int n = 0; n < 2; ++n) _Pragma("unroll") for (int k = 0; k < 2; ++k) \
;         acc[ai][bj][m][n] = __builtin_amdgcn_mfma_f32_16x16x32_bf16(Bt[n][k], At[m][k], acc[ai][bj][m][n], 0, 0, 0); __builtin_amdgcn_s_setprio(0); } while (0)
; #define PG8_WAIT_V(n) asm volatile("s_waitcnt vmcnt(" #n ")" ::: "memory")
; #define PG8_WAIT_L(n) asm volatile("s_waitcnt lgkmcnt(" #n ")" ::: "memory")
; #define PG8_BAR __builtin_amdgcn_s_barrier()
; #define PG8_SCHED __builtin_amdgcn_sched_barrier(0)
; template <class Epi, class Sched, bool ALIGN_EPI = false, bool SP2 = false>
; __device__ __forceinline__ void gemm_phase(PG8_LAS unsigned char* lds, const Gemm g, const Sched& S, const Epi& E) {
;     ...
;             PG8_LDA(At, 0, 1); PG8_STAGE(PG8_SB(0, 0), b2, voffB); PG8_STAGE(PG8_SB(0, 1), b2 + hstep, voffB); PG8_STAGE(PG8_SA(0, 0), a2, voffA);
;             PG8_WAIT_V(8); PG8_WAIT_L(0); PG8_BAR; PG8_MMA(1, 0, At, B0); PG8_MMA(1, 1, At, B1); PG8_BAR; PG8_SCHED;
;             PG8_LDB(B0, 1, 0); PG8_LDB(B1, 1, 1); PG8_SCHED; PG8_LDA(At, 1, 0); PG8_STAGE(PG8_SA(0, 1), a2 + hstep, voffA);
;             PG8_WAIT_V(8); PG8_WAIT_L(0); PG8_BAR; PG8_MMA(0, 0, At, B0); PG8_MMA(0, 1, At, B1); PG8_BAR; PG8_SCHED;
	s_setprio 1
	s_waitcnt lgkmcnt(0)
	v_mfma_f32_16x16x32_bf16 v[62:65], v[140:143], v[172:175], 0
	v_mfma_f32_16x16x32_bf16 v[58:61], v[148:151], v[172:175], 0
	v_mfma_f32_16x16x32_bf16 v[54:57], v[140:143], v[180:183], 0
	v_mfma_f32_16x16x32_bf16 v[50:53], v[148:151], v[180:183], 0
	v_mfma_f32_16x16x32_bf16 v[38:41], v[140:143], v[188:191], 0
	v_mfma_f32_16x16x32_bf16 v[34:37], v[148:151], v[188:191], 0
	v_mfma_f32_16x16x32_bf16 v[22:25], v[140:143], v[196:199], 0
	v_mfma_f32_16x16x32_bf16 v[18:21], v[148:151], v[196:199], 0
	v_mfma_f32_16x16x32_bf16 v[62:65], v[144:147], v[176:179], v[62:65]
	v_mfma_f32_16x16x32_bf16 v[58:61], v[152:155], v[176:179], v[58:61]
	v_mfma_f32_16x16x32_bf16 v[54:57], v[144:147], v[184:187], v[54:57]
	v_mfma_f32_16x16x32_bf16 v[50:53], v[152:155], v[184:187], v[50:53]
	v_mfma_f32_16x16x32_bf16 v[38:41], v[144:147], v[192:195], v[38:41]
	v_mfma_f32_16x16x32_bf16 v[34:37], v[152:155], v[192:195], v[34:37]
	v_mfma_f32_16x16x32_bf16 v[22:25], v[144:147], v[200:203], v[22:25]
	v_mfma_f32_16x16x32_bf16 v[18:21], v[152:155], v[200:203], v[18:21]
	s_setprio 0
	s_setprio 1
	v_mfma_f32_16x16x32_bf16 v[46:49], v[156:159], v[172:175], 0
	v_mfma_f32_16x16x32_bf16 v[42:45], v[164:167], v[172:175], 0
	v_mfma_f32_16x16x32_bf16 v[30:33], v[156:159], v[180:183], 0
	v_mfma_f32_16x16x32_bf16 v[26:29], v[164:167], v[180:183], 0
	v_mfma_f32_16x16x32_bf16 v[14:17], v[156:159], v[188:191], 0
	v_mfma_f32_16x16x32_bf16 v[10:13], v[164:167], v[188:191], 0
	v_mfma_f32_16x16x32_bf16 v[6:9], v[156:159], v[196:199], 0
	v_mfma_f32_16x16x32_bf16 v[2:5], v[164:167], v[196:199], 0
	v_mfma_f32_16x16x32_bf16 v[46:49], v[160:163], v[176:179], v[46:49]
	v_mfma_f32_16x16x32_bf16 v[42:45], v[168:171], v[176:179], v[42:45]
	v_mfma_f32_16x16x32_bf16 v[30:33], v[160:163], v[184:187], v[30:33]
	v_mfma_f32_16x16x32_bf16 v[26:29], v[168:171], v[184:187], v[26:29]
	v_mfma_f32_16x16x32_bf16 v[14:17], v[160:163], v[192:195], v[14:17]
	v_mfma_f32_16x16x32_bf16 v[10:13], v[168:171], v[192:195], v[10:13]
	v_mfma_f32_16x16x32_bf16 v[6:9], v[160:163], v[200:203], v[6:9]
	v_mfma_f32_16x16x32_bf16 v[2:5], v[168:171], v[200:203], v[2:5]
	s_setprio 0
	s_barrier
	v_add_u32_e32 v152, s66, v134
	v_add_u32_e32 v168, s65, v134
	ds_read_b128 v[140:143], v152
	ds_read_b128 v[144:147], v152 offset:1024
	ds_read_b128 v[148:151], v152 offset:2048
	ds_read_b128 v[152:155], v152 offset:3072
	ds_read_b128 v[156:159], v168
	ds_read_b128 v[160:163], v168 offset:1024
	ds_read_b128 v[164:167], v168 offset:2048
	ds_read_b128 v[168:171], v168 offset:3072
	s_mov_b32 m0, s53
	v_lshl_add_u64 v[212:213], s[36:37], 0, v[132:133]
	ds_read_b128 v[172:175], v139 offset:32768
	ds_read_b128 v[176:179], v139 offset:33792
	ds_read_b128 v[180:183], v139 offset:34816
	ds_read_b128 v[184:187], v139 offset:35840
	ds_read_b128 v[188:191], v139 offset:36864
	ds_read_b128 v[192:195], v139 offset:37888
	ds_read_b128 v[196:199], v139 offset:38912
	ds_read_b128 v[200:203], v139 offset:39936
	global_load_lds_dwordx4 v[212:213], off
	v_lshl_add_u64 v[212:213], s[36:37], 0, v[130:131]
	s_mov_b32 m0, s54
	s_nop 0
	global_load_lds_dwordx4 v[212:213], off
	s_waitcnt vmcnt(8)
	s_waitcnt lgkmcnt(0)
	s_barrier
	s_setprio 1
	s_waitcnt lgkmcnt(0)
	v_mfma_f32_16x16x32_bf16 v[126:129], v[140:143], v[172:175], v[126:129]
	v_mfma_f32_16x16x32_bf16 v[122:125], v[148:151], v[172:175], v[122:125]
	v_mfma_f32_16x16x32_bf16 v[118:121], v[140:143], v[180:183], v[118:121]
	v_mfma_f32_16x16x32_bf16 v[114:117], v[148:151], v[180:183], v[114:117]
	v_mfma_f32_16x16x32_bf16 v[106:109], v[140:143], v[188:191], v[106:109]
	v_mfma_f32_16x16x32_bf16 v[98:101], v[148:151], v[188:191], v[98:101]
	v_mfma_f32_16x16x32_bf16 v[90:93], v[140:143], v[196:199], v[90:93]
	v_mfma_f32_16x16x32_bf16 v[82:85], v[148:151], v[196:199], v[82:85]
	v_mfma_f32_16x16x32_bf16 v[126:129], v[144:147], v[176:179], v[126:129]
	v_mfma_f32_16x16x32_bf16 v[122:125], v[152:155], v[176:179], v[122:125]
	v_mfma_f32_16x16x32_bf16 v[118:121], v[144:147], v[184:187], v[118:121]
	v_mfma_f32_16x16x32_bf16 v[114:117], v[152:155], v[184:187], v[114:117]
	v_mfma_f32_16x16x32_bf16 v[106:109], v[144:147], v[192:195], v[106:109]
	v_mfma_f32_16x16x32_bf16 v[98:101], v[152:155], v[192:195], v[98:101]
	v_mfma_f32_16x16x32_bf16 v[90:93], v[144:147], v[200:203], v[90:93]
	v_mfma_f32_16x16x32_bf16 v[82:85], v[152:155], v[200:203], v[82:85]
	s_setprio 0
	s_setprio 1
	v_mfma_f32_16x16x32_bf16 v[110:113], v[156:159], v[172:175], v[110:113]
	v_mfma_f32_16x16x32_bf16 v[102:105], v[164:167], v[172:175], v[102:105]
	v_mfma_f32_16x16x32_bf16 v[94:97], v[156:159], v[180:183], v[94:97]
	v_mfma_f32_16x16x32_bf16 v[86:89], v[164:167], v[180:183], v[86:89]
	v_mfma_f32_16x16x32_bf16 v[78:81], v[156:159], v[188:191], v[78:81]
	v_mfma_f32_16x16x32_bf16 v[74:77], v[164:167], v[188:191], v[74:77]
	v_mfma_f32_16x16x32_bf16 v[70:73], v[156:159], v[196:199], v[70:73]
	v_mfma_f32_16x16x32_bf16 v[66:69], v[164:167], v[196:199], v[66:69]
	v_mfma_f32_16x16x32_bf16 v[110:113], v[160:163], v[176:179], v[110:113]
	v_mfma_f32_16x16x32_bf16 v[102:105], v[168:171], v[176:179], v[102:105]
	v_mfma_f32_16x16x32_bf16 v[94:97], v[160:163], v[184:187], v[94:97]
	v_mfma_f32_16x16x32_bf16 v[86:89], v[168:171], v[184:187], v[86:89]
	v_mfma_f32_16x16x32_bf16 v[78:81], v[160:163], v[192:195], v[78:81]
	v_mfma_f32_16x16x32_bf16 v[74:77], v[168:171], v[192:195], v[74:77]
	v_mfma_f32_16x16x32_bf16 v[70:73], v[160:163], v[200:203], v[70:73]
	v_mfma_f32_16x16x32_bf16 v[66:69], v[168:171], v[200:203], v[66:69]
	s_setprio 0
	s_barrier
; #define PG8_STAGE(bufoff, gbase, voff) do { _Pragma("unroll") for (int _i = 0; _i < 2; ++_i) \
;         __builtin_amdgcn_global_load_lds((const unsigned*)((const char*)(gbase) + (voff)[_i]), (PG8_LAS unsigned*)(lds + (bufoff) + ldsw + _i * 8192), 16, 0, 0); } while (0)
; #define PG8_LDA(dst, b, h) do { _Pragma("unroll") for (int m = 0; m < 4; ++m) _Pragma("unroll") for (int k = 0; k < 2; ++k) dst[m][k] = *(const PG8_LAS bf16x8*)(lds + PG8_SA(b, h) + aoff + m * 2048 + k * 1024); } while (0)
; #define PG8_WAIT_V(n) asm volatile("s_waitcnt vmcnt(" #n ")" ::: "memory")
; #define PG8_BAR __builtin_amdgcn_s_barrier()
; template <class Epi, class Sched, bool ALIGN_EPI = false, bool SP2 = false>
; __device__ __forceinline__ void gemm_phase(PG8_LAS unsigned char* lds, const Gemm g, const Sched& S, const Epi& E) {
;     ...
;         for (int t = 0; t < nt; t += 2) {
;             if constexpr (Epi::MIDHOOK) { if (t == (nt >> 1)) E.mid(acc, cur, wr, wc, fr, fq); }
;             const bool last = (t == nt - 2);
;             const char* a1 = cA + (size_t)(t + 1) * kstep;
;             const char* a2 = last ? nA : cA + (size_t)(t + 2) * kstep; const char* b2 = last ? nB : cB + (size_t)(t + 2) * kstep;
;             const char* a3 = a2 + kstep; const char* b3 = b2 + kstep;
;             if (last && has_next) S.a_ready(nxt);
;             if constexpr (SP2) {
;             PG8_LDB(B0, 0, 0); PG8_LDB(B1, 0, 1); PG8_SCHED; PG8_LDA(At, 0, 0); PG8_STAGE(PG8_SA(1, 1), a1 + hstep, voffA);
;             PG8_WAIT_V(8); PG8_WAIT_L(0); PG8_BAR; PG8_MMA(0, 0, At, B0); PG8_MMA(0, 1, At, B1); PG8_BAR; PG8_SCHED;
;             PG8_LDA(At, 0, 1); PG8_STAGE(PG8_SB(0, 0), b2, voffB); PG8_STAGE(PG8_SB(0, 1), b2 + hstep, voffB); PG8_STAGE(PG8_SA(0, 0), a2, voffA);
;             PG8_WAIT_V(8); PG8_WAIT_L(0); PG8_BAR; PG8_MMA(1, 0, At, B0); PG8_MMA(1, 1, At, B1); PG8_BAR; PG8_SCHED;
;             PG8_LDB(B0, 1, 0); PG8_LDB(B1, 1, 1); PG8_SCHED; PG8_LDA(At, 1, 0); PG8_STAGE(PG8_SA(0, 1), a2 + hstep, voffA);
;             PG8_WAIT_V(8); PG8_WAIT_L(0); PG8_BAR; PG8_MMA(0, 0, At, B0); PG8_MMA(0, 1, At, B1); PG8_BAR; PG8_SCHED;
;             PG8_LDA(At, 1, 1); PG8_STAGE(PG8_SB(1, 0), b3, voffB); PG8_STAGE(PG8_SB(1, 1), b3 + hstep, voffB); PG8_STAGE(PG8_SA(1, 0), a3, voffA);
;             PG8_WAIT_V(8); PG8_WAIT_L(0); PG8_BAR; PG8_MMA(1, 0, At, B0); PG8_MMA(1, 1, At, B1); PG8_BAR; PG8_SCHED;
	s_mov_b32 m0, s64
	v_lshl_add_u64 v[204:205], v[204:205], 0, s[12:13]
	ds_read_b128 v[172:175], v139 offset:49152
	ds_read_b128 v[176:179], v139 offset:50176
	ds_read_b128 v[180:183], v139 offset:51200
	ds_read_b128 v[184:187], v139 offset:52224
	ds_read_b128 v[188:191], v139 offset:53248
	ds_read_b128 v[192:195], v139 offset:54272
	ds_read_b128 v[196:199], v139 offset:55296
	ds_read_b128 v[200:203], v139 offset:56320
	global_load_lds_dwordx4 v[204:205], off
	v_lshl_add_u64 v[204:205], v[206:207], 0, s[12:13]
	s_mov_b32 m0, s21
	s_nop 0
	global_load_lds_dwordx4 v[204:205], off
	v_lshl_add_u64 v[204:205], s[30:31], 0, v[132:133]
	s_mov_b32 m0, s23
	s_nop 0
	global_load_lds_dwordx4 v[204:205], off
	v_lshl_add_u64 v[204:205], s[30:31], 0, v[130:131]
	s_mov_b32 m0, s7
	s_nop 0
	global_load_lds_dwordx4 v[204:205], off
	v_lshl_add_u64 v[204:205], v[208:209], 0, s[12:13]
	s_mov_b32 m0, s57
	s_nop 0
	global_load_lds_dwordx4 v[204:205], off
	v_lshl_add_u64 v[204:205], v[210:211], 0, s[12:13]
	s_mov_b32 m0, s58
	s_nop 0
	global_load_lds_dwordx4 v[204:205], off
	s_waitcnt vmcnt(8)
	s_waitcnt lgkmcnt(0)
	s_barrier
	s_setprio 1
	s_waitcnt lgkmcnt(0)
	v_mfma_f32_16x16x32_bf16 v[62:65], v[140:143], v[172:175], v[62:65]
	v_mfma_f32_16x16x32_bf16 v[58:61], v[148:151], v[172:175], v[58:61]
	v_mfma_f32_16x16x32_bf16 v[54:57], v[140:143], v[180:183], v[54:57]
	v_mfma_f32_16x16x32_bf16 v[50:53], v[148:151], v[180:183], v[50:53]
	v_mfma_f32_16x16x32_bf16 v[38:41], v[140:143], v[188:191], v[38:41]
	v_mfma_f32_16x16x32_bf16 v[34:37], v[148:151], v[188:191], v[34:37]
	v_mfma_f32_16x16x32_bf16 v[22:25], v[140:143], v[196:199], v[22:25]
	v_mfma_f32_16x16x32_bf16 v[18:21], v[148:151], v[196:199], v[18:21]
	v_mfma_f32_16x16x32_bf16 v[62:65], v[144:147], v[176:179], v[62:65]
	v_mfma_f32_16x16x32_bf16 v[58:61], v[152:155], v[176:179], v[58:61]
	v_mfma_f32_16x16x32_bf16 v[54:57], v[144:147], v[184:187], v[54:57]
	v_mfma_f32_16x16x32_bf16 v[50:53], v[152:155], v[184:187], v[50:53]
	v_mfma_f32_16x16x32_bf16 v[38:41], v[144:147], v[192:195], v[38:41]
	v_mfma_f32_16x16x32_bf16 v[34:37], v[152:155], v[192:195], v[34:37]
	v_mfma_f32_16x16x32_bf16 v[22:25], v[144:147], v[200:203], v[22:25]
	v_mfma_f32_16x16x32_bf16 v[18:21], v[152:155], v[200:203], v[18:21]
	s_setprio 0
	s_setprio 1
	v_mfma_f32_16x16x32_bf16 v[46:49], v[156:159], v[172:175], v[46:49]
	v_mfma_f32_16x16x32_bf16 v[42:45], v[164:167], v[172:175], v[42:45]
	v_mfma_f32_16x16x32_bf16 v[30:33], v[156:159], v[180:183], v[30:33]
	v_mfma_f32_16x16x32_bf16 v[26:29], v[164:167], v[180:183], v[26:29]
	v_mfma_f32_16x16x32_bf16 v[14:17], v[156:159], v[188:191], v[14:17]
	v_mfma_f32_16x16x32_bf16 v[10:13], v[164:167], v[188:191], v[10:13]
	v_mfma_f32_16x16x32_bf16 v[6:9], v[156:159], v[196:199], v[6:9]
	v_mfma_f32_16x16x32_bf16 v[2:5], v[164:167], v[196:199], v[2:5]
	v_mfma_f32_16x16x32_bf16 v[46:49], v[160:163], v[176:179], v[46:49]
	v_mfma_f32_16x16x32_bf16 v[42:45], v[168:171], v[176:179], v[42:45]
	v_mfma_f32_16x16x32_bf16 v[30:33], v[160:163], v[184:187], v[30:33]
	v_mfma_f32_16x16x32_bf16 v[26:29], v[168:171], v[184:187], v[26:29]
	v_mfma_f32_16x16x32_bf16 v[14:17], v[160:163], v[192:195], v[14:17]
	v_mfma_f32_16x16x32_bf16 v[10:13], v[168:171], v[192:195], v[10:13]
	v_mfma_f32_16x16x32_bf16 v[6:9], v[160:163], v[200:203], v[6:9]
	v_mfma_f32_16x16x32_bf16 v[2:5], v[168:171], v[200:203], v[2:5]
	s_setprio 0
	s_barrier
	s_movk_i32 s7, 0x100
	s_andn2_b64 vcc, exec, s[28:29]
	s_mov_b64 s[30:31], -1
	s_mov_b64 s[28:29], 0
	s_cbranch_vccnz .Lkx_1428
.LBB0_1428:
	s_add_u32 s21, s16, s7
	s_addc_u32 s23, s17, 0
	s_add_u32 s38, s21, 0x100
	s_addc_u32 s39, s23, 0
	s_and_b64 s[36:37], s[30:31], exec
	s_cselect_b32 s39, s25, s39
	s_cselect_b32 s38, s24, s38
	s_add_u32 s7, s14, s7
	s_addc_u32 s36, s15, 0
	s_add_u32 s7, s7, 0x100
	s_addc_u32 s36, s36, 0
	s_and_b64 s[30:31], s[30:31], exec
	s_cselect_b32 s41, s27, s36
	s_cselect_b32 s40, s26, s7
	s_add_u32 s46, s21, 0x80080
	s_addc_u32 s47, s23, 0
	s_add_i32 s70, s60, s44
	ds_read_b128 v[140:143], v137
	ds_read_b128 v[144:147], v137 offset:1024
	ds_read_b128 v[148:151], v137 offset:2048
	ds_read_b128 v[152:155], v137 offset:3072
	ds_read_b128 v[156:159], v138
	ds_read_b128 v[160:163], v138 offset:1024
	ds_read_b128 v[164:167], v138 offset:2048
	ds_read_b128 v[168:171], v138 offset:3072
	s_add_i32 m0, s51, 0xc000
	s_add_i32 s71, s51, 0xe000
	s_add_i32 s67, s70, 0x2000
	s_add_u32 s42, s40, 0x80000
	s_addc_u32 s43, s41, 0
	s_add_i32 s69, s61, s44
	s_add_i32 s68, s69, 0x2000
	s_add_i32 s66, 0, 0x18000
	s_add_i32 s65, 0, 0x1c000
	s_add_u32 s36, s38, 0x80000
	s_addc_u32 s37, s39, 0
	s_add_i32 s64, s66, s44
	s_add_i32 s21, s64, 0x2000
	s_add_u32 s30, s40, 0x80080
	s_addc_u32 s31, s41, 0
	s_add_i32 s23, s65, s44
	s_add_i32 s7, s23, 0x2000
	v_lshl_add_u64 v[204:205], s[46:47], 0, v[132:133]
	ds_read_b128 v[172:175], v139
	ds_read_b128 v[176:179], v139 offset:1024
	ds_read_b128 v[180:183], v139 offset:2048
	ds_read_b128 v[184:187], v139 offset:3072
	ds_read_b128 v[188:191], v139 offset:4096
	ds_read_b128 v[192:195], v139 offset:5120
	ds_read_b128 v[196:199], v139 offset:6144
	ds_read_b128 v[200:203], v139 offset:7168
	global_load_lds_dwordx4 v[204:205], off
	v_lshl_add_u64 v[204:205], s[46:47], 0, v[130:131]
	s_mov_b32 m0, s71
	s_nop 0
	global_load_lds_dwordx4 v[204:205], off
	s_waitcnt vmcnt(8)
	s_waitcnt lgkmcnt(0)
	s_barrier
; #define PG8_STAGE(bufoff, gbase, voff) do { _Pragma("unroll") for (int _i = 0; _i < 2; ++_i) \
;         __builtin_amdgcn_global_load_lds((const unsigned*)((const char*)(gbase) + (voff)[_i]), (PG8_LAS unsigned*)(lds + (bufoff) + ldsw + _i * 8192), 16, 0, 0); } while (0)
; #define PG8_LDA(dst, b, h) do { _Pragma("unroll") for (int m = 0; m < 4; ++m) _Pragma("unroll") for (int k = 0; k < 2; ++k) dst[m][k] = *(const PG8_LAS bf16x8*)(lds + PG8_SA(b, h) + aoff + m * 2048 + k * 1024); } while (0)
; #define PG8_LDB(dst, b, h) do { _Pragma("unroll") for (int n = 0; n < 2; ++n) _Pragma("unroll") for (int k = 0; k < 2; ++k) dst[n][k] = *(const PG8_LAS bf16x8*)(lds + PG8_SB(b, h) + boff + n * 2048 + k * 1024); } while (0)
; #define PG8_MMA(ai, bj, At, Bt) do { __builtin_amdgcn_s_setprio(1); _Pragma("unroll") for (int m = 0; m < 4; ++m) _Pragma("unroll") for (int n = 0; n < 2; ++n) _Pragma("unroll") for (int k = 0; k < 2; ++k) \
;         acc[ai][bj][m][n] = __builtin_amdgcn_mfma_f32_16x16x32_bf16(Bt[n][k], At[m][k], acc[ai][bj][m][n], 0, 0, 0); __builtin_amdgcn_s_setprio(0); } while (0)
; #define PG8_WAIT_V(n) asm volatile("s_waitcnt vmcnt(" #n ")" ::: "memory")
; #define PG8_WAIT_L(n) asm volatile("s_waitcnt lgkmcnt(" #n ")" ::: "memory")
; #define PG8_BAR __builtin_amdgcn_s_barrier()
; #define PG8_SCHED __builtin_amdgcn_sched_barrier(0)
; template <class Epi, class Sched, bool ALIGN_EPI = false, bool SP2 = false>
; __device__ __forceinline__ void gemm_phase(PG8_LAS unsigned char* lds, const Gemm g, const Sched& S, const Epi& E) {
;     ...
;             PG8_LDB(B0, 0, 0); PG8_LDB(B1, 0, 1); PG8_SCHED; PG8_LDA(At, 0, 0); PG8_STAGE(PG8_SA(1, 1), a1 + hstep, voffA);
;             PG8_WAIT_V(8); PG8_WAIT_L(0); PG8_BAR; PG8_MMA(0, 0, At, B0); PG8_MMA(0, 1, At, B1); PG8_BAR; PG8_SCHED;
;             PG8_LDA(At, 0, 1); PG8_STAGE(PG8_SB(0, 0), b2, voffB); PG8_STAGE(PG8_SB(0, 1), b2 + hstep, voffB); PG8_STAGE(PG8_SA(0, 0), a2, voffA);
;             PG8_WAIT_V(8); PG8_WAIT_L(0); PG8_BAR; PG8_MMA(1, 0, At, B0); PG8_MMA(1, 1, At, B1); PG8_BAR; PG8_SCHED;
	s_setprio 1
	s_waitcnt lgkmcnt(0)
	v_mfma_f32_16x16x32_bf16 v[126:129], v[140:143], v[172:175], v[126:129]
	v_mfma_f32_16x16x32_bf16 v[122:125], v[148:151], v[172:175], v[122:125]
	v_mfma_f32_16x16x32_bf16 v[118:121], v[140:143], v[180:183], v[118:121]
	v_mfma_f32_16x16x32_bf16 v[114:117], v[148:151], v[180:183], v[114:117]
	v_mfma_f32_16x16x32_bf16 v[106:109], v[140:143], v[188:191], v[106:109]
	v_mfma_f32_16x16x32_bf16 v[98:101], v[148:151], v[188:191], v[98:101]
	v_mfma_f32_16x16x32_bf16 v[90:93], v[140:143], v[196:199], v[90:93]
	v_mfma_f32_16x16x32_bf16 v[82:85], v[148:151], v[196:199], v[82:85]
	v_mfma_f32_16x16x32_bf16 v[126:129], v[144:147], v[176:179], v[126:129]
	v_mfma_f32_16x16x32_bf16 v[122:125], v[152:155], v[176:179], v[122:125]
	v_mfma_f32_16x16x32_bf16 v[118:121], v[144:147], v[184:187], v[118:121]
	v_mfma_f32_16x16x32_bf16 v[114:117], v[152:155], v[184:187], v[114:117]
	v_mfma_f32_16x16x32_bf16 v[106:109], v[144:147], v[192:195], v[106:109]
	v_mfma_f32_16x16x32_bf16 v[98:101], v[152:155], v[192:195], v[98:101]
	v_mfma_f32_16x16x32_bf16 v[90:93], v[144:147], v[200:203], v[90:93]
	v_mfma_f32_16x16x32_bf16 v[82:85], v[152:155], v[200:203], v[82:85]
	s_setprio 0
	s_setprio 1
	v_mfma_f32_16x16x32_bf16 v[110:113], v[156:159], v[172:175], v[110:113]
	v_mfma_f32_16x16x32_bf16 v[102:105], v[164:167], v[172:175], v[102:105]
	v_mfma_f32_16x16x32_bf16 v[94:97], v[156:159], v[180:183], v[94:97]
	v_mfma_f32_16x16x32_bf16 v[86:89], v[164:167], v[180:183], v[86:89]
	v_mfma_f32_16x16x32_bf16 v[78:81], v[156:159], v[188:191], v[78:81]
	v_mfma_f32_16x16x32_bf16 v[74:77], v[164:167], v[188:191], v[74:77]
	v_mfma_f32_16x16x32_bf16 v[70:73], v[156:159], v[196:199], v[70:73]
	v_mfma_f32_16x16x32_bf16 v[66:69], v[164:167], v[196:199], v[66:69]
	v_mfma_f32_16x16x32_bf16 v[110:113], v[160:163], v[176:179], v[110:113]
	v_mfma_f32_16x16x32_bf16 v[102:105], v[168:171], v[176:179], v[102:105]
	v_mfma_f32_16x16x32_bf16 v[94:97], v[160:163], v[184:187], v[94:97]
	v_mfma_f32_16x16x32_bf16 v[86:89], v[168:171], v[184:187], v[86:89]
	v_mfma_f32_16x16x32_bf16 v[78:81], v[160:163], v[192:195], v[78:81]
	v_mfma_f32_16x16x32_bf16 v[74:77], v[168:171], v[192:195], v[74:77]
	v_mfma_f32_16x16x32_bf16 v[70:73], v[160:163], v[200:203], v[70:73]
	v_mfma_f32_16x16x32_bf16 v[66:69], v[168:171], v[200:203], v[66:69]
	s_setprio 0
	s_barrier
	s_mov_b32 m0, s70
	v_lshl_add_u64 v[204:205], s[40:41], 0, v[132:133]
	ds_read_b128 v[172:175], v139 offset:16384
	ds_read_b128 v[176:179], v139 offset:17408
	ds_read_b128 v[180:183], v139 offset:18432
	ds_read_b128 v[184:187], v139 offset:19456
	ds_read_b128 v[188:191], v139 offset:20480
	ds_read_b128 v[192:195], v139 offset:21504
	ds_read_b128 v[196:199], v139 offset:22528
	ds_read_b128 v[200:203], v139 offset:23552
	global_load_lds_dwordx4 v[204:205], off
	v_lshl_add_u64 v[206:207], s[40:41], 0, v[130:131]
	s_mov_b32 m0, s67
	v_lshl_add_u64 v[208:209], s[42:43], 0, v[132:133]
	global_load_lds_dwordx4 v[206:207], off
	s_mov_b32 m0, s69
	v_lshl_add_u64 v[210:211], s[38:39], 0, v[130:131]
	global_load_lds_dwordx4 v[208:209], off
	v_lshl_add_u64 v[208:209], s[42:43], 0, v[130:131]
	s_mov_b32 m0, s68
	s_nop 0
	global_load_lds_dwordx4 v[208:209], off
	v_lshl_add_u64 v[208:209], s[38:39], 0, v[132:133]
	s_mov_b32 m0, s51
	s_nop 0
	global_load_lds_dwordx4 v[208:209], off
	s_mov_b32 m0, s52
	s_nop 0
	global_load_lds_dwordx4 v[210:211], off
	s_waitcnt vmcnt(8)
	s_waitcnt lgkmcnt(0)
	s_barrier
	s_setprio 1
	s_waitcnt lgkmcnt(0)
	v_mfma_f32_16x16x32_bf16 v[62:65], v[140:143], v[172:175], v[62:65]
	v_mfma_f32_16x16x32_bf16 v[58:61], v[148:151], v[172:175], v[58:61]
	v_mfma_f32_16x16x32_bf16 v[54:57], v[140:143], v[180:183], v[54:57]
	v_mfma_f32_16x16x32_bf16 v[50:53], v[148:151], v[180:183], v[50:53]
	v_mfma_f32_16x16x32_bf16 v[38:41], v[140:143], v[188:191], v[38:41]
	v_mfma_f32_16x16x32_bf16 v[34:37], v[148:151], v[188:191], v[34:37]
	v_mfma_f32_16x16x32_bf16 v[22:25], v[140:143], v[196:199], v[22:25]
	v_mfma_f32_16x16x32_bf16 v[18:21], v[148:151], v[196:199], v[18:21]
	v_mfma_f32_16x16x32_bf16 v[62:65], v[144:147], v[176:179], v[62:65]
	v_mfma_f32_16x16x32_bf16 v[58:61], v[152:155], v[176:179], v[58:61]
	v_mfma_f32_16x16x32_bf16 v[54:57], v[144:147], v[184:187], v[54:57]
	v_mfma_f32_16x16x32_bf16 v[50:53], v[152:155], v[184:187], v[50:53]
	v_mfma_f32_16x16x32_bf16 v[38:41], v[144:147], v[192:195], v[38:41]
	v_mfma_f32_16x16x32_bf16 v[34:37], v[152:155], v[192:195], v[34:37]
	v_mfma_f32_16x16x32_bf16 v[22:25], v[144:147], v[200:203], v[22:25]
	v_mfma_f32_16x16x32_bf16 v[18:21], v[152:155], v[200:203], v[18:21]
	s_setprio 0
	s_setprio 1
	v_mfma_f32_16x16x32_bf16 v[46:49], v[156:159], v[172:175], v[46:49]
	v_mfma_f32_16x16x32_bf16 v[42:45], v[164:167], v[172:175], v[42:45]
	v_mfma_f32_16x16x32_bf16 v[30:33], v[156:159], v[180:183], v[30:33]
	v_mfma_f32_16x16x32_bf16 v[26:29], v[164:167], v[180:183], v[26:29]
	v_mfma_f32_16x16x32_bf16 v[14:17], v[156:159], v[188:191], v[14:17]
	v_mfma_f32_16x16x32_bf16 v[10:13], v[164:167], v[188:191], v[10:13]
	v_mfma_f32_16x16x32_bf16 v[6:9], v[156:159], v[196:199], v[6:9]
	v_mfma_f32_16x16x32_bf16 v[2:5], v[164:167], v[196:199], v[2:5]
	v_mfma_f32_16x16x32_bf16 v[46:49], v[160:163], v[176:179], v[46:49]
	v_mfma_f32_16x16x32_bf16 v[42:45], v[168:171], v[176:179], v[42:45]
	v_mfma_f32_16x16x32_bf16 v[30:33], v[160:163], v[184:187], v[30:33]
	v_mfma_f32_16x16x32_bf16 v[26:29], v[168:171], v[184:187], v[26:29]
	v_mfma_f32_16x16x32_bf16 v[14:17], v[160:163], v[192:195], v[14:17]
	v_mfma_f32_16x16x32_bf16 v[10:13], v[168:171], v[192:195], v[10:13]
	v_mfma_f32_16x16x32_bf16 v[6:9], v[160:163], v[200:203], v[6:9]
	v_mfma_f32_16x16x32_bf16 v[2:5], v[168:171], v[200:203], v[2:5]
	s_setprio 0
	s_barrier
; #define PG8_STAGE(bufoff, gbase, voff) do { _Pragma("unroll") for (int _i = 0; _i < 2; ++_i) \
;         __builtin_amdgcn_global_load_lds((const unsigned*)((const char*)(gbase) + (voff)[_i]), (PG8_LAS unsigned*)(lds + (bufoff) + ldsw + _i * 8192), 16, 0, 0); } while (0)
; #define PG8_LDA(dst, b, h) do { _Pragma("unroll") for (int m = 0; m < 4; ++m) _Pragma("unroll") for (int k = 0; k < 2; ++k) dst[m][k] = *(const PG8_LAS bf16x8*)(lds + PG8_SA(b, h) + aoff + m * 2048 + k * 1024); } while (0)
; #define PG8_LDB(dst, b, h) do { _Pragma("unroll") for (int n = 0; n < 2; ++n) _Pragma("unroll") for (int k = 0; k < 2; ++k) dst[n][k] = *(const PG8_LAS bf16x8*)(lds + PG8_SB(b, h) + boff + n * 2048 + k * 1024); } while (0)
; #define PG8_MMA(ai, bj, At, Bt) do { __builtin_amdgcn_s_setprio(1); _Pragma("unroll") for (int m = 0; m < 4; ++m) _Pragma("unroll") for (int n = 0; n < 2; ++n) _Pragma("unroll") for (int k = 0; k < 2; ++k) \
;         acc[ai][bj][m][n] = __builtin_amdgcn_mfma_f32_16x16x32_bf16(Bt[n][k], At[m][k], acc[ai][bj][m][n], 0, 0, 0); __builtin_amdgcn_s_setprio(0); } while (0)
; #define PG8_WAIT_V(n) asm volatile("s_waitcnt vmcnt(" #n ")" ::: "memory")
; #define PG8_WAIT_L(n) asm volatile("s_waitcnt lgkmcnt(" #n ")" ::: "memory")
; #define PG8_BAR __builtin_amdgcn_s_barrier()
; #define PG8_SCHED __builtin_amdgcn_sched_barrier(0)
; template <class Epi, class Sched, bool ALIGN_EPI = false, bool SP2 = false>
; __device__ __forceinline__ void gemm_phase(PG8_LAS unsigned char* lds, const Gemm g, const Sched& S, const Epi& E) {
;     ...
;             PG8_LDB(B0, 1, 0); PG8_LDB(B1, 1, 1); PG8_SCHED; PG8_LDA(At, 1, 0); PG8_STAGE(PG8_SA(0, 1), a2 + hstep, voffA);
;             PG8_WAIT_V(8); PG8_WAIT_L(0); PG8_BAR; PG8_MMA(0, 0, At, B0); PG8_MMA(0, 1, At, B1); PG8_BAR; PG8_SCHED;
;             PG8_LDA(At, 1, 1); PG8_STAGE(PG8_SB(1, 0), b3, voffB); PG8_STAGE(PG8_SB(1, 1), b3 + hstep, voffB); PG8_STAGE(PG8_SA(1, 0), a3, voffA);
;             PG8_WAIT_V(8); PG8_WAIT_L(0); PG8_BAR; PG8_MMA(1, 0, At, B0); PG8_MMA(1, 1, At, B1); PG8_BAR; PG8_SCHED;
	v_add_u32_e32 v152, s66, v134
	v_add_u32_e32 v168, s65, v134
	ds_read_b128 v[140:143], v152
	ds_read_b128 v[144:147], v152 offset:1024
	ds_read_b128 v[148:151], v152 offset:2048
	ds_read_b128 v[152:155], v152 offset:3072
	ds_read_b128 v[156:159], v168
	ds_read_b128 v[160:163], v168 offset:1024
	ds_read_b128 v[164:167], v168 offset:2048
	ds_read_b128 v[168:171], v168 offset:3072
	s_mov_b32 m0, s53
	v_lshl_add_u64 v[212:213], s[36:37], 0, v[132:133]
	ds_read_b128 v[172:175], v139 offset:32768
	ds_read_b128 v[176:179], v139 offset:33792
	ds_read_b128 v[180:183], v139 offset:34816
	ds_read_b128 v[184:187], v139 offset:35840
	ds_read_b128 v[188:191], v139 offset:36864
	ds_read_b128 v[192:195], v139 offset:37888
	ds_read_b128 v[196:199], v139 offset:38912
	ds_read_b128 v[200:203], v139 offset:39936
	global_load_lds_dwordx4 v[212:213], off
	v_lshl_add_u64 v[212:213], s[36:37], 0, v[130:131]
	s_mov_b32 m0, s54
	s_nop 0
	global_load_lds_dwordx4 v[212:213], off
	s_waitcnt vmcnt(8)
	s_waitcnt lgkmcnt(0)
	s_barrier
	s_setprio 1
	s_waitcnt lgkmcnt(0)
	v_mfma_f32_16x16x32_bf16 v[126:129], v[140:143], v[172:175], v[126:129]
	v_mfma_f32_16x16x32_bf16 v[122:125], v[148:151], v[172:175], v[122:125]
	v_mfma_f32_16x16x32_bf16 v[118:121], v[140:143], v[180:183], v[118:121]
	v_mfma_f32_16x16x32_bf16 v[114:117], v[148:151], v[180:183], v[114:117]
	v_mfma_f32_16x16x32_bf16 v[106:109], v[140:143], v[188:191], v[106:109]
	v_mfma_f32_16x16x32_bf16 v[98:101], v[148:151], v[188:191], v[98:101]
	v_mfma_f32_16x16x32_bf16 v[90:93], v[140:143], v[196:199], v[90:93]
	v_mfma_f32_16x16x32_bf16 v[82:85], v[148:151], v[196:199], v[82:85]
	v_mfma_f32_16x16x32_bf16 v[126:129], v[144:147], v[176:179], v[126:129]
	v_mfma_f32_16x16x32_bf16 v[122:125], v[152:155], v[176:179], v[122:125]
	v_mfma_f32_16x16x32_bf16 v[118:121], v[144:147], v[184:187], v[118:121]
	v_mfma_f32_16x16x32_bf16 v[114:117], v[152:155], v[184:187], v[114:117]
	v_mfma_f32_16x16x32_bf16 v[106:109], v[144:147], v[192:195], v[106:109]
	v_mfma_f32_16x16x32_bf16 v[98:101], v[152:155], v[192:195], v[98:101]
	v_mfma_f32_16x16x32_bf16 v[90:93], v[144:147], v[200:203], v[90:93]
	v_mfma_f32_16x16x32_bf16 v[82:85], v[152:155], v[200:203], v[82:85]
	s_setprio 0
	s_setprio 1
	v_mfma_f32_16x16x32_bf16 v[110:113], v[156:159], v[172:175], v[110:113]
	v_mfma_f32_16x16x32_bf16 v[102:105], v[164:167], v[172:175], v[102:105]
	v_mfma_f32_16x16x32_bf16 v[94:97], v[156:159], v[180:183], v[94:97]
	v_mfma_f32_16x16x32_bf16 v[86:89], v[164:167], v[180:183], v[86:89]
	v_mfma_f32_16x16x32_bf16 v[78:81], v[156:159], v[188:191], v[78:81]
	v_mfma_f32_16x16x32_bf16 v[74:77], v[164:167], v[188:191], v[74:77]
	v_mfma_f32_16x16x32_bf16 v[70:73], v[156:159], v[196:199], v[70:73]
	v_mfma_f32_16x16x32_bf16 v[66:69], v[164:167], v[196:199], v[66:69]
	v_mfma_f32_16x16x32_bf16 v[110:113], v[160:163], v[176:179], v[110:113]
	v_mfma_f32_16x16x32_bf16 v[102:105], v[168:171], v[176:179], v[102:105]
	v_mfma_f32_16x16x32_bf16 v[94:97], v[160:163], v[184:187], v[94:97]
	v_mfma_f32_16x16x32_bf16 v[86:89], v[168:171], v[184:187], v[86:89]
	v_mfma_f32_16x16x32_bf16 v[78:81], v[160:163], v[192:195], v[78:81]
	v_mfma_f32_16x16x32_bf16 v[74:77], v[168:171], v[192:195], v[74:77]
	v_mfma_f32_16x16x32_bf16 v[70:73], v[160:163], v[200:203], v[70:73]
	v_mfma_f32_16x16x32_bf16 v[66:69], v[168:171], v[200:203], v[66:69]
	s_setprio 0
	s_barrier
	s_mov_b32 m0, s64
	v_lshl_add_u64 v[204:205], v[204:205], 0, s[12:13]
	ds_read_b128 v[172:175], v139 offset:49152
	ds_read_b128 v[176:179], v139 offset:50176
	ds_read_b128 v[180:183], v139 offset:51200
	ds_read_b128 v[184:187], v139 offset:52224
	ds_read_b128 v[188:191], v139 offset:53248
	ds_read_b128 v[192:195], v139 offset:54272
	ds_read_b128 v[196:199], v139 offset:55296
	ds_read_b128 v[200:203], v139 offset:56320
	global_load_lds_dwordx4 v[204:205], off
	v_lshl_add_u64 v[204:205], v[206:207], 0, s[12:13]
	s_mov_b32 m0, s21
	s_nop 0
	global_load_lds_dwordx4 v[204:205], off
	v_lshl_add_u64 v[204:205], s[30:31], 0, v[132:133]
	s_mov_b32 m0, s23
	s_nop 0
	global_load_lds_dwordx4 v[204:205], off
	v_lshl_add_u64 v[204:205], s[30:31], 0, v[130:131]
	s_mov_b32 m0, s7
	s_nop 0
	global_load_lds_dwordx4 v[204:205], off
	v_lshl_add_u64 v[204:205], v[208:209], 0, s[12:13]
	s_mov_b32 m0, s57
	s_nop 0
	global_load_lds_dwordx4 v[204:205], off
	v_lshl_add_u64 v[204:205], v[210:211], 0, s[12:13]
	s_mov_b32 m0, s58
	s_nop 0
	global_load_lds_dwordx4 v[204:205], off
	s_waitcnt vmcnt(8)
	s_waitcnt lgkmcnt(0)
	s_barrier
	s_setprio 1
	s_waitcnt lgkmcnt(0)
	v_mfma_f32_16x16x32_bf16 v[62:65], v[140:143], v[172:175], v[62:65]
	v_mfma_f32_16x16x32_bf16 v[58:61], v[148:151], v[172:175], v[58:61]
	v_mfma_f32_16x16x32_bf16 v[54:57], v[140:143], v[180:183], v[54:57]
	v_mfma_f32_16x16x32_bf16 v[50:53], v[148:151], v[180:183], v[50:53]
	v_mfma_f32_16x16x32_bf16 v[38:41], v[140:143], v[188:191], v[38:41]
	v_mfma_f32_16x16x32_bf16 v[34:37], v[148:151], v[188:191], v[34:37]
	v_mfma_f32_16x16x32_bf16 v[22:25], v[140:143], v[196:199], v[22:25]
	v_mfma_f32_16x16x32_bf16 v[18:21], v[148:151], v[196:199], v[18:21]
	v_mfma_f32_16x16x32_bf16 v[62:65], v[144:147], v[176:179], v[62:65]
	v_mfma_f32_16x16x32_bf16 v[58:61], v[152:155], v[176:179], v[58:61]
	v_mfma_f32_16x16x32_bf16 v[54:57], v[144:147], v[184:187], v[54:57]
	v_mfma_f32_16x16x32_bf16 v[50:53], v[152:155], v[184:187], v[50:53]
	v_mfma_f32_16x16x32_bf16 v[38:41], v[144:147], v[192:195], v[38:41]
	v_mfma_f32_16x16x32_bf16 v[34:37], v[152:155], v[192:195], v[34:37]
	v_mfma_f32_16x16x32_bf16 v[22:25], v[144:147], v[200:203], v[22:25]
	v_mfma_f32_16x16x32_bf16 v[18:21], v[152:155], v[200:203], v[18:21]
	s_setprio 0
	s_setprio 1
	v_mfma_f32_16x16x32_bf16 v[46:49], v[156:159], v[172:175], v[46:49]
	v_mfma_f32_16x16x32_bf16 v[42:45], v[164:167], v[172:175], v[42:45]
	v_mfma_f32_16x16x32_bf16 v[30:33], v[156:159], v[180:183], v[30:33]
	v_mfma_f32_16x16x32_bf16 v[26:29], v[164:167], v[180:183], v[26:29]
	v_mfma_f32_16x16x32_bf16 v[14:17], v[156:159], v[188:191], v[14:17]
	v_mfma_f32_16x16x32_bf16 v[10:13], v[164:167], v[188:191], v[10:13]
	v_mfma_f32_16x16x32_bf16 v[6:9], v[156:159], v[196:199], v[6:9]
	v_mfma_f32_16x16x32_bf16 v[2:5], v[164:167], v[196:199], v[2:5]
	v_mfma_f32_16x16x32_bf16 v[46:49], v[160:163], v[176:179], v[46:49]
	v_mfma_f32_16x16x32_bf16 v[42:45], v[168:171], v[176:179], v[42:45]
	v_mfma_f32_16x16x32_bf16 v[30:33], v[160:163], v[184:187], v[30:33]
	v_mfma_f32_16x16x32_bf16 v[26:29], v[168:171], v[184:187], v[26:29]
	v_mfma_f32_16x16x32_bf16 v[14:17], v[160:163], v[192:195], v[14:17]
	v_mfma_f32_16x16x32_bf16 v[10:13], v[168:171], v[192:195], v[10:13]
	v_mfma_f32_16x16x32_bf16 v[6:9], v[160:163], v[200:203], v[6:9]
	v_mfma_f32_16x16x32_bf16 v[2:5], v[168:171], v[200:203], v[2:5]
	s_setprio 0
	s_barrier
	s_movk_i32 s7, 0x100
	s_andn2_b64 vcc, exec, s[28:29]
	s_mov_b64 s[30:31], -1
	s_mov_b64 s[28:29], 0
	s_cbranch_vccz .LBB0_1428

; #define PG8_STAGE(bufoff, gbase, voff) do { _Pragma("unroll") for (int _i = 0; _i < 2; ++_i) \
;         __builtin_amdgcn_global_load_lds((const unsigned*)((const char*)(gbase) + (voff)[_i]), (PG8_LAS unsigned*)(lds + (bufoff) + ldsw + _i * 8192), 16, 0, 0); } while (0)
; #define PG8_LDA(dst, b, h) do { _Pragma("unroll") for (int m = 0; m < 4; ++m) _Pragma("unroll") for (int k = 0; k < 2; ++k) dst[m][k] = *(const PG8_LAS bf16x8*)(lds + PG8_SA(b, h) + aoff + m * 2048 + k * 1024); } while (0)
; #define PG8_WAIT_V(n) asm volatile("s_waitcnt vmcnt(" #n ")" ::: "memory")
; #define PG8_BAR __builtin_amdgcn_s_barrier()
; template <class Epi, class Sched, bool ALIGN_EPI = false, bool SP2 = false>
; __device__ __forceinline__ void gemm_phase(PG8_LAS unsigned char* lds, const Gemm g, const Sched& S, const Epi& E) {
;     ...
;         const char* nA = has_next ? (const char*)g.A + (size_t)nxt.pm * tstep + (size_t)nxt.kt0 * kstep : cA; const char* nB = has_next ? (const char*)g.Bt + (size_t)nxt.pn * tstep + (size_t)nxt.kt0 * kstep : cB;
;         for (int t = 0; t < nt; t += 2) {
;             if constexpr (Epi::MIDHOOK) { if (t == (nt >> 1)) E.mid(acc, cur, wr, wc, fr, fq); }
;             const bool last = (t == nt - 2);
;             const char* a1 = cA + (size_t)(t + 1) * kstep;
;             const char* a2 = last ? nA : cA + (size_t)(t + 2) * kstep; const char* b2 = last ? nB : cB + (size_t)(t + 2) * kstep;
;             const char* a3 = a2 + kstep; const char* b3 = b2 + kstep;
;             if (last && has_next) S.a_ready(nxt);
;             if constexpr (SP2) {
;             PG8_LDB(B0, 0, 0); PG8_LDB(B1, 0, 1); PG8_SCHED; PG8_LDA(At, 0, 0); PG8_STAGE(PG8_SA(1, 1), a1 + hstep, voffA);
;             PG8_WAIT_V(8); PG8_WAIT_L(0); PG8_BAR; PG8_MMA(0, 0, At, B0); PG8_MMA(0, 1, At, B1); PG8_BAR; PG8_SCHED;
;             PG8_LDA(At, 0, 1); PG8_STAGE(PG8_SB(0, 0), b2, voffB); PG8_STAGE(PG8_SB(0, 1), b2 + hstep, voffB); PG8_STAGE(PG8_SA(0, 0), a2, voffA);
;             PG8_WAIT_V(8); PG8_WAIT_L(0); PG8_BAR; PG8_MMA(1, 0, At, B0); PG8_MMA(1, 1, At, B1); PG8_BAR; PG8_SCHED;
;     ...
; #pragma unroll
;         for (int a = 0; a < 2; ++a)
; #pragma unroll
;             for (int b = 0; b < 2; ++b)
; #pragma unroll
;                 for (int m = 0; m < 4; ++m)
; #pragma unroll
;                     for (int n = 0; n < 2; ++n) acc[a][b][m][n] = (f32x4){0.f, 0.f, 0.f, 0.f};
.LBB0_1550:
	s_ashr_i32 s17, s16, 31
	s_lshl_b64 s[18:19], s[16:17], 20
	s_add_u32 s18, s94, s18
	s_addc_u32 s19, s95, s19
	s_and_b64 s[20:21], s[0:1], exec
	s_cselect_b32 s17, s19, s25
	s_cselect_b32 s48, s18, s24
	s_ashr_i32 s15, s14, 31
	s_lshl_b64 s[20:21], s[14:15], 20
	s_add_u32 s20, s3, s20
	s_addc_u32 s21, s30, s21
	s_and_b64 s[28:29], s[0:1], exec
	s_cselect_b32 s15, s21, s27
	s_cselect_b32 s49, s20, s26
	s_add_u32 s24, s24, 0x80080
	s_addc_u32 s25, s25, 0
	s_add_u32 s50, s26, 0x100
	s_addc_u32 s51, s27, 0
	s_mov_b32 s52, -2
	s_waitcnt lgkmcnt(0)
	ds_read_b128 v[146:149], v153
	ds_read_b128 v[156:159], v153 offset:1024
	ds_read_b128 v[160:163], v153 offset:2048
	ds_read_b128 v[164:167], v153 offset:3072
	ds_read_b128 v[168:171], v154
	ds_read_b128 v[172:175], v154 offset:1024
	ds_read_b128 v[176:179], v154 offset:2048
	ds_read_b128 v[180:183], v154 offset:3072
	s_add_u32 s26, s24, 0xfff80080
	s_addc_u32 s27, s25, -1
	s_cmp_eq_u32 s52, 28
	s_cselect_b32 s29, s17, s27
	s_cselect_b32 s28, s48, s26
	s_cselect_b32 s27, s15, s51
	s_cselect_b32 s26, s49, s50
	v_lshl_add_u64 v[216:217], s[24:25], 0, v[138:139]
	s_add_i32 m0, s23, 0xc000
	ds_read_b128 v[184:187], v155
	ds_read_b128 v[188:191], v155 offset:1024
	ds_read_b128 v[192:195], v155 offset:2048
	ds_read_b128 v[196:199], v155 offset:3072
	ds_read_b128 v[200:203], v155 offset:4096
	ds_read_b128 v[204:207], v155 offset:5120
	ds_read_b128 v[208:211], v155 offset:6144
	ds_read_b128 v[212:215], v155 offset:7168
	global_load_lds_dwordx4 v[216:217], off
	v_lshl_add_u64 v[216:217], s[24:25], 0, v[140:141]
	s_add_i32 m0, s23, 0xe000
	s_nop 0
	global_load_lds_dwordx4 v[216:217], off
	s_waitcnt vmcnt(8)
	s_waitcnt lgkmcnt(0)
	s_barrier
	s_setprio 1
	s_waitcnt lgkmcnt(0)
	v_mfma_f32_16x16x32_bf16 v[126:129], v[146:149], v[184:187], 0
	v_mfma_f32_16x16x32_bf16 v[122:125], v[160:163], v[184:187], 0
	v_mfma_f32_16x16x32_bf16 v[110:113], v[146:149], v[192:195], 0
	v_mfma_f32_16x16x32_bf16 v[106:109], v[160:163], v[192:195], 0
	v_mfma_f32_16x16x32_bf16 v[94:97], v[146:149], v[200:203], 0
	v_mfma_f32_16x16x32_bf16 v[90:93], v[160:163], v[200:203], 0
	v_mfma_f32_16x16x32_bf16 v[78:81], v[146:149], v[208:211], 0
	v_mfma_f32_16x16x32_bf16 v[74:77], v[160:163], v[208:211], 0
	v_mfma_f32_16x16x32_bf16 v[126:129], v[156:159], v[188:191], v[126:129]
	v_mfma_f32_16x16x32_bf16 v[122:125], v[164:167], v[188:191], v[122:125]
	v_mfma_f32_16x16x32_bf16 v[110:113], v[156:159], v[196:199], v[110:113]
	v_mfma_f32_16x16x32_bf16 v[106:109], v[164:167], v[196:199], v[106:109]
	v_mfma_f32_16x16x32_bf16 v[94:97], v[156:159], v[204:207], v[94:97]
	v_mfma_f32_16x16x32_bf16 v[90:93], v[164:167], v[204:207], v[90:93]
	v_mfma_f32_16x16x32_bf16 v[78:81], v[156:159], v[212:215], v[78:81]
	v_mfma_f32_16x16x32_bf16 v[74:77], v[164:167], v[212:215], v[74:77]
	s_setprio 0
	s_setprio 1
	v_mfma_f32_16x16x32_bf16 v[118:121], v[168:171], v[184:187], 0
	v_mfma_f32_16x16x32_bf16 v[114:117], v[176:179], v[184:187], 0
	v_mfma_f32_16x16x32_bf16 v[102:105], v[168:171], v[192:195], 0
	v_mfma_f32_16x16x32_bf16 v[98:101], v[176:179], v[192:195], 0
	v_mfma_f32_16x16x32_bf16 v[86:89], v[168:171], v[200:203], 0
	v_mfma_f32_16x16x32_bf16 v[82:85], v[176:179], v[200:203], 0
	v_mfma_f32_16x16x32_bf16 v[70:73], v[168:171], v[208:211], 0
	v_mfma_f32_16x16x32_bf16 v[66:69], v[176:179], v[208:211], 0
	v_mfma_f32_16x16x32_bf16 v[118:121], v[172:175], v[188:191], v[118:121]
	v_mfma_f32_16x16x32_bf16 v[114:117], v[180:183], v[188:191], v[114:117]
	v_mfma_f32_16x16x32_bf16 v[102:105], v[172:175], v[196:199], v[102:105]
	v_mfma_f32_16x16x32_bf16 v[98:101], v[180:183], v[196:199], v[98:101]
	v_mfma_f32_16x16x32_bf16 v[86:89], v[172:175], v[204:207], v[86:89]
	v_mfma_f32_16x16x32_bf16 v[82:85], v[180:183], v[204:207], v[82:85]
	v_mfma_f32_16x16x32_bf16 v[70:73], v[172:175], v[212:215], v[70:73]
	v_mfma_f32_16x16x32_bf16 v[66:69], v[180:183], v[212:215], v[66:69]
	s_setprio 0
	s_barrier
	s_add_i32 s53, s44, s31
	v_lshl_add_u64 v[216:217], s[26:27], 0, v[134:135]
	s_mov_b32 m0, s53
	ds_read_b128 v[184:187], v155 offset:16384
	ds_read_b128 v[188:191], v155 offset:17408
	ds_read_b128 v[192:195], v155 offset:18432
	ds_read_b128 v[196:199], v155 offset:19456
	ds_read_b128 v[200:203], v155 offset:20480
	ds_read_b128 v[204:207], v155 offset:21504
	ds_read_b128 v[208:211], v155 offset:22528
	ds_read_b128 v[212:215], v155 offset:23552
	global_load_lds_dwordx4 v[216:217], off
	s_add_i32 m0, s53, 0x2000
	s_add_u32 s54, s26, 0x80000
	v_lshl_add_u64 v[218:219], s[26:27], 0, v[130:131]
	s_addc_u32 s55, s27, 0
	s_add_i32 s53, s45, s31
	global_load_lds_dwordx4 v[218:219], off
	v_lshl_add_u64 v[220:221], s[54:55], 0, v[134:135]
	s_mov_b32 m0, s53
	v_lshl_add_u64 v[222:223], s[28:29], 0, v[132:133]
	global_load_lds_dwordx4 v[220:221], off
	v_lshl_add_u64 v[220:221], s[54:55], 0, v[130:131]
	s_add_i32 m0, s53, 0x2000
	s_nop 0
	global_load_lds_dwordx4 v[220:221], off
	v_lshl_add_u64 v[220:221], s[28:29], 0, v[136:137]
	s_mov_b32 m0, s23
	s_nop 0
	global_load_lds_dwordx4 v[220:221], off
	s_mov_b32 m0, s37
	s_nop 0
	global_load_lds_dwordx4 v[222:223], off
	s_waitcnt vmcnt(8)
	s_waitcnt lgkmcnt(0)
	s_barrier
; #define PG8_STAGE(bufoff, gbase, voff) do { _Pragma("unroll") for (int _i = 0; _i < 2; ++_i) \
;         __builtin_amdgcn_global_load_lds((const unsigned*)((const char*)(gbase) + (voff)[_i]), (PG8_LAS unsigned*)(lds + (bufoff) + ldsw + _i * 8192), 16, 0, 0); } while (0)
; #define PG8_LDA(dst, b, h) do { _Pragma("unroll") for (int m = 0; m < 4; ++m) _Pragma("unroll") for (int k = 0; k < 2; ++k) dst[m][k] = *(const PG8_LAS bf16x8*)(lds + PG8_SA(b, h) + aoff + m * 2048 + k * 1024); } while (0)
; #define PG8_LDB(dst, b, h) do { _Pragma("unroll") for (int n = 0; n < 2; ++n) _Pragma("unroll") for (int k = 0; k < 2; ++k) dst[n][k] = *(const PG8_LAS bf16x8*)(lds + PG8_SB(b, h) + boff + n * 2048 + k * 1024); } while (0)
; #define PG8_MMA(ai, bj, At, Bt) do { __builtin_amdgcn_s_setprio(1); _Pragma("unroll") for (int m = 0; m < 4; ++m) _Pragma("unroll") for (int n = 0; n < 2; ++n) _Pragma("unroll") for (int k = 0; k < 2; ++k) \
;         acc[ai][bj][m][n] = __builtin_amdgcn_mfma_f32_16x16x32_bf16(Bt[n][k], At[m][k], acc[ai][bj][m][n], 0, 0, 0); __builtin_amdgcn_s_setprio(0); } while (0)
; #define PG8_WAIT_V(n) asm volatile("s_waitcnt vmcnt(" #n ")" ::: "memory")
; #define PG8_WAIT_L(n) asm volatile("s_waitcnt lgkmcnt(" #n ")" ::: "memory")
; #define PG8_BAR __builtin_amdgcn_s_barrier()
; #define PG8_SCHED __builtin_amdgcn_sched_barrier(0)
; template <class Epi, class Sched, bool ALIGN_EPI = false, bool SP2 = false>
; __device__ __forceinline__ void gemm_phase(PG8_LAS unsigned char* lds, const Gemm g, const Sched& S, const Epi& E) {
;     ...
;             PG8_LDA(At, 0, 1); PG8_STAGE(PG8_SB(0, 0), b2, voffB); PG8_STAGE(PG8_SB(0, 1), b2 + hstep, voffB); PG8_STAGE(PG8_SA(0, 0), a2, voffA);
;             PG8_WAIT_V(8); PG8_WAIT_L(0); PG8_BAR; PG8_MMA(1, 0, At, B0); PG8_MMA(1, 1, At, B1); PG8_BAR; PG8_SCHED;
;             PG8_LDB(B0, 1, 0); PG8_LDB(B1, 1, 1); PG8_SCHED; PG8_LDA(At, 1, 0); PG8_STAGE(PG8_SA(0, 1), a2 + hstep, voffA);
;             PG8_WAIT_V(8); PG8_WAIT_L(0); PG8_BAR; PG8_MMA(0, 0, At, B0); PG8_MMA(0, 1, At, B1); PG8_BAR; PG8_SCHED;
	s_setprio 1
	s_waitcnt lgkmcnt(0)
	v_mfma_f32_16x16x32_bf16 v[62:65], v[146:149], v[184:187], 0
	v_mfma_f32_16x16x32_bf16 v[58:61], v[160:163], v[184:187], 0
	v_mfma_f32_16x16x32_bf16 v[46:49], v[146:149], v[192:195], 0
	v_mfma_f32_16x16x32_bf16 v[42:45], v[160:163], v[192:195], 0
	v_mfma_f32_16x16x32_bf16 v[30:33], v[146:149], v[200:203], 0
	v_mfma_f32_16x16x32_bf16 v[26:29], v[160:163], v[200:203], 0
	v_mfma_f32_16x16x32_bf16 v[14:17], v[146:149], v[208:211], 0
	v_mfma_f32_16x16x32_bf16 v[10:13], v[160:163], v[208:211], 0
	v_mfma_f32_16x16x32_bf16 v[62:65], v[156:159], v[188:191], v[62:65]
	v_mfma_f32_16x16x32_bf16 v[58:61], v[164:167], v[188:191], v[58:61]
	v_mfma_f32_16x16x32_bf16 v[46:49], v[156:159], v[196:199], v[46:49]
	v_mfma_f32_16x16x32_bf16 v[42:45], v[164:167], v[196:199], v[42:45]
	v_mfma_f32_16x16x32_bf16 v[30:33], v[156:159], v[204:207], v[30:33]
	v_mfma_f32_16x16x32_bf16 v[26:29], v[164:167], v[204:207], v[26:29]
	v_mfma_f32_16x16x32_bf16 v[14:17], v[156:159], v[212:215], v[14:17]
	v_mfma_f32_16x16x32_bf16 v[10:13], v[164:167], v[212:215], v[10:13]
	s_setprio 0
	s_setprio 1
	v_mfma_f32_16x16x32_bf16 v[54:57], v[168:171], v[184:187], 0
	v_mfma_f32_16x16x32_bf16 v[50:53], v[176:179], v[184:187], 0
	v_mfma_f32_16x16x32_bf16 v[38:41], v[168:171], v[192:195], 0
	v_mfma_f32_16x16x32_bf16 v[34:37], v[176:179], v[192:195], 0
	v_mfma_f32_16x16x32_bf16 v[22:25], v[168:171], v[200:203], 0
	v_mfma_f32_16x16x32_bf16 v[18:21], v[176:179], v[200:203], 0
	v_mfma_f32_16x16x32_bf16 v[6:9], v[168:171], v[208:211], 0
	v_mfma_f32_16x16x32_bf16 v[2:5], v[176:179], v[208:211], 0
	v_mfma_f32_16x16x32_bf16 v[54:57], v[172:175], v[188:191], v[54:57]
	v_mfma_f32_16x16x32_bf16 v[50:53], v[180:183], v[188:191], v[50:53]
	v_mfma_f32_16x16x32_bf16 v[38:41], v[172:175], v[196:199], v[38:41]
	v_mfma_f32_16x16x32_bf16 v[34:37], v[180:183], v[196:199], v[34:37]
	v_mfma_f32_16x16x32_bf16 v[22:25], v[172:175], v[204:207], v[22:25]
	v_mfma_f32_16x16x32_bf16 v[18:21], v[180:183], v[204:207], v[18:21]
	v_mfma_f32_16x16x32_bf16 v[6:9], v[172:175], v[212:215], v[6:9]
	v_mfma_f32_16x16x32_bf16 v[2:5], v[180:183], v[212:215], v[2:5]
	s_setprio 0
	s_barrier
	s_add_i32 s53, 0, 0x18000
	s_add_i32 s54, 0, 0x1c000
	v_add_u32_e32 v164, s53, v151
	v_add_u32_e32 v180, s54, v151
	ds_read_b128 v[146:149], v164
	ds_read_b128 v[156:159], v164 offset:1024
	ds_read_b128 v[160:163], v164 offset:2048
	ds_read_b128 v[164:167], v164 offset:3072
	ds_read_b128 v[168:171], v180
	ds_read_b128 v[172:175], v180 offset:1024
	ds_read_b128 v[176:179], v180 offset:2048
	ds_read_b128 v[180:183], v180 offset:3072
	s_add_u32 s28, s28, 0x80000
	s_addc_u32 s29, s29, 0
	s_mov_b32 m0, s38
	v_lshl_add_u64 v[224:225], s[28:29], 0, v[136:137]
	ds_read_b128 v[184:187], v155 offset:32768
	ds_read_b128 v[188:191], v155 offset:33792
	ds_read_b128 v[192:195], v155 offset:34816
	ds_read_b128 v[196:199], v155 offset:35840
	ds_read_b128 v[200:203], v155 offset:36864
	ds_read_b128 v[204:207], v155 offset:37888
	ds_read_b128 v[208:211], v155 offset:38912
	ds_read_b128 v[212:215], v155 offset:39936
	global_load_lds_dwordx4 v[224:225], off
	v_lshl_add_u64 v[224:225], s[28:29], 0, v[132:133]
	s_mov_b32 m0, s39
	s_nop 0
	global_load_lds_dwordx4 v[224:225], off
	s_waitcnt vmcnt(8)
	s_waitcnt lgkmcnt(0)
	s_barrier
	s_setprio 1
	s_waitcnt lgkmcnt(0)
	v_mfma_f32_16x16x32_bf16 v[126:129], v[146:149], v[184:187], v[126:129]
	v_mfma_f32_16x16x32_bf16 v[122:125], v[160:163], v[184:187], v[122:125]
	v_mfma_f32_16x16x32_bf16 v[110:113], v[146:149], v[192:195], v[110:113]
	v_mfma_f32_16x16x32_bf16 v[106:109], v[160:163], v[192:195], v[106:109]
	v_mfma_f32_16x16x32_bf16 v[94:97], v[146:149], v[200:203], v[94:97]
	v_mfma_f32_16x16x32_bf16 v[90:93], v[160:163], v[200:203], v[90:93]
	v_mfma_f32_16x16x32_bf16 v[78:81], v[146:149], v[208:211], v[78:81]
	v_mfma_f32_16x16x32_bf16 v[74:77], v[160:163], v[208:211], v[74:77]
	v_mfma_f32_16x16x32_bf16 v[126:129], v[156:159], v[188:191], v[126:129]
	v_mfma_f32_16x16x32_bf16 v[122:125], v[164:167], v[188:191], v[122:125]
	v_mfma_f32_16x16x32_bf16 v[110:113], v[156:159], v[196:199], v[110:113]
	v_mfma_f32_16x16x32_bf16 v[106:109], v[164:167], v[196:199], v[106:109]
	v_mfma_f32_16x16x32_bf16 v[94:97], v[156:159], v[204:207], v[94:97]
	v_mfma_f32_16x16x32_bf16 v[90:93], v[164:167], v[204:207], v[90:93]
	v_mfma_f32_16x16x32_bf16 v[78:81], v[156:159], v[212:215], v[78:81]
	v_mfma_f32_16x16x32_bf16 v[74:77], v[164:167], v[212:215], v[74:77]
	s_setprio 0
	s_setprio 1
	v_mfma_f32_16x16x32_bf16 v[118:121], v[168:171], v[184:187], v[118:121]
	v_mfma_f32_16x16x32_bf16 v[114:117], v[176:179], v[184:187], v[114:117]
	v_mfma_f32_16x16x32_bf16 v[102:105], v[168:171], v[192:195], v[102:105]
	v_mfma_f32_16x16x32_bf16 v[98:101], v[176:179], v[192:195], v[98:101]
	v_mfma_f32_16x16x32_bf16 v[86:89], v[168:171], v[200:203], v[86:89]
	v_mfma_f32_16x16x32_bf16 v[82:85], v[176:179], v[200:203], v[82:85]
	v_mfma_f32_16x16x32_bf16 v[70:73], v[168:171], v[208:211], v[70:73]
	v_mfma_f32_16x16x32_bf16 v[66:69], v[176:179], v[208:211], v[66:69]
	v_mfma_f32_16x16x32_bf16 v[118:121], v[172:175], v[188:191], v[118:121]
	v_mfma_f32_16x16x32_bf16 v[114:117], v[180:183], v[188:191], v[114:117]
	v_mfma_f32_16x16x32_bf16 v[102:105], v[172:175], v[196:199], v[102:105]
	v_mfma_f32_16x16x32_bf16 v[98:101], v[180:183], v[196:199], v[98:101]
	v_mfma_f32_16x16x32_bf16 v[86:89], v[172:175], v[204:207], v[86:89]
	v_mfma_f32_16x16x32_bf16 v[82:85], v[180:183], v[204:207], v[82:85]
	v_mfma_f32_16x16x32_bf16 v[70:73], v[172:175], v[212:215], v[70:73]
	v_mfma_f32_16x16x32_bf16 v[66:69], v[180:183], v[212:215], v[66:69]
	s_setprio 0
	s_barrier
; #define PG8_STAGE(bufoff, gbase, voff) do { _Pragma("unroll") for (int _i = 0; _i < 2; ++_i) \
;         __builtin_amdgcn_global_load_lds((const unsigned*)((const char*)(gbase) + (voff)[_i]), (PG8_LAS unsigned*)(lds + (bufoff) + ldsw + _i * 8192), 16, 0, 0); } while (0)
; #define PG8_LDA(dst, b, h) do { _Pragma("unroll") for (int m = 0; m < 4; ++m) _Pragma("unroll") for (int k = 0; k < 2; ++k) dst[m][k] = *(const PG8_LAS bf16x8*)(lds + PG8_SA(b, h) + aoff + m * 2048 + k * 1024); } while (0)
; #define PG8_WAIT_V(n) asm volatile("s_waitcnt vmcnt(" #n ")" ::: "memory")
; #define PG8_BAR __builtin_amdgcn_s_barrier()
; template <class Epi, class Sched, bool ALIGN_EPI = false, bool SP2 = false>
; __device__ __forceinline__ void gemm_phase(PG8_LAS unsigned char* lds, const Gemm g, const Sched& S, const Epi& E) {
;     ...
;         for (int t = 0; t < nt; t += 2) {
;             if constexpr (Epi::MIDHOOK) { if (t == (nt >> 1)) E.mid(acc, cur, wr, wc, fr, fq); }
;             const bool last = (t == nt - 2);
;             const char* a1 = cA + (size_t)(t + 1) * kstep;
;             const char* a2 = last ? nA : cA + (size_t)(t + 2) * kstep; const char* b2 = last ? nB : cB + (size_t)(t + 2) * kstep;
;             const char* a3 = a2 + kstep; const char* b3 = b2 + kstep;
;             if (last && has_next) S.a_ready(nxt);
;             if constexpr (SP2) {
;             PG8_LDB(B0, 0, 0); PG8_LDB(B1, 0, 1); PG8_SCHED; PG8_LDA(At, 0, 0); PG8_STAGE(PG8_SA(1, 1), a1 + hstep, voffA);
;             PG8_WAIT_V(8); PG8_WAIT_L(0); PG8_BAR; PG8_MMA(0, 0, At, B0); PG8_MMA(0, 1, At, B1); PG8_BAR; PG8_SCHED;
;             PG8_LDA(At, 0, 1); PG8_STAGE(PG8_SB(0, 0), b2, voffB); PG8_STAGE(PG8_SB(0, 1), b2 + hstep, voffB); PG8_STAGE(PG8_SA(0, 0), a2, voffA);
;             PG8_WAIT_V(8); PG8_WAIT_L(0); PG8_BAR; PG8_MMA(1, 0, At, B0); PG8_MMA(1, 1, At, B1); PG8_BAR; PG8_SCHED;
;             PG8_LDB(B0, 1, 0); PG8_LDB(B1, 1, 1); PG8_SCHED; PG8_LDA(At, 1, 0); PG8_STAGE(PG8_SA(0, 1), a2 + hstep, voffA);
;             PG8_WAIT_V(8); PG8_WAIT_L(0); PG8_BAR; PG8_MMA(0, 0, At, B0); PG8_MMA(0, 1, At, B1); PG8_BAR; PG8_SCHED;
;             PG8_LDA(At, 1, 1); PG8_STAGE(PG8_SB(1, 0), b3, voffB); PG8_STAGE(PG8_SB(1, 1), b3 + hstep, voffB); PG8_STAGE(PG8_SA(1, 0), a3, voffA);
;             PG8_WAIT_V(8); PG8_WAIT_L(0); PG8_BAR; PG8_MMA(1, 0, At, B0); PG8_MMA(1, 1, At, B1); PG8_BAR; PG8_SCHED;
	s_add_i32 s28, s53, s31
	v_lshl_add_u64 v[216:217], v[216:217], 0, s[10:11]
	s_mov_b32 m0, s28
	ds_read_b128 v[184:187], v155 offset:49152
	ds_read_b128 v[188:191], v155 offset:50176
	ds_read_b128 v[192:195], v155 offset:51200
	ds_read_b128 v[196:199], v155 offset:52224
	ds_read_b128 v[200:203], v155 offset:53248
	ds_read_b128 v[204:207], v155 offset:54272
	ds_read_b128 v[208:211], v155 offset:55296
	ds_read_b128 v[212:215], v155 offset:56320
	global_load_lds_dwordx4 v[216:217], off
	s_add_i32 m0, s28, 0x2000
	s_add_u32 s26, s26, 0x80080
	v_lshl_add_u64 v[216:217], v[218:219], 0, s[10:11]
	s_addc_u32 s27, s27, 0
	s_add_i32 s28, s54, s31
	global_load_lds_dwordx4 v[216:217], off
	v_lshl_add_u64 v[216:217], s[26:27], 0, v[134:135]
	s_mov_b32 m0, s28
	s_nop 0
	global_load_lds_dwordx4 v[216:217], off
	v_lshl_add_u64 v[216:217], s[26:27], 0, v[130:131]
	s_add_i32 m0, s28, 0x2000
	s_nop 0
	global_load_lds_dwordx4 v[216:217], off
	v_lshl_add_u64 v[216:217], v[220:221], 0, s[10:11]
	s_mov_b32 m0, s42
	s_nop 0
	global_load_lds_dwordx4 v[216:217], off
	v_lshl_add_u64 v[216:217], v[222:223], 0, s[10:11]
	s_mov_b32 m0, s43
	s_nop 0
	global_load_lds_dwordx4 v[216:217], off
	s_waitcnt vmcnt(8)
	s_waitcnt lgkmcnt(0)
	s_barrier
	s_setprio 1
	s_waitcnt lgkmcnt(0)
	v_mfma_f32_16x16x32_bf16 v[62:65], v[146:149], v[184:187], v[62:65]
	v_mfma_f32_16x16x32_bf16 v[58:61], v[160:163], v[184:187], v[58:61]
	v_mfma_f32_16x16x32_bf16 v[46:49], v[146:149], v[192:195], v[46:49]
	v_mfma_f32_16x16x32_bf16 v[42:45], v[160:163], v[192:195], v[42:45]
	v_mfma_f32_16x16x32_bf16 v[30:33], v[146:149], v[200:203], v[30:33]
	v_mfma_f32_16x16x32_bf16 v[26:29], v[160:163], v[200:203], v[26:29]
	v_mfma_f32_16x16x32_bf16 v[14:17], v[146:149], v[208:211], v[14:17]
	v_mfma_f32_16x16x32_bf16 v[10:13], v[160:163], v[208:211], v[10:13]
	v_mfma_f32_16x16x32_bf16 v[62:65], v[156:159], v[188:191], v[62:65]
	v_mfma_f32_16x16x32_bf16 v[58:61], v[164:167], v[188:191], v[58:61]
	v_mfma_f32_16x16x32_bf16 v[46:49], v[156:159], v[196:199], v[46:49]
	v_mfma_f32_16x16x32_bf16 v[42:45], v[164:167], v[196:199], v[42:45]
	v_mfma_f32_16x16x32_bf16 v[30:33], v[156:159], v[204:207], v[30:33]
	v_mfma_f32_16x16x32_bf16 v[26:29], v[164:167], v[204:207], v[26:29]
	v_mfma_f32_16x16x32_bf16 v[14:17], v[156:159], v[212:215], v[14:17]
	v_mfma_f32_16x16x32_bf16 v[10:13], v[164:167], v[212:215], v[10:13]
	s_setprio 0
	s_setprio 1
	v_mfma_f32_16x16x32_bf16 v[54:57], v[168:171], v[184:187], v[54:57]
	v_mfma_f32_16x16x32_bf16 v[50:53], v[176:179], v[184:187], v[50:53]
	v_mfma_f32_16x16x32_bf16 v[38:41], v[168:171], v[192:195], v[38:41]
	v_mfma_f32_16x16x32_bf16 v[34:37], v[176:179], v[192:195], v[34:37]
	v_mfma_f32_16x16x32_bf16 v[22:25], v[168:171], v[200:203], v[22:25]
	v_mfma_f32_16x16x32_bf16 v[18:21], v[176:179], v[200:203], v[18:21]
	v_mfma_f32_16x16x32_bf16 v[6:9], v[168:171], v[208:211], v[6:9]
	v_mfma_f32_16x16x32_bf16 v[2:5], v[176:179], v[208:211], v[2:5]
	v_mfma_f32_16x16x32_bf16 v[54:57], v[172:175], v[188:191], v[54:57]
	v_mfma_f32_16x16x32_bf16 v[50:53], v[180:183], v[188:191], v[50:53]
	v_mfma_f32_16x16x32_bf16 v[38:41], v[172:175], v[196:199], v[38:41]
	v_mfma_f32_16x16x32_bf16 v[34:37], v[180:183], v[196:199], v[34:37]
	v_mfma_f32_16x16x32_bf16 v[22:25], v[172:175], v[204:207], v[22:25]
	v_mfma_f32_16x16x32_bf16 v[18:21], v[180:183], v[204:207], v[18:21]
	v_mfma_f32_16x16x32_bf16 v[6:9], v[172:175], v[212:215], v[6:9]
	v_mfma_f32_16x16x32_bf16 v[2:5], v[180:183], v[212:215], v[2:5]
	s_setprio 0
	s_barrier
	s_add_i32 s52, s52, 2
	s_add_u32 s24, s24, 0x100
	s_addc_u32 s25, s25, 0
	s_add_u32 s50, s50, 0x100
	s_addc_u32 s51, s51, 0
	s_cmp_gt_u32 s52, 29
	s_cbranch_scc1 .Lkx_1551
.LBB0_1551:
	ds_read_b128 v[146:149], v153
	ds_read_b128 v[156:159], v153 offset:1024
	ds_read_b128 v[160:163], v153 offset:2048
	ds_read_b128 v[164:167], v153 offset:3072
	ds_read_b128 v[168:171], v154
	ds_read_b128 v[172:175], v154 offset:1024
	ds_read_b128 v[176:179], v154 offset:2048
	ds_read_b128 v[180:183], v154 offset:3072
	s_add_u32 s26, s24, 0xfff80080
	s_addc_u32 s27, s25, -1
	s_cmp_eq_u32 s52, 28
	s_cselect_b32 s29, s17, s27
	s_cselect_b32 s28, s48, s26
	s_cselect_b32 s27, s15, s51
	s_cselect_b32 s26, s49, s50
	v_lshl_add_u64 v[216:217], s[24:25], 0, v[138:139]
	s_add_i32 m0, s23, 0xc000
	ds_read_b128 v[184:187], v155
	ds_read_b128 v[188:191], v155 offset:1024
	ds_read_b128 v[192:195], v155 offset:2048
	ds_read_b128 v[196:199], v155 offset:3072
	ds_read_b128 v[200:203], v155 offset:4096
	ds_read_b128 v[204:207], v155 offset:5120
	ds_read_b128 v[208:211], v155 offset:6144
	ds_read_b128 v[212:215], v155 offset:7168
	global_load_lds_dwordx4 v[216:217], off
	v_lshl_add_u64 v[216:217], s[24:25], 0, v[140:141]
	s_add_i32 m0, s23, 0xe000
	s_nop 0
	global_load_lds_dwordx4 v[216:217], off
	s_waitcnt vmcnt(8)
	s_waitcnt lgkmcnt(0)
	s_barrier
; #define PG8_STAGE(bufoff, gbase, voff) do { _Pragma("unroll") for (int _i = 0; _i < 2; ++_i) \
;         __builtin_amdgcn_global_load_lds((const unsigned*)((const char*)(gbase) + (voff)[_i]), (PG8_LAS unsigned*)(lds + (bufoff) + ldsw + _i * 8192), 16, 0, 0); } while (0)
; #define PG8_LDA(dst, b, h) do { _Pragma("unroll") for (int m = 0; m < 4; ++m) _Pragma("unroll") for (int k = 0; k < 2; ++k) dst[m][k] = *(const PG8_LAS bf16x8*)(lds + PG8_SA(b, h) + aoff + m * 2048 + k * 1024); } while (0)
; #define PG8_LDB(dst, b, h) do { _Pragma("unroll") for (int n = 0; n < 2; ++n) _Pragma("unroll") for (int k = 0; k < 2; ++k) dst[n][k] = *(const PG8_LAS bf16x8*)(lds + PG8_SB(b, h) + boff + n * 2048 + k * 1024); } while (0)
; #define PG8_MMA(ai, bj, At, Bt) do { __builtin_amdgcn_s_setprio(1); _Pragma("unroll") for (int m = 0; m < 4; ++m) _Pragma("unroll") for (int n = 0; n < 2; ++n) _Pragma("unroll") for (int k = 0; k < 2; ++k) \
;         acc[ai][bj][m][n] = __builtin_amdgcn_mfma_f32_16x16x32_bf16(Bt[n][k], At[m][k], acc[ai][bj][m][n], 0, 0, 0); __builtin_amdgcn_s_setprio(0); } while (0)
; #define PG8_WAIT_V(n) asm volatile("s_waitcnt vmcnt(" #n ")" ::: "memory")
; #define PG8_WAIT_L(n) asm volatile("s_waitcnt lgkmcnt(" #n ")" ::: "memory")
; #define PG8_BAR __builtin_amdgcn_s_barrier()
; #define PG8_SCHED __builtin_amdgcn_sched_barrier(0)
; template <class Epi, class Sched, bool ALIGN_EPI = false, bool SP2 = false>
; __device__ __forceinline__ void gemm_phase(PG8_LAS unsigned char* lds, const Gemm g, const Sched& S, const Epi& E) {
;     ...
;             PG8_LDB(B0, 0, 0); PG8_LDB(B1, 0, 1); PG8_SCHED; PG8_LDA(At, 0, 0); PG8_STAGE(PG8_SA(1, 1), a1 + hstep, voffA);
;             PG8_WAIT_V(8); PG8_WAIT_L(0); PG8_BAR; PG8_MMA(0, 0, At, B0); PG8_MMA(0, 1, At, B1); PG8_BAR; PG8_SCHED;
;             PG8_LDA(At, 0, 1); PG8_STAGE(PG8_SB(0, 0), b2, voffB); PG8_STAGE(PG8_SB(0, 1), b2 + hstep, voffB); PG8_STAGE(PG8_SA(0, 0), a2, voffA);
;             PG8_WAIT_V(8); PG8_WAIT_L(0); PG8_BAR; PG8_MMA(1, 0, At, B0); PG8_MMA(1, 1, At, B1); PG8_BAR; PG8_SCHED;
	s_setprio 1
	s_waitcnt lgkmcnt(0)
	v_mfma_f32_16x16x32_bf16 v[126:129], v[146:149], v[184:187], v[126:129]
	v_mfma_f32_16x16x32_bf16 v[122:125], v[160:163], v[184:187], v[122:125]
	v_mfma_f32_16x16x32_bf16 v[110:113], v[146:149], v[192:195], v[110:113]
	v_mfma_f32_16x16x32_bf16 v[106:109], v[160:163], v[192:195], v[106:109]
	v_mfma_f32_16x16x32_bf16 v[94:97], v[146:149], v[200:203], v[94:97]
	v_mfma_f32_16x16x32_bf16 v[90:93], v[160:163], v[200:203], v[90:93]
	v_mfma_f32_16x16x32_bf16 v[78:81], v[146:149], v[208:211], v[78:81]
	v_mfma_f32_16x16x32_bf16 v[74:77], v[160:163], v[208:211], v[74:77]
	v_mfma_f32_16x16x32_bf16 v[126:129], v[156:159], v[188:191], v[126:129]
	v_mfma_f32_16x16x32_bf16 v[122:125], v[164:167], v[188:191], v[122:125]
	v_mfma_f32_16x16x32_bf16 v[110:113], v[156:159], v[196:199], v[110:113]
	v_mfma_f32_16x16x32_bf16 v[106:109], v[164:167], v[196:199], v[106:109]
	v_mfma_f32_16x16x32_bf16 v[94:97], v[156:159], v[204:207], v[94:97]
	v_mfma_f32_16x16x32_bf16 v[90:93], v[164:167], v[204:207], v[90:93]
	v_mfma_f32_16x16x32_bf16 v[78:81], v[156:159], v[212:215], v[78:81]
	v_mfma_f32_16x16x32_bf16 v[74:77], v[164:167], v[212:215], v[74:77]
	s_setprio 0
	s_setprio 1
	v_mfma_f32_16x16x32_bf16 v[118:121], v[168:171], v[184:187], v[118:121]
	v_mfma_f32_16x16x32_bf16 v[114:117], v[176:179], v[184:187], v[114:117]
	v_mfma_f32_16x16x32_bf16 v[102:105], v[168:171], v[192:195], v[102:105]
	v_mfma_f32_16x16x32_bf16 v[98:101], v[176:179], v[192:195], v[98:101]
	v_mfma_f32_16x16x32_bf16 v[86:89], v[168:171], v[200:203], v[86:89]
	v_mfma_f32_16x16x32_bf16 v[82:85], v[176:179], v[200:203], v[82:85]
	v_mfma_f32_16x16x32_bf16 v[70:73], v[168:171], v[208:211], v[70:73]
	v_mfma_f32_16x16x32_bf16 v[66:69], v[176:179], v[208:211], v[66:69]
	v_mfma_f32_16x16x32_bf16 v[118:121], v[172:175], v[188:191], v[118:121]
	v_mfma_f32_16x16x32_bf16 v[114:117], v[180:183], v[188:191], v[114:117]
	v_mfma_f32_16x16x32_bf16 v[102:105], v[172:175], v[196:199], v[102:105]
	v_mfma_f32_16x16x32_bf16 v[98:101], v[180:183], v[196:199], v[98:101]
	v_mfma_f32_16x16x32_bf16 v[86:89], v[172:175], v[204:207], v[86:89]
	v_mfma_f32_16x16x32_bf16 v[82:85], v[180:183], v[204:207], v[82:85]
	v_mfma_f32_16x16x32_bf16 v[70:73], v[172:175], v[212:215], v[70:73]
	v_mfma_f32_16x16x32_bf16 v[66:69], v[180:183], v[212:215], v[66:69]
	s_setprio 0
	s_barrier
	s_add_i32 s53, s44, s31
	v_lshl_add_u64 v[216:217], s[26:27], 0, v[134:135]
	s_mov_b32 m0, s53
	ds_read_b128 v[184:187], v155 offset:16384
	ds_read_b128 v[188:191], v155 offset:17408
	ds_read_b128 v[192:195], v155 offset:18432
	ds_read_b128 v[196:199], v155 offset:19456
	ds_read_b128 v[200:203], v155 offset:20480
	ds_read_b128 v[204:207], v155 offset:21504
	ds_read_b128 v[208:211], v155 offset:22528
	ds_read_b128 v[212:215], v155 offset:23552
	global_load_lds_dwordx4 v[216:217], off
	s_add_i32 m0, s53, 0x2000
	s_add_u32 s54, s26, 0x80000
	v_lshl_add_u64 v[218:219], s[26:27], 0, v[130:131]
	s_addc_u32 s55, s27, 0
	s_add_i32 s53, s45, s31
	global_load_lds_dwordx4 v[218:219], off
	v_lshl_add_u64 v[220:221], s[54:55], 0, v[134:135]
	s_mov_b32 m0, s53
	v_lshl_add_u64 v[222:223], s[28:29], 0, v[132:133]
	global_load_lds_dwordx4 v[220:221], off
	v_lshl_add_u64 v[220:221], s[54:55], 0, v[130:131]
	s_add_i32 m0, s53, 0x2000
	s_nop 0
	global_load_lds_dwordx4 v[220:221], off
	v_lshl_add_u64 v[220:221], s[28:29], 0, v[136:137]
	s_mov_b32 m0, s23
	s_nop 0
	global_load_lds_dwordx4 v[220:221], off
	s_mov_b32 m0, s37
	s_nop 0
	global_load_lds_dwordx4 v[222:223], off
	s_waitcnt vmcnt(8)
	s_waitcnt lgkmcnt(0)
	s_barrier
	s_setprio 1
	s_waitcnt lgkmcnt(0)
	v_mfma_f32_16x16x32_bf16 v[62:65], v[146:149], v[184:187], v[62:65]
	v_mfma_f32_16x16x32_bf16 v[58:61], v[160:163], v[184:187], v[58:61]
	v_mfma_f32_16x16x32_bf16 v[46:49], v[146:149], v[192:195], v[46:49]
	v_mfma_f32_16x16x32_bf16 v[42:45], v[160:163], v[192:195], v[42:45]
	v_mfma_f32_16x16x32_bf16 v[30:33], v[146:149], v[200:203], v[30:33]
	v_mfma_f32_16x16x32_bf16 v[26:29], v[160:163], v[200:203], v[26:29]
	v_mfma_f32_16x16x32_bf16 v[14:17], v[146:149], v[208:211], v[14:17]
	v_mfma_f32_16x16x32_bf16 v[10:13], v[160:163], v[208:211], v[10:13]
	v_mfma_f32_16x16x32_bf16 v[62:65], v[156:159], v[188:191], v[62:65]
	v_mfma_f32_16x16x32_bf16 v[58:61], v[164:167], v[188:191], v[58:61]
	v_mfma_f32_16x16x32_bf16 v[46:49], v[156:159], v[196:199], v[46:49]
	v_mfma_f32_16x16x32_bf16 v[42:45], v[164:167], v[196:199], v[42:45]
	v_mfma_f32_16x16x32_bf16 v[30:33], v[156:159], v[204:207], v[30:33]
	v_mfma_f32_16x16x32_bf16 v[26:29], v[164:167], v[204:207], v[26:29]
	v_mfma_f32_16x16x32_bf16 v[14:17], v[156:159], v[212:215], v[14:17]
	v_mfma_f32_16x16x32_bf16 v[10:13], v[164:167], v[212:215], v[10:13]
	s_setprio 0
	s_setprio 1
	v_mfma_f32_16x16x32_bf16 v[54:57], v[168:171], v[184:187], v[54:57]
	v_mfma_f32_16x16x32_bf16 v[50:53], v[176:179], v[184:187], v[50:53]
	v_mfma_f32_16x16x32_bf16 v[38:41], v[168:171], v[192:195], v[38:41]
	v_mfma_f32_16x16x32_bf16 v[34:37], v[176:179], v[192:195], v[34:37]
	v_mfma_f32_16x16x32_bf16 v[22:25], v[168:171], v[200:203], v[22:25]
	v_mfma_f32_16x16x32_bf16 v[18:21], v[176:179], v[200:203], v[18:21]
	v_mfma_f32_16x16x32_bf16 v[6:9], v[168:171], v[208:211], v[6:9]
	v_mfma_f32_16x16x32_bf16 v[2:5], v[176:179], v[208:211], v[2:5]
	v_mfma_f32_16x16x32_bf16 v[54:57], v[172:175], v[188:191], v[54:57]
	v_mfma_f32_16x16x32_bf16 v[50:53], v[180:183], v[188:191], v[50:53]
	v_mfma_f32_16x16x32_bf16 v[38:41], v[172:175], v[196:199], v[38:41]
	v_mfma_f32_16x16x32_bf16 v[34:37], v[180:183], v[196:199], v[34:37]
	v_mfma_f32_16x16x32_bf16 v[22:25], v[172:175], v[204:207], v[22:25]
	v_mfma_f32_16x16x32_bf16 v[18:21], v[180:183], v[204:207], v[18:21]
	v_mfma_f32_16x16x32_bf16 v[6:9], v[172:175], v[212:215], v[6:9]
	v_mfma_f32_16x16x32_bf16 v[2:5], v[180:183], v[212:215], v[2:5]
	s_setprio 0
	s_barrier
; #define PG8_STAGE(bufoff, gbase, voff) do { _Pragma("unroll") for (int _i = 0; _i < 2; ++_i) \
;         __builtin_amdgcn_global_load_lds((const unsigned*)((const char*)(gbase) + (voff)[_i]), (PG8_LAS unsigned*)(lds + (bufoff) + ldsw + _i * 8192), 16, 0, 0); } while (0)
; #define PG8_LDA(dst, b, h) do { _Pragma("unroll") for (int m = 0; m < 4; ++m) _Pragma("unroll") for (int k = 0; k < 2; ++k) dst[m][k] = *(const PG8_LAS bf16x8*)(lds + PG8_SA(b, h) + aoff + m * 2048 + k * 1024); } while (0)
; #define PG8_LDB(dst, b, h) do { _Pragma("unroll") for (int n = 0; n < 2; ++n) _Pragma("unroll") for (int k = 0; k < 2; ++k) dst[n][k] = *(const PG8_LAS bf16x8*)(lds + PG8_SB(b, h) + boff + n * 2048 + k * 1024); } while (0)
; #define PG8_MMA(ai, bj, At, Bt) do { __builtin_amdgcn_s_setprio(1); _Pragma("unroll") for (int m = 0; m < 4; ++m) _Pragma("unroll") for (int n = 0; n < 2; ++n) _Pragma("unroll") for (int k = 0; k < 2; ++k) \
;         acc[ai][bj][m][n] = __builtin_amdgcn_mfma_f32_16x16x32_bf16(Bt[n][k], At[m][k], acc[ai][bj][m][n], 0, 0, 0); __builtin_amdgcn_s_setprio(0); } while (0)
; #define PG8_WAIT_V(n) asm volatile("s_waitcnt vmcnt(" #n ")" ::: "memory")
; #define PG8_WAIT_L(n) asm volatile("s_waitcnt lgkmcnt(" #n ")" ::: "memory")
; #define PG8_BAR __builtin_amdgcn_s_barrier()
; #define PG8_SCHED __builtin_amdgcn_sched_barrier(0)
; template <class Epi, class Sched, bool ALIGN_EPI = false, bool SP2 = false>
; __device__ __forceinline__ void gemm_phase(PG8_LAS unsigned char* lds, const Gemm g, const Sched& S, const Epi& E) {
;     ...
;             PG8_LDB(B0, 1, 0); PG8_LDB(B1, 1, 1); PG8_SCHED; PG8_LDA(At, 1, 0); PG8_STAGE(PG8_SA(0, 1), a2 + hstep, voffA);
;             PG8_WAIT_V(8); PG8_WAIT_L(0); PG8_BAR; PG8_MMA(0, 0, At, B0); PG8_MMA(0, 1, At, B1); PG8_BAR; PG8_SCHED;
	s_add_i32 s53, 0, 0x18000
	s_add_i32 s54, 0, 0x1c000
	v_add_u32_e32 v164, s53, v151
	v_add_u32_e32 v180, s54, v151
	ds_read_b128 v[146:149], v164
	ds_read_b128 v[156:159], v164 offset:1024
	ds_read_b128 v[160:163], v164 offset:2048
	ds_read_b128 v[164:167], v164 offset:3072
	ds_read_b128 v[168:171], v180
	ds_read_b128 v[172:175], v180 offset:1024
	ds_read_b128 v[176:179], v180 offset:2048
	ds_read_b128 v[180:183], v180 offset:3072
	s_add_u32 s28, s28, 0x80000
	s_addc_u32 s29, s29, 0
	s_mov_b32 m0, s38
	v_lshl_add_u64 v[224:225], s[28:29], 0, v[136:137]
	ds_read_b128 v[184:187], v155 offset:32768
	ds_read_b128 v[188:191], v155 offset:33792
	ds_read_b128 v[192:195], v155 offset:34816
	ds_read_b128 v[196:199], v155 offset:35840
	ds_read_b128 v[200:203], v155 offset:36864
	ds_read_b128 v[204:207], v155 offset:37888
	ds_read_b128 v[208:211], v155 offset:38912
	ds_read_b128 v[212:215], v155 offset:39936
	global_load_lds_dwordx4 v[224:225], off
	v_lshl_add_u64 v[224:225], s[28:29], 0, v[132:133]
	s_mov_b32 m0, s39
	s_nop 0
	global_load_lds_dwordx4 v[224:225], off
	s_waitcnt vmcnt(8)
	s_waitcnt lgkmcnt(0)
	s_barrier
	s_setprio 1
	s_waitcnt lgkmcnt(0)
	v_mfma_f32_16x16x32_bf16 v[126:129], v[146:149], v[184:187], v[126:129]
	v_mfma_f32_16x16x32_bf16 v[122:125], v[160:163], v[184:187], v[122:125]
	v_mfma_f32_16x16x32_bf16 v[110:113], v[146:149], v[192:195], v[110:113]
	v_mfma_f32_16x16x32_bf16 v[106:109], v[160:163], v[192:195], v[106:109]
	v_mfma_f32_16x16x32_bf16 v[94:97], v[146:149], v[200:203], v[94:97]
	v_mfma_f32_16x16x32_bf16 v[90:93], v[160:163], v[200:203], v[90:93]
	v_mfma_f32_16x16x32_bf16 v[78:81], v[146:149], v[208:211], v[78:81]
	v_mfma_f32_16x16x32_bf16 v[74:77], v[160:163], v[208:211], v[74:77]
	v_mfma_f32_16x16x32_bf16 v[126:129], v[156:159], v[188:191], v[126:129]
	v_mfma_f32_16x16x32_bf16 v[122:125], v[164:167], v[188:191], v[122:125]
	v_mfma_f32_16x16x32_bf16 v[110:113], v[156:159], v[196:199], v[110:113]
	v_mfma_f32_16x16x32_bf16 v[106:109], v[164:167], v[196:199], v[106:109]
	v_mfma_f32_16x16x32_bf16 v[94:97], v[156:159], v[204:207], v[94:97]
	v_mfma_f32_16x16x32_bf16 v[90:93], v[164:167], v[204:207], v[90:93]
	v_mfma_f32_16x16x32_bf16 v[78:81], v[156:159], v[212:215], v[78:81]
	v_mfma_f32_16x16x32_bf16 v[74:77], v[164:167], v[212:215], v[74:77]
	s_setprio 0
	s_setprio 1
	v_mfma_f32_16x16x32_bf16 v[118:121], v[168:171], v[184:187], v[118:121]
	v_mfma_f32_16x16x32_bf16 v[114:117], v[176:179], v[184:187], v[114:117]
	v_mfma_f32_16x16x32_bf16 v[102:105], v[168:171], v[192:195], v[102:105]
	v_mfma_f32_16x16x32_bf16 v[98:101], v[176:179], v[192:195], v[98:101]
	v_mfma_f32_16x16x32_bf16 v[86:89], v[168:171], v[200:203], v[86:89]
	v_mfma_f32_16x16x32_bf16 v[82:85], v[176:179], v[200:203], v[82:85]
	v_mfma_f32_16x16x32_bf16 v[70:73], v[168:171], v[208:211], v[70:73]
	v_mfma_f32_16x16x32_bf16 v[66:69], v[176:179], v[208:211], v[66:69]
	v_mfma_f32_16x16x32_bf16 v[118:121], v[172:175], v[188:191], v[118:121]
	v_mfma_f32_16x16x32_bf16 v[114:117], v[180:183], v[188:191], v[114:117]
	v_mfma_f32_16x16x32_bf16 v[102:105], v[172:175], v[196:199], v[102:105]
	v_mfma_f32_16x16x32_bf16 v[98:101], v[180:183], v[196:199], v[98:101]
	v_mfma_f32_16x16x32_bf16 v[86:89], v[172:175], v[204:207], v[86:89]
	v_mfma_f32_16x16x32_bf16 v[82:85], v[180:183], v[204:207], v[82:85]
	v_mfma_f32_16x16x32_bf16 v[70:73], v[172:175], v[212:215], v[70:73]
	v_mfma_f32_16x16x32_bf16 v[66:69], v[180:183], v[212:215], v[66:69]
	s_setprio 0
	s_barrier
; #define PG8_STAGE(bufoff, gbase, voff) do { _Pragma("unroll") for (int _i = 0; _i < 2; ++_i) \
;         __builtin_amdgcn_global_load_lds((const unsigned*)((const char*)(gbase) + (voff)[_i]), (PG8_LAS unsigned*)(lds + (bufoff) + ldsw + _i * 8192), 16, 0, 0); } while (0)
; #define PG8_LDA(dst, b, h) do { _Pragma("unroll") for (int m = 0; m < 4; ++m) _Pragma("unroll") for (int k = 0; k < 2; ++k) dst[m][k] = *(const PG8_LAS bf16x8*)(lds + PG8_SA(b, h) + aoff + m * 2048 + k * 1024); } while (0)
; #define PG8_WAIT_V(n) asm volatile("s_waitcnt vmcnt(" #n ")" ::: "memory")
; #define PG8_BAR __builtin_amdgcn_s_barrier()
; template <class Epi, class Sched, bool ALIGN_EPI = false, bool SP2 = false>
; __device__ __forceinline__ void gemm_phase(PG8_LAS unsigned char* lds, const Gemm g, const Sched& S, const Epi& E) {
;     ...
;         for (int t = 0; t < nt; t += 2) {
;             if constexpr (Epi::MIDHOOK) { if (t == (nt >> 1)) E.mid(acc, cur, wr, wc, fr, fq); }
;             const bool last = (t == nt - 2);
;             const char* a1 = cA + (size_t)(t + 1) * kstep;
;             const char* a2 = last ? nA : cA + (size_t)(t + 2) * kstep; const char* b2 = last ? nB : cB + (size_t)(t + 2) * kstep;
;             const char* a3 = a2 + kstep; const char* b3 = b2 + kstep;
;             if (last && has_next) S.a_ready(nxt);
;             if constexpr (SP2) {
;             PG8_LDB(B0, 0, 0); PG8_LDB(B1, 0, 1); PG8_SCHED; PG8_LDA(At, 0, 0); PG8_STAGE(PG8_SA(1, 1), a1 + hstep, voffA);
;             PG8_WAIT_V(8); PG8_WAIT_L(0); PG8_BAR; PG8_MMA(0, 0, At, B0); PG8_MMA(0, 1, At, B1); PG8_BAR; PG8_SCHED;
;             PG8_LDA(At, 0, 1); PG8_STAGE(PG8_SB(0, 0), b2, voffB); PG8_STAGE(PG8_SB(0, 1), b2 + hstep, voffB); PG8_STAGE(PG8_SA(0, 0), a2, voffA);
;             PG8_WAIT_V(8); PG8_WAIT_L(0); PG8_BAR; PG8_MMA(1, 0, At, B0); PG8_MMA(1, 1, At, B1); PG8_BAR; PG8_SCHED;
;             PG8_LDB(B0, 1, 0); PG8_LDB(B1, 1, 1); PG8_SCHED; PG8_LDA(At, 1, 0); PG8_STAGE(PG8_SA(0, 1), a2 + hstep, voffA);
;             PG8_WAIT_V(8); PG8_WAIT_L(0); PG8_BAR; PG8_MMA(0, 0, At, B0); PG8_MMA(0, 1, At, B1); PG8_BAR; PG8_SCHED;
;             PG8_LDA(At, 1, 1); PG8_STAGE(PG8_SB(1, 0), b3, voffB); PG8_STAGE(PG8_SB(1, 1), b3 + hstep, voffB); PG8_STAGE(PG8_SA(1, 0), a3, voffA);
;             PG8_WAIT_V(8); PG8_WAIT_L(0); PG8_BAR; PG8_MMA(1, 0, At, B0); PG8_MMA(1, 1, At, B1); PG8_BAR; PG8_SCHED;
	s_add_i32 s28, s53, s31
	v_lshl_add_u64 v[216:217], v[216:217], 0, s[10:11]
	s_mov_b32 m0, s28
	ds_read_b128 v[184:187], v155 offset:49152
	ds_read_b128 v[188:191], v155 offset:50176
	ds_read_b128 v[192:195], v155 offset:51200
	ds_read_b128 v[196:199], v155 offset:52224
	ds_read_b128 v[200:203], v155 offset:53248
	ds_read_b128 v[204:207], v155 offset:54272
	ds_read_b128 v[208:211], v155 offset:55296
	ds_read_b128 v[212:215], v155 offset:56320
	global_load_lds_dwordx4 v[216:217], off
	s_add_i32 m0, s28, 0x2000
	s_add_u32 s26, s26, 0x80080
	v_lshl_add_u64 v[216:217], v[218:219], 0, s[10:11]
	s_addc_u32 s27, s27, 0
	s_add_i32 s28, s54, s31
	global_load_lds_dwordx4 v[216:217], off
	v_lshl_add_u64 v[216:217], s[26:27], 0, v[134:135]
	s_mov_b32 m0, s28
	s_nop 0
	global_load_lds_dwordx4 v[216:217], off
	v_lshl_add_u64 v[216:217], s[26:27], 0, v[130:131]
	s_add_i32 m0, s28, 0x2000
	s_nop 0
	global_load_lds_dwordx4 v[216:217], off
	v_lshl_add_u64 v[216:217], v[220:221], 0, s[10:11]
	s_mov_b32 m0, s42
	s_nop 0
	global_load_lds_dwordx4 v[216:217], off
	v_lshl_add_u64 v[216:217], v[222:223], 0, s[10:11]
	s_mov_b32 m0, s43
	s_nop 0
	global_load_lds_dwordx4 v[216:217], off
	s_waitcnt vmcnt(8)
	s_waitcnt lgkmcnt(0)
	s_barrier
	s_setprio 1
	s_waitcnt lgkmcnt(0)
	v_mfma_f32_16x16x32_bf16 v[62:65], v[146:149], v[184:187], v[62:65]
	v_mfma_f32_16x16x32_bf16 v[58:61], v[160:163], v[184:187], v[58:61]
	v_mfma_f32_16x16x32_bf16 v[46:49], v[146:149], v[192:195], v[46:49]
	v_mfma_f32_16x16x32_bf16 v[42:45], v[160:163], v[192:195], v[42:45]
	v_mfma_f32_16x16x32_bf16 v[30:33], v[146:149], v[200:203], v[30:33]
	v_mfma_f32_16x16x32_bf16 v[26:29], v[160:163], v[200:203], v[26:29]
	v_mfma_f32_16x16x32_bf16 v[14:17], v[146:149], v[208:211], v[14:17]
	v_mfma_f32_16x16x32_bf16 v[10:13], v[160:163], v[208:211], v[10:13]
	v_mfma_f32_16x16x32_bf16 v[62:65], v[156:159], v[188:191], v[62:65]
	v_mfma_f32_16x16x32_bf16 v[58:61], v[164:167], v[188:191], v[58:61]
	v_mfma_f32_16x16x32_bf16 v[46:49], v[156:159], v[196:199], v[46:49]
	v_mfma_f32_16x16x32_bf16 v[42:45], v[164:167], v[196:199], v[42:45]
	v_mfma_f32_16x16x32_bf16 v[30:33], v[156:159], v[204:207], v[30:33]
	v_mfma_f32_16x16x32_bf16 v[26:29], v[164:167], v[204:207], v[26:29]
	v_mfma_f32_16x16x32_bf16 v[14:17], v[156:159], v[212:215], v[14:17]
	v_mfma_f32_16x16x32_bf16 v[10:13], v[164:167], v[212:215], v[10:13]
	s_setprio 0
	s_setprio 1
	v_mfma_f32_16x16x32_bf16 v[54:57], v[168:171], v[184:187], v[54:57]
	v_mfma_f32_16x16x32_bf16 v[50:53], v[176:179], v[184:187], v[50:53]
	v_mfma_f32_16x16x32_bf16 v[38:41], v[168:171], v[192:195], v[38:41]
	v_mfma_f32_16x16x32_bf16 v[34:37], v[176:179], v[192:195], v[34:37]
	v_mfma_f32_16x16x32_bf16 v[22:25], v[168:171], v[200:203], v[22:25]
	v_mfma_f32_16x16x32_bf16 v[18:21], v[176:179], v[200:203], v[18:21]
	v_mfma_f32_16x16x32_bf16 v[6:9], v[168:171], v[208:211], v[6:9]
	v_mfma_f32_16x16x32_bf16 v[2:5], v[176:179], v[208:211], v[2:5]
	v_mfma_f32_16x16x32_bf16 v[54:57], v[172:175], v[188:191], v[54:57]
	v_mfma_f32_16x16x32_bf16 v[50:53], v[180:183], v[188:191], v[50:53]
	v_mfma_f32_16x16x32_bf16 v[38:41], v[172:175], v[196:199], v[38:41]
	v_mfma_f32_16x16x32_bf16 v[34:37], v[180:183], v[196:199], v[34:37]
	v_mfma_f32_16x16x32_bf16 v[22:25], v[172:175], v[204:207], v[22:25]
	v_mfma_f32_16x16x32_bf16 v[18:21], v[180:183], v[204:207], v[18:21]
	v_mfma_f32_16x16x32_bf16 v[6:9], v[172:175], v[212:215], v[6:9]
	v_mfma_f32_16x16x32_bf16 v[2:5], v[180:183], v[212:215], v[2:5]
	s_setprio 0
	s_barrier
	s_add_i32 s52, s52, 2
	s_add_u32 s24, s24, 0x100
	s_addc_u32 s25, s25, 0
	s_add_u32 s50, s50, 0x100
	s_addc_u32 s51, s51, 0
	s_cmp_gt_u32 s52, 29
	s_cbranch_scc0 .LBB0_1551

; #define PG8_STAGE(bufoff, gbase, voff) do { _Pragma("unroll") for (int _i = 0; _i < 2; ++_i) \
;         __builtin_amdgcn_global_load_lds((const unsigned*)((const char*)(gbase) + (voff)[_i]), (PG8_LAS unsigned*)(lds + (bufoff) + ldsw + _i * 8192), 16, 0, 0); } while (0)
; #define PG8_LDA(dst, b, h) do { _Pragma("unroll") for (int m = 0; m < 4; ++m) _Pragma("unroll") for (int k = 0; k < 2; ++k) dst[m][k] = *(const PG8_LAS bf16x8*)(lds + PG8_SA(b, h) + aoff + m * 2048 + k * 1024); } while (0)
; #define PG8_WAIT_V(n) asm volatile("s_waitcnt vmcnt(" #n ")" ::: "memory")
; #define PG8_BAR __builtin_amdgcn_s_barrier()
; template <class Epi, class Sched, bool ALIGN_EPI = false, bool SP2 = false>
; __device__ __forceinline__ void gemm_phase(PG8_LAS unsigned char* lds, const Gemm g, const Sched& S, const Epi& E) {
;     ...
;         const char* nA = has_next ? (const char*)g.A + (size_t)nxt.pm * tstep + (size_t)nxt.kt0 * kstep : cA; const char* nB = has_next ? (const char*)g.Bt + (size_t)nxt.pn * tstep + (size_t)nxt.kt0 * kstep : cB;
;         for (int t = 0; t < nt; t += 2) {
;             if constexpr (Epi::MIDHOOK) { if (t == (nt >> 1)) E.mid(acc, cur, wr, wc, fr, fq); }
;             const bool last = (t == nt - 2);
;             const char* a1 = cA + (size_t)(t + 1) * kstep;
;             const char* a2 = last ? nA : cA + (size_t)(t + 2) * kstep; const char* b2 = last ? nB : cB + (size_t)(t + 2) * kstep;
;             const char* a3 = a2 + kstep; const char* b3 = b2 + kstep;
;             if (last && has_next) S.a_ready(nxt);
;             if constexpr (SP2) {
;             PG8_LDB(B0, 0, 0); PG8_LDB(B1, 0, 1); PG8_SCHED; PG8_LDA(At, 0, 0); PG8_STAGE(PG8_SA(1, 1), a1 + hstep, voffA);
;             PG8_WAIT_V(8); PG8_WAIT_L(0); PG8_BAR; PG8_MMA(0, 0, At, B0); PG8_MMA(0, 1, At, B1); PG8_BAR; PG8_SCHED;
;             PG8_LDA(At, 0, 1); PG8_STAGE(PG8_SB(0, 0), b2, voffB); PG8_STAGE(PG8_SB(0, 1), b2 + hstep, voffB); PG8_STAGE(PG8_SA(0, 0), a2, voffA);
;             PG8_WAIT_V(8); PG8_WAIT_L(0); PG8_BAR; PG8_MMA(1, 0, At, B0); PG8_MMA(1, 1, At, B1); PG8_BAR; PG8_SCHED;
;     ...
; #pragma unroll
;         for (int a = 0; a < 2; ++a)
; #pragma unroll
;             for (int b = 0; b < 2; ++b)
; #pragma unroll
;                 for (int m = 0; m < 4; ++m)
; #pragma unroll
;                     for (int n = 0; n < 2; ++n) acc[a][b][m][n] = (f32x4){0.f, 0.f, 0.f, 0.f};
.LBB0_1655:
	s_add_u32 s56, s26, 0x100
	s_addc_u32 s57, s27, 0
	s_mov_b32 s58, -2
	s_waitcnt lgkmcnt(0)
	ds_read_b128 v[154:157], v151
	ds_read_b128 v[158:161], v151 offset:1024
	ds_read_b128 v[162:165], v151 offset:2048
	ds_read_b128 v[166:169], v151 offset:3072
	ds_read_b128 v[170:173], v152
	ds_read_b128 v[174:177], v152 offset:1024
	ds_read_b128 v[178:181], v152 offset:2048
	ds_read_b128 v[182:185], v152 offset:3072
	s_add_u32 s26, s24, 0x100
	s_addc_u32 s27, s25, 0
	s_cmpk_eq_i32 s58, 0x54
	s_cselect_b32 s31, s7, s27
	s_cselect_b32 s30, s6, s26
	s_cselect_b32 s29, s23, s57
	s_cselect_b32 s28, s22, s56
	v_lshl_add_u64 v[146:147], s[24:25], 0, v[138:139]
	s_add_i32 m0, s38, 0xc000
	ds_read_b128 v[186:189], v153
	ds_read_b128 v[190:193], v153 offset:1024
	ds_read_b128 v[194:197], v153 offset:2048
	ds_read_b128 v[198:201], v153 offset:3072
	ds_read_b128 v[202:205], v153 offset:4096
	ds_read_b128 v[206:209], v153 offset:5120
	ds_read_b128 v[210:213], v153 offset:6144
	ds_read_b128 v[214:217], v153 offset:7168
	global_load_lds_dwordx4 v[146:147], off
	v_lshl_add_u64 v[146:147], s[24:25], 0, v[140:141]
	s_add_i32 m0, s38, 0xe000
	s_nop 0
	global_load_lds_dwordx4 v[146:147], off
	s_waitcnt vmcnt(8)
	s_waitcnt lgkmcnt(0)
	s_barrier
	s_setprio 1
	s_waitcnt lgkmcnt(0)
	v_mfma_f32_16x16x32_bf16 v[126:129], v[154:157], v[186:189], 0
	v_mfma_f32_16x16x32_bf16 v[122:125], v[162:165], v[186:189], 0
	v_mfma_f32_16x16x32_bf16 v[118:121], v[154:157], v[194:197], 0
	v_mfma_f32_16x16x32_bf16 v[110:113], v[162:165], v[194:197], 0
	v_mfma_f32_16x16x32_bf16 v[102:105], v[154:157], v[202:205], 0
	v_mfma_f32_16x16x32_bf16 v[94:97], v[162:165], v[202:205], 0
	v_mfma_f32_16x16x32_bf16 v[86:89], v[154:157], v[210:213], 0
	v_mfma_f32_16x16x32_bf16 v[78:81], v[162:165], v[210:213], 0
	v_mfma_f32_16x16x32_bf16 v[126:129], v[158:161], v[190:193], v[126:129]
	v_mfma_f32_16x16x32_bf16 v[122:125], v[166:169], v[190:193], v[122:125]
	v_mfma_f32_16x16x32_bf16 v[118:121], v[158:161], v[198:201], v[118:121]
	v_mfma_f32_16x16x32_bf16 v[110:113], v[166:169], v[198:201], v[110:113]
	v_mfma_f32_16x16x32_bf16 v[102:105], v[158:161], v[206:209], v[102:105]
	v_mfma_f32_16x16x32_bf16 v[94:97], v[166:169], v[206:209], v[94:97]
	v_mfma_f32_16x16x32_bf16 v[86:89], v[158:161], v[214:217], v[86:89]
	v_mfma_f32_16x16x32_bf16 v[78:81], v[166:169], v[214:217], v[78:81]
	s_setprio 0
	s_setprio 1
	v_mfma_f32_16x16x32_bf16 v[114:117], v[170:173], v[186:189], 0
	v_mfma_f32_16x16x32_bf16 v[106:109], v[178:181], v[186:189], 0
	v_mfma_f32_16x16x32_bf16 v[98:101], v[170:173], v[194:197], 0
	v_mfma_f32_16x16x32_bf16 v[90:93], v[178:181], v[194:197], 0
	v_mfma_f32_16x16x32_bf16 v[82:85], v[170:173], v[202:205], 0
	v_mfma_f32_16x16x32_bf16 v[74:77], v[178:181], v[202:205], 0
	v_mfma_f32_16x16x32_bf16 v[70:73], v[170:173], v[210:213], 0
	v_mfma_f32_16x16x32_bf16 v[66:69], v[178:181], v[210:213], 0
	v_mfma_f32_16x16x32_bf16 v[114:117], v[174:177], v[190:193], v[114:117]
	v_mfma_f32_16x16x32_bf16 v[106:109], v[182:185], v[190:193], v[106:109]
	v_mfma_f32_16x16x32_bf16 v[98:101], v[174:177], v[198:201], v[98:101]
	v_mfma_f32_16x16x32_bf16 v[90:93], v[182:185], v[198:201], v[90:93]
	v_mfma_f32_16x16x32_bf16 v[82:85], v[174:177], v[206:209], v[82:85]
	v_mfma_f32_16x16x32_bf16 v[74:77], v[182:185], v[206:209], v[74:77]
	v_mfma_f32_16x16x32_bf16 v[70:73], v[174:177], v[214:217], v[70:73]
	v_mfma_f32_16x16x32_bf16 v[66:69], v[182:185], v[214:217], v[66:69]
	s_setprio 0
	s_barrier
	s_add_i32 s24, s46, s36
	v_lshl_add_u64 v[146:147], s[28:29], 0, v[134:135]
	s_mov_b32 m0, s24
	ds_read_b128 v[186:189], v153 offset:16384
	ds_read_b128 v[190:193], v153 offset:17408
	ds_read_b128 v[194:197], v153 offset:18432
	ds_read_b128 v[198:201], v153 offset:19456
	ds_read_b128 v[202:205], v153 offset:20480
	ds_read_b128 v[206:209], v153 offset:21504
	ds_read_b128 v[210:213], v153 offset:22528
	ds_read_b128 v[214:217], v153 offset:23552
	global_load_lds_dwordx4 v[146:147], off
	s_add_i32 m0, s24, 0x2000
	s_add_u32 s24, s28, 0x160000
	v_lshl_add_u64 v[218:219], s[28:29], 0, v[130:131]
	s_addc_u32 s25, s29, 0
	s_add_i32 s59, s47, s36
	global_load_lds_dwordx4 v[218:219], off
	v_lshl_add_u64 v[220:221], s[24:25], 0, v[134:135]
	s_mov_b32 m0, s59
	v_lshl_add_u64 v[222:223], s[30:31], 0, v[132:133]
	global_load_lds_dwordx4 v[220:221], off
	v_lshl_add_u64 v[220:221], s[24:25], 0, v[130:131]
	s_add_i32 m0, s59, 0x2000
	s_nop 0
	global_load_lds_dwordx4 v[220:221], off
	v_lshl_add_u64 v[220:221], s[30:31], 0, v[136:137]
	s_mov_b32 m0, s38
	s_nop 0
	global_load_lds_dwordx4 v[220:221], off
	s_mov_b32 m0, s39
	s_nop 0
	global_load_lds_dwordx4 v[222:223], off
	s_waitcnt vmcnt(8)
	s_waitcnt lgkmcnt(0)
	s_barrier
; #define PG8_STAGE(bufoff, gbase, voff) do { _Pragma("unroll") for (int _i = 0; _i < 2; ++_i) \
;         __builtin_amdgcn_global_load_lds((const unsigned*)((const char*)(gbase) + (voff)[_i]), (PG8_LAS unsigned*)(lds + (bufoff) + ldsw + _i * 8192), 16, 0, 0); } while (0)
; #define PG8_LDA(dst, b, h) do { _Pragma("unroll") for (int m = 0; m < 4; ++m) _Pragma("unroll") for (int k = 0; k < 2; ++k) dst[m][k] = *(const PG8_LAS bf16x8*)(lds + PG8_SA(b, h) + aoff + m * 2048 + k * 1024); } while (0)
; #define PG8_LDB(dst, b, h) do { _Pragma("unroll") for (int n = 0; n < 2; ++n) _Pragma("unroll") for (int k = 0; k < 2; ++k) dst[n][k] = *(const PG8_LAS bf16x8*)(lds + PG8_SB(b, h) + boff + n * 2048 + k * 1024); } while (0)
; #define PG8_MMA(ai, bj, At, Bt) do { __builtin_amdgcn_s_setprio(1); _Pragma("unroll") for (int m = 0; m < 4; ++m) _Pragma("unroll") for (int n = 0; n < 2; ++n) _Pragma("unroll") for (int k = 0; k < 2; ++k) \
;         acc[ai][bj][m][n] = __builtin_amdgcn_mfma_f32_16x16x32_bf16(Bt[n][k], At[m][k], acc[ai][bj][m][n], 0, 0, 0); __builtin_amdgcn_s_setprio(0); } while (0)
; #define PG8_WAIT_V(n) asm volatile("s_waitcnt vmcnt(" #n ")" ::: "memory")
; #define PG8_WAIT_L(n) asm volatile("s_waitcnt lgkmcnt(" #n ")" ::: "memory")
; #define PG8_BAR __builtin_amdgcn_s_barrier()
; #define PG8_SCHED __builtin_amdgcn_sched_barrier(0)
; template <class Epi, class Sched, bool ALIGN_EPI = false, bool SP2 = false>
; __device__ __forceinline__ void gemm_phase(PG8_LAS unsigned char* lds, const Gemm g, const Sched& S, const Epi& E) {
;     ...
;             PG8_LDA(At, 0, 1); PG8_STAGE(PG8_SB(0, 0), b2, voffB); PG8_STAGE(PG8_SB(0, 1), b2 + hstep, voffB); PG8_STAGE(PG8_SA(0, 0), a2, voffA);
;             PG8_WAIT_V(8); PG8_WAIT_L(0); PG8_BAR; PG8_MMA(1, 0, At, B0); PG8_MMA(1, 1, At, B1); PG8_BAR; PG8_SCHED;
;             PG8_LDB(B0, 1, 0); PG8_LDB(B1, 1, 1); PG8_SCHED; PG8_LDA(At, 1, 0); PG8_STAGE(PG8_SA(0, 1), a2 + hstep, voffA);
;             PG8_WAIT_V(8); PG8_WAIT_L(0); PG8_BAR; PG8_MMA(0, 0, At, B0); PG8_MMA(0, 1, At, B1); PG8_BAR; PG8_SCHED;
	s_setprio 1
	s_waitcnt lgkmcnt(0)
	v_mfma_f32_16x16x32_bf16 v[62:65], v[154:157], v[186:189], 0
	v_mfma_f32_16x16x32_bf16 v[58:61], v[162:165], v[186:189], 0
	v_mfma_f32_16x16x32_bf16 v[54:57], v[154:157], v[194:197], 0
	v_mfma_f32_16x16x32_bf16 v[46:49], v[162:165], v[194:197], 0
	v_mfma_f32_16x16x32_bf16 v[38:41], v[154:157], v[202:205], 0
	v_mfma_f32_16x16x32_bf16 v[30:33], v[162:165], v[202:205], 0
	v_mfma_f32_16x16x32_bf16 v[22:25], v[154:157], v[210:213], 0
	v_mfma_f32_16x16x32_bf16 v[14:17], v[162:165], v[210:213], 0
	v_mfma_f32_16x16x32_bf16 v[62:65], v[158:161], v[190:193], v[62:65]
	v_mfma_f32_16x16x32_bf16 v[58:61], v[166:169], v[190:193], v[58:61]
	v_mfma_f32_16x16x32_bf16 v[54:57], v[158:161], v[198:201], v[54:57]
	v_mfma_f32_16x16x32_bf16 v[46:49], v[166:169], v[198:201], v[46:49]
	v_mfma_f32_16x16x32_bf16 v[38:41], v[158:161], v[206:209], v[38:41]
	v_mfma_f32_16x16x32_bf16 v[30:33], v[166:169], v[206:209], v[30:33]
	v_mfma_f32_16x16x32_bf16 v[22:25], v[158:161], v[214:217], v[22:25]
	v_mfma_f32_16x16x32_bf16 v[14:17], v[166:169], v[214:217], v[14:17]
	s_setprio 0
	s_setprio 1
	v_mfma_f32_16x16x32_bf16 v[50:53], v[170:173], v[186:189], 0
	v_mfma_f32_16x16x32_bf16 v[42:45], v[178:181], v[186:189], 0
	v_mfma_f32_16x16x32_bf16 v[34:37], v[170:173], v[194:197], 0
	v_mfma_f32_16x16x32_bf16 v[26:29], v[178:181], v[194:197], 0
	v_mfma_f32_16x16x32_bf16 v[18:21], v[170:173], v[202:205], 0
	v_mfma_f32_16x16x32_bf16 v[10:13], v[178:181], v[202:205], 0
	v_mfma_f32_16x16x32_bf16 v[6:9], v[170:173], v[210:213], 0
	v_mfma_f32_16x16x32_bf16 v[2:5], v[178:181], v[210:213], 0
	v_mfma_f32_16x16x32_bf16 v[50:53], v[174:177], v[190:193], v[50:53]
	v_mfma_f32_16x16x32_bf16 v[42:45], v[182:185], v[190:193], v[42:45]
	v_mfma_f32_16x16x32_bf16 v[34:37], v[174:177], v[198:201], v[34:37]
	v_mfma_f32_16x16x32_bf16 v[26:29], v[182:185], v[198:201], v[26:29]
	v_mfma_f32_16x16x32_bf16 v[18:21], v[174:177], v[206:209], v[18:21]
	v_mfma_f32_16x16x32_bf16 v[10:13], v[182:185], v[206:209], v[10:13]
	v_mfma_f32_16x16x32_bf16 v[6:9], v[174:177], v[214:217], v[6:9]
	v_mfma_f32_16x16x32_bf16 v[2:5], v[182:185], v[214:217], v[2:5]
	s_setprio 0
	s_barrier
	s_add_i32 s59, 0, 0x18000
	s_add_i32 s60, 0, 0x1c000
	v_add_u32_e32 v166, s59, v149
	v_add_u32_e32 v182, s60, v149
	ds_read_b128 v[154:157], v166
	ds_read_b128 v[158:161], v166 offset:1024
	ds_read_b128 v[162:165], v166 offset:2048
	ds_read_b128 v[166:169], v166 offset:3072
	ds_read_b128 v[170:173], v182
	ds_read_b128 v[174:177], v182 offset:1024
	ds_read_b128 v[178:181], v182 offset:2048
	ds_read_b128 v[182:185], v182 offset:3072
	s_add_u32 s24, s30, 0x160000
	s_addc_u32 s25, s31, 0
	s_mov_b32 m0, s40
	v_lshl_add_u64 v[224:225], s[24:25], 0, v[136:137]
	ds_read_b128 v[186:189], v153 offset:32768
	ds_read_b128 v[190:193], v153 offset:33792
	ds_read_b128 v[194:197], v153 offset:34816
	ds_read_b128 v[198:201], v153 offset:35840
	ds_read_b128 v[202:205], v153 offset:36864
	ds_read_b128 v[206:209], v153 offset:37888
	ds_read_b128 v[210:213], v153 offset:38912
	ds_read_b128 v[214:217], v153 offset:39936
	global_load_lds_dwordx4 v[224:225], off
	v_lshl_add_u64 v[224:225], s[24:25], 0, v[132:133]
	s_mov_b32 m0, s41
	s_nop 0
	global_load_lds_dwordx4 v[224:225], off
	s_waitcnt vmcnt(8)
	s_waitcnt lgkmcnt(0)
	s_barrier
	s_setprio 1
	s_waitcnt lgkmcnt(0)
	v_mfma_f32_16x16x32_bf16 v[126:129], v[154:157], v[186:189], v[126:129]
	v_mfma_f32_16x16x32_bf16 v[122:125], v[162:165], v[186:189], v[122:125]
	v_mfma_f32_16x16x32_bf16 v[118:121], v[154:157], v[194:197], v[118:121]
	v_mfma_f32_16x16x32_bf16 v[110:113], v[162:165], v[194:197], v[110:113]
	v_mfma_f32_16x16x32_bf16 v[102:105], v[154:157], v[202:205], v[102:105]
	v_mfma_f32_16x16x32_bf16 v[94:97], v[162:165], v[202:205], v[94:97]
	v_mfma_f32_16x16x32_bf16 v[86:89], v[154:157], v[210:213], v[86:89]
	v_mfma_f32_16x16x32_bf16 v[78:81], v[162:165], v[210:213], v[78:81]
	v_mfma_f32_16x16x32_bf16 v[126:129], v[158:161], v[190:193], v[126:129]
	v_mfma_f32_16x16x32_bf16 v[122:125], v[166:169], v[190:193], v[122:125]
	v_mfma_f32_16x16x32_bf16 v[118:121], v[158:161], v[198:201], v[118:121]
	v_mfma_f32_16x16x32_bf16 v[110:113], v[166:169], v[198:201], v[110:113]
	v_mfma_f32_16x16x32_bf16 v[102:105], v[158:161], v[206:209], v[102:105]
	v_mfma_f32_16x16x32_bf16 v[94:97], v[166:169], v[206:209], v[94:97]
	v_mfma_f32_16x16x32_bf16 v[86:89], v[158:161], v[214:217], v[86:89]
	v_mfma_f32_16x16x32_bf16 v[78:81], v[166:169], v[214:217], v[78:81]
	s_setprio 0
	s_setprio 1
	v_mfma_f32_16x16x32_bf16 v[114:117], v[170:173], v[186:189], v[114:117]
	v_mfma_f32_16x16x32_bf16 v[106:109], v[178:181], v[186:189], v[106:109]
	v_mfma_f32_16x16x32_bf16 v[98:101], v[170:173], v[194:197], v[98:101]
	v_mfma_f32_16x16x32_bf16 v[90:93], v[178:181], v[194:197], v[90:93]
	v_mfma_f32_16x16x32_bf16 v[82:85], v[170:173], v[202:205], v[82:85]
	v_mfma_f32_16x16x32_bf16 v[74:77], v[178:181], v[202:205], v[74:77]
	v_mfma_f32_16x16x32_bf16 v[70:73], v[170:173], v[210:213], v[70:73]
	v_mfma_f32_16x16x32_bf16 v[66:69], v[178:181], v[210:213], v[66:69]
	v_mfma_f32_16x16x32_bf16 v[114:117], v[174:177], v[190:193], v[114:117]
	v_mfma_f32_16x16x32_bf16 v[106:109], v[182:185], v[190:193], v[106:109]
	v_mfma_f32_16x16x32_bf16 v[98:101], v[174:177], v[198:201], v[98:101]
	v_mfma_f32_16x16x32_bf16 v[90:93], v[182:185], v[198:201], v[90:93]
	v_mfma_f32_16x16x32_bf16 v[82:85], v[174:177], v[206:209], v[82:85]
	v_mfma_f32_16x16x32_bf16 v[74:77], v[182:185], v[206:209], v[74:77]
	v_mfma_f32_16x16x32_bf16 v[70:73], v[174:177], v[214:217], v[70:73]
	v_mfma_f32_16x16x32_bf16 v[66:69], v[182:185], v[214:217], v[66:69]
	s_setprio 0
	s_barrier
; #define PG8_STAGE(bufoff, gbase, voff) do { _Pragma("unroll") for (int _i = 0; _i < 2; ++_i) \
;         __builtin_amdgcn_global_load_lds((const unsigned*)((const char*)(gbase) + (voff)[_i]), (PG8_LAS unsigned*)(lds + (bufoff) + ldsw + _i * 8192), 16, 0, 0); } while (0)
; #define PG8_LDA(dst, b, h) do { _Pragma("unroll") for (int m = 0; m < 4; ++m) _Pragma("unroll") for (int k = 0; k < 2; ++k) dst[m][k] = *(const PG8_LAS bf16x8*)(lds + PG8_SA(b, h) + aoff + m * 2048 + k * 1024); } while (0)
; #define PG8_WAIT_V(n) asm volatile("s_waitcnt vmcnt(" #n ")" ::: "memory")
; #define PG8_BAR __builtin_amdgcn_s_barrier()
; template <class Epi, class Sched, bool ALIGN_EPI = false, bool SP2 = false>
; __device__ __forceinline__ void gemm_phase(PG8_LAS unsigned char* lds, const Gemm g, const Sched& S, const Epi& E) {
;     ...
;         for (int t = 0; t < nt; t += 2) {
;             if constexpr (Epi::MIDHOOK) { if (t == (nt >> 1)) E.mid(acc, cur, wr, wc, fr, fq); }
;             const bool last = (t == nt - 2);
;             const char* a1 = cA + (size_t)(t + 1) * kstep;
;             const char* a2 = last ? nA : cA + (size_t)(t + 2) * kstep; const char* b2 = last ? nB : cB + (size_t)(t + 2) * kstep;
;             const char* a3 = a2 + kstep; const char* b3 = b2 + kstep;
;             if (last && has_next) S.a_ready(nxt);
;             if constexpr (SP2) {
;             PG8_LDB(B0, 0, 0); PG8_LDB(B1, 0, 1); PG8_SCHED; PG8_LDA(At, 0, 0); PG8_STAGE(PG8_SA(1, 1), a1 + hstep, voffA);
;             PG8_WAIT_V(8); PG8_WAIT_L(0); PG8_BAR; PG8_MMA(0, 0, At, B0); PG8_MMA(0, 1, At, B1); PG8_BAR; PG8_SCHED;
;             PG8_LDA(At, 0, 1); PG8_STAGE(PG8_SB(0, 0), b2, voffB); PG8_STAGE(PG8_SB(0, 1), b2 + hstep, voffB); PG8_STAGE(PG8_SA(0, 0), a2, voffA);
;             PG8_WAIT_V(8); PG8_WAIT_L(0); PG8_BAR; PG8_MMA(1, 0, At, B0); PG8_MMA(1, 1, At, B1); PG8_BAR; PG8_SCHED;
;             PG8_LDB(B0, 1, 0); PG8_LDB(B1, 1, 1); PG8_SCHED; PG8_LDA(At, 1, 0); PG8_STAGE(PG8_SA(0, 1), a2 + hstep, voffA);
;             PG8_WAIT_V(8); PG8_WAIT_L(0); PG8_BAR; PG8_MMA(0, 0, At, B0); PG8_MMA(0, 1, At, B1); PG8_BAR; PG8_SCHED;
;             PG8_LDA(At, 1, 1); PG8_STAGE(PG8_SB(1, 0), b3, voffB); PG8_STAGE(PG8_SB(1, 1), b3 + hstep, voffB); PG8_STAGE(PG8_SA(1, 0), a3, voffA);
;             PG8_WAIT_V(8); PG8_WAIT_L(0); PG8_BAR; PG8_MMA(1, 0, At, B0); PG8_MMA(1, 1, At, B1); PG8_BAR; PG8_SCHED;
	s_add_i32 s24, s59, s36
	v_lshl_add_u64 v[146:147], v[146:147], 0, s[10:11]
	s_mov_b32 m0, s24
	ds_read_b128 v[186:189], v153 offset:49152
	ds_read_b128 v[190:193], v153 offset:50176
	ds_read_b128 v[194:197], v153 offset:51200
	ds_read_b128 v[198:201], v153 offset:52224
	ds_read_b128 v[202:205], v153 offset:53248
	ds_read_b128 v[206:209], v153 offset:54272
	ds_read_b128 v[210:213], v153 offset:55296
	ds_read_b128 v[214:217], v153 offset:56320
	global_load_lds_dwordx4 v[146:147], off
	s_add_i32 m0, s24, 0x2000
	s_add_u32 s24, s28, 0x160080
	v_lshl_add_u64 v[146:147], v[218:219], 0, s[10:11]
	s_addc_u32 s25, s29, 0
	s_add_i32 s28, s60, s36
	global_load_lds_dwordx4 v[146:147], off
	v_lshl_add_u64 v[146:147], s[24:25], 0, v[134:135]
	s_mov_b32 m0, s28
	s_nop 0
	global_load_lds_dwordx4 v[146:147], off
	v_lshl_add_u64 v[146:147], s[24:25], 0, v[130:131]
	s_add_i32 m0, s28, 0x2000
	s_nop 0
	global_load_lds_dwordx4 v[146:147], off
	v_lshl_add_u64 v[146:147], v[220:221], 0, s[10:11]
	s_mov_b32 m0, s44
	s_nop 0
	global_load_lds_dwordx4 v[146:147], off
	v_lshl_add_u64 v[146:147], v[222:223], 0, s[10:11]
	s_mov_b32 m0, s45
	s_nop 0
	global_load_lds_dwordx4 v[146:147], off
	s_waitcnt vmcnt(8)
	s_waitcnt lgkmcnt(0)
	s_barrier
	s_setprio 1
	s_waitcnt lgkmcnt(0)
	v_mfma_f32_16x16x32_bf16 v[62:65], v[154:157], v[186:189], v[62:65]
	v_mfma_f32_16x16x32_bf16 v[58:61], v[162:165], v[186:189], v[58:61]
	v_mfma_f32_16x16x32_bf16 v[54:57], v[154:157], v[194:197], v[54:57]
	v_mfma_f32_16x16x32_bf16 v[46:49], v[162:165], v[194:197], v[46:49]
	v_mfma_f32_16x16x32_bf16 v[38:41], v[154:157], v[202:205], v[38:41]
	v_mfma_f32_16x16x32_bf16 v[30:33], v[162:165], v[202:205], v[30:33]
	v_mfma_f32_16x16x32_bf16 v[22:25], v[154:157], v[210:213], v[22:25]
	v_mfma_f32_16x16x32_bf16 v[14:17], v[162:165], v[210:213], v[14:17]
	v_mfma_f32_16x16x32_bf16 v[62:65], v[158:161], v[190:193], v[62:65]
	v_mfma_f32_16x16x32_bf16 v[58:61], v[166:169], v[190:193], v[58:61]
	v_mfma_f32_16x16x32_bf16 v[54:57], v[158:161], v[198:201], v[54:57]
	v_mfma_f32_16x16x32_bf16 v[46:49], v[166:169], v[198:201], v[46:49]
	v_mfma_f32_16x16x32_bf16 v[38:41], v[158:161], v[206:209], v[38:41]
	v_mfma_f32_16x16x32_bf16 v[30:33], v[166:169], v[206:209], v[30:33]
	v_mfma_f32_16x16x32_bf16 v[22:25], v[158:161], v[214:217], v[22:25]
	v_mfma_f32_16x16x32_bf16 v[14:17], v[166:169], v[214:217], v[14:17]
	s_setprio 0
	s_setprio 1
	v_mfma_f32_16x16x32_bf16 v[50:53], v[170:173], v[186:189], v[50:53]
	v_mfma_f32_16x16x32_bf16 v[42:45], v[178:181], v[186:189], v[42:45]
	v_mfma_f32_16x16x32_bf16 v[34:37], v[170:173], v[194:197], v[34:37]
	v_mfma_f32_16x16x32_bf16 v[26:29], v[178:181], v[194:197], v[26:29]
	v_mfma_f32_16x16x32_bf16 v[18:21], v[170:173], v[202:205], v[18:21]
	v_mfma_f32_16x16x32_bf16 v[10:13], v[178:181], v[202:205], v[10:13]
	v_mfma_f32_16x16x32_bf16 v[6:9], v[170:173], v[210:213], v[6:9]
	v_mfma_f32_16x16x32_bf16 v[2:5], v[178:181], v[210:213], v[2:5]
	v_mfma_f32_16x16x32_bf16 v[50:53], v[174:177], v[190:193], v[50:53]
	v_mfma_f32_16x16x32_bf16 v[42:45], v[182:185], v[190:193], v[42:45]
	v_mfma_f32_16x16x32_bf16 v[34:37], v[174:177], v[198:201], v[34:37]
	v_mfma_f32_16x16x32_bf16 v[26:29], v[182:185], v[198:201], v[26:29]
	v_mfma_f32_16x16x32_bf16 v[18:21], v[174:177], v[206:209], v[18:21]
	v_mfma_f32_16x16x32_bf16 v[10:13], v[182:185], v[206:209], v[10:13]
	v_mfma_f32_16x16x32_bf16 v[6:9], v[174:177], v[214:217], v[6:9]
	v_mfma_f32_16x16x32_bf16 v[2:5], v[182:185], v[214:217], v[2:5]
	s_setprio 0
	s_barrier
	s_add_i32 s58, s58, 2
	s_add_u32 s56, s56, 0x100
	s_addc_u32 s57, s57, 0
	s_cmpk_gt_u32 s58, 0x55
	s_mov_b64 s[24:25], s[26:27]
	s_cbranch_scc1 .Lkx_1656
.LBB0_1656:
	ds_read_b128 v[154:157], v151
	ds_read_b128 v[158:161], v151 offset:1024
	ds_read_b128 v[162:165], v151 offset:2048
	ds_read_b128 v[166:169], v151 offset:3072
	ds_read_b128 v[170:173], v152
	ds_read_b128 v[174:177], v152 offset:1024
	ds_read_b128 v[178:181], v152 offset:2048
	ds_read_b128 v[182:185], v152 offset:3072
	s_add_u32 s26, s24, 0x100
	s_addc_u32 s27, s25, 0
	s_cmpk_eq_i32 s58, 0x54
	s_cselect_b32 s31, s7, s27
	s_cselect_b32 s30, s6, s26
	s_cselect_b32 s29, s23, s57
	s_cselect_b32 s28, s22, s56
	v_lshl_add_u64 v[146:147], s[24:25], 0, v[138:139]
	s_add_i32 m0, s38, 0xc000
	ds_read_b128 v[186:189], v153
	ds_read_b128 v[190:193], v153 offset:1024
	ds_read_b128 v[194:197], v153 offset:2048
	ds_read_b128 v[198:201], v153 offset:3072
	ds_read_b128 v[202:205], v153 offset:4096
	ds_read_b128 v[206:209], v153 offset:5120
	ds_read_b128 v[210:213], v153 offset:6144
	ds_read_b128 v[214:217], v153 offset:7168
	global_load_lds_dwordx4 v[146:147], off
	v_lshl_add_u64 v[146:147], s[24:25], 0, v[140:141]
	s_add_i32 m0, s38, 0xe000
	s_nop 0
	global_load_lds_dwordx4 v[146:147], off
	s_waitcnt vmcnt(8)
	s_waitcnt lgkmcnt(0)
	s_barrier
; #define PG8_STAGE(bufoff, gbase, voff) do { _Pragma("unroll") for (int _i = 0; _i < 2; ++_i) \
;         __builtin_amdgcn_global_load_lds((const unsigned*)((const char*)(gbase) + (voff)[_i]), (PG8_LAS unsigned*)(lds + (bufoff) + ldsw + _i * 8192), 16, 0, 0); } while (0)
; #define PG8_LDA(dst, b, h) do { _Pragma("unroll") for (int m = 0; m < 4; ++m) _Pragma("unroll") for (int k = 0; k < 2; ++k) dst[m][k] = *(const PG8_LAS bf16x8*)(lds + PG8_SA(b, h) + aoff + m * 2048 + k * 1024); } while (0)
; #define PG8_LDB(dst, b, h) do { _Pragma("unroll") for (int n = 0; n < 2; ++n) _Pragma("unroll") for (int k = 0; k < 2; ++k) dst[n][k] = *(const PG8_LAS bf16x8*)(lds + PG8_SB(b, h) + boff + n * 2048 + k * 1024); } while (0)
; #define PG8_MMA(ai, bj, At, Bt) do { __builtin_amdgcn_s_setprio(1); _Pragma("unroll") for (int m = 0; m < 4; ++m) _Pragma("unroll") for (int n = 0; n < 2; ++n) _Pragma("unroll") for (int k = 0; k < 2; ++k) \
;         acc[ai][bj][m][n] = __builtin_amdgcn_mfma_f32_16x16x32_bf16(Bt[n][k], At[m][k], acc[ai][bj][m][n], 0, 0, 0); __builtin_amdgcn_s_setprio(0); } while (0)
; #define PG8_WAIT_V(n) asm volatile("s_waitcnt vmcnt(" #n ")" ::: "memory")
; #define PG8_WAIT_L(n) asm volatile("s_waitcnt lgkmcnt(" #n ")" ::: "memory")
; #define PG8_BAR __builtin_amdgcn_s_barrier()
; #define PG8_SCHED __builtin_amdgcn_sched_barrier(0)
; template <class Epi, class Sched, bool ALIGN_EPI = false, bool SP2 = false>
; __device__ __forceinline__ void gemm_phase(PG8_LAS unsigned char* lds, const Gemm g, const Sched& S, const Epi& E) {
;     ...
;             PG8_LDB(B0, 0, 0); PG8_LDB(B1, 0, 1); PG8_SCHED; PG8_LDA(At, 0, 0); PG8_STAGE(PG8_SA(1, 1), a1 + hstep, voffA);
;             PG8_WAIT_V(8); PG8_WAIT_L(0); PG8_BAR; PG8_MMA(0, 0, At, B0); PG8_MMA(0, 1, At, B1); PG8_BAR; PG8_SCHED;
;             PG8_LDA(At, 0, 1); PG8_STAGE(PG8_SB(0, 0), b2, voffB); PG8_STAGE(PG8_SB(0, 1), b2 + hstep, voffB); PG8_STAGE(PG8_SA(0, 0), a2, voffA);
;             PG8_WAIT_V(8); PG8_WAIT_L(0); PG8_BAR; PG8_MMA(1, 0, At, B0); PG8_MMA(1, 1, At, B1); PG8_BAR; PG8_SCHED;
	s_setprio 1
	s_waitcnt lgkmcnt(0)
	v_mfma_f32_16x16x32_bf16 v[126:129], v[154:157], v[186:189], v[126:129]
	v_mfma_f32_16x16x32_bf16 v[122:125], v[162:165], v[186:189], v[122:125]
	v_mfma_f32_16x16x32_bf16 v[118:121], v[154:157], v[194:197], v[118:121]
	v_mfma_f32_16x16x32_bf16 v[110:113], v[162:165], v[194:197], v[110:113]
	v_mfma_f32_16x16x32_bf16 v[102:105], v[154:157], v[202:205], v[102:105]
	v_mfma_f32_16x16x32_bf16 v[94:97], v[162:165], v[202:205], v[94:97]
	v_mfma_f32_16x16x32_bf16 v[86:89], v[154:157], v[210:213], v[86:89]
	v_mfma_f32_16x16x32_bf16 v[78:81], v[162:165], v[210:213], v[78:81]
	v_mfma_f32_16x16x32_bf16 v[126:129], v[158:161], v[190:193], v[126:129]
	v_mfma_f32_16x16x32_bf16 v[122:125], v[166:169], v[190:193], v[122:125]
	v_mfma_f32_16x16x32_bf16 v[118:121], v[158:161], v[198:201], v[118:121]
	v_mfma_f32_16x16x32_bf16 v[110:113], v[166:169], v[198:201], v[110:113]
	v_mfma_f32_16x16x32_bf16 v[102:105], v[158:161], v[206:209], v[102:105]
	v_mfma_f32_16x16x32_bf16 v[94:97], v[166:169], v[206:209], v[94:97]
	v_mfma_f32_16x16x32_bf16 v[86:89], v[158:161], v[214:217], v[86:89]
	v_mfma_f32_16x16x32_bf16 v[78:81], v[166:169], v[214:217], v[78:81]
	s_setprio 0
	s_setprio 1
	v_mfma_f32_16x16x32_bf16 v[114:117], v[170:173], v[186:189], v[114:117]
	v_mfma_f32_16x16x32_bf16 v[106:109], v[178:181], v[186:189], v[106:109]
	v_mfma_f32_16x16x32_bf16 v[98:101], v[170:173], v[194:197], v[98:101]
	v_mfma_f32_16x16x32_bf16 v[90:93], v[178:181], v[194:197], v[90:93]
	v_mfma_f32_16x16x32_bf16 v[82:85], v[170:173], v[202:205], v[82:85]
	v_mfma_f32_16x16x32_bf16 v[74:77], v[178:181], v[202:205], v[74:77]
	v_mfma_f32_16x16x32_bf16 v[70:73], v[170:173], v[210:213], v[70:73]
	v_mfma_f32_16x16x32_bf16 v[66:69], v[178:181], v[210:213], v[66:69]
	v_mfma_f32_16x16x32_bf16 v[114:117], v[174:177], v[190:193], v[114:117]
	v_mfma_f32_16x16x32_bf16 v[106:109], v[182:185], v[190:193], v[106:109]
	v_mfma_f32_16x16x32_bf16 v[98:101], v[174:177], v[198:201], v[98:101]
	v_mfma_f32_16x16x32_bf16 v[90:93], v[182:185], v[198:201], v[90:93]
	v_mfma_f32_16x16x32_bf16 v[82:85], v[174:177], v[206:209], v[82:85]
	v_mfma_f32_16x16x32_bf16 v[74:77], v[182:185], v[206:209], v[74:77]
	v_mfma_f32_16x16x32_bf16 v[70:73], v[174:177], v[214:217], v[70:73]
	v_mfma_f32_16x16x32_bf16 v[66:69], v[182:185], v[214:217], v[66:69]
	s_setprio 0
	s_barrier
	s_add_i32 s24, s46, s36
	v_lshl_add_u64 v[146:147], s[28:29], 0, v[134:135]
	s_mov_b32 m0, s24
	ds_read_b128 v[186:189], v153 offset:16384
	ds_read_b128 v[190:193], v153 offset:17408
	ds_read_b128 v[194:197], v153 offset:18432
	ds_read_b128 v[198:201], v153 offset:19456
	ds_read_b128 v[202:205], v153 offset:20480
	ds_read_b128 v[206:209], v153 offset:21504
	ds_read_b128 v[210:213], v153 offset:22528
	ds_read_b128 v[214:217], v153 offset:23552
	global_load_lds_dwordx4 v[146:147], off
	s_add_i32 m0, s24, 0x2000
	s_add_u32 s24, s28, 0x160000
	v_lshl_add_u64 v[218:219], s[28:29], 0, v[130:131]
	s_addc_u32 s25, s29, 0
	s_add_i32 s59, s47, s36
	global_load_lds_dwordx4 v[218:219], off
	v_lshl_add_u64 v[220:221], s[24:25], 0, v[134:135]
	s_mov_b32 m0, s59
	v_lshl_add_u64 v[222:223], s[30:31], 0, v[132:133]
	global_load_lds_dwordx4 v[220:221], off
	v_lshl_add_u64 v[220:221], s[24:25], 0, v[130:131]
	s_add_i32 m0, s59, 0x2000
	s_nop 0
	global_load_lds_dwordx4 v[220:221], off
	v_lshl_add_u64 v[220:221], s[30:31], 0, v[136:137]
	s_mov_b32 m0, s38
	s_nop 0
	global_load_lds_dwordx4 v[220:221], off
	s_mov_b32 m0, s39
	s_nop 0
	global_load_lds_dwordx4 v[222:223], off
	s_waitcnt vmcnt(8)
	s_waitcnt lgkmcnt(0)
	s_barrier
	s_setprio 1
	s_waitcnt lgkmcnt(0)
	v_mfma_f32_16x16x32_bf16 v[62:65], v[154:157], v[186:189], v[62:65]
	v_mfma_f32_16x16x32_bf16 v[58:61], v[162:165], v[186:189], v[58:61]
	v_mfma_f32_16x16x32_bf16 v[54:57], v[154:157], v[194:197], v[54:57]
	v_mfma_f32_16x16x32_bf16 v[46:49], v[162:165], v[194:197], v[46:49]
	v_mfma_f32_16x16x32_bf16 v[38:41], v[154:157], v[202:205], v[38:41]
	v_mfma_f32_16x16x32_bf16 v[30:33], v[162:165], v[202:205], v[30:33]
	v_mfma_f32_16x16x32_bf16 v[22:25], v[154:157], v[210:213], v[22:25]
	v_mfma_f32_16x16x32_bf16 v[14:17], v[162:165], v[210:213], v[14:17]
	v_mfma_f32_16x16x32_bf16 v[62:65], v[158:161], v[190:193], v[62:65]
	v_mfma_f32_16x16x32_bf16 v[58:61], v[166:169], v[190:193], v[58:61]
	v_mfma_f32_16x16x32_bf16 v[54:57], v[158:161], v[198:201], v[54:57]
	v_mfma_f32_16x16x32_bf16 v[46:49], v[166:169], v[198:201], v[46:49]
	v_mfma_f32_16x16x32_bf16 v[38:41], v[158:161], v[206:209], v[38:41]
	v_mfma_f32_16x16x32_bf16 v[30:33], v[166:169], v[206:209], v[30:33]
	v_mfma_f32_16x16x32_bf16 v[22:25], v[158:161], v[214:217], v[22:25]
	v_mfma_f32_16x16x32_bf16 v[14:17], v[166:169], v[214:217], v[14:17]
	s_setprio 0
	s_setprio 1
	v_mfma_f32_16x16x32_bf16 v[50:53], v[170:173], v[186:189], v[50:53]
	v_mfma_f32_16x16x32_bf16 v[42:45], v[178:181], v[186:189], v[42:45]
	v_mfma_f32_16x16x32_bf16 v[34:37], v[170:173], v[194:197], v[34:37]
	v_mfma_f32_16x16x32_bf16 v[26:29], v[178:181], v[194:197], v[26:29]
	v_mfma_f32_16x16x32_bf16 v[18:21], v[170:173], v[202:205], v[18:21]
	v_mfma_f32_16x16x32_bf16 v[10:13], v[178:181], v[202:205], v[10:13]
	v_mfma_f32_16x16x32_bf16 v[6:9], v[170:173], v[210:213], v[6:9]
	v_mfma_f32_16x16x32_bf16 v[2:5], v[178:181], v[210:213], v[2:5]
	v_mfma_f32_16x16x32_bf16 v[50:53], v[174:177], v[190:193], v[50:53]
	v_mfma_f32_16x16x32_bf16 v[42:45], v[182:185], v[190:193], v[42:45]
	v_mfma_f32_16x16x32_bf16 v[34:37], v[174:177], v[198:201], v[34:37]
	v_mfma_f32_16x16x32_bf16 v[26:29], v[182:185], v[198:201], v[26:29]
	v_mfma_f32_16x16x32_bf16 v[18:21], v[174:177], v[206:209], v[18:21]
	v_mfma_f32_16x16x32_bf16 v[10:13], v[182:185], v[206:209], v[10:13]
	v_mfma_f32_16x16x32_bf16 v[6:9], v[174:177], v[214:217], v[6:9]
	v_mfma_f32_16x16x32_bf16 v[2:5], v[182:185], v[214:217], v[2:5]
	s_setprio 0
	s_barrier
; #define PG8_STAGE(bufoff, gbase, voff) do { _Pragma("unroll") for (int _i = 0; _i < 2; ++_i) \
;         __builtin_amdgcn_global_load_lds((const unsigned*)((const char*)(gbase) + (voff)[_i]), (PG8_LAS unsigned*)(lds + (bufoff) + ldsw + _i * 8192), 16, 0, 0); } while (0)
; #define PG8_LDA(dst, b, h) do { _Pragma("unroll") for (int m = 0; m < 4; ++m) _Pragma("unroll") for (int k = 0; k < 2; ++k) dst[m][k] = *(const PG8_LAS bf16x8*)(lds + PG8_SA(b, h) + aoff + m * 2048 + k * 1024); } while (0)
; #define PG8_LDB(dst, b, h) do { _Pragma("unroll") for (int n = 0; n < 2; ++n) _Pragma("unroll") for (int k = 0; k < 2; ++k) dst[n][k] = *(const PG8_LAS bf16x8*)(lds + PG8_SB(b, h) + boff + n * 2048 + k * 1024); } while (0)
; #define PG8_MMA(ai, bj, At, Bt) do { __builtin_amdgcn_s_setprio(1); _Pragma("unroll") for (int m = 0; m < 4; ++m) _Pragma("unroll") for (int n = 0; n < 2; ++n) _Pragma("unroll") for (int k = 0; k < 2; ++k) \
;         acc[ai][bj][m][n] = __builtin_amdgcn_mfma_f32_16x16x32_bf16(Bt[n][k], At[m][k], acc[ai][bj][m][n], 0, 0, 0); __builtin_amdgcn_s_setprio(0); } while (0)
; #define PG8_WAIT_V(n) asm volatile("s_waitcnt vmcnt(" #n ")" ::: "memory")
; #define PG8_WAIT_L(n) asm volatile("s_waitcnt lgkmcnt(" #n ")" ::: "memory")
; #define PG8_BAR __builtin_amdgcn_s_barrier()
; #define PG8_SCHED __builtin_amdgcn_sched_barrier(0)
; template <class Epi, class Sched, bool ALIGN_EPI = false, bool SP2 = false>
; __device__ __forceinline__ void gemm_phase(PG8_LAS unsigned char* lds, const Gemm g, const Sched& S, const Epi& E) {
;     ...
;             PG8_LDB(B0, 1, 0); PG8_LDB(B1, 1, 1); PG8_SCHED; PG8_LDA(At, 1, 0); PG8_STAGE(PG8_SA(0, 1), a2 + hstep, voffA);
;             PG8_WAIT_V(8); PG8_WAIT_L(0); PG8_BAR; PG8_MMA(0, 0, At, B0); PG8_MMA(0, 1, At, B1); PG8_BAR; PG8_SCHED;
	s_add_i32 s59, 0, 0x18000
	s_add_i32 s60, 0, 0x1c000
	v_add_u32_e32 v166, s59, v149
	v_add_u32_e32 v182, s60, v149
	ds_read_b128 v[154:157], v166
	ds_read_b128 v[158:161], v166 offset:1024
	ds_read_b128 v[162:165], v166 offset:2048
	ds_read_b128 v[166:169], v166 offset:3072
	ds_read_b128 v[170:173], v182
	ds_read_b128 v[174:177], v182 offset:1024
	ds_read_b128 v[178:181], v182 offset:2048
	ds_read_b128 v[182:185], v182 offset:3072
	s_add_u32 s24, s30, 0x160000
	s_addc_u32 s25, s31, 0
	s_mov_b32 m0, s40
	v_lshl_add_u64 v[224:225], s[24:25], 0, v[136:137]
	ds_read_b128 v[186:189], v153 offset:32768
	ds_read_b128 v[190:193], v153 offset:33792
	ds_read_b128 v[194:197], v153 offset:34816
	ds_read_b128 v[198:201], v153 offset:35840
	ds_read_b128 v[202:205], v153 offset:36864
	ds_read_b128 v[206:209], v153 offset:37888
	ds_read_b128 v[210:213], v153 offset:38912
	ds_read_b128 v[214:217], v153 offset:39936
	global_load_lds_dwordx4 v[224:225], off
	v_lshl_add_u64 v[224:225], s[24:25], 0, v[132:133]
	s_mov_b32 m0, s41
	s_nop 0
	global_load_lds_dwordx4 v[224:225], off
	s_waitcnt vmcnt(8)
	s_waitcnt lgkmcnt(0)
	s_barrier
	s_setprio 1
	s_waitcnt lgkmcnt(0)
	v_mfma_f32_16x16x32_bf16 v[126:129], v[154:157], v[186:189], v[126:129]
	v_mfma_f32_16x16x32_bf16 v[122:125], v[162:165], v[186:189], v[122:125]
	v_mfma_f32_16x16x32_bf16 v[118:121], v[154:157], v[194:197], v[118:121]
	v_mfma_f32_16x16x32_bf16 v[110:113], v[162:165], v[194:197], v[110:113]
	v_mfma_f32_16x16x32_bf16 v[102:105], v[154:157], v[202:205], v[102:105]
	v_mfma_f32_16x16x32_bf16 v[94:97], v[162:165], v[202:205], v[94:97]
	v_mfma_f32_16x16x32_bf16 v[86:89], v[154:157], v[210:213], v[86:89]
	v_mfma_f32_16x16x32_bf16 v[78:81], v[162:165], v[210:213], v[78:81]
	v_mfma_f32_16x16x32_bf16 v[126:129], v[158:161], v[190:193], v[126:129]
	v_mfma_f32_16x16x32_bf16 v[122:125], v[166:169], v[190:193], v[122:125]
	v_mfma_f32_16x16x32_bf16 v[118:121], v[158:161], v[198:201], v[118:121]
	v_mfma_f32_16x16x32_bf16 v[110:113], v[166:169], v[198:201], v[110:113]
	v_mfma_f32_16x16x32_bf16 v[102:105], v[158:161], v[206:209], v[102:105]
	v_mfma_f32_16x16x32_bf16 v[94:97], v[166:169], v[206:209], v[94:97]
	v_mfma_f32_16x16x32_bf16 v[86:89], v[158:161], v[214:217], v[86:89]
	v_mfma_f32_16x16x32_bf16 v[78:81], v[166:169], v[214:217], v[78:81]
	s_setprio 0
	s_setprio 1
	v_mfma_f32_16x16x32_bf16 v[114:117], v[170:173], v[186:189], v[114:117]
	v_mfma_f32_16x16x32_bf16 v[106:109], v[178:181], v[186:189], v[106:109]
	v_mfma_f32_16x16x32_bf16 v[98:101], v[170:173], v[194:197], v[98:101]
	v_mfma_f32_16x16x32_bf16 v[90:93], v[178:181], v[194:197], v[90:93]
	v_mfma_f32_16x16x32_bf16 v[82:85], v[170:173], v[202:205], v[82:85]
	v_mfma_f32_16x16x32_bf16 v[74:77], v[178:181], v[202:205], v[74:77]
	v_mfma_f32_16x16x32_bf16 v[70:73], v[170:173], v[210:213], v[70:73]
	v_mfma_f32_16x16x32_bf16 v[66:69], v[178:181], v[210:213], v[66:69]
	v_mfma_f32_16x16x32_bf16 v[114:117], v[174:177], v[190:193], v[114:117]
	v_mfma_f32_16x16x32_bf16 v[106:109], v[182:185], v[190:193], v[106:109]
	v_mfma_f32_16x16x32_bf16 v[98:101], v[174:177], v[198:201], v[98:101]
	v_mfma_f32_16x16x32_bf16 v[90:93], v[182:185], v[198:201], v[90:93]
	v_mfma_f32_16x16x32_bf16 v[82:85], v[174:177], v[206:209], v[82:85]
	v_mfma_f32_16x16x32_bf16 v[74:77], v[182:185], v[206:209], v[74:77]
	v_mfma_f32_16x16x32_bf16 v[70:73], v[174:177], v[214:217], v[70:73]
	v_mfma_f32_16x16x32_bf16 v[66:69], v[182:185], v[214:217], v[66:69]
	s_setprio 0
	s_barrier
; #define PG8_STAGE(bufoff, gbase, voff) do { _Pragma("unroll") for (int _i = 0; _i < 2; ++_i) \
;         __builtin_amdgcn_global_load_lds((const unsigned*)((const char*)(gbase) + (voff)[_i]), (PG8_LAS unsigned*)(lds + (bufoff) + ldsw + _i * 8192), 16, 0, 0); } while (0)
; #define PG8_LDA(dst, b, h) do { _Pragma("unroll") for (int m = 0; m < 4; ++m) _Pragma("unroll") for (int k = 0; k < 2; ++k) dst[m][k] = *(const PG8_LAS bf16x8*)(lds + PG8_SA(b, h) + aoff + m * 2048 + k * 1024); } while (0)
; #define PG8_MMA(ai, bj, At, Bt) do { __builtin_amdgcn_s_setprio(1); _Pragma("unroll") for (int m = 0; m < 4; ++m) _Pragma("unroll") for (int n = 0; n < 2; ++n) _Pragma("unroll") for (int k = 0; k < 2; ++k) \
;         acc[ai][bj][m][n] = __builtin_amdgcn_mfma_f32_16x16x32_bf16(Bt[n][k], At[m][k], acc[ai][bj][m][n], 0, 0, 0); __builtin_amdgcn_s_setprio(0); } while (0)
; #define PG8_WAIT_V(n) asm volatile("s_waitcnt vmcnt(" #n ")" ::: "memory")
; #define PG8_WAIT_L(n) asm volatile("s_waitcnt lgkmcnt(" #n ")" ::: "memory")
; #define PG8_BAR __builtin_amdgcn_s_barrier()
; #define PG8_SCHED __builtin_amdgcn_sched_barrier(0)
; template <class Epi, class Sched, bool ALIGN_EPI = false, bool SP2 = false>
; __device__ __forceinline__ void gemm_phase(PG8_LAS unsigned char* lds, const Gemm g, const Sched& S, const Epi& E) {
;     ...
;         for (int t = 0; t < nt; t += 2) {
;             if constexpr (Epi::MIDHOOK) { if (t == (nt >> 1)) E.mid(acc, cur, wr, wc, fr, fq); }
;             const bool last = (t == nt - 2);
;             const char* a1 = cA + (size_t)(t + 1) * kstep;
;             const char* a2 = last ? nA : cA + (size_t)(t + 2) * kstep; const char* b2 = last ? nB : cB + (size_t)(t + 2) * kstep;
;             const char* a3 = a2 + kstep; const char* b3 = b2 + kstep;
;     ...
;             PG8_LDA(At, 1, 1); PG8_STAGE(PG8_SB(1, 0), b3, voffB); PG8_STAGE(PG8_SB(1, 1), b3 + hstep, voffB); PG8_STAGE(PG8_SA(1, 0), a3, voffA);
;             PG8_WAIT_V(8); PG8_WAIT_L(0); PG8_BAR; PG8_MMA(1, 0, At, B0); PG8_MMA(1, 1, At, B1); PG8_BAR; PG8_SCHED;
	s_add_i32 s24, s59, s36
	v_lshl_add_u64 v[146:147], v[146:147], 0, s[10:11]
	s_mov_b32 m0, s24
	ds_read_b128 v[186:189], v153 offset:49152
	ds_read_b128 v[190:193], v153 offset:50176
	ds_read_b128 v[194:197], v153 offset:51200
	ds_read_b128 v[198:201], v153 offset:52224
	ds_read_b128 v[202:205], v153 offset:53248
	ds_read_b128 v[206:209], v153 offset:54272
	ds_read_b128 v[210:213], v153 offset:55296
	ds_read_b128 v[214:217], v153 offset:56320
	global_load_lds_dwordx4 v[146:147], off
	s_add_i32 m0, s24, 0x2000
	s_add_u32 s24, s28, 0x160080
	v_lshl_add_u64 v[146:147], v[218:219], 0, s[10:11]
	s_addc_u32 s25, s29, 0
	s_add_i32 s28, s60, s36
	global_load_lds_dwordx4 v[146:147], off
	v_lshl_add_u64 v[146:147], s[24:25], 0, v[134:135]
	s_mov_b32 m0, s28
	s_nop 0
	global_load_lds_dwordx4 v[146:147], off
	v_lshl_add_u64 v[146:147], s[24:25], 0, v[130:131]
	s_add_i32 m0, s28, 0x2000
	s_nop 0
	global_load_lds_dwordx4 v[146:147], off
	v_lshl_add_u64 v[146:147], v[220:221], 0, s[10:11]
	s_mov_b32 m0, s44
	s_nop 0
	global_load_lds_dwordx4 v[146:147], off
	v_lshl_add_u64 v[146:147], v[222:223], 0, s[10:11]
	s_mov_b32 m0, s45
	s_nop 0
	global_load_lds_dwordx4 v[146:147], off
	s_waitcnt vmcnt(8)
	s_waitcnt lgkmcnt(0)
	s_barrier
	s_setprio 1
	s_waitcnt lgkmcnt(0)
	v_mfma_f32_16x16x32_bf16 v[62:65], v[154:157], v[186:189], v[62:65]
	v_mfma_f32_16x16x32_bf16 v[58:61], v[162:165], v[186:189], v[58:61]
	v_mfma_f32_16x16x32_bf16 v[54:57], v[154:157], v[194:197], v[54:57]
	v_mfma_f32_16x16x32_bf16 v[46:49], v[162:165], v[194:197], v[46:49]
	v_mfma_f32_16x16x32_bf16 v[38:41], v[154:157], v[202:205], v[38:41]
	v_mfma_f32_16x16x32_bf16 v[30:33], v[162:165], v[202:205], v[30:33]
	v_mfma_f32_16x16x32_bf16 v[22:25], v[154:157], v[210:213], v[22:25]
	v_mfma_f32_16x16x32_bf16 v[14:17], v[162:165], v[210:213], v[14:17]
	v_mfma_f32_16x16x32_bf16 v[62:65], v[158:161], v[190:193], v[62:65]
	v_mfma_f32_16x16x32_bf16 v[58:61], v[166:169], v[190:193], v[58:61]
	v_mfma_f32_16x16x32_bf16 v[54:57], v[158:161], v[198:201], v[54:57]
	v_mfma_f32_16x16x32_bf16 v[46:49], v[166:169], v[198:201], v[46:49]
	v_mfma_f32_16x16x32_bf16 v[38:41], v[158:161], v[206:209], v[38:41]
	v_mfma_f32_16x16x32_bf16 v[30:33], v[166:169], v[206:209], v[30:33]
	v_mfma_f32_16x16x32_bf16 v[22:25], v[158:161], v[214:217], v[22:25]
	v_mfma_f32_16x16x32_bf16 v[14:17], v[166:169], v[214:217], v[14:17]
	s_setprio 0
	s_setprio 1
	v_mfma_f32_16x16x32_bf16 v[50:53], v[170:173], v[186:189], v[50:53]
	v_mfma_f32_16x16x32_bf16 v[42:45], v[178:181], v[186:189], v[42:45]
	v_mfma_f32_16x16x32_bf16 v[34:37], v[170:173], v[194:197], v[34:37]
	v_mfma_f32_16x16x32_bf16 v[26:29], v[178:181], v[194:197], v[26:29]
	v_mfma_f32_16x16x32_bf16 v[18:21], v[170:173], v[202:205], v[18:21]
	v_mfma_f32_16x16x32_bf16 v[10:13], v[178:181], v[202:205], v[10:13]
	v_mfma_f32_16x16x32_bf16 v[6:9], v[170:173], v[210:213], v[6:9]
	v_mfma_f32_16x16x32_bf16 v[2:5], v[178:181], v[210:213], v[2:5]
	v_mfma_f32_16x16x32_bf16 v[50:53], v[174:177], v[190:193], v[50:53]
	v_mfma_f32_16x16x32_bf16 v[42:45], v[182:185], v[190:193], v[42:45]
	v_mfma_f32_16x16x32_bf16 v[34:37], v[174:177], v[198:201], v[34:37]
	v_mfma_f32_16x16x32_bf16 v[26:29], v[182:185], v[198:201], v[26:29]
	v_mfma_f32_16x16x32_bf16 v[18:21], v[174:177], v[206:209], v[18:21]
	v_mfma_f32_16x16x32_bf16 v[10:13], v[182:185], v[206:209], v[10:13]
	v_mfma_f32_16x16x32_bf16 v[6:9], v[174:177], v[214:217], v[6:9]
	v_mfma_f32_16x16x32_bf16 v[2:5], v[182:185], v[214:217], v[2:5]
	s_setprio 0
	s_barrier
	s_add_i32 s58, s58, 2
	s_add_u32 s56, s56, 0x100
	s_addc_u32 s57, s57, 0
	s_cmpk_gt_u32 s58, 0x55
	s_mov_b64 s[24:25], s[26:27]
	s_cbranch_scc0 .LBB0_1656

;     __device__ bool next(int i, Unit& u) const { if (!s.next(i, u)) return false; const int p = u.pn; u.pn = p < 56 ? (p % 7) * 8 + p / 7 : p; return true; }
;     __device__ bool next(int i, Unit& u) const { Unit t; if (!s.next(i >> 1, t)) return false; const int pass = i & 1; u.pm = t.pm + pass * (M / BM); u.pn = t.pn + pass * (D / BM); u.kt0 = 0; return true; }
; #define PG8_STAGE(bufoff, gbase, voff) do { _Pragma("unroll") for (int _i = 0; _i < 2; ++_i) \
;         __builtin_amdgcn_global_load_lds((const unsigned*)((const char*)(gbase) + (voff)[_i]), (PG8_LAS unsigned*)(lds + (bufoff) + ldsw + _i * 8192), 16, 0, 0); } while (0)
; #define PG8_WAIT_V(n) asm volatile("s_waitcnt vmcnt(" #n ")" ::: "memory")
; #define PG8_WAIT_L(n) asm volatile("s_waitcnt lgkmcnt(" #n ")" ::: "memory")
; #define PG8_BAR __builtin_amdgcn_s_barrier()
; template <class Epi, class Sched, bool ALIGN_EPI = false, bool SP2 = false>
; __device__ __forceinline__ void gemm_phase(PG8_LAS unsigned char* lds, const Gemm g, const Sched& S, const Epi& E) {
;     ...
;         const bool has_next = S.next(ui + 1, nxt);
;         const char* nA = has_next ? (const char*)g.A + (size_t)nxt.pm * tstep + (size_t)nxt.kt0 * kstep : cA; const char* nB = has_next ? (const char*)g.Bt + (size_t)nxt.pn * tstep + (size_t)nxt.kt0 * kstep : cB;
;         for (int t = 0; t < nt; t += 2) {
;             if constexpr (Epi::MIDHOOK) { if (t == (nt >> 1)) E.mid(acc, cur, wr, wc, fr, fq); }
;             const bool last = (t == nt - 2);
;             const char* a1 = cA + (size_t)(t + 1) * kstep;
;             const char* a2 = last ? nA : cA + (size_t)(t + 2) * kstep; const char* b2 = last ? nB : cB + (size_t)(t + 2) * kstep;
;             const char* a3 = a2 + kstep; const char* b3 = b2 + kstep;
;             if (last && has_next) S.a_ready(nxt);
;             if constexpr (SP2) {
;             PG8_LDB(B0, 0, 0); PG8_LDB(B1, 0, 1); PG8_SCHED; PG8_LDA(At, 0, 0); PG8_STAGE(PG8_SA(1, 1), a1 + hstep, voffA);
;             PG8_WAIT_V(8); PG8_WAIT_L(0); PG8_BAR; PG8_MMA(0, 0, At, B0); PG8_MMA(0, 1, At, B1); PG8_BAR; PG8_SCHED;
;     ...
; #pragma unroll
;         for (int a = 0; a < 2; ++a)
; #pragma unroll
;             for (int b = 0; b < 2; ++b)
; #pragma unroll
;                 for (int m = 0; m < 4; ++m)
; #pragma unroll
;                     for (int n = 0; n < 2; ++n) acc[a][b][m][n] = (f32x4){0.f, 0.f, 0.f, 0.f};
.LBB0_1675:
	s_add_u32 s7, s28, 0x100
	s_addc_u32 s59, s29, 0
	s_mov_b32 s60, -2
	s_waitcnt lgkmcnt(0)
	ds_read_b128 v[144:147], v141
	ds_read_b128 v[148:151], v141 offset:1024
	ds_read_b128 v[152:155], v141 offset:2048
	ds_read_b128 v[156:159], v141 offset:3072
	ds_read_b128 v[160:163], v142
	ds_read_b128 v[164:167], v142 offset:1024
	ds_read_b128 v[168:171], v142 offset:2048
	ds_read_b128 v[172:175], v142 offset:3072
	s_add_u32 s28, s26, 0x100
	s_addc_u32 s29, s27, 0
	s_cmp_eq_u32 s60, 18
	s_cselect_b32 s37, s23, s29
	s_cselect_b32 s36, s22, s28
	s_cselect_b32 s31, s25, s59
	s_cselect_b32 s30, s24, s7
	v_lshl_add_u64 v[208:209], s[26:27], 0, v[134:135]
	s_add_i32 m0, s41, 0xc000
	ds_read_b128 v[176:179], v143
	ds_read_b128 v[180:183], v143 offset:1024
	ds_read_b128 v[184:187], v143 offset:2048
	ds_read_b128 v[188:191], v143 offset:3072
	ds_read_b128 v[192:195], v143 offset:4096
	ds_read_b128 v[196:199], v143 offset:5120
	ds_read_b128 v[200:203], v143 offset:6144
	ds_read_b128 v[204:207], v143 offset:7168
	global_load_lds_dwordx4 v[208:209], off
	v_lshl_add_u64 v[208:209], s[26:27], 0, v[136:137]
	s_add_i32 m0, s41, 0xe000
	s_nop 0
	global_load_lds_dwordx4 v[208:209], off
	s_waitcnt vmcnt(8)
	s_waitcnt lgkmcnt(0)
	s_barrier
	s_setprio 1
	s_waitcnt lgkmcnt(0)
	v_mfma_f32_16x16x32_bf16 v[126:129], v[144:147], v[176:179], 0
	v_mfma_f32_16x16x32_bf16 v[122:125], v[152:155], v[176:179], 0
	v_mfma_f32_16x16x32_bf16 v[118:121], v[144:147], v[184:187], 0
	v_mfma_f32_16x16x32_bf16 v[114:117], v[152:155], v[184:187], 0
	v_mfma_f32_16x16x32_bf16 v[106:109], v[144:147], v[192:195], 0
	v_mfma_f32_16x16x32_bf16 v[98:101], v[152:155], v[192:195], 0
	v_mfma_f32_16x16x32_bf16 v[90:93], v[144:147], v[200:203], 0
	v_mfma_f32_16x16x32_bf16 v[82:85], v[152:155], v[200:203], 0
	v_mfma_f32_16x16x32_bf16 v[126:129], v[148:151], v[180:183], v[126:129]
	v_mfma_f32_16x16x32_bf16 v[122:125], v[156:159], v[180:183], v[122:125]
	v_mfma_f32_16x16x32_bf16 v[118:121], v[148:151], v[188:191], v[118:121]
	v_mfma_f32_16x16x32_bf16 v[114:117], v[156:159], v[188:191], v[114:117]
	v_mfma_f32_16x16x32_bf16 v[106:109], v[148:151], v[196:199], v[106:109]
	v_mfma_f32_16x16x32_bf16 v[98:101], v[156:159], v[196:199], v[98:101]
	v_mfma_f32_16x16x32_bf16 v[90:93], v[148:151], v[204:207], v[90:93]
	v_mfma_f32_16x16x32_bf16 v[82:85], v[156:159], v[204:207], v[82:85]
	s_setprio 0
	s_setprio 1
	v_mfma_f32_16x16x32_bf16 v[110:113], v[160:163], v[176:179], 0
	v_mfma_f32_16x16x32_bf16 v[102:105], v[168:171], v[176:179], 0
	v_mfma_f32_16x16x32_bf16 v[94:97], v[160:163], v[184:187], 0
	v_mfma_f32_16x16x32_bf16 v[86:89], v[168:171], v[184:187], 0
	v_mfma_f32_16x16x32_bf16 v[78:81], v[160:163], v[192:195], 0
	v_mfma_f32_16x16x32_bf16 v[74:77], v[168:171], v[192:195], 0
	v_mfma_f32_16x16x32_bf16 v[70:73], v[160:163], v[200:203], 0
	v_mfma_f32_16x16x32_bf16 v[66:69], v[168:171], v[200:203], 0
	v_mfma_f32_16x16x32_bf16 v[110:113], v[164:167], v[180:183], v[110:113]
	v_mfma_f32_16x16x32_bf16 v[102:105], v[172:175], v[180:183], v[102:105]
	v_mfma_f32_16x16x32_bf16 v[94:97], v[164:167], v[188:191], v[94:97]
	v_mfma_f32_16x16x32_bf16 v[86:89], v[172:175], v[188:191], v[86:89]
	v_mfma_f32_16x16x32_bf16 v[78:81], v[164:167], v[196:199], v[78:81]
	v_mfma_f32_16x16x32_bf16 v[74:77], v[172:175], v[196:199], v[74:77]
	v_mfma_f32_16x16x32_bf16 v[70:73], v[164:167], v[204:207], v[70:73]
	v_mfma_f32_16x16x32_bf16 v[66:69], v[172:175], v[204:207], v[66:69]
	s_setprio 0
	s_barrier
	s_add_i32 s26, s50, s39
	v_lshl_add_u64 v[208:209], s[30:31], 0, v[132:133]
	s_mov_b32 m0, s26
	ds_read_b128 v[176:179], v143 offset:16384
	ds_read_b128 v[180:183], v143 offset:17408
	ds_read_b128 v[184:187], v143 offset:18432
	ds_read_b128 v[188:191], v143 offset:19456
	ds_read_b128 v[192:195], v143 offset:20480
	ds_read_b128 v[196:199], v143 offset:21504
	ds_read_b128 v[200:203], v143 offset:22528
	ds_read_b128 v[204:207], v143 offset:23552
	global_load_lds_dwordx4 v[208:209], off
	s_add_i32 m0, s26, 0x2000
	s_add_u32 s26, s30, 0x160000
	v_lshl_add_u64 v[210:211], s[30:31], 0, v[130:131]
	s_addc_u32 s27, s31, 0
	s_add_i32 s61, s51, s39
	global_load_lds_dwordx4 v[210:211], off
	v_lshl_add_u64 v[212:213], s[26:27], 0, v[132:133]
	s_mov_b32 m0, s61
	v_lshl_add_u64 v[214:215], s[36:37], 0, v[130:131]
	global_load_lds_dwordx4 v[212:213], off
	v_lshl_add_u64 v[212:213], s[26:27], 0, v[130:131]
	s_add_i32 m0, s61, 0x2000
	s_nop 0
	global_load_lds_dwordx4 v[212:213], off
	v_lshl_add_u64 v[212:213], s[36:37], 0, v[132:133]
	s_mov_b32 m0, s41
	s_nop 0
	global_load_lds_dwordx4 v[212:213], off
	s_mov_b32 m0, s42
	s_nop 0
	global_load_lds_dwordx4 v[214:215], off
	s_waitcnt vmcnt(8)
	s_waitcnt lgkmcnt(0)
	s_barrier
; #define PG8_STAGE(bufoff, gbase, voff) do { _Pragma("unroll") for (int _i = 0; _i < 2; ++_i) \
;         __builtin_amdgcn_global_load_lds((const unsigned*)((const char*)(gbase) + (voff)[_i]), (PG8_LAS unsigned*)(lds + (bufoff) + ldsw + _i * 8192), 16, 0, 0); } while (0)
; #define PG8_LDA(dst, b, h) do { _Pragma("unroll") for (int m = 0; m < 4; ++m) _Pragma("unroll") for (int k = 0; k < 2; ++k) dst[m][k] = *(const PG8_LAS bf16x8*)(lds + PG8_SA(b, h) + aoff + m * 2048 + k * 1024); } while (0)
; #define PG8_LDB(dst, b, h) do { _Pragma("unroll") for (int n = 0; n < 2; ++n) _Pragma("unroll") for (int k = 0; k < 2; ++k) dst[n][k] = *(const PG8_LAS bf16x8*)(lds + PG8_SB(b, h) + boff + n * 2048 + k * 1024); } while (0)
; #define PG8_MMA(ai, bj, At, Bt) do { __builtin_amdgcn_s_setprio(1); _Pragma("unroll") for (int m = 0; m < 4; ++m) _Pragma("unroll") for (int n = 0; n < 2; ++n) _Pragma("unroll") for (int k = 0; k < 2; ++k) \
;         acc[ai][bj][m][n] = __builtin_amdgcn_mfma_f32_16x16x32_bf16(Bt[n][k], At[m][k], acc[ai][bj][m][n], 0, 0, 0); __builtin_amdgcn_s_setprio(0); } while (0)
; #define PG8_WAIT_V(n) asm volatile("s_waitcnt vmcnt(" #n ")" ::: "memory")
; #define PG8_WAIT_L(n) asm volatile("s_waitcnt lgkmcnt(" #n ")" ::: "memory")
; #define PG8_BAR __builtin_amdgcn_s_barrier()
; #define PG8_SCHED __builtin_amdgcn_sched_barrier(0)
; template <class Epi, class Sched, bool ALIGN_EPI = false, bool SP2 = false>
; __device__ __forceinline__ void gemm_phase(PG8_LAS unsigned char* lds, const Gemm g, const Sched& S, const Epi& E) {
;     ...
;             PG8_LDA(At, 0, 1); PG8_STAGE(PG8_SB(0, 0), b2, voffB); PG8_STAGE(PG8_SB(0, 1), b2 + hstep, voffB); PG8_STAGE(PG8_SA(0, 0), a2, voffA);
;             PG8_WAIT_V(8); PG8_WAIT_L(0); PG8_BAR; PG8_MMA(1, 0, At, B0); PG8_MMA(1, 1, At, B1); PG8_BAR; PG8_SCHED;
;             PG8_LDB(B0, 1, 0); PG8_LDB(B1, 1, 1); PG8_SCHED; PG8_LDA(At, 1, 0); PG8_STAGE(PG8_SA(0, 1), a2 + hstep, voffA);
;             PG8_WAIT_V(8); PG8_WAIT_L(0); PG8_BAR; PG8_MMA(0, 0, At, B0); PG8_MMA(0, 1, At, B1); PG8_BAR; PG8_SCHED;
	s_setprio 1
	s_waitcnt lgkmcnt(0)
	v_mfma_f32_16x16x32_bf16 v[62:65], v[144:147], v[176:179], 0
	v_mfma_f32_16x16x32_bf16 v[58:61], v[152:155], v[176:179], 0
	v_mfma_f32_16x16x32_bf16 v[54:57], v[144:147], v[184:187], 0
	v_mfma_f32_16x16x32_bf16 v[50:53], v[152:155], v[184:187], 0
	v_mfma_f32_16x16x32_bf16 v[42:45], v[144:147], v[192:195], 0
	v_mfma_f32_16x16x32_bf16 v[34:37], v[152:155], v[192:195], 0
	v_mfma_f32_16x16x32_bf16 v[26:29], v[144:147], v[200:203], 0
	v_mfma_f32_16x16x32_bf16 v[18:21], v[152:155], v[200:203], 0
	v_mfma_f32_16x16x32_bf16 v[62:65], v[148:151], v[180:183], v[62:65]
	v_mfma_f32_16x16x32_bf16 v[58:61], v[156:159], v[180:183], v[58:61]
	v_mfma_f32_16x16x32_bf16 v[54:57], v[148:151], v[188:191], v[54:57]
	v_mfma_f32_16x16x32_bf16 v[50:53], v[156:159], v[188:191], v[50:53]
	v_mfma_f32_16x16x32_bf16 v[42:45], v[148:151], v[196:199], v[42:45]
	v_mfma_f32_16x16x32_bf16 v[34:37], v[156:159], v[196:199], v[34:37]
	v_mfma_f32_16x16x32_bf16 v[26:29], v[148:151], v[204:207], v[26:29]
	v_mfma_f32_16x16x32_bf16 v[18:21], v[156:159], v[204:207], v[18:21]
	s_setprio 0
	s_setprio 1
	v_mfma_f32_16x16x32_bf16 v[46:49], v[160:163], v[176:179], 0
	v_mfma_f32_16x16x32_bf16 v[38:41], v[168:171], v[176:179], 0
	v_mfma_f32_16x16x32_bf16 v[30:33], v[160:163], v[184:187], 0
	v_mfma_f32_16x16x32_bf16 v[22:25], v[168:171], v[184:187], 0
	v_mfma_f32_16x16x32_bf16 v[14:17], v[160:163], v[192:195], 0
	v_mfma_f32_16x16x32_bf16 v[10:13], v[168:171], v[192:195], 0
	v_mfma_f32_16x16x32_bf16 v[6:9], v[160:163], v[200:203], 0
	v_mfma_f32_16x16x32_bf16 v[2:5], v[168:171], v[200:203], 0
	v_mfma_f32_16x16x32_bf16 v[46:49], v[164:167], v[180:183], v[46:49]
	v_mfma_f32_16x16x32_bf16 v[38:41], v[172:175], v[180:183], v[38:41]
	v_mfma_f32_16x16x32_bf16 v[30:33], v[164:167], v[188:191], v[30:33]
	v_mfma_f32_16x16x32_bf16 v[22:25], v[172:175], v[188:191], v[22:25]
	v_mfma_f32_16x16x32_bf16 v[14:17], v[164:167], v[196:199], v[14:17]
	v_mfma_f32_16x16x32_bf16 v[10:13], v[172:175], v[196:199], v[10:13]
	v_mfma_f32_16x16x32_bf16 v[6:9], v[164:167], v[204:207], v[6:9]
	v_mfma_f32_16x16x32_bf16 v[2:5], v[172:175], v[204:207], v[2:5]
	s_setprio 0
	s_barrier
	s_add_i32 s61, 0, 0x18000
	s_add_i32 s62, 0, 0x1c000
	v_add_u32_e32 v156, s61, v138
	v_add_u32_e32 v172, s62, v138
	ds_read_b128 v[144:147], v156
	ds_read_b128 v[148:151], v156 offset:1024
	ds_read_b128 v[152:155], v156 offset:2048
	ds_read_b128 v[156:159], v156 offset:3072
	ds_read_b128 v[160:163], v172
	ds_read_b128 v[164:167], v172 offset:1024
	ds_read_b128 v[168:171], v172 offset:2048
	ds_read_b128 v[172:175], v172 offset:3072
	s_add_u32 s26, s36, 0x160000
	s_addc_u32 s27, s37, 0
	s_mov_b32 m0, s43
	v_lshl_add_u64 v[216:217], s[26:27], 0, v[132:133]
	ds_read_b128 v[176:179], v143 offset:32768
	ds_read_b128 v[180:183], v143 offset:33792
	ds_read_b128 v[184:187], v143 offset:34816
	ds_read_b128 v[188:191], v143 offset:35840
	ds_read_b128 v[192:195], v143 offset:36864
	ds_read_b128 v[196:199], v143 offset:37888
	ds_read_b128 v[200:203], v143 offset:38912
	ds_read_b128 v[204:207], v143 offset:39936
	global_load_lds_dwordx4 v[216:217], off
	v_lshl_add_u64 v[216:217], s[26:27], 0, v[130:131]
	s_mov_b32 m0, s44
	s_nop 0
	global_load_lds_dwordx4 v[216:217], off
	s_waitcnt vmcnt(8)
	s_waitcnt lgkmcnt(0)
	s_barrier
	s_setprio 1
	s_waitcnt lgkmcnt(0)
	v_mfma_f32_16x16x32_bf16 v[126:129], v[144:147], v[176:179], v[126:129]
	v_mfma_f32_16x16x32_bf16 v[122:125], v[152:155], v[176:179], v[122:125]
	v_mfma_f32_16x16x32_bf16 v[118:121], v[144:147], v[184:187], v[118:121]
	v_mfma_f32_16x16x32_bf16 v[114:117], v[152:155], v[184:187], v[114:117]
	v_mfma_f32_16x16x32_bf16 v[106:109], v[144:147], v[192:195], v[106:109]
	v_mfma_f32_16x16x32_bf16 v[98:101], v[152:155], v[192:195], v[98:101]
	v_mfma_f32_16x16x32_bf16 v[90:93], v[144:147], v[200:203], v[90:93]
	v_mfma_f32_16x16x32_bf16 v[82:85], v[152:155], v[200:203], v[82:85]
	v_mfma_f32_16x16x32_bf16 v[126:129], v[148:151], v[180:183], v[126:129]
	v_mfma_f32_16x16x32_bf16 v[122:125], v[156:159], v[180:183], v[122:125]
	v_mfma_f32_16x16x32_bf16 v[118:121], v[148:151], v[188:191], v[118:121]
	v_mfma_f32_16x16x32_bf16 v[114:117], v[156:159], v[188:191], v[114:117]
	v_mfma_f32_16x16x32_bf16 v[106:109], v[148:151], v[196:199], v[106:109]
	v_mfma_f32_16x16x32_bf16 v[98:101], v[156:159], v[196:199], v[98:101]
	v_mfma_f32_16x16x32_bf16 v[90:93], v[148:151], v[204:207], v[90:93]
	v_mfma_f32_16x16x32_bf16 v[82:85], v[156:159], v[204:207], v[82:85]
	s_setprio 0
	s_setprio 1
	v_mfma_f32_16x16x32_bf16 v[110:113], v[160:163], v[176:179], v[110:113]
	v_mfma_f32_16x16x32_bf16 v[102:105], v[168:171], v[176:179], v[102:105]
	v_mfma_f32_16x16x32_bf16 v[94:97], v[160:163], v[184:187], v[94:97]
	v_mfma_f32_16x16x32_bf16 v[86:89], v[168:171], v[184:187], v[86:89]
	v_mfma_f32_16x16x32_bf16 v[78:81], v[160:163], v[192:195], v[78:81]
	v_mfma_f32_16x16x32_bf16 v[74:77], v[168:171], v[192:195], v[74:77]
	v_mfma_f32_16x16x32_bf16 v[70:73], v[160:163], v[200:203], v[70:73]
	v_mfma_f32_16x16x32_bf16 v[66:69], v[168:171], v[200:203], v[66:69]
	v_mfma_f32_16x16x32_bf16 v[110:113], v[164:167], v[180:183], v[110:113]
	v_mfma_f32_16x16x32_bf16 v[102:105], v[172:175], v[180:183], v[102:105]
	v_mfma_f32_16x16x32_bf16 v[94:97], v[164:167], v[188:191], v[94:97]
	v_mfma_f32_16x16x32_bf16 v[86:89], v[172:175], v[188:191], v[86:89]
	v_mfma_f32_16x16x32_bf16 v[78:81], v[164:167], v[196:199], v[78:81]
	v_mfma_f32_16x16x32_bf16 v[74:77], v[172:175], v[196:199], v[74:77]
	v_mfma_f32_16x16x32_bf16 v[70:73], v[164:167], v[204:207], v[70:73]
	v_mfma_f32_16x16x32_bf16 v[66:69], v[172:175], v[204:207], v[66:69]
	s_setprio 0
	s_barrier
; #define PG8_STAGE(bufoff, gbase, voff) do { _Pragma("unroll") for (int _i = 0; _i < 2; ++_i) \
;         __builtin_amdgcn_global_load_lds((const unsigned*)((const char*)(gbase) + (voff)[_i]), (PG8_LAS unsigned*)(lds + (bufoff) + ldsw + _i * 8192), 16, 0, 0); } while (0)
; #define PG8_LDA(dst, b, h) do { _Pragma("unroll") for (int m = 0; m < 4; ++m) _Pragma("unroll") for (int k = 0; k < 2; ++k) dst[m][k] = *(const PG8_LAS bf16x8*)(lds + PG8_SA(b, h) + aoff + m * 2048 + k * 1024); } while (0)
; #define PG8_MMA(ai, bj, At, Bt) do { __builtin_amdgcn_s_setprio(1); _Pragma("unroll") for (int m = 0; m < 4; ++m) _Pragma("unroll") for (int n = 0; n < 2; ++n) _Pragma("unroll") for (int k = 0; k < 2; ++k) \
;         acc[ai][bj][m][n] = __builtin_amdgcn_mfma_f32_16x16x32_bf16(Bt[n][k], At[m][k], acc[ai][bj][m][n], 0, 0, 0); __builtin_amdgcn_s_setprio(0); } while (0)
; #define PG8_WAIT_V(n) asm volatile("s_waitcnt vmcnt(" #n ")" ::: "memory")
; #define PG8_WAIT_L(n) asm volatile("s_waitcnt lgkmcnt(" #n ")" ::: "memory")
; #define PG8_BAR __builtin_amdgcn_s_barrier()
; #define PG8_SCHED __builtin_amdgcn_sched_barrier(0)
; template <class Epi, class Sched, bool ALIGN_EPI = false, bool SP2 = false>
; __device__ __forceinline__ void gemm_phase(PG8_LAS unsigned char* lds, const Gemm g, const Sched& S, const Epi& E) {
;     ...
;         for (int t = 0; t < nt; t += 2) {
;             if constexpr (Epi::MIDHOOK) { if (t == (nt >> 1)) E.mid(acc, cur, wr, wc, fr, fq); }
;             const bool last = (t == nt - 2);
;             const char* a1 = cA + (size_t)(t + 1) * kstep;
;             const char* a2 = last ? nA : cA + (size_t)(t + 2) * kstep; const char* b2 = last ? nB : cB + (size_t)(t + 2) * kstep;
;             const char* a3 = a2 + kstep; const char* b3 = b2 + kstep;
;     ...
;             PG8_LDA(At, 1, 1); PG8_STAGE(PG8_SB(1, 0), b3, voffB); PG8_STAGE(PG8_SB(1, 1), b3 + hstep, voffB); PG8_STAGE(PG8_SA(1, 0), a3, voffA);
;             PG8_WAIT_V(8); PG8_WAIT_L(0); PG8_BAR; PG8_MMA(1, 0, At, B0); PG8_MMA(1, 1, At, B1); PG8_BAR; PG8_SCHED;
	s_add_i32 s26, s61, s39
	v_lshl_add_u64 v[208:209], v[208:209], 0, s[12:13]
	s_mov_b32 m0, s26
	ds_read_b128 v[176:179], v143 offset:49152
	ds_read_b128 v[180:183], v143 offset:50176
	ds_read_b128 v[184:187], v143 offset:51200
	ds_read_b128 v[188:191], v143 offset:52224
	ds_read_b128 v[192:195], v143 offset:53248
	ds_read_b128 v[196:199], v143 offset:54272
	ds_read_b128 v[200:203], v143 offset:55296
	ds_read_b128 v[204:207], v143 offset:56320
	global_load_lds_dwordx4 v[208:209], off
	s_add_i32 m0, s26, 0x2000
	s_add_u32 s26, s30, 0x160080
	v_lshl_add_u64 v[208:209], v[210:211], 0, s[12:13]
	s_addc_u32 s27, s31, 0
	s_add_i32 s30, s62, s39
	global_load_lds_dwordx4 v[208:209], off
	v_lshl_add_u64 v[208:209], s[26:27], 0, v[132:133]
	s_mov_b32 m0, s30
	s_nop 0
	global_load_lds_dwordx4 v[208:209], off
	v_lshl_add_u64 v[208:209], s[26:27], 0, v[130:131]
	s_add_i32 m0, s30, 0x2000
	s_nop 0
	global_load_lds_dwordx4 v[208:209], off
	v_lshl_add_u64 v[208:209], v[212:213], 0, s[12:13]
	s_mov_b32 m0, s47
	s_nop 0
	global_load_lds_dwordx4 v[208:209], off
	v_lshl_add_u64 v[208:209], v[214:215], 0, s[12:13]
	s_mov_b32 m0, s48
	s_nop 0
	global_load_lds_dwordx4 v[208:209], off
	s_waitcnt vmcnt(8)
	s_waitcnt lgkmcnt(0)
	s_barrier
	s_setprio 1
	s_waitcnt lgkmcnt(0)
	v_mfma_f32_16x16x32_bf16 v[62:65], v[144:147], v[176:179], v[62:65]
	v_mfma_f32_16x16x32_bf16 v[58:61], v[152:155], v[176:179], v[58:61]
	v_mfma_f32_16x16x32_bf16 v[54:57], v[144:147], v[184:187], v[54:57]
	v_mfma_f32_16x16x32_bf16 v[50:53], v[152:155], v[184:187], v[50:53]
	v_mfma_f32_16x16x32_bf16 v[42:45], v[144:147], v[192:195], v[42:45]
	v_mfma_f32_16x16x32_bf16 v[34:37], v[152:155], v[192:195], v[34:37]
	v_mfma_f32_16x16x32_bf16 v[26:29], v[144:147], v[200:203], v[26:29]
	v_mfma_f32_16x16x32_bf16 v[18:21], v[152:155], v[200:203], v[18:21]
	v_mfma_f32_16x16x32_bf16 v[62:65], v[148:151], v[180:183], v[62:65]
	v_mfma_f32_16x16x32_bf16 v[58:61], v[156:159], v[180:183], v[58:61]
	v_mfma_f32_16x16x32_bf16 v[54:57], v[148:151], v[188:191], v[54:57]
	v_mfma_f32_16x16x32_bf16 v[50:53], v[156:159], v[188:191], v[50:53]
	v_mfma_f32_16x16x32_bf16 v[42:45], v[148:151], v[196:199], v[42:45]
	v_mfma_f32_16x16x32_bf16 v[34:37], v[156:159], v[196:199], v[34:37]
	v_mfma_f32_16x16x32_bf16 v[26:29], v[148:151], v[204:207], v[26:29]
	v_mfma_f32_16x16x32_bf16 v[18:21], v[156:159], v[204:207], v[18:21]
	s_setprio 0
	s_setprio 1
	v_mfma_f32_16x16x32_bf16 v[46:49], v[160:163], v[176:179], v[46:49]
	v_mfma_f32_16x16x32_bf16 v[38:41], v[168:171], v[176:179], v[38:41]
	v_mfma_f32_16x16x32_bf16 v[30:33], v[160:163], v[184:187], v[30:33]
	v_mfma_f32_16x16x32_bf16 v[22:25], v[168:171], v[184:187], v[22:25]
	v_mfma_f32_16x16x32_bf16 v[14:17], v[160:163], v[192:195], v[14:17]
	v_mfma_f32_16x16x32_bf16 v[10:13], v[168:171], v[192:195], v[10:13]
	v_mfma_f32_16x16x32_bf16 v[6:9], v[160:163], v[200:203], v[6:9]
	v_mfma_f32_16x16x32_bf16 v[2:5], v[168:171], v[200:203], v[2:5]
	v_mfma_f32_16x16x32_bf16 v[46:49], v[164:167], v[180:183], v[46:49]
	v_mfma_f32_16x16x32_bf16 v[38:41], v[172:175], v[180:183], v[38:41]
	v_mfma_f32_16x16x32_bf16 v[30:33], v[164:167], v[188:191], v[30:33]
	v_mfma_f32_16x16x32_bf16 v[22:25], v[172:175], v[188:191], v[22:25]
	v_mfma_f32_16x16x32_bf16 v[14:17], v[164:167], v[196:199], v[14:17]
	v_mfma_f32_16x16x32_bf16 v[10:13], v[172:175], v[196:199], v[10:13]
	v_mfma_f32_16x16x32_bf16 v[6:9], v[164:167], v[204:207], v[6:9]
	v_mfma_f32_16x16x32_bf16 v[2:5], v[172:175], v[204:207], v[2:5]
	s_setprio 0
	s_barrier
	s_add_i32 s60, s60, 2
	s_add_u32 s7, s7, 0x100
	s_addc_u32 s59, s59, 0
	s_cmp_gt_u32 s60, 19
	s_mov_b64 s[26:27], s[28:29]
	s_cbranch_scc1 .Lkx_1676
.LBB0_1676:
	ds_read_b128 v[144:147], v141
	ds_read_b128 v[148:151], v141 offset:1024
	ds_read_b128 v[152:155], v141 offset:2048
	ds_read_b128 v[156:159], v141 offset:3072
	ds_read_b128 v[160:163], v142
	ds_read_b128 v[164:167], v142 offset:1024
	ds_read_b128 v[168:171], v142 offset:2048
	ds_read_b128 v[172:175], v142 offset:3072
	s_add_u32 s28, s26, 0x100
	s_addc_u32 s29, s27, 0
	s_cmp_eq_u32 s60, 18
	s_cselect_b32 s37, s23, s29
	s_cselect_b32 s36, s22, s28
	s_cselect_b32 s31, s25, s59
	s_cselect_b32 s30, s24, s7
	v_lshl_add_u64 v[208:209], s[26:27], 0, v[134:135]
	s_add_i32 m0, s41, 0xc000
	ds_read_b128 v[176:179], v143
	ds_read_b128 v[180:183], v143 offset:1024
	ds_read_b128 v[184:187], v143 offset:2048
	ds_read_b128 v[188:191], v143 offset:3072
	ds_read_b128 v[192:195], v143 offset:4096
	ds_read_b128 v[196:199], v143 offset:5120
	ds_read_b128 v[200:203], v143 offset:6144
	ds_read_b128 v[204:207], v143 offset:7168
	global_load_lds_dwordx4 v[208:209], off
	v_lshl_add_u64 v[208:209], s[26:27], 0, v[136:137]
	s_add_i32 m0, s41, 0xe000
	s_nop 0
	global_load_lds_dwordx4 v[208:209], off
	s_waitcnt vmcnt(8)
	s_waitcnt lgkmcnt(0)
	s_barrier
; #define PG8_STAGE(bufoff, gbase, voff) do { _Pragma("unroll") for (int _i = 0; _i < 2; ++_i) \
;         __builtin_amdgcn_global_load_lds((const unsigned*)((const char*)(gbase) + (voff)[_i]), (PG8_LAS unsigned*)(lds + (bufoff) + ldsw + _i * 8192), 16, 0, 0); } while (0)
; #define PG8_LDA(dst, b, h) do { _Pragma("unroll") for (int m = 0; m < 4; ++m) _Pragma("unroll") for (int k = 0; k < 2; ++k) dst[m][k] = *(const PG8_LAS bf16x8*)(lds + PG8_SA(b, h) + aoff + m * 2048 + k * 1024); } while (0)
; #define PG8_LDB(dst, b, h) do { _Pragma("unroll") for (int n = 0; n < 2; ++n) _Pragma("unroll") for (int k = 0; k < 2; ++k) dst[n][k] = *(const PG8_LAS bf16x8*)(lds + PG8_SB(b, h) + boff + n * 2048 + k * 1024); } while (0)
; #define PG8_MMA(ai, bj, At, Bt) do { __builtin_amdgcn_s_setprio(1); _Pragma("unroll") for (int m = 0; m < 4; ++m) _Pragma("unroll") for (int n = 0; n < 2; ++n) _Pragma("unroll") for (int k = 0; k < 2; ++k) \
;         acc[ai][bj][m][n] = __builtin_amdgcn_mfma_f32_16x16x32_bf16(Bt[n][k], At[m][k], acc[ai][bj][m][n], 0, 0, 0); __builtin_amdgcn_s_setprio(0); } while (0)
; #define PG8_WAIT_V(n) asm volatile("s_waitcnt vmcnt(" #n ")" ::: "memory")
; #define PG8_WAIT_L(n) asm volatile("s_waitcnt lgkmcnt(" #n ")" ::: "memory")
; #define PG8_BAR __builtin_amdgcn_s_barrier()
; #define PG8_SCHED __builtin_amdgcn_sched_barrier(0)
; template <class Epi, class Sched, bool ALIGN_EPI = false, bool SP2 = false>
; __device__ __forceinline__ void gemm_phase(PG8_LAS unsigned char* lds, const Gemm g, const Sched& S, const Epi& E) {
;     ...
;             PG8_LDB(B0, 0, 0); PG8_LDB(B1, 0, 1); PG8_SCHED; PG8_LDA(At, 0, 0); PG8_STAGE(PG8_SA(1, 1), a1 + hstep, voffA);
;             PG8_WAIT_V(8); PG8_WAIT_L(0); PG8_BAR; PG8_MMA(0, 0, At, B0); PG8_MMA(0, 1, At, B1); PG8_BAR; PG8_SCHED;
;             PG8_LDA(At, 0, 1); PG8_STAGE(PG8_SB(0, 0), b2, voffB); PG8_STAGE(PG8_SB(0, 1), b2 + hstep, voffB); PG8_STAGE(PG8_SA(0, 0), a2, voffA);
;             PG8_WAIT_V(8); PG8_WAIT_L(0); PG8_BAR; PG8_MMA(1, 0, At, B0); PG8_MMA(1, 1, At, B1); PG8_BAR; PG8_SCHED;
	s_setprio 1
	s_waitcnt lgkmcnt(0)
	v_mfma_f32_16x16x32_bf16 v[126:129], v[144:147], v[176:179], v[126:129]
	v_mfma_f32_16x16x32_bf16 v[122:125], v[152:155], v[176:179], v[122:125]
	v_mfma_f32_16x16x32_bf16 v[118:121], v[144:147], v[184:187], v[118:121]
	v_mfma_f32_16x16x32_bf16 v[114:117], v[152:155], v[184:187], v[114:117]
	v_mfma_f32_16x16x32_bf16 v[106:109], v[144:147], v[192:195], v[106:109]
	v_mfma_f32_16x16x32_bf16 v[98:101], v[152:155], v[192:195], v[98:101]
	v_mfma_f32_16x16x32_bf16 v[90:93], v[144:147], v[200:203], v[90:93]
	v_mfma_f32_16x16x32_bf16 v[82:85], v[152:155], v[200:203], v[82:85]
	v_mfma_f32_16x16x32_bf16 v[126:129], v[148:151], v[180:183], v[126:129]
	v_mfma_f32_16x16x32_bf16 v[122:125], v[156:159], v[180:183], v[122:125]
	v_mfma_f32_16x16x32_bf16 v[118:121], v[148:151], v[188:191], v[118:121]
	v_mfma_f32_16x16x32_bf16 v[114:117], v[156:159], v[188:191], v[114:117]
	v_mfma_f32_16x16x32_bf16 v[106:109], v[148:151], v[196:199], v[106:109]
	v_mfma_f32_16x16x32_bf16 v[98:101], v[156:159], v[196:199], v[98:101]
	v_mfma_f32_16x16x32_bf16 v[90:93], v[148:151], v[204:207], v[90:93]
	v_mfma_f32_16x16x32_bf16 v[82:85], v[156:159], v[204:207], v[82:85]
	s_setprio 0
	s_setprio 1
	v_mfma_f32_16x16x32_bf16 v[110:113], v[160:163], v[176:179], v[110:113]
	v_mfma_f32_16x16x32_bf16 v[102:105], v[168:171], v[176:179], v[102:105]
	v_mfma_f32_16x16x32_bf16 v[94:97], v[160:163], v[184:187], v[94:97]
	v_mfma_f32_16x16x32_bf16 v[86:89], v[168:171], v[184:187], v[86:89]
	v_mfma_f32_16x16x32_bf16 v[78:81], v[160:163], v[192:195], v[78:81]
	v_mfma_f32_16x16x32_bf16 v[74:77], v[168:171], v[192:195], v[74:77]
	v_mfma_f32_16x16x32_bf16 v[70:73], v[160:163], v[200:203], v[70:73]
	v_mfma_f32_16x16x32_bf16 v[66:69], v[168:171], v[200:203], v[66:69]
	v_mfma_f32_16x16x32_bf16 v[110:113], v[164:167], v[180:183], v[110:113]
	v_mfma_f32_16x16x32_bf16 v[102:105], v[172:175], v[180:183], v[102:105]
	v_mfma_f32_16x16x32_bf16 v[94:97], v[164:167], v[188:191], v[94:97]
	v_mfma_f32_16x16x32_bf16 v[86:89], v[172:175], v[188:191], v[86:89]
	v_mfma_f32_16x16x32_bf16 v[78:81], v[164:167], v[196:199], v[78:81]
	v_mfma_f32_16x16x32_bf16 v[74:77], v[172:175], v[196:199], v[74:77]
	v_mfma_f32_16x16x32_bf16 v[70:73], v[164:167], v[204:207], v[70:73]
	v_mfma_f32_16x16x32_bf16 v[66:69], v[172:175], v[204:207], v[66:69]
	s_setprio 0
	s_barrier
	s_add_i32 s26, s50, s39
	v_lshl_add_u64 v[208:209], s[30:31], 0, v[132:133]
	s_mov_b32 m0, s26
	ds_read_b128 v[176:179], v143 offset:16384
	ds_read_b128 v[180:183], v143 offset:17408
	ds_read_b128 v[184:187], v143 offset:18432
	ds_read_b128 v[188:191], v143 offset:19456
	ds_read_b128 v[192:195], v143 offset:20480
	ds_read_b128 v[196:199], v143 offset:21504
	ds_read_b128 v[200:203], v143 offset:22528
	ds_read_b128 v[204:207], v143 offset:23552
	global_load_lds_dwordx4 v[208:209], off
	s_add_i32 m0, s26, 0x2000
	s_add_u32 s26, s30, 0x160000
	v_lshl_add_u64 v[210:211], s[30:31], 0, v[130:131]
	s_addc_u32 s27, s31, 0
	s_add_i32 s61, s51, s39
	global_load_lds_dwordx4 v[210:211], off
	v_lshl_add_u64 v[212:213], s[26:27], 0, v[132:133]
	s_mov_b32 m0, s61
	v_lshl_add_u64 v[214:215], s[36:37], 0, v[130:131]
	global_load_lds_dwordx4 v[212:213], off
	v_lshl_add_u64 v[212:213], s[26:27], 0, v[130:131]
	s_add_i32 m0, s61, 0x2000
	s_nop 0
	global_load_lds_dwordx4 v[212:213], off
	v_lshl_add_u64 v[212:213], s[36:37], 0, v[132:133]
	s_mov_b32 m0, s41
	s_nop 0
	global_load_lds_dwordx4 v[212:213], off
	s_mov_b32 m0, s42
	s_nop 0
	global_load_lds_dwordx4 v[214:215], off
	s_waitcnt vmcnt(8)
	s_waitcnt lgkmcnt(0)
	s_barrier
	s_setprio 1
	s_waitcnt lgkmcnt(0)
	v_mfma_f32_16x16x32_bf16 v[62:65], v[144:147], v[176:179], v[62:65]
	v_mfma_f32_16x16x32_bf16 v[58:61], v[152:155], v[176:179], v[58:61]
	v_mfma_f32_16x16x32_bf16 v[54:57], v[144:147], v[184:187], v[54:57]
	v_mfma_f32_16x16x32_bf16 v[50:53], v[152:155], v[184:187], v[50:53]
	v_mfma_f32_16x16x32_bf16 v[42:45], v[144:147], v[192:195], v[42:45]
	v_mfma_f32_16x16x32_bf16 v[34:37], v[152:155], v[192:195], v[34:37]
	v_mfma_f32_16x16x32_bf16 v[26:29], v[144:147], v[200:203], v[26:29]
	v_mfma_f32_16x16x32_bf16 v[18:21], v[152:155], v[200:203], v[18:21]
	v_mfma_f32_16x16x32_bf16 v[62:65], v[148:151], v[180:183], v[62:65]
	v_mfma_f32_16x16x32_bf16 v[58:61], v[156:159], v[180:183], v[58:61]
	v_mfma_f32_16x16x32_bf16 v[54:57], v[148:151], v[188:191], v[54:57]
	v_mfma_f32_16x16x32_bf16 v[50:53], v[156:159], v[188:191], v[50:53]
	v_mfma_f32_16x16x32_bf16 v[42:45], v[148:151], v[196:199], v[42:45]
	v_mfma_f32_16x16x32_bf16 v[34:37], v[156:159], v[196:199], v[34:37]
	v_mfma_f32_16x16x32_bf16 v[26:29], v[148:151], v[204:207], v[26:29]
	v_mfma_f32_16x16x32_bf16 v[18:21], v[156:159], v[204:207], v[18:21]
	s_setprio 0
	s_setprio 1
	v_mfma_f32_16x16x32_bf16 v[46:49], v[160:163], v[176:179], v[46:49]
	v_mfma_f32_16x16x32_bf16 v[38:41], v[168:171], v[176:179], v[38:41]
	v_mfma_f32_16x16x32_bf16 v[30:33], v[160:163], v[184:187], v[30:33]
	v_mfma_f32_16x16x32_bf16 v[22:25], v[168:171], v[184:187], v[22:25]
	v_mfma_f32_16x16x32_bf16 v[14:17], v[160:163], v[192:195], v[14:17]
	v_mfma_f32_16x16x32_bf16 v[10:13], v[168:171], v[192:195], v[10:13]
	v_mfma_f32_16x16x32_bf16 v[6:9], v[160:163], v[200:203], v[6:9]
	v_mfma_f32_16x16x32_bf16 v[2:5], v[168:171], v[200:203], v[2:5]
	v_mfma_f32_16x16x32_bf16 v[46:49], v[164:167], v[180:183], v[46:49]
	v_mfma_f32_16x16x32_bf16 v[38:41], v[172:175], v[180:183], v[38:41]
	v_mfma_f32_16x16x32_bf16 v[30:33], v[164:167], v[188:191], v[30:33]
	v_mfma_f32_16x16x32_bf16 v[22:25], v[172:175], v[188:191], v[22:25]
	v_mfma_f32_16x16x32_bf16 v[14:17], v[164:167], v[196:199], v[14:17]
	v_mfma_f32_16x16x32_bf16 v[10:13], v[172:175], v[196:199], v[10:13]
	v_mfma_f32_16x16x32_bf16 v[6:9], v[164:167], v[204:207], v[6:9]
	v_mfma_f32_16x16x32_bf16 v[2:5], v[172:175], v[204:207], v[2:5]
	s_setprio 0
	s_barrier
; #define PG8_STAGE(bufoff, gbase, voff) do { _Pragma("unroll") for (int _i = 0; _i < 2; ++_i) \
;         __builtin_amdgcn_global_load_lds((const unsigned*)((const char*)(gbase) + (voff)[_i]), (PG8_LAS unsigned*)(lds + (bufoff) + ldsw + _i * 8192), 16, 0, 0); } while (0)
; #define PG8_LDA(dst, b, h) do { _Pragma("unroll") for (int m = 0; m < 4; ++m) _Pragma("unroll") for (int k = 0; k < 2; ++k) dst[m][k] = *(const PG8_LAS bf16x8*)(lds + PG8_SA(b, h) + aoff + m * 2048 + k * 1024); } while (0)
; #define PG8_LDB(dst, b, h) do { _Pragma("unroll") for (int n = 0; n < 2; ++n) _Pragma("unroll") for (int k = 0; k < 2; ++k) dst[n][k] = *(const PG8_LAS bf16x8*)(lds + PG8_SB(b, h) + boff + n * 2048 + k * 1024); } while (0)
; #define PG8_MMA(ai, bj, At, Bt) do { __builtin_amdgcn_s_setprio(1); _Pragma("unroll") for (int m = 0; m < 4; ++m) _Pragma("unroll") for (int n = 0; n < 2; ++n) _Pragma("unroll") for (int k = 0; k < 2; ++k) \
;         acc[ai][bj][m][n] = __builtin_amdgcn_mfma_f32_16x16x32_bf16(Bt[n][k], At[m][k], acc[ai][bj][m][n], 0, 0, 0); __builtin_amdgcn_s_setprio(0); } while (0)
; #define PG8_WAIT_V(n) asm volatile("s_waitcnt vmcnt(" #n ")" ::: "memory")
; #define PG8_WAIT_L(n) asm volatile("s_waitcnt lgkmcnt(" #n ")" ::: "memory")
; #define PG8_BAR __builtin_amdgcn_s_barrier()
; #define PG8_SCHED __builtin_amdgcn_sched_barrier(0)
; template <class Epi, class Sched, bool ALIGN_EPI = false, bool SP2 = false>
; __device__ __forceinline__ void gemm_phase(PG8_LAS unsigned char* lds, const Gemm g, const Sched& S, const Epi& E) {
;     ...
;             PG8_LDB(B0, 1, 0); PG8_LDB(B1, 1, 1); PG8_SCHED; PG8_LDA(At, 1, 0); PG8_STAGE(PG8_SA(0, 1), a2 + hstep, voffA);
;             PG8_WAIT_V(8); PG8_WAIT_L(0); PG8_BAR; PG8_MMA(0, 0, At, B0); PG8_MMA(0, 1, At, B1); PG8_BAR; PG8_SCHED;
	s_add_i32 s61, 0, 0x18000
	s_add_i32 s62, 0, 0x1c000
	v_add_u32_e32 v156, s61, v138
	v_add_u32_e32 v172, s62, v138
	ds_read_b128 v[144:147], v156
	ds_read_b128 v[148:151], v156 offset:1024
	ds_read_b128 v[152:155], v156 offset:2048
	ds_read_b128 v[156:159], v156 offset:3072
	ds_read_b128 v[160:163], v172
	ds_read_b128 v[164:167], v172 offset:1024
	ds_read_b128 v[168:171], v172 offset:2048
	ds_read_b128 v[172:175], v172 offset:3072
	s_add_u32 s26, s36, 0x160000
	s_addc_u32 s27, s37, 0
	s_mov_b32 m0, s43
	v_lshl_add_u64 v[216:217], s[26:27], 0, v[132:133]
	ds_read_b128 v[176:179], v143 offset:32768
	ds_read_b128 v[180:183], v143 offset:33792
	ds_read_b128 v[184:187], v143 offset:34816
	ds_read_b128 v[188:191], v143 offset:35840
	ds_read_b128 v[192:195], v143 offset:36864
	ds_read_b128 v[196:199], v143 offset:37888
	ds_read_b128 v[200:203], v143 offset:38912
	ds_read_b128 v[204:207], v143 offset:39936
	global_load_lds_dwordx4 v[216:217], off
	v_lshl_add_u64 v[216:217], s[26:27], 0, v[130:131]
	s_mov_b32 m0, s44
	s_nop 0
	global_load_lds_dwordx4 v[216:217], off
	s_waitcnt vmcnt(8)
	s_waitcnt lgkmcnt(0)
	s_barrier
	s_setprio 1
	s_waitcnt lgkmcnt(0)
	v_mfma_f32_16x16x32_bf16 v[126:129], v[144:147], v[176:179], v[126:129]
	v_mfma_f32_16x16x32_bf16 v[122:125], v[152:155], v[176:179], v[122:125]
	v_mfma_f32_16x16x32_bf16 v[118:121], v[144:147], v[184:187], v[118:121]
	v_mfma_f32_16x16x32_bf16 v[114:117], v[152:155], v[184:187], v[114:117]
	v_mfma_f32_16x16x32_bf16 v[106:109], v[144:147], v[192:195], v[106:109]
	v_mfma_f32_16x16x32_bf16 v[98:101], v[152:155], v[192:195], v[98:101]
	v_mfma_f32_16x16x32_bf16 v[90:93], v[144:147], v[200:203], v[90:93]
	v_mfma_f32_16x16x32_bf16 v[82:85], v[152:155], v[200:203], v[82:85]
	v_mfma_f32_16x16x32_bf16 v[126:129], v[148:151], v[180:183], v[126:129]
	v_mfma_f32_16x16x32_bf16 v[122:125], v[156:159], v[180:183], v[122:125]
	v_mfma_f32_16x16x32_bf16 v[118:121], v[148:151], v[188:191], v[118:121]
	v_mfma_f32_16x16x32_bf16 v[114:117], v[156:159], v[188:191], v[114:117]
	v_mfma_f32_16x16x32_bf16 v[106:109], v[148:151], v[196:199], v[106:109]
	v_mfma_f32_16x16x32_bf16 v[98:101], v[156:159], v[196:199], v[98:101]
	v_mfma_f32_16x16x32_bf16 v[90:93], v[148:151], v[204:207], v[90:93]
	v_mfma_f32_16x16x32_bf16 v[82:85], v[156:159], v[204:207], v[82:85]
	s_setprio 0
	s_setprio 1
	v_mfma_f32_16x16x32_bf16 v[110:113], v[160:163], v[176:179], v[110:113]
	v_mfma_f32_16x16x32_bf16 v[102:105], v[168:171], v[176:179], v[102:105]
	v_mfma_f32_16x16x32_bf16 v[94:97], v[160:163], v[184:187], v[94:97]
	v_mfma_f32_16x16x32_bf16 v[86:89], v[168:171], v[184:187], v[86:89]
	v_mfma_f32_16x16x32_bf16 v[78:81], v[160:163], v[192:195], v[78:81]
	v_mfma_f32_16x16x32_bf16 v[74:77], v[168:171], v[192:195], v[74:77]
	v_mfma_f32_16x16x32_bf16 v[70:73], v[160:163], v[200:203], v[70:73]
	v_mfma_f32_16x16x32_bf16 v[66:69], v[168:171], v[200:203], v[66:69]
	v_mfma_f32_16x16x32_bf16 v[110:113], v[164:167], v[180:183], v[110:113]
	v_mfma_f32_16x16x32_bf16 v[102:105], v[172:175], v[180:183], v[102:105]
	v_mfma_f32_16x16x32_bf16 v[94:97], v[164:167], v[188:191], v[94:97]
	v_mfma_f32_16x16x32_bf16 v[86:89], v[172:175], v[188:191], v[86:89]
	v_mfma_f32_16x16x32_bf16 v[78:81], v[164:167], v[196:199], v[78:81]
	v_mfma_f32_16x16x32_bf16 v[74:77], v[172:175], v[196:199], v[74:77]
	v_mfma_f32_16x16x32_bf16 v[70:73], v[164:167], v[204:207], v[70:73]
	v_mfma_f32_16x16x32_bf16 v[66:69], v[172:175], v[204:207], v[66:69]
	s_setprio 0
	s_barrier
; #define PG8_STAGE(bufoff, gbase, voff) do { _Pragma("unroll") for (int _i = 0; _i < 2; ++_i) \
;         __builtin_amdgcn_global_load_lds((const unsigned*)((const char*)(gbase) + (voff)[_i]), (PG8_LAS unsigned*)(lds + (bufoff) + ldsw + _i * 8192), 16, 0, 0); } while (0)
; #define PG8_LDA(dst, b, h) do { _Pragma("unroll") for (int m = 0; m < 4; ++m) _Pragma("unroll") for (int k = 0; k < 2; ++k) dst[m][k] = *(const PG8_LAS bf16x8*)(lds + PG8_SA(b, h) + aoff + m * 2048 + k * 1024); } while (0)
; #define PG8_MMA(ai, bj, At, Bt) do { __builtin_amdgcn_s_setprio(1); _Pragma("unroll") for (int m = 0; m < 4; ++m) _Pragma("unroll") for (int n = 0; n < 2; ++n) _Pragma("unroll") for (int k = 0; k < 2; ++k) \
;         acc[ai][bj][m][n] = __builtin_amdgcn_mfma_f32_16x16x32_bf16(Bt[n][k], At[m][k], acc[ai][bj][m][n], 0, 0, 0); __builtin_amdgcn_s_setprio(0); } while (0)
; #define PG8_WAIT_V(n) asm volatile("s_waitcnt vmcnt(" #n ")" ::: "memory")
; #define PG8_WAIT_L(n) asm volatile("s_waitcnt lgkmcnt(" #n ")" ::: "memory")
; #define PG8_BAR __builtin_amdgcn_s_barrier()
; #define PG8_SCHED __builtin_amdgcn_sched_barrier(0)
; template <class Epi, class Sched, bool ALIGN_EPI = false, bool SP2 = false>
; __device__ __forceinline__ void gemm_phase(PG8_LAS unsigned char* lds, const Gemm g, const Sched& S, const Epi& E) {
;     ...
;         for (int t = 0; t < nt; t += 2) {
;             if constexpr (Epi::MIDHOOK) { if (t == (nt >> 1)) E.mid(acc, cur, wr, wc, fr, fq); }
;             const bool last = (t == nt - 2);
;             const char* a1 = cA + (size_t)(t + 1) * kstep;
;             const char* a2 = last ? nA : cA + (size_t)(t + 2) * kstep; const char* b2 = last ? nB : cB + (size_t)(t + 2) * kstep;
;             const char* a3 = a2 + kstep; const char* b3 = b2 + kstep;
;     ...
;             PG8_LDA(At, 1, 1); PG8_STAGE(PG8_SB(1, 0), b3, voffB); PG8_STAGE(PG8_SB(1, 1), b3 + hstep, voffB); PG8_STAGE(PG8_SA(1, 0), a3, voffA);
;             PG8_WAIT_V(8); PG8_WAIT_L(0); PG8_BAR; PG8_MMA(1, 0, At, B0); PG8_MMA(1, 1, At, B1); PG8_BAR; PG8_SCHED;
	s_add_i32 s26, s61, s39
	v_lshl_add_u64 v[208:209], v[208:209], 0, s[12:13]
	s_mov_b32 m0, s26
	ds_read_b128 v[176:179], v143 offset:49152
	ds_read_b128 v[180:183], v143 offset:50176
	ds_read_b128 v[184:187], v143 offset:51200
	ds_read_b128 v[188:191], v143 offset:52224
	ds_read_b128 v[192:195], v143 offset:53248
	ds_read_b128 v[196:199], v143 offset:54272
	ds_read_b128 v[200:203], v143 offset:55296
	ds_read_b128 v[204:207], v143 offset:56320
	global_load_lds_dwordx4 v[208:209], off
	s_add_i32 m0, s26, 0x2000
	s_add_u32 s26, s30, 0x160080
	v_lshl_add_u64 v[208:209], v[210:211], 0, s[12:13]
	s_addc_u32 s27, s31, 0
	s_add_i32 s30, s62, s39
	global_load_lds_dwordx4 v[208:209], off
	v_lshl_add_u64 v[208:209], s[26:27], 0, v[132:133]
	s_mov_b32 m0, s30
	s_nop 0
	global_load_lds_dwordx4 v[208:209], off
	v_lshl_add_u64 v[208:209], s[26:27], 0, v[130:131]
	s_add_i32 m0, s30, 0x2000
	s_nop 0
	global_load_lds_dwordx4 v[208:209], off
	v_lshl_add_u64 v[208:209], v[212:213], 0, s[12:13]
	s_mov_b32 m0, s47
	s_nop 0
	global_load_lds_dwordx4 v[208:209], off
	v_lshl_add_u64 v[208:209], v[214:215], 0, s[12:13]
	s_mov_b32 m0, s48
	s_nop 0
	global_load_lds_dwordx4 v[208:209], off
	s_waitcnt vmcnt(8)
	s_waitcnt lgkmcnt(0)
	s_barrier
	s_setprio 1
	s_waitcnt lgkmcnt(0)
	v_mfma_f32_16x16x32_bf16 v[62:65], v[144:147], v[176:179], v[62:65]
	v_mfma_f32_16x16x32_bf16 v[58:61], v[152:155], v[176:179], v[58:61]
	v_mfma_f32_16x16x32_bf16 v[54:57], v[144:147], v[184:187], v[54:57]
	v_mfma_f32_16x16x32_bf16 v[50:53], v[152:155], v[184:187], v[50:53]
	v_mfma_f32_16x16x32_bf16 v[42:45], v[144:147], v[192:195], v[42:45]
	v_mfma_f32_16x16x32_bf16 v[34:37], v[152:155], v[192:195], v[34:37]
	v_mfma_f32_16x16x32_bf16 v[26:29], v[144:147], v[200:203], v[26:29]
	v_mfma_f32_16x16x32_bf16 v[18:21], v[152:155], v[200:203], v[18:21]
	v_mfma_f32_16x16x32_bf16 v[62:65], v[148:151], v[180:183], v[62:65]
	v_mfma_f32_16x16x32_bf16 v[58:61], v[156:159], v[180:183], v[58:61]
	v_mfma_f32_16x16x32_bf16 v[54:57], v[148:151], v[188:191], v[54:57]
	v_mfma_f32_16x16x32_bf16 v[50:53], v[156:159], v[188:191], v[50:53]
	v_mfma_f32_16x16x32_bf16 v[42:45], v[148:151], v[196:199], v[42:45]
	v_mfma_f32_16x16x32_bf16 v[34:37], v[156:159], v[196:199], v[34:37]
	v_mfma_f32_16x16x32_bf16 v[26:29], v[148:151], v[204:207], v[26:29]
	v_mfma_f32_16x16x32_bf16 v[18:21], v[156:159], v[204:207], v[18:21]
	s_setprio 0
	s_setprio 1
	v_mfma_f32_16x16x32_bf16 v[46:49], v[160:163], v[176:179], v[46:49]
	v_mfma_f32_16x16x32_bf16 v[38:41], v[168:171], v[176:179], v[38:41]
	v_mfma_f32_16x16x32_bf16 v[30:33], v[160:163], v[184:187], v[30:33]
	v_mfma_f32_16x16x32_bf16 v[22:25], v[168:171], v[184:187], v[22:25]
	v_mfma_f32_16x16x32_bf16 v[14:17], v[160:163], v[192:195], v[14:17]
	v_mfma_f32_16x16x32_bf16 v[10:13], v[168:171], v[192:195], v[10:13]
	v_mfma_f32_16x16x32_bf16 v[6:9], v[160:163], v[200:203], v[6:9]
	v_mfma_f32_16x16x32_bf16 v[2:5], v[168:171], v[200:203], v[2:5]
	v_mfma_f32_16x16x32_bf16 v[46:49], v[164:167], v[180:183], v[46:49]
	v_mfma_f32_16x16x32_bf16 v[38:41], v[172:175], v[180:183], v[38:41]
	v_mfma_f32_16x16x32_bf16 v[30:33], v[164:167], v[188:191], v[30:33]
	v_mfma_f32_16x16x32_bf16 v[22:25], v[172:175], v[188:191], v[22:25]
	v_mfma_f32_16x16x32_bf16 v[14:17], v[164:167], v[196:199], v[14:17]
	v_mfma_f32_16x16x32_bf16 v[10:13], v[172:175], v[196:199], v[10:13]
	v_mfma_f32_16x16x32_bf16 v[6:9], v[164:167], v[204:207], v[6:9]
	v_mfma_f32_16x16x32_bf16 v[2:5], v[172:175], v[204:207], v[2:5]
	s_setprio 0
	s_barrier
	s_add_i32 s60, s60, 2
	s_add_u32 s7, s7, 0x100
	s_addc_u32 s59, s59, 0
	s_cmp_gt_u32 s60, 19
	s_mov_b64 s[26:27], s[28:29]
	s_cbranch_scc0 .LBB0_1676

;     __device__ bool next(int i, Unit& u) const { if (!s.next(i, u)) return false; const int p = u.pn; u.pn = p < 56 ? (p % 7) * 8 + p / 7 : p; return true; }
;     __device__ bool next(int i, Unit& u) const { Unit t; if (!s.next(i >> 1, t)) return false; const int pass = i & 1; u.pm = t.pm + pass * (M / BM); u.pn = t.pn + pass * (D / BM); u.kt0 = 0; return true; }
; #define PG8_STAGE(bufoff, gbase, voff) do { _Pragma("unroll") for (int _i = 0; _i < 2; ++_i) \
;         __builtin_amdgcn_global_load_lds((const unsigned*)((const char*)(gbase) + (voff)[_i]), (PG8_LAS unsigned*)(lds + (bufoff) + ldsw + _i * 8192), 16, 0, 0); } while (0)
; #define PG8_WAIT_V(n) asm volatile("s_waitcnt vmcnt(" #n ")" ::: "memory")
; #define PG8_WAIT_L(n) asm volatile("s_waitcnt lgkmcnt(" #n ")" ::: "memory")
; #define PG8_BAR __builtin_amdgcn_s_barrier()
; template <class Epi, class Sched, bool ALIGN_EPI = false, bool SP2 = false>
; __device__ __forceinline__ void gemm_phase(PG8_LAS unsigned char* lds, const Gemm g, const Sched& S, const Epi& E) {
;     ...
;         const bool has_next = S.next(ui + 1, nxt);
;         const char* nA = has_next ? (const char*)g.A + (size_t)nxt.pm * tstep + (size_t)nxt.kt0 * kstep : cA; const char* nB = has_next ? (const char*)g.Bt + (size_t)nxt.pn * tstep + (size_t)nxt.kt0 * kstep : cB;
;         for (int t = 0; t < nt; t += 2) {
;             if constexpr (Epi::MIDHOOK) { if (t == (nt >> 1)) E.mid(acc, cur, wr, wc, fr, fq); }
;             const bool last = (t == nt - 2);
;             const char* a1 = cA + (size_t)(t + 1) * kstep;
;             const char* a2 = last ? nA : cA + (size_t)(t + 2) * kstep; const char* b2 = last ? nB : cB + (size_t)(t + 2) * kstep;
;             const char* a3 = a2 + kstep; const char* b3 = b2 + kstep;
;             if (last && has_next) S.a_ready(nxt);
;             if constexpr (SP2) {
;             PG8_LDB(B0, 0, 0); PG8_LDB(B1, 0, 1); PG8_SCHED; PG8_LDA(At, 0, 0); PG8_STAGE(PG8_SA(1, 1), a1 + hstep, voffA);
;             PG8_WAIT_V(8); PG8_WAIT_L(0); PG8_BAR; PG8_MMA(0, 0, At, B0); PG8_MMA(0, 1, At, B1); PG8_BAR; PG8_SCHED;
;     ...
; #pragma unroll
;         for (int a = 0; a < 2; ++a)
; #pragma unroll
;             for (int b = 0; b < 2; ++b)
; #pragma unroll
;                 for (int m = 0; m < 4; ++m)
; #pragma unroll
;                     for (int n = 0; n < 2; ++n) acc[a][b][m][n] = (f32x4){0.f, 0.f, 0.f, 0.f};
.LBB0_1692:
	s_ashr_i32 s19, s18, 31
	s_lshl_b64 s[20:21], s[18:19], 17
	s_add_u32 s20, s46, s20
	s_addc_u32 s21, s47, s21
	s_and_b64 s[22:23], s[0:1], exec
	s_cselect_b32 s19, s21, s27
	s_cselect_b32 s63, s20, s26
	s_ashr_i32 s17, s16, 31
	s_lshl_b64 s[22:23], s[16:17], 17
	s_add_u32 s22, s48, s22
	s_addc_u32 s23, s49, s23
	s_and_b64 s[28:29], s[0:1], exec
	s_cselect_b32 s17, s23, s25
	s_cselect_b32 s64, s22, s24
	s_mov_b32 s36, 0
	s_mov_b64 s[28:29], -1
	s_mov_b64 s[30:31], 0
	s_waitcnt lgkmcnt(0)
	s_add_u32 s37, s26, s36
	s_addc_u32 s42, s27, 0
	s_add_u32 s40, s37, 0x100
	s_addc_u32 s41, s42, 0
	s_and_b64 s[38:39], s[30:31], exec
	s_cselect_b32 s39, s19, s41
	s_cselect_b32 s38, s63, s40
	s_add_u32 s36, s24, s36
	s_addc_u32 s40, s25, 0
	s_add_u32 s36, s36, 0x100
	s_addc_u32 s40, s40, 0
	s_and_b64 s[30:31], s[30:31], exec
	s_cselect_b32 s41, s17, s40
	s_cselect_b32 s40, s64, s36
	s_add_u32 s44, s37, 0x10080
	ds_read_b128 v[150:153], v147
	ds_read_b128 v[154:157], v147 offset:1024
	ds_read_b128 v[158:161], v147 offset:2048
	ds_read_b128 v[162:165], v147 offset:3072
	ds_read_b128 v[166:169], v148
	ds_read_b128 v[170:173], v148 offset:1024
	ds_read_b128 v[174:177], v148 offset:2048
	ds_read_b128 v[178:181], v148 offset:3072
	s_addc_u32 s45, s42, 0
	s_add_i32 s74, s57, s33
	s_add_i32 m0, s50, 0xc000
	s_add_i32 s75, s50, 0xe000
	s_add_i32 s71, s74, 0x2000
	s_add_u32 s42, s40, 0x10000
	s_addc_u32 s43, s41, 0
	s_add_i32 s73, s58, s33
	s_add_i32 s72, s73, 0x2000
	s_add_i32 s70, 0, 0x18000
	s_add_i32 s69, 0, 0x1c000
	s_add_u32 s36, s38, 0x10000
	s_addc_u32 s37, s39, 0
	s_add_i32 s68, s70, s33
	s_add_i32 s66, s68, 0x2000
	s_add_u32 s30, s40, 0x10080
	s_addc_u32 s31, s41, 0
	s_add_i32 s67, s69, s33
	s_add_i32 s65, s67, 0x2000
	v_lshl_add_u64 v[142:143], s[44:45], 0, v[136:137]
	ds_read_b128 v[182:185], v149
	ds_read_b128 v[186:189], v149 offset:1024
	ds_read_b128 v[190:193], v149 offset:2048
	ds_read_b128 v[194:197], v149 offset:3072
	ds_read_b128 v[198:201], v149 offset:4096
	ds_read_b128 v[202:205], v149 offset:5120
	ds_read_b128 v[206:209], v149 offset:6144
	ds_read_b128 v[210:213], v149 offset:7168
	global_load_lds_dwordx4 v[142:143], off
	v_lshl_add_u64 v[142:143], s[44:45], 0, v[132:133]
	s_mov_b32 m0, s75
	s_nop 0
	global_load_lds_dwordx4 v[142:143], off
	s_waitcnt vmcnt(8)
	s_waitcnt lgkmcnt(0)
	s_barrier
	s_setprio 1
	s_waitcnt lgkmcnt(0)
	v_mfma_f32_16x16x32_bf16 v[126:129], v[150:153], v[182:185], 0
	v_mfma_f32_16x16x32_bf16 v[122:125], v[158:161], v[182:185], 0
	v_mfma_f32_16x16x32_bf16 v[118:121], v[150:153], v[190:193], 0
	v_mfma_f32_16x16x32_bf16 v[110:113], v[158:161], v[190:193], 0
	v_mfma_f32_16x16x32_bf16 v[102:105], v[150:153], v[198:201], 0
	v_mfma_f32_16x16x32_bf16 v[94:97], v[158:161], v[198:201], 0
	v_mfma_f32_16x16x32_bf16 v[86:89], v[150:153], v[206:209], 0
	v_mfma_f32_16x16x32_bf16 v[78:81], v[158:161], v[206:209], 0
	v_mfma_f32_16x16x32_bf16 v[126:129], v[154:157], v[186:189], v[126:129]
	v_mfma_f32_16x16x32_bf16 v[122:125], v[162:165], v[186:189], v[122:125]
	v_mfma_f32_16x16x32_bf16 v[118:121], v[154:157], v[194:197], v[118:121]
	v_mfma_f32_16x16x32_bf16 v[110:113], v[162:165], v[194:197], v[110:113]
	v_mfma_f32_16x16x32_bf16 v[102:105], v[154:157], v[202:205], v[102:105]
	v_mfma_f32_16x16x32_bf16 v[94:97], v[162:165], v[202:205], v[94:97]
	v_mfma_f32_16x16x32_bf16 v[86:89], v[154:157], v[210:213], v[86:89]
	v_mfma_f32_16x16x32_bf16 v[78:81], v[162:165], v[210:213], v[78:81]
	s_setprio 0
	s_setprio 1
	v_mfma_f32_16x16x32_bf16 v[114:117], v[166:169], v[182:185], 0
	v_mfma_f32_16x16x32_bf16 v[106:109], v[174:177], v[182:185], 0
	v_mfma_f32_16x16x32_bf16 v[98:101], v[166:169], v[190:193], 0
	v_mfma_f32_16x16x32_bf16 v[90:93], v[174:177], v[190:193], 0
	v_mfma_f32_16x16x32_bf16 v[82:85], v[166:169], v[198:201], 0
	v_mfma_f32_16x16x32_bf16 v[74:77], v[174:177], v[198:201], 0
	v_mfma_f32_16x16x32_bf16 v[70:73], v[166:169], v[206:209], 0
	v_mfma_f32_16x16x32_bf16 v[66:69], v[174:177], v[206:209], 0
	v_mfma_f32_16x16x32_bf16 v[114:117], v[170:173], v[186:189], v[114:117]
	v_mfma_f32_16x16x32_bf16 v[106:109], v[178:181], v[186:189], v[106:109]
	v_mfma_f32_16x16x32_bf16 v[98:101], v[170:173], v[194:197], v[98:101]
	v_mfma_f32_16x16x32_bf16 v[90:93], v[178:181], v[194:197], v[90:93]
	v_mfma_f32_16x16x32_bf16 v[82:85], v[170:173], v[202:205], v[82:85]
	v_mfma_f32_16x16x32_bf16 v[74:77], v[178:181], v[202:205], v[74:77]
	v_mfma_f32_16x16x32_bf16 v[70:73], v[170:173], v[210:213], v[70:73]
	v_mfma_f32_16x16x32_bf16 v[66:69], v[178:181], v[210:213], v[66:69]
	s_setprio 0
	s_barrier
	s_mov_b32 m0, s74
	v_lshl_add_u64 v[142:143], s[40:41], 0, v[134:135]
	ds_read_b128 v[182:185], v149 offset:16384
	ds_read_b128 v[186:189], v149 offset:17408
	ds_read_b128 v[190:193], v149 offset:18432
	ds_read_b128 v[194:197], v149 offset:19456
	ds_read_b128 v[198:201], v149 offset:20480
	ds_read_b128 v[202:205], v149 offset:21504
	ds_read_b128 v[206:209], v149 offset:22528
	ds_read_b128 v[210:213], v149 offset:23552
	global_load_lds_dwordx4 v[142:143], off
	v_lshl_add_u64 v[214:215], s[40:41], 0, v[130:131]
	s_mov_b32 m0, s71
	v_lshl_add_u64 v[216:217], s[42:43], 0, v[134:135]
	global_load_lds_dwordx4 v[214:215], off
	s_mov_b32 m0, s73
	v_lshl_add_u64 v[218:219], s[38:39], 0, v[132:133]
	global_load_lds_dwordx4 v[216:217], off
	v_lshl_add_u64 v[216:217], s[42:43], 0, v[130:131]
	s_mov_b32 m0, s72
	s_nop 0
	global_load_lds_dwordx4 v[216:217], off
	v_lshl_add_u64 v[216:217], s[38:39], 0, v[136:137]
	s_mov_b32 m0, s50
	s_nop 0
	global_load_lds_dwordx4 v[216:217], off
	s_mov_b32 m0, s51
	s_nop 0
	global_load_lds_dwordx4 v[218:219], off
	s_waitcnt vmcnt(8)
	s_waitcnt lgkmcnt(0)
	s_barrier
; #define PG8_STAGE(bufoff, gbase, voff) do { _Pragma("unroll") for (int _i = 0; _i < 2; ++_i) \
;         __builtin_amdgcn_global_load_lds((const unsigned*)((const char*)(gbase) + (voff)[_i]), (PG8_LAS unsigned*)(lds + (bufoff) + ldsw + _i * 8192), 16, 0, 0); } while (0)
; #define PG8_LDA(dst, b, h) do { _Pragma("unroll") for (int m = 0; m < 4; ++m) _Pragma("unroll") for (int k = 0; k < 2; ++k) dst[m][k] = *(const PG8_LAS bf16x8*)(lds + PG8_SA(b, h) + aoff + m * 2048 + k * 1024); } while (0)
; #define PG8_LDB(dst, b, h) do { _Pragma("unroll") for (int n = 0; n < 2; ++n) _Pragma("unroll") for (int k = 0; k < 2; ++k) dst[n][k] = *(const PG8_LAS bf16x8*)(lds + PG8_SB(b, h) + boff + n * 2048 + k * 1024); } while (0)
; #define PG8_MMA(ai, bj, At, Bt) do { __builtin_amdgcn_s_setprio(1); _Pragma("unroll") for (int m = 0; m < 4; ++m) _Pragma("unroll") for (int n = 0; n < 2; ++n) _Pragma("unroll") for (int k = 0; k < 2; ++k) \
;         acc[ai][bj][m][n] = __builtin_amdgcn_mfma_f32_16x16x32_bf16(Bt[n][k], At[m][k], acc[ai][bj][m][n], 0, 0, 0); __builtin_amdgcn_s_setprio(0); } while (0)
; #define PG8_WAIT_V(n) asm volatile("s_waitcnt vmcnt(" #n ")" ::: "memory")
; #define PG8_WAIT_L(n) asm volatile("s_waitcnt lgkmcnt(" #n ")" ::: "memory")
; #define PG8_BAR __builtin_amdgcn_s_barrier()
; #define PG8_SCHED __builtin_amdgcn_sched_barrier(0)
; template <class Epi, class Sched, bool ALIGN_EPI = false, bool SP2 = false>
; __device__ __forceinline__ void gemm_phase(PG8_LAS unsigned char* lds, const Gemm g, const Sched& S, const Epi& E) {
;     ...
;             PG8_LDA(At, 0, 1); PG8_STAGE(PG8_SB(0, 0), b2, voffB); PG8_STAGE(PG8_SB(0, 1), b2 + hstep, voffB); PG8_STAGE(PG8_SA(0, 0), a2, voffA);
;             PG8_WAIT_V(8); PG8_WAIT_L(0); PG8_BAR; PG8_MMA(1, 0, At, B0); PG8_MMA(1, 1, At, B1); PG8_BAR; PG8_SCHED;
;             PG8_LDB(B0, 1, 0); PG8_LDB(B1, 1, 1); PG8_SCHED; PG8_LDA(At, 1, 0); PG8_STAGE(PG8_SA(0, 1), a2 + hstep, voffA);
;             PG8_WAIT_V(8); PG8_WAIT_L(0); PG8_BAR; PG8_MMA(0, 0, At, B0); PG8_MMA(0, 1, At, B1); PG8_BAR; PG8_SCHED;
	s_setprio 1
	s_waitcnt lgkmcnt(0)
	v_mfma_f32_16x16x32_bf16 v[62:65], v[150:153], v[182:185], 0
	v_mfma_f32_16x16x32_bf16 v[58:61], v[158:161], v[182:185], 0
	v_mfma_f32_16x16x32_bf16 v[54:57], v[150:153], v[190:193], 0
	v_mfma_f32_16x16x32_bf16 v[46:49], v[158:161], v[190:193], 0
	v_mfma_f32_16x16x32_bf16 v[38:41], v[150:153], v[198:201], 0
	v_mfma_f32_16x16x32_bf16 v[30:33], v[158:161], v[198:201], 0
	v_mfma_f32_16x16x32_bf16 v[22:25], v[150:153], v[206:209], 0
	v_mfma_f32_16x16x32_bf16 v[14:17], v[158:161], v[206:209], 0
	v_mfma_f32_16x16x32_bf16 v[62:65], v[154:157], v[186:189], v[62:65]
	v_mfma_f32_16x16x32_bf16 v[58:61], v[162:165], v[186:189], v[58:61]
	v_mfma_f32_16x16x32_bf16 v[54:57], v[154:157], v[194:197], v[54:57]
	v_mfma_f32_16x16x32_bf16 v[46:49], v[162:165], v[194:197], v[46:49]
	v_mfma_f32_16x16x32_bf16 v[38:41], v[154:157], v[202:205], v[38:41]
	v_mfma_f32_16x16x32_bf16 v[30:33], v[162:165], v[202:205], v[30:33]
	v_mfma_f32_16x16x32_bf16 v[22:25], v[154:157], v[210:213], v[22:25]
	v_mfma_f32_16x16x32_bf16 v[14:17], v[162:165], v[210:213], v[14:17]
	s_setprio 0
	s_setprio 1
	v_mfma_f32_16x16x32_bf16 v[50:53], v[166:169], v[182:185], 0
	v_mfma_f32_16x16x32_bf16 v[42:45], v[174:177], v[182:185], 0
	v_mfma_f32_16x16x32_bf16 v[34:37], v[166:169], v[190:193], 0
	v_mfma_f32_16x16x32_bf16 v[26:29], v[174:177], v[190:193], 0
	v_mfma_f32_16x16x32_bf16 v[18:21], v[166:169], v[198:201], 0
	v_mfma_f32_16x16x32_bf16 v[10:13], v[174:177], v[198:201], 0
	v_mfma_f32_16x16x32_bf16 v[6:9], v[166:169], v[206:209], 0
	v_mfma_f32_16x16x32_bf16 v[2:5], v[174:177], v[206:209], 0
	v_mfma_f32_16x16x32_bf16 v[50:53], v[170:173], v[186:189], v[50:53]
	v_mfma_f32_16x16x32_bf16 v[42:45], v[178:181], v[186:189], v[42:45]
	v_mfma_f32_16x16x32_bf16 v[34:37], v[170:173], v[194:197], v[34:37]
	v_mfma_f32_16x16x32_bf16 v[26:29], v[178:181], v[194:197], v[26:29]
	v_mfma_f32_16x16x32_bf16 v[18:21], v[170:173], v[202:205], v[18:21]
	v_mfma_f32_16x16x32_bf16 v[10:13], v[178:181], v[202:205], v[10:13]
	v_mfma_f32_16x16x32_bf16 v[6:9], v[170:173], v[210:213], v[6:9]
	v_mfma_f32_16x16x32_bf16 v[2:5], v[178:181], v[210:213], v[2:5]
	s_setprio 0
	s_barrier
	v_add_u32_e32 v162, s70, v145
	v_add_u32_e32 v178, s69, v145
	ds_read_b128 v[150:153], v162
	ds_read_b128 v[154:157], v162 offset:1024
	ds_read_b128 v[158:161], v162 offset:2048
	ds_read_b128 v[162:165], v162 offset:3072
	ds_read_b128 v[166:169], v178
	ds_read_b128 v[170:173], v178 offset:1024
	ds_read_b128 v[174:177], v178 offset:2048
	ds_read_b128 v[178:181], v178 offset:3072
	s_mov_b32 m0, s52
	v_lshl_add_u64 v[220:221], s[36:37], 0, v[136:137]
	ds_read_b128 v[182:185], v149 offset:32768
	ds_read_b128 v[186:189], v149 offset:33792
	ds_read_b128 v[190:193], v149 offset:34816
	ds_read_b128 v[194:197], v149 offset:35840
	ds_read_b128 v[198:201], v149 offset:36864
	ds_read_b128 v[202:205], v149 offset:37888
	ds_read_b128 v[206:209], v149 offset:38912
	ds_read_b128 v[210:213], v149 offset:39936
	global_load_lds_dwordx4 v[220:221], off
	v_lshl_add_u64 v[220:221], s[36:37], 0, v[132:133]
	s_mov_b32 m0, s53
	s_nop 0
	global_load_lds_dwordx4 v[220:221], off
	s_waitcnt vmcnt(8)
	s_waitcnt lgkmcnt(0)
	s_barrier
	s_setprio 1
	s_waitcnt lgkmcnt(0)
	v_mfma_f32_16x16x32_bf16 v[126:129], v[150:153], v[182:185], v[126:129]
	v_mfma_f32_16x16x32_bf16 v[122:125], v[158:161], v[182:185], v[122:125]
	v_mfma_f32_16x16x32_bf16 v[118:121], v[150:153], v[190:193], v[118:121]
	v_mfma_f32_16x16x32_bf16 v[110:113], v[158:161], v[190:193], v[110:113]
	v_mfma_f32_16x16x32_bf16 v[102:105], v[150:153], v[198:201], v[102:105]
	v_mfma_f32_16x16x32_bf16 v[94:97], v[158:161], v[198:201], v[94:97]
	v_mfma_f32_16x16x32_bf16 v[86:89], v[150:153], v[206:209], v[86:89]
	v_mfma_f32_16x16x32_bf16 v[78:81], v[158:161], v[206:209], v[78:81]
	v_mfma_f32_16x16x32_bf16 v[126:129], v[154:157], v[186:189], v[126:129]
	v_mfma_f32_16x16x32_bf16 v[122:125], v[162:165], v[186:189], v[122:125]
	v_mfma_f32_16x16x32_bf16 v[118:121], v[154:157], v[194:197], v[118:121]
	v_mfma_f32_16x16x32_bf16 v[110:113], v[162:165], v[194:197], v[110:113]
	v_mfma_f32_16x16x32_bf16 v[102:105], v[154:157], v[202:205], v[102:105]
	v_mfma_f32_16x16x32_bf16 v[94:97], v[162:165], v[202:205], v[94:97]
	v_mfma_f32_16x16x32_bf16 v[86:89], v[154:157], v[210:213], v[86:89]
	v_mfma_f32_16x16x32_bf16 v[78:81], v[162:165], v[210:213], v[78:81]
	s_setprio 0
	s_setprio 1
	v_mfma_f32_16x16x32_bf16 v[114:117], v[166:169], v[182:185], v[114:117]
	v_mfma_f32_16x16x32_bf16 v[106:109], v[174:177], v[182:185], v[106:109]
	v_mfma_f32_16x16x32_bf16 v[98:101], v[166:169], v[190:193], v[98:101]
	v_mfma_f32_16x16x32_bf16 v[90:93], v[174:177], v[190:193], v[90:93]
	v_mfma_f32_16x16x32_bf16 v[82:85], v[166:169], v[198:201], v[82:85]
	v_mfma_f32_16x16x32_bf16 v[74:77], v[174:177], v[198:201], v[74:77]
	v_mfma_f32_16x16x32_bf16 v[70:73], v[166:169], v[206:209], v[70:73]
	v_mfma_f32_16x16x32_bf16 v[66:69], v[174:177], v[206:209], v[66:69]
	v_mfma_f32_16x16x32_bf16 v[114:117], v[170:173], v[186:189], v[114:117]
	v_mfma_f32_16x16x32_bf16 v[106:109], v[178:181], v[186:189], v[106:109]
	v_mfma_f32_16x16x32_bf16 v[98:101], v[170:173], v[194:197], v[98:101]
	v_mfma_f32_16x16x32_bf16 v[90:93], v[178:181], v[194:197], v[90:93]
	v_mfma_f32_16x16x32_bf16 v[82:85], v[170:173], v[202:205], v[82:85]
	v_mfma_f32_16x16x32_bf16 v[74:77], v[178:181], v[202:205], v[74:77]
	v_mfma_f32_16x16x32_bf16 v[70:73], v[170:173], v[210:213], v[70:73]
	v_mfma_f32_16x16x32_bf16 v[66:69], v[178:181], v[210:213], v[66:69]
	s_setprio 0
	s_barrier
; #define PG8_STAGE(bufoff, gbase, voff) do { _Pragma("unroll") for (int _i = 0; _i < 2; ++_i) \
;         __builtin_amdgcn_global_load_lds((const unsigned*)((const char*)(gbase) + (voff)[_i]), (PG8_LAS unsigned*)(lds + (bufoff) + ldsw + _i * 8192), 16, 0, 0); } while (0)
; #define PG8_LDA(dst, b, h) do { _Pragma("unroll") for (int m = 0; m < 4; ++m) _Pragma("unroll") for (int k = 0; k < 2; ++k) dst[m][k] = *(const PG8_LAS bf16x8*)(lds + PG8_SA(b, h) + aoff + m * 2048 + k * 1024); } while (0)
; #define PG8_MMA(ai, bj, At, Bt) do { __builtin_amdgcn_s_setprio(1); _Pragma("unroll") for (int m = 0; m < 4; ++m) _Pragma("unroll") for (int n = 0; n < 2; ++n) _Pragma("unroll") for (int k = 0; k < 2; ++k) \
;         acc[ai][bj][m][n] = __builtin_amdgcn_mfma_f32_16x16x32_bf16(Bt[n][k], At[m][k], acc[ai][bj][m][n], 0, 0, 0); __builtin_amdgcn_s_setprio(0); } while (0)
; #define PG8_WAIT_V(n) asm volatile("s_waitcnt vmcnt(" #n ")" ::: "memory")
; #define PG8_WAIT_L(n) asm volatile("s_waitcnt lgkmcnt(" #n ")" ::: "memory")
; #define PG8_BAR __builtin_amdgcn_s_barrier()
; #define PG8_SCHED __builtin_amdgcn_sched_barrier(0)
; template <class Epi, class Sched, bool ALIGN_EPI = false, bool SP2 = false>
; __device__ __forceinline__ void gemm_phase(PG8_LAS unsigned char* lds, const Gemm g, const Sched& S, const Epi& E) {
;     ...
;         for (int t = 0; t < nt; t += 2) {
;             if constexpr (Epi::MIDHOOK) { if (t == (nt >> 1)) E.mid(acc, cur, wr, wc, fr, fq); }
;             const bool last = (t == nt - 2);
;             const char* a1 = cA + (size_t)(t + 1) * kstep;
;             const char* a2 = last ? nA : cA + (size_t)(t + 2) * kstep; const char* b2 = last ? nB : cB + (size_t)(t + 2) * kstep;
;             const char* a3 = a2 + kstep; const char* b3 = b2 + kstep;
;     ...
;             PG8_LDA(At, 1, 1); PG8_STAGE(PG8_SB(1, 0), b3, voffB); PG8_STAGE(PG8_SB(1, 1), b3 + hstep, voffB); PG8_STAGE(PG8_SA(1, 0), a3, voffA);
;             PG8_WAIT_V(8); PG8_WAIT_L(0); PG8_BAR; PG8_MMA(1, 0, At, B0); PG8_MMA(1, 1, At, B1); PG8_BAR; PG8_SCHED;
	s_mov_b32 m0, s68
	v_lshl_add_u64 v[142:143], v[142:143], 0, s[10:11]
	ds_read_b128 v[182:185], v149 offset:49152
	ds_read_b128 v[186:189], v149 offset:50176
	ds_read_b128 v[190:193], v149 offset:51200
	ds_read_b128 v[194:197], v149 offset:52224
	ds_read_b128 v[198:201], v149 offset:53248
	ds_read_b128 v[202:205], v149 offset:54272
	ds_read_b128 v[206:209], v149 offset:55296
	ds_read_b128 v[210:213], v149 offset:56320
	global_load_lds_dwordx4 v[142:143], off
	v_lshl_add_u64 v[142:143], v[214:215], 0, s[10:11]
	s_mov_b32 m0, s66
	s_nop 0
	global_load_lds_dwordx4 v[142:143], off
	v_lshl_add_u64 v[142:143], s[30:31], 0, v[134:135]
	s_mov_b32 m0, s67
	s_nop 0
	global_load_lds_dwordx4 v[142:143], off
	v_lshl_add_u64 v[142:143], s[30:31], 0, v[130:131]
	s_mov_b32 m0, s65
	s_nop 0
	global_load_lds_dwordx4 v[142:143], off
	v_lshl_add_u64 v[142:143], v[216:217], 0, s[10:11]
	s_mov_b32 m0, s55
	s_nop 0
	global_load_lds_dwordx4 v[142:143], off
	v_lshl_add_u64 v[142:143], v[218:219], 0, s[10:11]
	s_mov_b32 m0, s56
	s_nop 0
	global_load_lds_dwordx4 v[142:143], off
	s_waitcnt vmcnt(8)
	s_waitcnt lgkmcnt(0)
	s_barrier
	s_setprio 1
	s_waitcnt lgkmcnt(0)
	v_mfma_f32_16x16x32_bf16 v[62:65], v[150:153], v[182:185], v[62:65]
	v_mfma_f32_16x16x32_bf16 v[58:61], v[158:161], v[182:185], v[58:61]
	v_mfma_f32_16x16x32_bf16 v[54:57], v[150:153], v[190:193], v[54:57]
	v_mfma_f32_16x16x32_bf16 v[46:49], v[158:161], v[190:193], v[46:49]
	v_mfma_f32_16x16x32_bf16 v[38:41], v[150:153], v[198:201], v[38:41]
	v_mfma_f32_16x16x32_bf16 v[30:33], v[158:161], v[198:201], v[30:33]
	v_mfma_f32_16x16x32_bf16 v[22:25], v[150:153], v[206:209], v[22:25]
	v_mfma_f32_16x16x32_bf16 v[14:17], v[158:161], v[206:209], v[14:17]
	v_mfma_f32_16x16x32_bf16 v[62:65], v[154:157], v[186:189], v[62:65]
	v_mfma_f32_16x16x32_bf16 v[58:61], v[162:165], v[186:189], v[58:61]
	v_mfma_f32_16x16x32_bf16 v[54:57], v[154:157], v[194:197], v[54:57]
	v_mfma_f32_16x16x32_bf16 v[46:49], v[162:165], v[194:197], v[46:49]
	v_mfma_f32_16x16x32_bf16 v[38:41], v[154:157], v[202:205], v[38:41]
	v_mfma_f32_16x16x32_bf16 v[30:33], v[162:165], v[202:205], v[30:33]
	v_mfma_f32_16x16x32_bf16 v[22:25], v[154:157], v[210:213], v[22:25]
	v_mfma_f32_16x16x32_bf16 v[14:17], v[162:165], v[210:213], v[14:17]
	s_setprio 0
	s_setprio 1
	v_mfma_f32_16x16x32_bf16 v[50:53], v[166:169], v[182:185], v[50:53]
	v_mfma_f32_16x16x32_bf16 v[42:45], v[174:177], v[182:185], v[42:45]
	v_mfma_f32_16x16x32_bf16 v[34:37], v[166:169], v[190:193], v[34:37]
	v_mfma_f32_16x16x32_bf16 v[26:29], v[174:177], v[190:193], v[26:29]
	v_mfma_f32_16x16x32_bf16 v[18:21], v[166:169], v[198:201], v[18:21]
	v_mfma_f32_16x16x32_bf16 v[10:13], v[174:177], v[198:201], v[10:13]
	v_mfma_f32_16x16x32_bf16 v[6:9], v[166:169], v[206:209], v[6:9]
	v_mfma_f32_16x16x32_bf16 v[2:5], v[174:177], v[206:209], v[2:5]
	v_mfma_f32_16x16x32_bf16 v[50:53], v[170:173], v[186:189], v[50:53]
	v_mfma_f32_16x16x32_bf16 v[42:45], v[178:181], v[186:189], v[42:45]
	v_mfma_f32_16x16x32_bf16 v[34:37], v[170:173], v[194:197], v[34:37]
	v_mfma_f32_16x16x32_bf16 v[26:29], v[178:181], v[194:197], v[26:29]
	v_mfma_f32_16x16x32_bf16 v[18:21], v[170:173], v[202:205], v[18:21]
	v_mfma_f32_16x16x32_bf16 v[10:13], v[178:181], v[202:205], v[10:13]
	v_mfma_f32_16x16x32_bf16 v[6:9], v[170:173], v[210:213], v[6:9]
	v_mfma_f32_16x16x32_bf16 v[2:5], v[178:181], v[210:213], v[2:5]
	s_setprio 0
	s_barrier
	s_movk_i32 s36, 0x100
	s_andn2_b64 vcc, exec, s[28:29]
	s_mov_b64 s[30:31], -1
	s_mov_b64 s[28:29], 0
	s_cbranch_vccnz .Lkx_1693
.LBB0_1693:
	s_add_u32 s37, s26, s36
	s_addc_u32 s42, s27, 0
	s_add_u32 s40, s37, 0x100
	s_addc_u32 s41, s42, 0
	s_and_b64 s[38:39], s[30:31], exec
	s_cselect_b32 s39, s19, s41
	s_cselect_b32 s38, s63, s40
	s_add_u32 s36, s24, s36
	s_addc_u32 s40, s25, 0
	s_add_u32 s36, s36, 0x100
	s_addc_u32 s40, s40, 0
	s_and_b64 s[30:31], s[30:31], exec
	s_cselect_b32 s41, s17, s40
	s_cselect_b32 s40, s64, s36
	s_add_u32 s44, s37, 0x10080
	ds_read_b128 v[150:153], v147
	ds_read_b128 v[154:157], v147 offset:1024
	ds_read_b128 v[158:161], v147 offset:2048
	ds_read_b128 v[162:165], v147 offset:3072
	ds_read_b128 v[166:169], v148
	ds_read_b128 v[170:173], v148 offset:1024
	ds_read_b128 v[174:177], v148 offset:2048
	ds_read_b128 v[178:181], v148 offset:3072
	s_addc_u32 s45, s42, 0
	s_add_i32 s74, s57, s33
	s_add_i32 m0, s50, 0xc000
	s_add_i32 s75, s50, 0xe000
	s_add_i32 s71, s74, 0x2000
	s_add_u32 s42, s40, 0x10000
	s_addc_u32 s43, s41, 0
	s_add_i32 s73, s58, s33
	s_add_i32 s72, s73, 0x2000
	s_add_i32 s70, 0, 0x18000
	s_add_i32 s69, 0, 0x1c000
	s_add_u32 s36, s38, 0x10000
	s_addc_u32 s37, s39, 0
	s_add_i32 s68, s70, s33
	s_add_i32 s66, s68, 0x2000
	s_add_u32 s30, s40, 0x10080
	s_addc_u32 s31, s41, 0
	s_add_i32 s67, s69, s33
	s_add_i32 s65, s67, 0x2000
	v_lshl_add_u64 v[142:143], s[44:45], 0, v[136:137]
	ds_read_b128 v[182:185], v149
	ds_read_b128 v[186:189], v149 offset:1024
	ds_read_b128 v[190:193], v149 offset:2048
	ds_read_b128 v[194:197], v149 offset:3072
	ds_read_b128 v[198:201], v149 offset:4096
	ds_read_b128 v[202:205], v149 offset:5120
	ds_read_b128 v[206:209], v149 offset:6144
	ds_read_b128 v[210:213], v149 offset:7168
	global_load_lds_dwordx4 v[142:143], off
	v_lshl_add_u64 v[142:143], s[44:45], 0, v[132:133]
	s_mov_b32 m0, s75
	s_nop 0
	global_load_lds_dwordx4 v[142:143], off
	s_waitcnt vmcnt(8)
	s_waitcnt lgkmcnt(0)
	s_barrier
; #define PG8_STAGE(bufoff, gbase, voff) do { _Pragma("unroll") for (int _i = 0; _i < 2; ++_i) \
;         __builtin_amdgcn_global_load_lds((const unsigned*)((const char*)(gbase) + (voff)[_i]), (PG8_LAS unsigned*)(lds + (bufoff) + ldsw + _i * 8192), 16, 0, 0); } while (0)
; #define PG8_LDA(dst, b, h) do { _Pragma("unroll") for (int m = 0; m < 4; ++m) _Pragma("unroll") for (int k = 0; k < 2; ++k) dst[m][k] = *(const PG8_LAS bf16x8*)(lds + PG8_SA(b, h) + aoff + m * 2048 + k * 1024); } while (0)
; #define PG8_LDB(dst, b, h) do { _Pragma("unroll") for (int n = 0; n < 2; ++n) _Pragma("unroll") for (int k = 0; k < 2; ++k) dst[n][k] = *(const PG8_LAS bf16x8*)(lds + PG8_SB(b, h) + boff + n * 2048 + k * 1024); } while (0)
; #define PG8_MMA(ai, bj, At, Bt) do { __builtin_amdgcn_s_setprio(1); _Pragma("unroll") for (int m = 0; m < 4; ++m) _Pragma("unroll") for (int n = 0; n < 2; ++n) _Pragma("unroll") for (int k = 0; k < 2; ++k) \
;         acc[ai][bj][m][n] = __builtin_amdgcn_mfma_f32_16x16x32_bf16(Bt[n][k], At[m][k], acc[ai][bj][m][n], 0, 0, 0); __builtin_amdgcn_s_setprio(0); } while (0)
; #define PG8_WAIT_V(n) asm volatile("s_waitcnt vmcnt(" #n ")" ::: "memory")
; #define PG8_WAIT_L(n) asm volatile("s_waitcnt lgkmcnt(" #n ")" ::: "memory")
; #define PG8_BAR __builtin_amdgcn_s_barrier()
; #define PG8_SCHED __builtin_amdgcn_sched_barrier(0)
; template <class Epi, class Sched, bool ALIGN_EPI = false, bool SP2 = false>
; __device__ __forceinline__ void gemm_phase(PG8_LAS unsigned char* lds, const Gemm g, const Sched& S, const Epi& E) {
;     ...
;             PG8_LDA(At, 0, 1); PG8_STAGE(PG8_SB(0, 0), b2, voffB); PG8_STAGE(PG8_SB(0, 1), b2 + hstep, voffB); PG8_STAGE(PG8_SA(0, 0), a2, voffA);
;             PG8_WAIT_V(8); PG8_WAIT_L(0); PG8_BAR; PG8_MMA(1, 0, At, B0); PG8_MMA(1, 1, At, B1); PG8_BAR; PG8_SCHED;
;             PG8_LDB(B0, 1, 0); PG8_LDB(B1, 1, 1); PG8_SCHED; PG8_LDA(At, 1, 0); PG8_STAGE(PG8_SA(0, 1), a2 + hstep, voffA);
;             PG8_WAIT_V(8); PG8_WAIT_L(0); PG8_BAR; PG8_MMA(0, 0, At, B0); PG8_MMA(0, 1, At, B1); PG8_BAR; PG8_SCHED;
	s_setprio 1
	s_waitcnt lgkmcnt(0)
	v_mfma_f32_16x16x32_bf16 v[126:129], v[150:153], v[182:185], v[126:129]
	v_mfma_f32_16x16x32_bf16 v[122:125], v[158:161], v[182:185], v[122:125]
	v_mfma_f32_16x16x32_bf16 v[118:121], v[150:153], v[190:193], v[118:121]
	v_mfma_f32_16x16x32_bf16 v[110:113], v[158:161], v[190:193], v[110:113]
	v_mfma_f32_16x16x32_bf16 v[102:105], v[150:153], v[198:201], v[102:105]
	v_mfma_f32_16x16x32_bf16 v[94:97], v[158:161], v[198:201], v[94:97]
	v_mfma_f32_16x16x32_bf16 v[86:89], v[150:153], v[206:209], v[86:89]
	v_mfma_f32_16x16x32_bf16 v[78:81], v[158:161], v[206:209], v[78:81]
	v_mfma_f32_16x16x32_bf16 v[126:129], v[154:157], v[186:189], v[126:129]
	v_mfma_f32_16x16x32_bf16 v[122:125], v[162:165], v[186:189], v[122:125]
	v_mfma_f32_16x16x32_bf16 v[118:121], v[154:157], v[194:197], v[118:121]
	v_mfma_f32_16x16x32_bf16 v[110:113], v[162:165], v[194:197], v[110:113]
	v_mfma_f32_16x16x32_bf16 v[102:105], v[154:157], v[202:205], v[102:105]
	v_mfma_f32_16x16x32_bf16 v[94:97], v[162:165], v[202:205], v[94:97]
	v_mfma_f32_16x16x32_bf16 v[86:89], v[154:157], v[210:213], v[86:89]
	v_mfma_f32_16x16x32_bf16 v[78:81], v[162:165], v[210:213], v[78:81]
	s_setprio 0
	s_setprio 1
	v_mfma_f32_16x16x32_bf16 v[114:117], v[166:169], v[182:185], v[114:117]
	v_mfma_f32_16x16x32_bf16 v[106:109], v[174:177], v[182:185], v[106:109]
	v_mfma_f32_16x16x32_bf16 v[98:101], v[166:169], v[190:193], v[98:101]
	v_mfma_f32_16x16x32_bf16 v[90:93], v[174:177], v[190:193], v[90:93]
	v_mfma_f32_16x16x32_bf16 v[82:85], v[166:169], v[198:201], v[82:85]
	v_mfma_f32_16x16x32_bf16 v[74:77], v[174:177], v[198:201], v[74:77]
	v_mfma_f32_16x16x32_bf16 v[70:73], v[166:169], v[206:209], v[70:73]
	v_mfma_f32_16x16x32_bf16 v[66:69], v[174:177], v[206:209], v[66:69]
	v_mfma_f32_16x16x32_bf16 v[114:117], v[170:173], v[186:189], v[114:117]
	v_mfma_f32_16x16x32_bf16 v[106:109], v[178:181], v[186:189], v[106:109]
	v_mfma_f32_16x16x32_bf16 v[98:101], v[170:173], v[194:197], v[98:101]
	v_mfma_f32_16x16x32_bf16 v[90:93], v[178:181], v[194:197], v[90:93]
	v_mfma_f32_16x16x32_bf16 v[82:85], v[170:173], v[202:205], v[82:85]
	v_mfma_f32_16x16x32_bf16 v[74:77], v[178:181], v[202:205], v[74:77]
	v_mfma_f32_16x16x32_bf16 v[70:73], v[170:173], v[210:213], v[70:73]
	v_mfma_f32_16x16x32_bf16 v[66:69], v[178:181], v[210:213], v[66:69]
	s_setprio 0
	s_barrier
	s_mov_b32 m0, s74
	v_lshl_add_u64 v[142:143], s[40:41], 0, v[134:135]
	ds_read_b128 v[182:185], v149 offset:16384
	ds_read_b128 v[186:189], v149 offset:17408
	ds_read_b128 v[190:193], v149 offset:18432
	ds_read_b128 v[194:197], v149 offset:19456
	ds_read_b128 v[198:201], v149 offset:20480
	ds_read_b128 v[202:205], v149 offset:21504
	ds_read_b128 v[206:209], v149 offset:22528
	ds_read_b128 v[210:213], v149 offset:23552
	global_load_lds_dwordx4 v[142:143], off
	v_lshl_add_u64 v[214:215], s[40:41], 0, v[130:131]
	s_mov_b32 m0, s71
	v_lshl_add_u64 v[216:217], s[42:43], 0, v[134:135]
	global_load_lds_dwordx4 v[214:215], off
	s_mov_b32 m0, s73
	v_lshl_add_u64 v[218:219], s[38:39], 0, v[132:133]
	global_load_lds_dwordx4 v[216:217], off
	v_lshl_add_u64 v[216:217], s[42:43], 0, v[130:131]
	s_mov_b32 m0, s72
	s_nop 0
	global_load_lds_dwordx4 v[216:217], off
	v_lshl_add_u64 v[216:217], s[38:39], 0, v[136:137]
	s_mov_b32 m0, s50
	s_nop 0
	global_load_lds_dwordx4 v[216:217], off
	s_mov_b32 m0, s51
	s_nop 0
	global_load_lds_dwordx4 v[218:219], off
	s_waitcnt vmcnt(8)
	s_waitcnt lgkmcnt(0)
	s_barrier
	s_setprio 1
	s_waitcnt lgkmcnt(0)
	v_mfma_f32_16x16x32_bf16 v[62:65], v[150:153], v[182:185], v[62:65]
	v_mfma_f32_16x16x32_bf16 v[58:61], v[158:161], v[182:185], v[58:61]
	v_mfma_f32_16x16x32_bf16 v[54:57], v[150:153], v[190:193], v[54:57]
	v_mfma_f32_16x16x32_bf16 v[46:49], v[158:161], v[190:193], v[46:49]
	v_mfma_f32_16x16x32_bf16 v[38:41], v[150:153], v[198:201], v[38:41]
	v_mfma_f32_16x16x32_bf16 v[30:33], v[158:161], v[198:201], v[30:33]
	v_mfma_f32_16x16x32_bf16 v[22:25], v[150:153], v[206:209], v[22:25]
	v_mfma_f32_16x16x32_bf16 v[14:17], v[158:161], v[206:209], v[14:17]
	v_mfma_f32_16x16x32_bf16 v[62:65], v[154:157], v[186:189], v[62:65]
	v_mfma_f32_16x16x32_bf16 v[58:61], v[162:165], v[186:189], v[58:61]
	v_mfma_f32_16x16x32_bf16 v[54:57], v[154:157], v[194:197], v[54:57]
	v_mfma_f32_16x16x32_bf16 v[46:49], v[162:165], v[194:197], v[46:49]
	v_mfma_f32_16x16x32_bf16 v[38:41], v[154:157], v[202:205], v[38:41]
	v_mfma_f32_16x16x32_bf16 v[30:33], v[162:165], v[202:205], v[30:33]
	v_mfma_f32_16x16x32_bf16 v[22:25], v[154:157], v[210:213], v[22:25]
	v_mfma_f32_16x16x32_bf16 v[14:17], v[162:165], v[210:213], v[14:17]
	s_setprio 0
	s_setprio 1
	v_mfma_f32_16x16x32_bf16 v[50:53], v[166:169], v[182:185], v[50:53]
	v_mfma_f32_16x16x32_bf16 v[42:45], v[174:177], v[182:185], v[42:45]
	v_mfma_f32_16x16x32_bf16 v[34:37], v[166:169], v[190:193], v[34:37]
	v_mfma_f32_16x16x32_bf16 v[26:29], v[174:177], v[190:193], v[26:29]
	v_mfma_f32_16x16x32_bf16 v[18:21], v[166:169], v[198:201], v[18:21]
	v_mfma_f32_16x16x32_bf16 v[10:13], v[174:177], v[198:201], v[10:13]
	v_mfma_f32_16x16x32_bf16 v[6:9], v[166:169], v[206:209], v[6:9]
	v_mfma_f32_16x16x32_bf16 v[2:5], v[174:177], v[206:209], v[2:5]
	v_mfma_f32_16x16x32_bf16 v[50:53], v[170:173], v[186:189], v[50:53]
	v_mfma_f32_16x16x32_bf16 v[42:45], v[178:181], v[186:189], v[42:45]
	v_mfma_f32_16x16x32_bf16 v[34:37], v[170:173], v[194:197], v[34:37]
	v_mfma_f32_16x16x32_bf16 v[26:29], v[178:181], v[194:197], v[26:29]
	v_mfma_f32_16x16x32_bf16 v[18:21], v[170:173], v[202:205], v[18:21]
	v_mfma_f32_16x16x32_bf16 v[10:13], v[178:181], v[202:205], v[10:13]
	v_mfma_f32_16x16x32_bf16 v[6:9], v[170:173], v[210:213], v[6:9]
	v_mfma_f32_16x16x32_bf16 v[2:5], v[178:181], v[210:213], v[2:5]
	s_setprio 0
	s_barrier
; #define PG8_STAGE(bufoff, gbase, voff) do { _Pragma("unroll") for (int _i = 0; _i < 2; ++_i) \
;         __builtin_amdgcn_global_load_lds((const unsigned*)((const char*)(gbase) + (voff)[_i]), (PG8_LAS unsigned*)(lds + (bufoff) + ldsw + _i * 8192), 16, 0, 0); } while (0)
; #define PG8_LDA(dst, b, h) do { _Pragma("unroll") for (int m = 0; m < 4; ++m) _Pragma("unroll") for (int k = 0; k < 2; ++k) dst[m][k] = *(const PG8_LAS bf16x8*)(lds + PG8_SA(b, h) + aoff + m * 2048 + k * 1024); } while (0)
; #define PG8_LDB(dst, b, h) do { _Pragma("unroll") for (int n = 0; n < 2; ++n) _Pragma("unroll") for (int k = 0; k < 2; ++k) dst[n][k] = *(const PG8_LAS bf16x8*)(lds + PG8_SB(b, h) + boff + n * 2048 + k * 1024); } while (0)
; #define PG8_MMA(ai, bj, At, Bt) do { __builtin_amdgcn_s_setprio(1); _Pragma("unroll") for (int m = 0; m < 4; ++m) _Pragma("unroll") for (int n = 0; n < 2; ++n) _Pragma("unroll") for (int k = 0; k < 2; ++k) \
;         acc[ai][bj][m][n] = __builtin_amdgcn_mfma_f32_16x16x32_bf16(Bt[n][k], At[m][k], acc[ai][bj][m][n], 0, 0, 0); __builtin_amdgcn_s_setprio(0); } while (0)
; #define PG8_WAIT_V(n) asm volatile("s_waitcnt vmcnt(" #n ")" ::: "memory")
; #define PG8_WAIT_L(n) asm volatile("s_waitcnt lgkmcnt(" #n ")" ::: "memory")
; #define PG8_BAR __builtin_amdgcn_s_barrier()
; #define PG8_SCHED __builtin_amdgcn_sched_barrier(0)
; template <class Epi, class Sched, bool ALIGN_EPI = false, bool SP2 = false>
; __device__ __forceinline__ void gemm_phase(PG8_LAS unsigned char* lds, const Gemm g, const Sched& S, const Epi& E) {
;     ...
;             PG8_LDB(B0, 1, 0); PG8_LDB(B1, 1, 1); PG8_SCHED; PG8_LDA(At, 1, 0); PG8_STAGE(PG8_SA(0, 1), a2 + hstep, voffA);
;             PG8_WAIT_V(8); PG8_WAIT_L(0); PG8_BAR; PG8_MMA(0, 0, At, B0); PG8_MMA(0, 1, At, B1); PG8_BAR; PG8_SCHED;
;             PG8_LDA(At, 1, 1); PG8_STAGE(PG8_SB(1, 0), b3, voffB); PG8_STAGE(PG8_SB(1, 1), b3 + hstep, voffB); PG8_STAGE(PG8_SA(1, 0), a3, voffA);
;             PG8_WAIT_V(8); PG8_WAIT_L(0); PG8_BAR; PG8_MMA(1, 0, At, B0); PG8_MMA(1, 1, At, B1); PG8_BAR; PG8_SCHED;
	v_add_u32_e32 v162, s70, v145
	v_add_u32_e32 v178, s69, v145
	ds_read_b128 v[150:153], v162
	ds_read_b128 v[154:157], v162 offset:1024
	ds_read_b128 v[158:161], v162 offset:2048
	ds_read_b128 v[162:165], v162 offset:3072
	ds_read_b128 v[166:169], v178
	ds_read_b128 v[170:173], v178 offset:1024
	ds_read_b128 v[174:177], v178 offset:2048
	ds_read_b128 v[178:181], v178 offset:3072
	s_mov_b32 m0, s52
	v_lshl_add_u64 v[220:221], s[36:37], 0, v[136:137]
	ds_read_b128 v[182:185], v149 offset:32768
	ds_read_b128 v[186:189], v149 offset:33792
	ds_read_b128 v[190:193], v149 offset:34816
	ds_read_b128 v[194:197], v149 offset:35840
	ds_read_b128 v[198:201], v149 offset:36864
	ds_read_b128 v[202:205], v149 offset:37888
	ds_read_b128 v[206:209], v149 offset:38912
	ds_read_b128 v[210:213], v149 offset:39936
	global_load_lds_dwordx4 v[220:221], off
	v_lshl_add_u64 v[220:221], s[36:37], 0, v[132:133]
	s_mov_b32 m0, s53
	s_nop 0
	global_load_lds_dwordx4 v[220:221], off
	s_waitcnt vmcnt(8)
	s_waitcnt lgkmcnt(0)
	s_barrier
	s_setprio 1
	s_waitcnt lgkmcnt(0)
	v_mfma_f32_16x16x32_bf16 v[126:129], v[150:153], v[182:185], v[126:129]
	v_mfma_f32_16x16x32_bf16 v[122:125], v[158:161], v[182:185], v[122:125]
	v_mfma_f32_16x16x32_bf16 v[118:121], v[150:153], v[190:193], v[118:121]
	v_mfma_f32_16x16x32_bf16 v[110:113], v[158:161], v[190:193], v[110:113]
	v_mfma_f32_16x16x32_bf16 v[102:105], v[150:153], v[198:201], v[102:105]
	v_mfma_f32_16x16x32_bf16 v[94:97], v[158:161], v[198:201], v[94:97]
	v_mfma_f32_16x16x32_bf16 v[86:89], v[150:153], v[206:209], v[86:89]
	v_mfma_f32_16x16x32_bf16 v[78:81], v[158:161], v[206:209], v[78:81]
	v_mfma_f32_16x16x32_bf16 v[126:129], v[154:157], v[186:189], v[126:129]
	v_mfma_f32_16x16x32_bf16 v[122:125], v[162:165], v[186:189], v[122:125]
	v_mfma_f32_16x16x32_bf16 v[118:121], v[154:157], v[194:197], v[118:121]
	v_mfma_f32_16x16x32_bf16 v[110:113], v[162:165], v[194:197], v[110:113]
	v_mfma_f32_16x16x32_bf16 v[102:105], v[154:157], v[202:205], v[102:105]
	v_mfma_f32_16x16x32_bf16 v[94:97], v[162:165], v[202:205], v[94:97]
	v_mfma_f32_16x16x32_bf16 v[86:89], v[154:157], v[210:213], v[86:89]
	v_mfma_f32_16x16x32_bf16 v[78:81], v[162:165], v[210:213], v[78:81]
	s_setprio 0
	s_setprio 1
	v_mfma_f32_16x16x32_bf16 v[114:117], v[166:169], v[182:185], v[114:117]
	v_mfma_f32_16x16x32_bf16 v[106:109], v[174:177], v[182:185], v[106:109]
	v_mfma_f32_16x16x32_bf16 v[98:101], v[166:169], v[190:193], v[98:101]
	v_mfma_f32_16x16x32_bf16 v[90:93], v[174:177], v[190:193], v[90:93]
	v_mfma_f32_16x16x32_bf16 v[82:85], v[166:169], v[198:201], v[82:85]
	v_mfma_f32_16x16x32_bf16 v[74:77], v[174:177], v[198:201], v[74:77]
	v_mfma_f32_16x16x32_bf16 v[70:73], v[166:169], v[206:209], v[70:73]
	v_mfma_f32_16x16x32_bf16 v[66:69], v[174:177], v[206:209], v[66:69]
	v_mfma_f32_16x16x32_bf16 v[114:117], v[170:173], v[186:189], v[114:117]
	v_mfma_f32_16x16x32_bf16 v[106:109], v[178:181], v[186:189], v[106:109]
	v_mfma_f32_16x16x32_bf16 v[98:101], v[170:173], v[194:197], v[98:101]
	v_mfma_f32_16x16x32_bf16 v[90:93], v[178:181], v[194:197], v[90:93]
	v_mfma_f32_16x16x32_bf16 v[82:85], v[170:173], v[202:205], v[82:85]
	v_mfma_f32_16x16x32_bf16 v[74:77], v[178:181], v[202:205], v[74:77]
	v_mfma_f32_16x16x32_bf16 v[70:73], v[170:173], v[210:213], v[70:73]
	v_mfma_f32_16x16x32_bf16 v[66:69], v[178:181], v[210:213], v[66:69]
	s_setprio 0
	s_barrier
	s_mov_b32 m0, s68
	v_lshl_add_u64 v[142:143], v[142:143], 0, s[10:11]
	ds_read_b128 v[182:185], v149 offset:49152
	ds_read_b128 v[186:189], v149 offset:50176
	ds_read_b128 v[190:193], v149 offset:51200
	ds_read_b128 v[194:197], v149 offset:52224
	ds_read_b128 v[198:201], v149 offset:53248
	ds_read_b128 v[202:205], v149 offset:54272
	ds_read_b128 v[206:209], v149 offset:55296
	ds_read_b128 v[210:213], v149 offset:56320
	global_load_lds_dwordx4 v[142:143], off
	v_lshl_add_u64 v[142:143], v[214:215], 0, s[10:11]
	s_mov_b32 m0, s66
	s_nop 0
	global_load_lds_dwordx4 v[142:143], off
	v_lshl_add_u64 v[142:143], s[30:31], 0, v[134:135]
	s_mov_b32 m0, s67
	s_nop 0
	global_load_lds_dwordx4 v[142:143], off
	v_lshl_add_u64 v[142:143], s[30:31], 0, v[130:131]
	s_mov_b32 m0, s65
	s_nop 0
	global_load_lds_dwordx4 v[142:143], off
	v_lshl_add_u64 v[142:143], v[216:217], 0, s[10:11]
	s_mov_b32 m0, s55
	s_nop 0
	global_load_lds_dwordx4 v[142:143], off
	v_lshl_add_u64 v[142:143], v[218:219], 0, s[10:11]
	s_mov_b32 m0, s56
	s_nop 0
	global_load_lds_dwordx4 v[142:143], off
	s_waitcnt vmcnt(8)
	s_waitcnt lgkmcnt(0)
	s_barrier
	s_setprio 1
	s_waitcnt lgkmcnt(0)
	v_mfma_f32_16x16x32_bf16 v[62:65], v[150:153], v[182:185], v[62:65]
	v_mfma_f32_16x16x32_bf16 v[58:61], v[158:161], v[182:185], v[58:61]
	v_mfma_f32_16x16x32_bf16 v[54:57], v[150:153], v[190:193], v[54:57]
	v_mfma_f32_16x16x32_bf16 v[46:49], v[158:161], v[190:193], v[46:49]
	v_mfma_f32_16x16x32_bf16 v[38:41], v[150:153], v[198:201], v[38:41]
	v_mfma_f32_16x16x32_bf16 v[30:33], v[158:161], v[198:201], v[30:33]
	v_mfma_f32_16x16x32_bf16 v[22:25], v[150:153], v[206:209], v[22:25]
	v_mfma_f32_16x16x32_bf16 v[14:17], v[158:161], v[206:209], v[14:17]
	v_mfma_f32_16x16x32_bf16 v[62:65], v[154:157], v[186:189], v[62:65]
	v_mfma_f32_16x16x32_bf16 v[58:61], v[162:165], v[186:189], v[58:61]
	v_mfma_f32_16x16x32_bf16 v[54:57], v[154:157], v[194:197], v[54:57]
	v_mfma_f32_16x16x32_bf16 v[46:49], v[162:165], v[194:197], v[46:49]
	v_mfma_f32_16x16x32_bf16 v[38:41], v[154:157], v[202:205], v[38:41]
	v_mfma_f32_16x16x32_bf16 v[30:33], v[162:165], v[202:205], v[30:33]
	v_mfma_f32_16x16x32_bf16 v[22:25], v[154:157], v[210:213], v[22:25]
	v_mfma_f32_16x16x32_bf16 v[14:17], v[162:165], v[210:213], v[14:17]
	s_setprio 0
	s_setprio 1
	v_mfma_f32_16x16x32_bf16 v[50:53], v[166:169], v[182:185], v[50:53]
	v_mfma_f32_16x16x32_bf16 v[42:45], v[174:177], v[182:185], v[42:45]
	v_mfma_f32_16x16x32_bf16 v[34:37], v[166:169], v[190:193], v[34:37]
	v_mfma_f32_16x16x32_bf16 v[26:29], v[174:177], v[190:193], v[26:29]
	v_mfma_f32_16x16x32_bf16 v[18:21], v[166:169], v[198:201], v[18:21]
	v_mfma_f32_16x16x32_bf16 v[10:13], v[174:177], v[198:201], v[10:13]
	v_mfma_f32_16x16x32_bf16 v[6:9], v[166:169], v[206:209], v[6:9]
	v_mfma_f32_16x16x32_bf16 v[2:5], v[174:177], v[206:209], v[2:5]
	v_mfma_f32_16x16x32_bf16 v[50:53], v[170:173], v[186:189], v[50:53]
	v_mfma_f32_16x16x32_bf16 v[42:45], v[178:181], v[186:189], v[42:45]
	v_mfma_f32_16x16x32_bf16 v[34:37], v[170:173], v[194:197], v[34:37]
	v_mfma_f32_16x16x32_bf16 v[26:29], v[178:181], v[194:197], v[26:29]
	v_mfma_f32_16x16x32_bf16 v[18:21], v[170:173], v[202:205], v[18:21]
	v_mfma_f32_16x16x32_bf16 v[10:13], v[178:181], v[202:205], v[10:13]
	v_mfma_f32_16x16x32_bf16 v[6:9], v[170:173], v[210:213], v[6:9]
	v_mfma_f32_16x16x32_bf16 v[2:5], v[178:181], v[210:213], v[2:5]
	s_setprio 0
	s_barrier
	s_movk_i32 s36, 0x100
	s_andn2_b64 vcc, exec, s[28:29]
	s_mov_b64 s[30:31], -1
	s_mov_b64 s[28:29], 0
	s_cbranch_vccz .LBB0_1693

;     __device__ bool next(int i, Unit& u) const { if (!s.next(i, u)) return false; const int p = u.pn; u.pn = p < 56 ? (p % 7) * 8 + p / 7 : p; return true; }
;     __device__ bool next(int i, Unit& u) const { Unit t; if (!s.next(i >> 1, t)) return false; const int pass = i & 1; u.pm = t.pm + pass * (M / BM); u.pn = t.pn + pass * (D / BM); u.kt0 = 0; return true; }
; #define PG8_STAGE(bufoff, gbase, voff) do { _Pragma("unroll") for (int _i = 0; _i < 2; ++_i) \
;         __builtin_amdgcn_global_load_lds((const unsigned*)((const char*)(gbase) + (voff)[_i]), (PG8_LAS unsigned*)(lds + (bufoff) + ldsw + _i * 8192), 16, 0, 0); } while (0)
; #define PG8_WAIT_V(n) asm volatile("s_waitcnt vmcnt(" #n ")" ::: "memory")
; #define PG8_WAIT_L(n) asm volatile("s_waitcnt lgkmcnt(" #n ")" ::: "memory")
; #define PG8_BAR __builtin_amdgcn_s_barrier()
; template <class Epi, class Sched, bool ALIGN_EPI = false, bool SP2 = false>
; __device__ __forceinline__ void gemm_phase(PG8_LAS unsigned char* lds, const Gemm g, const Sched& S, const Epi& E) {
;     ...
;         const bool has_next = S.next(ui + 1, nxt);
;         const char* nA = has_next ? (const char*)g.A + (size_t)nxt.pm * tstep + (size_t)nxt.kt0 * kstep : cA; const char* nB = has_next ? (const char*)g.Bt + (size_t)nxt.pn * tstep + (size_t)nxt.kt0 * kstep : cB;
;         for (int t = 0; t < nt; t += 2) {
;             if constexpr (Epi::MIDHOOK) { if (t == (nt >> 1)) E.mid(acc, cur, wr, wc, fr, fq); }
;             const bool last = (t == nt - 2);
;             const char* a1 = cA + (size_t)(t + 1) * kstep;
;             const char* a2 = last ? nA : cA + (size_t)(t + 2) * kstep; const char* b2 = last ? nB : cB + (size_t)(t + 2) * kstep;
;             const char* a3 = a2 + kstep; const char* b3 = b2 + kstep;
;             if (last && has_next) S.a_ready(nxt);
;             if constexpr (SP2) {
;             PG8_LDB(B0, 0, 0); PG8_LDB(B1, 0, 1); PG8_SCHED; PG8_LDA(At, 0, 0); PG8_STAGE(PG8_SA(1, 1), a1 + hstep, voffA);
;             PG8_WAIT_V(8); PG8_WAIT_L(0); PG8_BAR; PG8_MMA(0, 0, At, B0); PG8_MMA(0, 1, At, B1); PG8_BAR; PG8_SCHED;
;     ...
; #pragma unroll
;         for (int a = 0; a < 2; ++a)
; #pragma unroll
;             for (int b = 0; b < 2; ++b)
; #pragma unroll
;                 for (int m = 0; m < 4; ++m)
; #pragma unroll
;                     for (int n = 0; n < 2; ++n) acc[a][b][m][n] = (f32x4){0.f, 0.f, 0.f, 0.f};
.LBB0_1819:
	s_ashr_i32 s25, s24, 31
	s_lshl_b64 s[26:27], s[24:25], 20
	s_add_u32 s26, s94, s26
	s_addc_u32 s27, s95, s27
	s_and_b64 s[28:29], s[0:1], exec
	s_cselect_b32 s25, s27, s37
	s_cselect_b32 s54, s26, s36
	s_ashr_i32 s23, s22, 31
	s_lshl_b64 s[28:29], s[22:23], 20
	s_add_u32 s28, s33, s28
	s_addc_u32 s29, s50, s29
	s_and_b64 s[40:41], s[0:1], exec
	s_cselect_b32 s23, s29, s39
	s_cselect_b32 s55, s28, s38
	s_add_u32 s36, s36, 0x80080
	s_addc_u32 s37, s37, 0
	s_add_u32 s56, s38, 0x100
	s_addc_u32 s57, s39, 0
	s_mov_b32 s58, -2
	s_waitcnt lgkmcnt(0)
	ds_read_b128 v[146:149], v155
	ds_read_b128 v[158:161], v155 offset:1024
	ds_read_b128 v[162:165], v155 offset:2048
	ds_read_b128 v[166:169], v155 offset:3072
	ds_read_b128 v[170:173], v156
	ds_read_b128 v[174:177], v156 offset:1024
	ds_read_b128 v[178:181], v156 offset:2048
	ds_read_b128 v[182:185], v156 offset:3072
	s_add_u32 s38, s36, 0xfff80080
	s_addc_u32 s39, s37, -1
	s_cmp_eq_u32 s58, 28
	s_cselect_b32 s41, s25, s39
	s_cselect_b32 s40, s54, s38
	s_cselect_b32 s39, s23, s57
	s_cselect_b32 s38, s55, s56
	v_lshl_add_u64 v[150:151], s[36:37], 0, v[138:139]
	s_add_i32 m0, s31, 0xc000
	ds_read_b128 v[186:189], v157
	ds_read_b128 v[190:193], v157 offset:1024
	ds_read_b128 v[194:197], v157 offset:2048
	ds_read_b128 v[198:201], v157 offset:3072
	ds_read_b128 v[202:205], v157 offset:4096
	ds_read_b128 v[206:209], v157 offset:5120
	ds_read_b128 v[210:213], v157 offset:6144
	ds_read_b128 v[214:217], v157 offset:7168
	global_load_lds_dwordx4 v[150:151], off
	v_lshl_add_u64 v[150:151], s[36:37], 0, v[140:141]
	s_add_i32 m0, s31, 0xe000
	s_nop 0
	global_load_lds_dwordx4 v[150:151], off
	s_waitcnt vmcnt(8)
	s_waitcnt lgkmcnt(0)
	s_barrier
	s_setprio 1
	s_waitcnt lgkmcnt(0)
	v_mfma_f32_16x16x32_bf16 v[126:129], v[146:149], v[186:189], 0
	v_mfma_f32_16x16x32_bf16 v[122:125], v[162:165], v[186:189], 0
	v_mfma_f32_16x16x32_bf16 v[110:113], v[146:149], v[194:197], 0
	v_mfma_f32_16x16x32_bf16 v[106:109], v[162:165], v[194:197], 0
	v_mfma_f32_16x16x32_bf16 v[94:97], v[146:149], v[202:205], 0
	v_mfma_f32_16x16x32_bf16 v[90:93], v[162:165], v[202:205], 0
	v_mfma_f32_16x16x32_bf16 v[78:81], v[146:149], v[210:213], 0
	v_mfma_f32_16x16x32_bf16 v[74:77], v[162:165], v[210:213], 0
	v_mfma_f32_16x16x32_bf16 v[126:129], v[158:161], v[190:193], v[126:129]
	v_mfma_f32_16x16x32_bf16 v[122:125], v[166:169], v[190:193], v[122:125]
	v_mfma_f32_16x16x32_bf16 v[110:113], v[158:161], v[198:201], v[110:113]
	v_mfma_f32_16x16x32_bf16 v[106:109], v[166:169], v[198:201], v[106:109]
	v_mfma_f32_16x16x32_bf16 v[94:97], v[158:161], v[206:209], v[94:97]
	v_mfma_f32_16x16x32_bf16 v[90:93], v[166:169], v[206:209], v[90:93]
	v_mfma_f32_16x16x32_bf16 v[78:81], v[158:161], v[214:217], v[78:81]
	v_mfma_f32_16x16x32_bf16 v[74:77], v[166:169], v[214:217], v[74:77]
	s_setprio 0
	s_setprio 1
	v_mfma_f32_16x16x32_bf16 v[118:121], v[170:173], v[186:189], 0
	v_mfma_f32_16x16x32_bf16 v[114:117], v[178:181], v[186:189], 0
	v_mfma_f32_16x16x32_bf16 v[102:105], v[170:173], v[194:197], 0
	v_mfma_f32_16x16x32_bf16 v[98:101], v[178:181], v[194:197], 0
	v_mfma_f32_16x16x32_bf16 v[86:89], v[170:173], v[202:205], 0
	v_mfma_f32_16x16x32_bf16 v[82:85], v[178:181], v[202:205], 0
	v_mfma_f32_16x16x32_bf16 v[70:73], v[170:173], v[210:213], 0
	v_mfma_f32_16x16x32_bf16 v[66:69], v[178:181], v[210:213], 0
	v_mfma_f32_16x16x32_bf16 v[118:121], v[174:177], v[190:193], v[118:121]
	v_mfma_f32_16x16x32_bf16 v[114:117], v[182:185], v[190:193], v[114:117]
	v_mfma_f32_16x16x32_bf16 v[102:105], v[174:177], v[198:201], v[102:105]
	v_mfma_f32_16x16x32_bf16 v[98:101], v[182:185], v[198:201], v[98:101]
	v_mfma_f32_16x16x32_bf16 v[86:89], v[174:177], v[206:209], v[86:89]
	v_mfma_f32_16x16x32_bf16 v[82:85], v[182:185], v[206:209], v[82:85]
	v_mfma_f32_16x16x32_bf16 v[70:73], v[174:177], v[214:217], v[70:73]
	v_mfma_f32_16x16x32_bf16 v[66:69], v[182:185], v[214:217], v[66:69]
	s_setprio 0
	s_barrier
	s_add_i32 s59, s51, s3
	v_lshl_add_u64 v[150:151], s[38:39], 0, v[134:135]
	s_mov_b32 m0, s59
	ds_read_b128 v[186:189], v157 offset:16384
	ds_read_b128 v[190:193], v157 offset:17408
	ds_read_b128 v[194:197], v157 offset:18432
	ds_read_b128 v[198:201], v157 offset:19456
	ds_read_b128 v[202:205], v157 offset:20480
	ds_read_b128 v[206:209], v157 offset:21504
	ds_read_b128 v[210:213], v157 offset:22528
	ds_read_b128 v[214:217], v157 offset:23552
	global_load_lds_dwordx4 v[150:151], off
	s_add_i32 m0, s59, 0x2000
	s_add_u32 s60, s38, 0x80000
	v_lshl_add_u64 v[218:219], s[38:39], 0, v[130:131]
	s_addc_u32 s61, s39, 0
	s_add_i32 s59, s52, s3
	global_load_lds_dwordx4 v[218:219], off
	v_lshl_add_u64 v[220:221], s[60:61], 0, v[134:135]
	s_mov_b32 m0, s59
	v_lshl_add_u64 v[222:223], s[40:41], 0, v[132:133]
	global_load_lds_dwordx4 v[220:221], off
	v_lshl_add_u64 v[220:221], s[60:61], 0, v[130:131]
	s_add_i32 m0, s59, 0x2000
	s_nop 0
	global_load_lds_dwordx4 v[220:221], off
	v_lshl_add_u64 v[220:221], s[40:41], 0, v[136:137]
	s_mov_b32 m0, s31
	s_nop 0
	global_load_lds_dwordx4 v[220:221], off
	s_mov_b32 m0, s43
	s_nop 0
	global_load_lds_dwordx4 v[222:223], off
	s_waitcnt vmcnt(8)
	s_waitcnt lgkmcnt(0)
	s_barrier
; #define PG8_STAGE(bufoff, gbase, voff) do { _Pragma("unroll") for (int _i = 0; _i < 2; ++_i) \
;         __builtin_amdgcn_global_load_lds((const unsigned*)((const char*)(gbase) + (voff)[_i]), (PG8_LAS unsigned*)(lds + (bufoff) + ldsw + _i * 8192), 16, 0, 0); } while (0)
; #define PG8_LDA(dst, b, h) do { _Pragma("unroll") for (int m = 0; m < 4; ++m) _Pragma("unroll") for (int k = 0; k < 2; ++k) dst[m][k] = *(const PG8_LAS bf16x8*)(lds + PG8_SA(b, h) + aoff + m * 2048 + k * 1024); } while (0)
; #define PG8_LDB(dst, b, h) do { _Pragma("unroll") for (int n = 0; n < 2; ++n) _Pragma("unroll") for (int k = 0; k < 2; ++k) dst[n][k] = *(const PG8_LAS bf16x8*)(lds + PG8_SB(b, h) + boff + n * 2048 + k * 1024); } while (0)
; #define PG8_MMA(ai, bj, At, Bt) do { __builtin_amdgcn_s_setprio(1); _Pragma("unroll") for (int m = 0; m < 4; ++m) _Pragma("unroll") for (int n = 0; n < 2; ++n) _Pragma("unroll") for (int k = 0; k < 2; ++k) \
;         acc[ai][bj][m][n] = __builtin_amdgcn_mfma_f32_16x16x32_bf16(Bt[n][k], At[m][k], acc[ai][bj][m][n], 0, 0, 0); __builtin_amdgcn_s_setprio(0); } while (0)
; #define PG8_WAIT_V(n) asm volatile("s_waitcnt vmcnt(" #n ")" ::: "memory")
; #define PG8_WAIT_L(n) asm volatile("s_waitcnt lgkmcnt(" #n ")" ::: "memory")
; #define PG8_BAR __builtin_amdgcn_s_barrier()
; #define PG8_SCHED __builtin_amdgcn_sched_barrier(0)
; template <class Epi, class Sched, bool ALIGN_EPI = false, bool SP2 = false>
; __device__ __forceinline__ void gemm_phase(PG8_LAS unsigned char* lds, const Gemm g, const Sched& S, const Epi& E) {
;     ...
;             PG8_LDA(At, 0, 1); PG8_STAGE(PG8_SB(0, 0), b2, voffB); PG8_STAGE(PG8_SB(0, 1), b2 + hstep, voffB); PG8_STAGE(PG8_SA(0, 0), a2, voffA);
;             PG8_WAIT_V(8); PG8_WAIT_L(0); PG8_BAR; PG8_MMA(1, 0, At, B0); PG8_MMA(1, 1, At, B1); PG8_BAR; PG8_SCHED;
;             PG8_LDB(B0, 1, 0); PG8_LDB(B1, 1, 1); PG8_SCHED; PG8_LDA(At, 1, 0); PG8_STAGE(PG8_SA(0, 1), a2 + hstep, voffA);
;             PG8_WAIT_V(8); PG8_WAIT_L(0); PG8_BAR; PG8_MMA(0, 0, At, B0); PG8_MMA(0, 1, At, B1); PG8_BAR; PG8_SCHED;
	s_setprio 1
	s_waitcnt lgkmcnt(0)
	v_mfma_f32_16x16x32_bf16 v[62:65], v[146:149], v[186:189], 0
	v_mfma_f32_16x16x32_bf16 v[58:61], v[162:165], v[186:189], 0
	v_mfma_f32_16x16x32_bf16 v[46:49], v[146:149], v[194:197], 0
	v_mfma_f32_16x16x32_bf16 v[42:45], v[162:165], v[194:197], 0
	v_mfma_f32_16x16x32_bf16 v[30:33], v[146:149], v[202:205], 0
	v_mfma_f32_16x16x32_bf16 v[26:29], v[162:165], v[202:205], 0
	v_mfma_f32_16x16x32_bf16 v[14:17], v[146:149], v[210:213], 0
	v_mfma_f32_16x16x32_bf16 v[10:13], v[162:165], v[210:213], 0
	v_mfma_f32_16x16x32_bf16 v[62:65], v[158:161], v[190:193], v[62:65]
	v_mfma_f32_16x16x32_bf16 v[58:61], v[166:169], v[190:193], v[58:61]
	v_mfma_f32_16x16x32_bf16 v[46:49], v[158:161], v[198:201], v[46:49]
	v_mfma_f32_16x16x32_bf16 v[42:45], v[166:169], v[198:201], v[42:45]
	v_mfma_f32_16x16x32_bf16 v[30:33], v[158:161], v[206:209], v[30:33]
	v_mfma_f32_16x16x32_bf16 v[26:29], v[166:169], v[206:209], v[26:29]
	v_mfma_f32_16x16x32_bf16 v[14:17], v[158:161], v[214:217], v[14:17]
	v_mfma_f32_16x16x32_bf16 v[10:13], v[166:169], v[214:217], v[10:13]
	s_setprio 0
	s_setprio 1
	v_mfma_f32_16x16x32_bf16 v[54:57], v[170:173], v[186:189], 0
	v_mfma_f32_16x16x32_bf16 v[50:53], v[178:181], v[186:189], 0
	v_mfma_f32_16x16x32_bf16 v[38:41], v[170:173], v[194:197], 0
	v_mfma_f32_16x16x32_bf16 v[34:37], v[178:181], v[194:197], 0
	v_mfma_f32_16x16x32_bf16 v[22:25], v[170:173], v[202:205], 0
	v_mfma_f32_16x16x32_bf16 v[18:21], v[178:181], v[202:205], 0
	v_mfma_f32_16x16x32_bf16 v[6:9], v[170:173], v[210:213], 0
	v_mfma_f32_16x16x32_bf16 v[2:5], v[178:181], v[210:213], 0
	v_mfma_f32_16x16x32_bf16 v[54:57], v[174:177], v[190:193], v[54:57]
	v_mfma_f32_16x16x32_bf16 v[50:53], v[182:185], v[190:193], v[50:53]
	v_mfma_f32_16x16x32_bf16 v[38:41], v[174:177], v[198:201], v[38:41]
	v_mfma_f32_16x16x32_bf16 v[34:37], v[182:185], v[198:201], v[34:37]
	v_mfma_f32_16x16x32_bf16 v[22:25], v[174:177], v[206:209], v[22:25]
	v_mfma_f32_16x16x32_bf16 v[18:21], v[182:185], v[206:209], v[18:21]
	v_mfma_f32_16x16x32_bf16 v[6:9], v[174:177], v[214:217], v[6:9]
	v_mfma_f32_16x16x32_bf16 v[2:5], v[182:185], v[214:217], v[2:5]
	s_setprio 0
	s_barrier
	s_add_i32 s59, 0, 0x18000
	s_add_i32 s60, 0, 0x1c000
	v_add_u32_e32 v166, s59, v153
	v_add_u32_e32 v182, s60, v153
	ds_read_b128 v[146:149], v166
	ds_read_b128 v[158:161], v166 offset:1024
	ds_read_b128 v[162:165], v166 offset:2048
	ds_read_b128 v[166:169], v166 offset:3072
	ds_read_b128 v[170:173], v182
	ds_read_b128 v[174:177], v182 offset:1024
	ds_read_b128 v[178:181], v182 offset:2048
	ds_read_b128 v[182:185], v182 offset:3072
	s_add_u32 s40, s40, 0x80000
	s_addc_u32 s41, s41, 0
	s_mov_b32 m0, s44
	v_lshl_add_u64 v[224:225], s[40:41], 0, v[136:137]
	ds_read_b128 v[186:189], v157 offset:32768
	ds_read_b128 v[190:193], v157 offset:33792
	ds_read_b128 v[194:197], v157 offset:34816
	ds_read_b128 v[198:201], v157 offset:35840
	ds_read_b128 v[202:205], v157 offset:36864
	ds_read_b128 v[206:209], v157 offset:37888
	ds_read_b128 v[210:213], v157 offset:38912
	ds_read_b128 v[214:217], v157 offset:39936
	global_load_lds_dwordx4 v[224:225], off
	v_lshl_add_u64 v[224:225], s[40:41], 0, v[132:133]
	s_mov_b32 m0, s45
	s_nop 0
	global_load_lds_dwordx4 v[224:225], off
	s_waitcnt vmcnt(8)
	s_waitcnt lgkmcnt(0)
	s_barrier
	s_setprio 1
	s_waitcnt lgkmcnt(0)
	v_mfma_f32_16x16x32_bf16 v[126:129], v[146:149], v[186:189], v[126:129]
	v_mfma_f32_16x16x32_bf16 v[122:125], v[162:165], v[186:189], v[122:125]
	v_mfma_f32_16x16x32_bf16 v[110:113], v[146:149], v[194:197], v[110:113]
	v_mfma_f32_16x16x32_bf16 v[106:109], v[162:165], v[194:197], v[106:109]
	v_mfma_f32_16x16x32_bf16 v[94:97], v[146:149], v[202:205], v[94:97]
	v_mfma_f32_16x16x32_bf16 v[90:93], v[162:165], v[202:205], v[90:93]
	v_mfma_f32_16x16x32_bf16 v[78:81], v[146:149], v[210:213], v[78:81]
	v_mfma_f32_16x16x32_bf16 v[74:77], v[162:165], v[210:213], v[74:77]
	v_mfma_f32_16x16x32_bf16 v[126:129], v[158:161], v[190:193], v[126:129]
	v_mfma_f32_16x16x32_bf16 v[122:125], v[166:169], v[190:193], v[122:125]
	v_mfma_f32_16x16x32_bf16 v[110:113], v[158:161], v[198:201], v[110:113]
	v_mfma_f32_16x16x32_bf16 v[106:109], v[166:169], v[198:201], v[106:109]
	v_mfma_f32_16x16x32_bf16 v[94:97], v[158:161], v[206:209], v[94:97]
	v_mfma_f32_16x16x32_bf16 v[90:93], v[166:169], v[206:209], v[90:93]
	v_mfma_f32_16x16x32_bf16 v[78:81], v[158:161], v[214:217], v[78:81]
	v_mfma_f32_16x16x32_bf16 v[74:77], v[166:169], v[214:217], v[74:77]
	s_setprio 0
	s_setprio 1
	v_mfma_f32_16x16x32_bf16 v[118:121], v[170:173], v[186:189], v[118:121]
	v_mfma_f32_16x16x32_bf16 v[114:117], v[178:181], v[186:189], v[114:117]
	v_mfma_f32_16x16x32_bf16 v[102:105], v[170:173], v[194:197], v[102:105]
	v_mfma_f32_16x16x32_bf16 v[98:101], v[178:181], v[194:197], v[98:101]
	v_mfma_f32_16x16x32_bf16 v[86:89], v[170:173], v[202:205], v[86:89]
	v_mfma_f32_16x16x32_bf16 v[82:85], v[178:181], v[202:205], v[82:85]
	v_mfma_f32_16x16x32_bf16 v[70:73], v[170:173], v[210:213], v[70:73]
	v_mfma_f32_16x16x32_bf16 v[66:69], v[178:181], v[210:213], v[66:69]
	v_mfma_f32_16x16x32_bf16 v[118:121], v[174:177], v[190:193], v[118:121]
	v_mfma_f32_16x16x32_bf16 v[114:117], v[182:185], v[190:193], v[114:117]
	v_mfma_f32_16x16x32_bf16 v[102:105], v[174:177], v[198:201], v[102:105]
	v_mfma_f32_16x16x32_bf16 v[98:101], v[182:185], v[198:201], v[98:101]
	v_mfma_f32_16x16x32_bf16 v[86:89], v[174:177], v[206:209], v[86:89]
	v_mfma_f32_16x16x32_bf16 v[82:85], v[182:185], v[206:209], v[82:85]
	v_mfma_f32_16x16x32_bf16 v[70:73], v[174:177], v[214:217], v[70:73]
	v_mfma_f32_16x16x32_bf16 v[66:69], v[182:185], v[214:217], v[66:69]
	s_setprio 0
	s_barrier
; #define PG8_STAGE(bufoff, gbase, voff) do { _Pragma("unroll") for (int _i = 0; _i < 2; ++_i) \
;         __builtin_amdgcn_global_load_lds((const unsigned*)((const char*)(gbase) + (voff)[_i]), (PG8_LAS unsigned*)(lds + (bufoff) + ldsw + _i * 8192), 16, 0, 0); } while (0)
; #define PG8_LDA(dst, b, h) do { _Pragma("unroll") for (int m = 0; m < 4; ++m) _Pragma("unroll") for (int k = 0; k < 2; ++k) dst[m][k] = *(const PG8_LAS bf16x8*)(lds + PG8_SA(b, h) + aoff + m * 2048 + k * 1024); } while (0)
; #define PG8_MMA(ai, bj, At, Bt) do { __builtin_amdgcn_s_setprio(1); _Pragma("unroll") for (int m = 0; m < 4; ++m) _Pragma("unroll") for (int n = 0; n < 2; ++n) _Pragma("unroll") for (int k = 0; k < 2; ++k) \
;         acc[ai][bj][m][n] = __builtin_amdgcn_mfma_f32_16x16x32_bf16(Bt[n][k], At[m][k], acc[ai][bj][m][n], 0, 0, 0); __builtin_amdgcn_s_setprio(0); } while (0)
; #define PG8_WAIT_V(n) asm volatile("s_waitcnt vmcnt(" #n ")" ::: "memory")
; #define PG8_WAIT_L(n) asm volatile("s_waitcnt lgkmcnt(" #n ")" ::: "memory")
; #define PG8_BAR __builtin_amdgcn_s_barrier()
; #define PG8_SCHED __builtin_amdgcn_sched_barrier(0)
; template <class Epi, class Sched, bool ALIGN_EPI = false, bool SP2 = false>
; __device__ __forceinline__ void gemm_phase(PG8_LAS unsigned char* lds, const Gemm g, const Sched& S, const Epi& E) {
;     ...
;         for (int t = 0; t < nt; t += 2) {
;             if constexpr (Epi::MIDHOOK) { if (t == (nt >> 1)) E.mid(acc, cur, wr, wc, fr, fq); }
;             const bool last = (t == nt - 2);
;             const char* a1 = cA + (size_t)(t + 1) * kstep;
;             const char* a2 = last ? nA : cA + (size_t)(t + 2) * kstep; const char* b2 = last ? nB : cB + (size_t)(t + 2) * kstep;
;             const char* a3 = a2 + kstep; const char* b3 = b2 + kstep;
;     ...
;             PG8_LDA(At, 1, 1); PG8_STAGE(PG8_SB(1, 0), b3, voffB); PG8_STAGE(PG8_SB(1, 1), b3 + hstep, voffB); PG8_STAGE(PG8_SA(1, 0), a3, voffA);
;             PG8_WAIT_V(8); PG8_WAIT_L(0); PG8_BAR; PG8_MMA(1, 0, At, B0); PG8_MMA(1, 1, At, B1); PG8_BAR; PG8_SCHED;
	s_add_i32 s40, s59, s3
	v_lshl_add_u64 v[150:151], v[150:151], 0, s[12:13]
	s_mov_b32 m0, s40
	ds_read_b128 v[186:189], v157 offset:49152
	ds_read_b128 v[190:193], v157 offset:50176
	ds_read_b128 v[194:197], v157 offset:51200
	ds_read_b128 v[198:201], v157 offset:52224
	ds_read_b128 v[202:205], v157 offset:53248
	ds_read_b128 v[206:209], v157 offset:54272
	ds_read_b128 v[210:213], v157 offset:55296
	ds_read_b128 v[214:217], v157 offset:56320
	global_load_lds_dwordx4 v[150:151], off
	s_add_i32 m0, s40, 0x2000
	s_add_u32 s38, s38, 0x80080
	v_lshl_add_u64 v[150:151], v[218:219], 0, s[12:13]
	s_addc_u32 s39, s39, 0
	s_add_i32 s40, s60, s3
	global_load_lds_dwordx4 v[150:151], off
	v_lshl_add_u64 v[150:151], s[38:39], 0, v[134:135]
	s_mov_b32 m0, s40
	s_nop 0
	global_load_lds_dwordx4 v[150:151], off
	v_lshl_add_u64 v[150:151], s[38:39], 0, v[130:131]
	s_add_i32 m0, s40, 0x2000
	s_nop 0
	global_load_lds_dwordx4 v[150:151], off
	v_lshl_add_u64 v[150:151], v[220:221], 0, s[12:13]
	s_mov_b32 m0, s48
	s_nop 0
	global_load_lds_dwordx4 v[150:151], off
	v_lshl_add_u64 v[150:151], v[222:223], 0, s[12:13]
	s_mov_b32 m0, s49
	s_nop 0
	global_load_lds_dwordx4 v[150:151], off
	s_waitcnt vmcnt(8)
	s_waitcnt lgkmcnt(0)
	s_barrier
	s_setprio 1
	s_waitcnt lgkmcnt(0)
	v_mfma_f32_16x16x32_bf16 v[62:65], v[146:149], v[186:189], v[62:65]
	v_mfma_f32_16x16x32_bf16 v[58:61], v[162:165], v[186:189], v[58:61]
	v_mfma_f32_16x16x32_bf16 v[46:49], v[146:149], v[194:197], v[46:49]
	v_mfma_f32_16x16x32_bf16 v[42:45], v[162:165], v[194:197], v[42:45]
	v_mfma_f32_16x16x32_bf16 v[30:33], v[146:149], v[202:205], v[30:33]
	v_mfma_f32_16x16x32_bf16 v[26:29], v[162:165], v[202:205], v[26:29]
	v_mfma_f32_16x16x32_bf16 v[14:17], v[146:149], v[210:213], v[14:17]
	v_mfma_f32_16x16x32_bf16 v[10:13], v[162:165], v[210:213], v[10:13]
	v_mfma_f32_16x16x32_bf16 v[62:65], v[158:161], v[190:193], v[62:65]
	v_mfma_f32_16x16x32_bf16 v[58:61], v[166:169], v[190:193], v[58:61]
	v_mfma_f32_16x16x32_bf16 v[46:49], v[158:161], v[198:201], v[46:49]
	v_mfma_f32_16x16x32_bf16 v[42:45], v[166:169], v[198:201], v[42:45]
	v_mfma_f32_16x16x32_bf16 v[30:33], v[158:161], v[206:209], v[30:33]
	v_mfma_f32_16x16x32_bf16 v[26:29], v[166:169], v[206:209], v[26:29]
	v_mfma_f32_16x16x32_bf16 v[14:17], v[158:161], v[214:217], v[14:17]
	v_mfma_f32_16x16x32_bf16 v[10:13], v[166:169], v[214:217], v[10:13]
	s_setprio 0
	s_setprio 1
	v_mfma_f32_16x16x32_bf16 v[54:57], v[170:173], v[186:189], v[54:57]
	v_mfma_f32_16x16x32_bf16 v[50:53], v[178:181], v[186:189], v[50:53]
	v_mfma_f32_16x16x32_bf16 v[38:41], v[170:173], v[194:197], v[38:41]
	v_mfma_f32_16x16x32_bf16 v[34:37], v[178:181], v[194:197], v[34:37]
	v_mfma_f32_16x16x32_bf16 v[22:25], v[170:173], v[202:205], v[22:25]
	v_mfma_f32_16x16x32_bf16 v[18:21], v[178:181], v[202:205], v[18:21]
	v_mfma_f32_16x16x32_bf16 v[6:9], v[170:173], v[210:213], v[6:9]
	v_mfma_f32_16x16x32_bf16 v[2:5], v[178:181], v[210:213], v[2:5]
	v_mfma_f32_16x16x32_bf16 v[54:57], v[174:177], v[190:193], v[54:57]
	v_mfma_f32_16x16x32_bf16 v[50:53], v[182:185], v[190:193], v[50:53]
	v_mfma_f32_16x16x32_bf16 v[38:41], v[174:177], v[198:201], v[38:41]
	v_mfma_f32_16x16x32_bf16 v[34:37], v[182:185], v[198:201], v[34:37]
	v_mfma_f32_16x16x32_bf16 v[22:25], v[174:177], v[206:209], v[22:25]
	v_mfma_f32_16x16x32_bf16 v[18:21], v[182:185], v[206:209], v[18:21]
	v_mfma_f32_16x16x32_bf16 v[6:9], v[174:177], v[214:217], v[6:9]
	v_mfma_f32_16x16x32_bf16 v[2:5], v[182:185], v[214:217], v[2:5]
	s_setprio 0
	s_barrier
	s_add_i32 s58, s58, 2
	s_add_u32 s36, s36, 0x100
	s_addc_u32 s37, s37, 0
	s_add_u32 s56, s56, 0x100
	s_addc_u32 s57, s57, 0
	s_cmp_gt_u32 s58, 29
	s_cbranch_scc1 .Lkx_1820
.LBB0_1820:
	ds_read_b128 v[146:149], v155
	ds_read_b128 v[158:161], v155 offset:1024
	ds_read_b128 v[162:165], v155 offset:2048
	ds_read_b128 v[166:169], v155 offset:3072
	ds_read_b128 v[170:173], v156
	ds_read_b128 v[174:177], v156 offset:1024
	ds_read_b128 v[178:181], v156 offset:2048
	ds_read_b128 v[182:185], v156 offset:3072
	s_add_u32 s38, s36, 0xfff80080
	s_addc_u32 s39, s37, -1
	s_cmp_eq_u32 s58, 28
	s_cselect_b32 s41, s25, s39
	s_cselect_b32 s40, s54, s38
	s_cselect_b32 s39, s23, s57
	s_cselect_b32 s38, s55, s56
	v_lshl_add_u64 v[150:151], s[36:37], 0, v[138:139]
	s_add_i32 m0, s31, 0xc000
	ds_read_b128 v[186:189], v157
	ds_read_b128 v[190:193], v157 offset:1024
	ds_read_b128 v[194:197], v157 offset:2048
	ds_read_b128 v[198:201], v157 offset:3072
	ds_read_b128 v[202:205], v157 offset:4096
	ds_read_b128 v[206:209], v157 offset:5120
	ds_read_b128 v[210:213], v157 offset:6144
	ds_read_b128 v[214:217], v157 offset:7168
	global_load_lds_dwordx4 v[150:151], off
	v_lshl_add_u64 v[150:151], s[36:37], 0, v[140:141]
	s_add_i32 m0, s31, 0xe000
	s_nop 0
	global_load_lds_dwordx4 v[150:151], off
	s_waitcnt vmcnt(8)
	s_waitcnt lgkmcnt(0)
	s_barrier
; #define PG8_STAGE(bufoff, gbase, voff) do { _Pragma("unroll") for (int _i = 0; _i < 2; ++_i) \
;         __builtin_amdgcn_global_load_lds((const unsigned*)((const char*)(gbase) + (voff)[_i]), (PG8_LAS unsigned*)(lds + (bufoff) + ldsw + _i * 8192), 16, 0, 0); } while (0)
; #define PG8_LDA(dst, b, h) do { _Pragma("unroll") for (int m = 0; m < 4; ++m) _Pragma("unroll") for (int k = 0; k < 2; ++k) dst[m][k] = *(const PG8_LAS bf16x8*)(lds + PG8_SA(b, h) + aoff + m * 2048 + k * 1024); } while (0)
; #define PG8_LDB(dst, b, h) do { _Pragma("unroll") for (int n = 0; n < 2; ++n) _Pragma("unroll") for (int k = 0; k < 2; ++k) dst[n][k] = *(const PG8_LAS bf16x8*)(lds + PG8_SB(b, h) + boff + n * 2048 + k * 1024); } while (0)
; #define PG8_MMA(ai, bj, At, Bt) do { __builtin_amdgcn_s_setprio(1); _Pragma("unroll") for (int m = 0; m < 4; ++m) _Pragma("unroll") for (int n = 0; n < 2; ++n) _Pragma("unroll") for (int k = 0; k < 2; ++k) \
;         acc[ai][bj][m][n] = __builtin_amdgcn_mfma_f32_16x16x32_bf16(Bt[n][k], At[m][k], acc[ai][bj][m][n], 0, 0, 0); __builtin_amdgcn_s_setprio(0); } while (0)
; #define PG8_WAIT_V(n) asm volatile("s_waitcnt vmcnt(" #n ")" ::: "memory")
; #define PG8_WAIT_L(n) asm volatile("s_waitcnt lgkmcnt(" #n ")" ::: "memory")
; #define PG8_BAR __builtin_amdgcn_s_barrier()
; #define PG8_SCHED __builtin_amdgcn_sched_barrier(0)
; template <class Epi, class Sched, bool ALIGN_EPI = false, bool SP2 = false>
; __device__ __forceinline__ void gemm_phase(PG8_LAS unsigned char* lds, const Gemm g, const Sched& S, const Epi& E) {
;     ...
;             PG8_LDB(B0, 0, 0); PG8_LDB(B1, 0, 1); PG8_SCHED; PG8_LDA(At, 0, 0); PG8_STAGE(PG8_SA(1, 1), a1 + hstep, voffA);
;             PG8_WAIT_V(8); PG8_WAIT_L(0); PG8_BAR; PG8_MMA(0, 0, At, B0); PG8_MMA(0, 1, At, B1); PG8_BAR; PG8_SCHED;
;             PG8_LDA(At, 0, 1); PG8_STAGE(PG8_SB(0, 0), b2, voffB); PG8_STAGE(PG8_SB(0, 1), b2 + hstep, voffB); PG8_STAGE(PG8_SA(0, 0), a2, voffA);
;             PG8_WAIT_V(8); PG8_WAIT_L(0); PG8_BAR; PG8_MMA(1, 0, At, B0); PG8_MMA(1, 1, At, B1); PG8_BAR; PG8_SCHED;
	s_setprio 1
	s_waitcnt lgkmcnt(0)
	v_mfma_f32_16x16x32_bf16 v[126:129], v[146:149], v[186:189], v[126:129]
	v_mfma_f32_16x16x32_bf16 v[122:125], v[162:165], v[186:189], v[122:125]
	v_mfma_f32_16x16x32_bf16 v[110:113], v[146:149], v[194:197], v[110:113]
	v_mfma_f32_16x16x32_bf16 v[106:109], v[162:165], v[194:197], v[106:109]
	v_mfma_f32_16x16x32_bf16 v[94:97], v[146:149], v[202:205], v[94:97]
	v_mfma_f32_16x16x32_bf16 v[90:93], v[162:165], v[202:205], v[90:93]
	v_mfma_f32_16x16x32_bf16 v[78:81], v[146:149], v[210:213], v[78:81]
	v_mfma_f32_16x16x32_bf16 v[74:77], v[162:165], v[210:213], v[74:77]
	v_mfma_f32_16x16x32_bf16 v[126:129], v[158:161], v[190:193], v[126:129]
	v_mfma_f32_16x16x32_bf16 v[122:125], v[166:169], v[190:193], v[122:125]
	v_mfma_f32_16x16x32_bf16 v[110:113], v[158:161], v[198:201], v[110:113]
	v_mfma_f32_16x16x32_bf16 v[106:109], v[166:169], v[198:201], v[106:109]
	v_mfma_f32_16x16x32_bf16 v[94:97], v[158:161], v[206:209], v[94:97]
	v_mfma_f32_16x16x32_bf16 v[90:93], v[166:169], v[206:209], v[90:93]
	v_mfma_f32_16x16x32_bf16 v[78:81], v[158:161], v[214:217], v[78:81]
	v_mfma_f32_16x16x32_bf16 v[74:77], v[166:169], v[214:217], v[74:77]
	s_setprio 0
	s_setprio 1
	v_mfma_f32_16x16x32_bf16 v[118:121], v[170:173], v[186:189], v[118:121]
	v_mfma_f32_16x16x32_bf16 v[114:117], v[178:181], v[186:189], v[114:117]
	v_mfma_f32_16x16x32_bf16 v[102:105], v[170:173], v[194:197], v[102:105]
	v_mfma_f32_16x16x32_bf16 v[98:101], v[178:181], v[194:197], v[98:101]
	v_mfma_f32_16x16x32_bf16 v[86:89], v[170:173], v[202:205], v[86:89]
	v_mfma_f32_16x16x32_bf16 v[82:85], v[178:181], v[202:205], v[82:85]
	v_mfma_f32_16x16x32_bf16 v[70:73], v[170:173], v[210:213], v[70:73]
	v_mfma_f32_16x16x32_bf16 v[66:69], v[178:181], v[210:213], v[66:69]
	v_mfma_f32_16x16x32_bf16 v[118:121], v[174:177], v[190:193], v[118:121]
	v_mfma_f32_16x16x32_bf16 v[114:117], v[182:185], v[190:193], v[114:117]
	v_mfma_f32_16x16x32_bf16 v[102:105], v[174:177], v[198:201], v[102:105]
	v_mfma_f32_16x16x32_bf16 v[98:101], v[182:185], v[198:201], v[98:101]
	v_mfma_f32_16x16x32_bf16 v[86:89], v[174:177], v[206:209], v[86:89]
	v_mfma_f32_16x16x32_bf16 v[82:85], v[182:185], v[206:209], v[82:85]
	v_mfma_f32_16x16x32_bf16 v[70:73], v[174:177], v[214:217], v[70:73]
	v_mfma_f32_16x16x32_bf16 v[66:69], v[182:185], v[214:217], v[66:69]
	s_setprio 0
	s_barrier
	s_add_i32 s59, s51, s3
	v_lshl_add_u64 v[150:151], s[38:39], 0, v[134:135]
	s_mov_b32 m0, s59
	ds_read_b128 v[186:189], v157 offset:16384
	ds_read_b128 v[190:193], v157 offset:17408
	ds_read_b128 v[194:197], v157 offset:18432
	ds_read_b128 v[198:201], v157 offset:19456
	ds_read_b128 v[202:205], v157 offset:20480
	ds_read_b128 v[206:209], v157 offset:21504
	ds_read_b128 v[210:213], v157 offset:22528
	ds_read_b128 v[214:217], v157 offset:23552
	global_load_lds_dwordx4 v[150:151], off
	s_add_i32 m0, s59, 0x2000
	s_add_u32 s60, s38, 0x80000
	v_lshl_add_u64 v[218:219], s[38:39], 0, v[130:131]
	s_addc_u32 s61, s39, 0
	s_add_i32 s59, s52, s3
	global_load_lds_dwordx4 v[218:219], off
	v_lshl_add_u64 v[220:221], s[60:61], 0, v[134:135]
	s_mov_b32 m0, s59
	v_lshl_add_u64 v[222:223], s[40:41], 0, v[132:133]
	global_load_lds_dwordx4 v[220:221], off
	v_lshl_add_u64 v[220:221], s[60:61], 0, v[130:131]
	s_add_i32 m0, s59, 0x2000
	s_nop 0
	global_load_lds_dwordx4 v[220:221], off
	v_lshl_add_u64 v[220:221], s[40:41], 0, v[136:137]
	s_mov_b32 m0, s31
	s_nop 0
	global_load_lds_dwordx4 v[220:221], off
	s_mov_b32 m0, s43
	s_nop 0
	global_load_lds_dwordx4 v[222:223], off
	s_waitcnt vmcnt(8)
	s_waitcnt lgkmcnt(0)
	s_barrier
	s_setprio 1
	s_waitcnt lgkmcnt(0)
	v_mfma_f32_16x16x32_bf16 v[62:65], v[146:149], v[186:189], v[62:65]
	v_mfma_f32_16x16x32_bf16 v[58:61], v[162:165], v[186:189], v[58:61]
	v_mfma_f32_16x16x32_bf16 v[46:49], v[146:149], v[194:197], v[46:49]
	v_mfma_f32_16x16x32_bf16 v[42:45], v[162:165], v[194:197], v[42:45]
	v_mfma_f32_16x16x32_bf16 v[30:33], v[146:149], v[202:205], v[30:33]
	v_mfma_f32_16x16x32_bf16 v[26:29], v[162:165], v[202:205], v[26:29]
	v_mfma_f32_16x16x32_bf16 v[14:17], v[146:149], v[210:213], v[14:17]
	v_mfma_f32_16x16x32_bf16 v[10:13], v[162:165], v[210:213], v[10:13]
	v_mfma_f32_16x16x32_bf16 v[62:65], v[158:161], v[190:193], v[62:65]
	v_mfma_f32_16x16x32_bf16 v[58:61], v[166:169], v[190:193], v[58:61]
	v_mfma_f32_16x16x32_bf16 v[46:49], v[158:161], v[198:201], v[46:49]
	v_mfma_f32_16x16x32_bf16 v[42:45], v[166:169], v[198:201], v[42:45]
	v_mfma_f32_16x16x32_bf16 v[30:33], v[158:161], v[206:209], v[30:33]
	v_mfma_f32_16x16x32_bf16 v[26:29], v[166:169], v[206:209], v[26:29]
	v_mfma_f32_16x16x32_bf16 v[14:17], v[158:161], v[214:217], v[14:17]
	v_mfma_f32_16x16x32_bf16 v[10:13], v[166:169], v[214:217], v[10:13]
	s_setprio 0
	s_setprio 1
	v_mfma_f32_16x16x32_bf16 v[54:57], v[170:173], v[186:189], v[54:57]
	v_mfma_f32_16x16x32_bf16 v[50:53], v[178:181], v[186:189], v[50:53]
	v_mfma_f32_16x16x32_bf16 v[38:41], v[170:173], v[194:197], v[38:41]
	v_mfma_f32_16x16x32_bf16 v[34:37], v[178:181], v[194:197], v[34:37]
	v_mfma_f32_16x16x32_bf16 v[22:25], v[170:173], v[202:205], v[22:25]
	v_mfma_f32_16x16x32_bf16 v[18:21], v[178:181], v[202:205], v[18:21]
	v_mfma_f32_16x16x32_bf16 v[6:9], v[170:173], v[210:213], v[6:9]
	v_mfma_f32_16x16x32_bf16 v[2:5], v[178:181], v[210:213], v[2:5]
	v_mfma_f32_16x16x32_bf16 v[54:57], v[174:177], v[190:193], v[54:57]
	v_mfma_f32_16x16x32_bf16 v[50:53], v[182:185], v[190:193], v[50:53]
	v_mfma_f32_16x16x32_bf16 v[38:41], v[174:177], v[198:201], v[38:41]
	v_mfma_f32_16x16x32_bf16 v[34:37], v[182:185], v[198:201], v[34:37]
	v_mfma_f32_16x16x32_bf16 v[22:25], v[174:177], v[206:209], v[22:25]
	v_mfma_f32_16x16x32_bf16 v[18:21], v[182:185], v[206:209], v[18:21]
	v_mfma_f32_16x16x32_bf16 v[6:9], v[174:177], v[214:217], v[6:9]
	v_mfma_f32_16x16x32_bf16 v[2:5], v[182:185], v[214:217], v[2:5]
	s_setprio 0
	s_barrier
; #define PG8_STAGE(bufoff, gbase, voff) do { _Pragma("unroll") for (int _i = 0; _i < 2; ++_i) \
;         __builtin_amdgcn_global_load_lds((const unsigned*)((const char*)(gbase) + (voff)[_i]), (PG8_LAS unsigned*)(lds + (bufoff) + ldsw + _i * 8192), 16, 0, 0); } while (0)
; #define PG8_LDA(dst, b, h) do { _Pragma("unroll") for (int m = 0; m < 4; ++m) _Pragma("unroll") for (int k = 0; k < 2; ++k) dst[m][k] = *(const PG8_LAS bf16x8*)(lds + PG8_SA(b, h) + aoff + m * 2048 + k * 1024); } while (0)
; #define PG8_LDB(dst, b, h) do { _Pragma("unroll") for (int n = 0; n < 2; ++n) _Pragma("unroll") for (int k = 0; k < 2; ++k) dst[n][k] = *(const PG8_LAS bf16x8*)(lds + PG8_SB(b, h) + boff + n * 2048 + k * 1024); } while (0)
; #define PG8_MMA(ai, bj, At, Bt) do { __builtin_amdgcn_s_setprio(1); _Pragma("unroll") for (int m = 0; m < 4; ++m) _Pragma("unroll") for (int n = 0; n < 2; ++n) _Pragma("unroll") for (int k = 0; k < 2; ++k) \
;         acc[ai][bj][m][n] = __builtin_amdgcn_mfma_f32_16x16x32_bf16(Bt[n][k], At[m][k], acc[ai][bj][m][n], 0, 0, 0); __builtin_amdgcn_s_setprio(0); } while (0)
; #define PG8_WAIT_V(n) asm volatile("s_waitcnt vmcnt(" #n ")" ::: "memory")
; #define PG8_WAIT_L(n) asm volatile("s_waitcnt lgkmcnt(" #n ")" ::: "memory")
; #define PG8_BAR __builtin_amdgcn_s_barrier()
; #define PG8_SCHED __builtin_amdgcn_sched_barrier(0)
; template <class Epi, class Sched, bool ALIGN_EPI = false, bool SP2 = false>
; __device__ __forceinline__ void gemm_phase(PG8_LAS unsigned char* lds, const Gemm g, const Sched& S, const Epi& E) {
;     ...
;             PG8_LDB(B0, 1, 0); PG8_LDB(B1, 1, 1); PG8_SCHED; PG8_LDA(At, 1, 0); PG8_STAGE(PG8_SA(0, 1), a2 + hstep, voffA);
;             PG8_WAIT_V(8); PG8_WAIT_L(0); PG8_BAR; PG8_MMA(0, 0, At, B0); PG8_MMA(0, 1, At, B1); PG8_BAR; PG8_SCHED;
	s_add_i32 s59, 0, 0x18000
	s_add_i32 s60, 0, 0x1c000
	v_add_u32_e32 v166, s59, v153
	v_add_u32_e32 v182, s60, v153
	ds_read_b128 v[146:149], v166
	ds_read_b128 v[158:161], v166 offset:1024
	ds_read_b128 v[162:165], v166 offset:2048
	ds_read_b128 v[166:169], v166 offset:3072
	ds_read_b128 v[170:173], v182
	ds_read_b128 v[174:177], v182 offset:1024
	ds_read_b128 v[178:181], v182 offset:2048
	ds_read_b128 v[182:185], v182 offset:3072
	s_add_u32 s40, s40, 0x80000
	s_addc_u32 s41, s41, 0
	s_mov_b32 m0, s44
	v_lshl_add_u64 v[224:225], s[40:41], 0, v[136:137]
	ds_read_b128 v[186:189], v157 offset:32768
	ds_read_b128 v[190:193], v157 offset:33792
	ds_read_b128 v[194:197], v157 offset:34816
	ds_read_b128 v[198:201], v157 offset:35840
	ds_read_b128 v[202:205], v157 offset:36864
	ds_read_b128 v[206:209], v157 offset:37888
	ds_read_b128 v[210:213], v157 offset:38912
	ds_read_b128 v[214:217], v157 offset:39936
	global_load_lds_dwordx4 v[224:225], off
	v_lshl_add_u64 v[224:225], s[40:41], 0, v[132:133]
	s_mov_b32 m0, s45
	s_nop 0
	global_load_lds_dwordx4 v[224:225], off
	s_waitcnt vmcnt(8)
	s_waitcnt lgkmcnt(0)
	s_barrier
	s_setprio 1
	s_waitcnt lgkmcnt(0)
	v_mfma_f32_16x16x32_bf16 v[126:129], v[146:149], v[186:189], v[126:129]
	v_mfma_f32_16x16x32_bf16 v[122:125], v[162:165], v[186:189], v[122:125]
	v_mfma_f32_16x16x32_bf16 v[110:113], v[146:149], v[194:197], v[110:113]
	v_mfma_f32_16x16x32_bf16 v[106:109], v[162:165], v[194:197], v[106:109]
	v_mfma_f32_16x16x32_bf16 v[94:97], v[146:149], v[202:205], v[94:97]
	v_mfma_f32_16x16x32_bf16 v[90:93], v[162:165], v[202:205], v[90:93]
	v_mfma_f32_16x16x32_bf16 v[78:81], v[146:149], v[210:213], v[78:81]
	v_mfma_f32_16x16x32_bf16 v[74:77], v[162:165], v[210:213], v[74:77]
	v_mfma_f32_16x16x32_bf16 v[126:129], v[158:161], v[190:193], v[126:129]
	v_mfma_f32_16x16x32_bf16 v[122:125], v[166:169], v[190:193], v[122:125]
	v_mfma_f32_16x16x32_bf16 v[110:113], v[158:161], v[198:201], v[110:113]
	v_mfma_f32_16x16x32_bf16 v[106:109], v[166:169], v[198:201], v[106:109]
	v_mfma_f32_16x16x32_bf16 v[94:97], v[158:161], v[206:209], v[94:97]
	v_mfma_f32_16x16x32_bf16 v[90:93], v[166:169], v[206:209], v[90:93]
	v_mfma_f32_16x16x32_bf16 v[78:81], v[158:161], v[214:217], v[78:81]
	v_mfma_f32_16x16x32_bf16 v[74:77], v[166:169], v[214:217], v[74:77]
	s_setprio 0
	s_setprio 1
	v_mfma_f32_16x16x32_bf16 v[118:121], v[170:173], v[186:189], v[118:121]
	v_mfma_f32_16x16x32_bf16 v[114:117], v[178:181], v[186:189], v[114:117]
	v_mfma_f32_16x16x32_bf16 v[102:105], v[170:173], v[194:197], v[102:105]
	v_mfma_f32_16x16x32_bf16 v[98:101], v[178:181], v[194:197], v[98:101]
	v_mfma_f32_16x16x32_bf16 v[86:89], v[170:173], v[202:205], v[86:89]
	v_mfma_f32_16x16x32_bf16 v[82:85], v[178:181], v[202:205], v[82:85]
	v_mfma_f32_16x16x32_bf16 v[70:73], v[170:173], v[210:213], v[70:73]
	v_mfma_f32_16x16x32_bf16 v[66:69], v[178:181], v[210:213], v[66:69]
	v_mfma_f32_16x16x32_bf16 v[118:121], v[174:177], v[190:193], v[118:121]
	v_mfma_f32_16x16x32_bf16 v[114:117], v[182:185], v[190:193], v[114:117]
	v_mfma_f32_16x16x32_bf16 v[102:105], v[174:177], v[198:201], v[102:105]
	v_mfma_f32_16x16x32_bf16 v[98:101], v[182:185], v[198:201], v[98:101]
	v_mfma_f32_16x16x32_bf16 v[86:89], v[174:177], v[206:209], v[86:89]
	v_mfma_f32_16x16x32_bf16 v[82:85], v[182:185], v[206:209], v[82:85]
	v_mfma_f32_16x16x32_bf16 v[70:73], v[174:177], v[214:217], v[70:73]
	v_mfma_f32_16x16x32_bf16 v[66:69], v[182:185], v[214:217], v[66:69]
	s_setprio 0
	s_barrier
; #define PG8_STAGE(bufoff, gbase, voff) do { _Pragma("unroll") for (int _i = 0; _i < 2; ++_i) \
;         __builtin_amdgcn_global_load_lds((const unsigned*)((const char*)(gbase) + (voff)[_i]), (PG8_LAS unsigned*)(lds + (bufoff) + ldsw + _i * 8192), 16, 0, 0); } while (0)
; #define PG8_LDA(dst, b, h) do { _Pragma("unroll") for (int m = 0; m < 4; ++m) _Pragma("unroll") for (int k = 0; k < 2; ++k) dst[m][k] = *(const PG8_LAS bf16x8*)(lds + PG8_SA(b, h) + aoff + m * 2048 + k * 1024); } while (0)
; #define PG8_MMA(ai, bj, At, Bt) do { __builtin_amdgcn_s_setprio(1); _Pragma("unroll") for (int m = 0; m < 4; ++m) _Pragma("unroll") for (int n = 0; n < 2; ++n) _Pragma("unroll") for (int k = 0; k < 2; ++k) \
;         acc[ai][bj][m][n] = __builtin_amdgcn_mfma_f32_16x16x32_bf16(Bt[n][k], At[m][k], acc[ai][bj][m][n], 0, 0, 0); __builtin_amdgcn_s_setprio(0); } while (0)
; #define PG8_WAIT_V(n) asm volatile("s_waitcnt vmcnt(" #n ")" ::: "memory")
; #define PG8_WAIT_L(n) asm volatile("s_waitcnt lgkmcnt(" #n ")" ::: "memory")
; #define PG8_BAR __builtin_amdgcn_s_barrier()
; #define PG8_SCHED __builtin_amdgcn_sched_barrier(0)
; template <class Epi, class Sched, bool ALIGN_EPI = false, bool SP2 = false>
; __device__ __forceinline__ void gemm_phase(PG8_LAS unsigned char* lds, const Gemm g, const Sched& S, const Epi& E) {
;     ...
;         for (int t = 0; t < nt; t += 2) {
;             if constexpr (Epi::MIDHOOK) { if (t == (nt >> 1)) E.mid(acc, cur, wr, wc, fr, fq); }
;             const bool last = (t == nt - 2);
;             const char* a1 = cA + (size_t)(t + 1) * kstep;
;             const char* a2 = last ? nA : cA + (size_t)(t + 2) * kstep; const char* b2 = last ? nB : cB + (size_t)(t + 2) * kstep;
;             const char* a3 = a2 + kstep; const char* b3 = b2 + kstep;
;     ...
;             PG8_LDA(At, 1, 1); PG8_STAGE(PG8_SB(1, 0), b3, voffB); PG8_STAGE(PG8_SB(1, 1), b3 + hstep, voffB); PG8_STAGE(PG8_SA(1, 0), a3, voffA);
;             PG8_WAIT_V(8); PG8_WAIT_L(0); PG8_BAR; PG8_MMA(1, 0, At, B0); PG8_MMA(1, 1, At, B1); PG8_BAR; PG8_SCHED;
	s_add_i32 s40, s59, s3
	v_lshl_add_u64 v[150:151], v[150:151], 0, s[12:13]
	s_mov_b32 m0, s40
	ds_read_b128 v[186:189], v157 offset:49152
	ds_read_b128 v[190:193], v157 offset:50176
	ds_read_b128 v[194:197], v157 offset:51200
	ds_read_b128 v[198:201], v157 offset:52224
	ds_read_b128 v[202:205], v157 offset:53248
	ds_read_b128 v[206:209], v157 offset:54272
	ds_read_b128 v[210:213], v157 offset:55296
	ds_read_b128 v[214:217], v157 offset:56320
	global_load_lds_dwordx4 v[150:151], off
	s_add_i32 m0, s40, 0x2000
	s_add_u32 s38, s38, 0x80080
	v_lshl_add_u64 v[150:151], v[218:219], 0, s[12:13]
	s_addc_u32 s39, s39, 0
	s_add_i32 s40, s60, s3
	global_load_lds_dwordx4 v[150:151], off
	v_lshl_add_u64 v[150:151], s[38:39], 0, v[134:135]
	s_mov_b32 m0, s40
	s_nop 0
	global_load_lds_dwordx4 v[150:151], off
	v_lshl_add_u64 v[150:151], s[38:39], 0, v[130:131]
	s_add_i32 m0, s40, 0x2000
	s_nop 0
	global_load_lds_dwordx4 v[150:151], off
	v_lshl_add_u64 v[150:151], v[220:221], 0, s[12:13]
	s_mov_b32 m0, s48
	s_nop 0
	global_load_lds_dwordx4 v[150:151], off
	v_lshl_add_u64 v[150:151], v[222:223], 0, s[12:13]
	s_mov_b32 m0, s49
	s_nop 0
	global_load_lds_dwordx4 v[150:151], off
	s_waitcnt vmcnt(8)
	s_waitcnt lgkmcnt(0)
	s_barrier
	s_setprio 1
	s_waitcnt lgkmcnt(0)
	v_mfma_f32_16x16x32_bf16 v[62:65], v[146:149], v[186:189], v[62:65]
	v_mfma_f32_16x16x32_bf16 v[58:61], v[162:165], v[186:189], v[58:61]
	v_mfma_f32_16x16x32_bf16 v[46:49], v[146:149], v[194:197], v[46:49]
	v_mfma_f32_16x16x32_bf16 v[42:45], v[162:165], v[194:197], v[42:45]
	v_mfma_f32_16x16x32_bf16 v[30:33], v[146:149], v[202:205], v[30:33]
	v_mfma_f32_16x16x32_bf16 v[26:29], v[162:165], v[202:205], v[26:29]
	v_mfma_f32_16x16x32_bf16 v[14:17], v[146:149], v[210:213], v[14:17]
	v_mfma_f32_16x16x32_bf16 v[10:13], v[162:165], v[210:213], v[10:13]
	v_mfma_f32_16x16x32_bf16 v[62:65], v[158:161], v[190:193], v[62:65]
	v_mfma_f32_16x16x32_bf16 v[58:61], v[166:169], v[190:193], v[58:61]
	v_mfma_f32_16x16x32_bf16 v[46:49], v[158:161], v[198:201], v[46:49]
	v_mfma_f32_16x16x32_bf16 v[42:45], v[166:169], v[198:201], v[42:45]
	v_mfma_f32_16x16x32_bf16 v[30:33], v[158:161], v[206:209], v[30:33]
	v_mfma_f32_16x16x32_bf16 v[26:29], v[166:169], v[206:209], v[26:29]
	v_mfma_f32_16x16x32_bf16 v[14:17], v[158:161], v[214:217], v[14:17]
	v_mfma_f32_16x16x32_bf16 v[10:13], v[166:169], v[214:217], v[10:13]
	s_setprio 0
	s_setprio 1
	v_mfma_f32_16x16x32_bf16 v[54:57], v[170:173], v[186:189], v[54:57]
	v_mfma_f32_16x16x32_bf16 v[50:53], v[178:181], v[186:189], v[50:53]
	v_mfma_f32_16x16x32_bf16 v[38:41], v[170:173], v[194:197], v[38:41]
	v_mfma_f32_16x16x32_bf16 v[34:37], v[178:181], v[194:197], v[34:37]
	v_mfma_f32_16x16x32_bf16 v[22:25], v[170:173], v[202:205], v[22:25]
	v_mfma_f32_16x16x32_bf16 v[18:21], v[178:181], v[202:205], v[18:21]
	v_mfma_f32_16x16x32_bf16 v[6:9], v[170:173], v[210:213], v[6:9]
	v_mfma_f32_16x16x32_bf16 v[2:5], v[178:181], v[210:213], v[2:5]
	v_mfma_f32_16x16x32_bf16 v[54:57], v[174:177], v[190:193], v[54:57]
	v_mfma_f32_16x16x32_bf16 v[50:53], v[182:185], v[190:193], v[50:53]
	v_mfma_f32_16x16x32_bf16 v[38:41], v[174:177], v[198:201], v[38:41]
	v_mfma_f32_16x16x32_bf16 v[34:37], v[182:185], v[198:201], v[34:37]
	v_mfma_f32_16x16x32_bf16 v[22:25], v[174:177], v[206:209], v[22:25]
	v_mfma_f32_16x16x32_bf16 v[18:21], v[182:185], v[206:209], v[18:21]
	v_mfma_f32_16x16x32_bf16 v[6:9], v[174:177], v[214:217], v[6:9]
	v_mfma_f32_16x16x32_bf16 v[2:5], v[182:185], v[214:217], v[2:5]
	s_setprio 0
	s_barrier
	s_add_i32 s58, s58, 2
	s_add_u32 s36, s36, 0x100
	s_addc_u32 s37, s37, 0
	s_add_u32 s56, s56, 0x100
	s_addc_u32 s57, s57, 0
	s_cmp_gt_u32 s58, 29
	s_cbranch_scc0 .LBB0_1820

;     __device__ bool next(int i, Unit& u) const { if (!s.next(i, u)) return false; const int p = u.pn; u.pn = p < 56 ? (p % 7) * 8 + p / 7 : p; return true; }
;     __device__ bool next(int i, Unit& u) const { Unit t; if (!s.next(i >> 1, t)) return false; const int pass = i & 1; u.pm = t.pm + pass * (M / BM); u.pn = t.pn + pass * (D / BM); u.kt0 = 0; return true; }
; #define PG8_STAGE(bufoff, gbase, voff) do { _Pragma("unroll") for (int _i = 0; _i < 2; ++_i) \
;         __builtin_amdgcn_global_load_lds((const unsigned*)((const char*)(gbase) + (voff)[_i]), (PG8_LAS unsigned*)(lds + (bufoff) + ldsw + _i * 8192), 16, 0, 0); } while (0)
; #define PG8_WAIT_V(n) asm volatile("s_waitcnt vmcnt(" #n ")" ::: "memory")
; #define PG8_WAIT_L(n) asm volatile("s_waitcnt lgkmcnt(" #n ")" ::: "memory")
; #define PG8_BAR __builtin_amdgcn_s_barrier()
; template <class Epi, class Sched, bool ALIGN_EPI = false, bool SP2 = false>
; __device__ __forceinline__ void gemm_phase(PG8_LAS unsigned char* lds, const Gemm g, const Sched& S, const Epi& E) {
;     ...
;         const bool has_next = S.next(ui + 1, nxt);
;         const char* nA = has_next ? (const char*)g.A + (size_t)nxt.pm * tstep + (size_t)nxt.kt0 * kstep : cA; const char* nB = has_next ? (const char*)g.Bt + (size_t)nxt.pn * tstep + (size_t)nxt.kt0 * kstep : cB;
;         for (int t = 0; t < nt; t += 2) {
;             if constexpr (Epi::MIDHOOK) { if (t == (nt >> 1)) E.mid(acc, cur, wr, wc, fr, fq); }
;             const bool last = (t == nt - 2);
;             const char* a1 = cA + (size_t)(t + 1) * kstep;
;             const char* a2 = last ? nA : cA + (size_t)(t + 2) * kstep; const char* b2 = last ? nB : cB + (size_t)(t + 2) * kstep;
;             const char* a3 = a2 + kstep; const char* b3 = b2 + kstep;
;             if (last && has_next) S.a_ready(nxt);
;             if constexpr (SP2) {
;             PG8_LDB(B0, 0, 0); PG8_LDB(B1, 0, 1); PG8_SCHED; PG8_LDA(At, 0, 0); PG8_STAGE(PG8_SA(1, 1), a1 + hstep, voffA);
;             PG8_WAIT_V(8); PG8_WAIT_L(0); PG8_BAR; PG8_MMA(0, 0, At, B0); PG8_MMA(0, 1, At, B1); PG8_BAR; PG8_SCHED;
;     ...
; #pragma unroll
;         for (int a = 0; a < 2; ++a)
; #pragma unroll
;             for (int b = 0; b < 2; ++b)
; #pragma unroll
;                 for (int m = 0; m < 4; ++m)
; #pragma unroll
;                     for (int n = 0; n < 2; ++n) acc[a][b][m][n] = (f32x4){0.f, 0.f, 0.f, 0.f};
.LBB0_1839:
	s_mov_b32 s3, 0
	s_mov_b64 s[36:37], -1
	s_mov_b64 s[38:39], 0
	s_waitcnt lgkmcnt(0)
	s_add_u32 s25, s12, s3
	s_addc_u32 s27, s13, 0
	s_add_u32 s42, s25, 0x100
	s_addc_u32 s43, s27, 0
	s_and_b64 s[40:41], s[38:39], exec
	s_cselect_b32 s43, s29, s43
	s_cselect_b32 s42, s28, s42
	s_add_u32 s3, s8, s3
	s_addc_u32 s40, s9, 0
	s_add_u32 s3, s3, 0x100
	s_addc_u32 s40, s40, 0
	s_and_b64 s[38:39], s[38:39], exec
	s_cselect_b32 s45, s31, s40
	s_cselect_b32 s44, s30, s3
	s_add_u32 s48, s25, 0x80080
	ds_read_b128 v[140:143], v137
	ds_read_b128 v[144:147], v137 offset:1024
	ds_read_b128 v[148:151], v137 offset:2048
	ds_read_b128 v[152:155], v137 offset:3072
	ds_read_b128 v[156:159], v138
	ds_read_b128 v[160:163], v138 offset:1024
	ds_read_b128 v[164:167], v138 offset:2048
	ds_read_b128 v[168:171], v138 offset:3072
	s_addc_u32 s49, s27, 0
	s_add_i32 s74, s63, s51
	s_add_i32 m0, s54, 0xc000
	s_add_i32 s77, s54, 0xe000
	s_add_i32 s71, s74, 0x2000
	s_add_u32 s46, s44, 0x80000
	s_addc_u32 s47, s45, 0
	s_add_i32 s73, s64, s51
	s_add_i32 s72, s73, 0x2000
	s_add_i32 s70, 0, 0x18000
	s_add_i32 s27, 0, 0x1c000
	s_add_u32 s40, s42, 0x80000
	s_addc_u32 s41, s43, 0
	s_add_i32 s25, s70, s51
	s_add_i32 s3, s25, 0x2000
	s_add_u32 s38, s44, 0x80080
	s_addc_u32 s39, s45, 0
	s_add_i32 s76, s27, s51
	s_add_i32 s75, s76, 0x2000
	v_lshl_add_u64 v[204:205], s[48:49], 0, v[132:133]
	ds_read_b128 v[172:175], v139
	ds_read_b128 v[176:179], v139 offset:1024
	ds_read_b128 v[180:183], v139 offset:2048
	ds_read_b128 v[184:187], v139 offset:3072
	ds_read_b128 v[188:191], v139 offset:4096
	ds_read_b128 v[192:195], v139 offset:5120
	ds_read_b128 v[196:199], v139 offset:6144
	ds_read_b128 v[200:203], v139 offset:7168
	global_load_lds_dwordx4 v[204:205], off
	v_lshl_add_u64 v[204:205], s[48:49], 0, v[130:131]
	s_mov_b32 m0, s77
	s_nop 0
	global_load_lds_dwordx4 v[204:205], off
	s_waitcnt vmcnt(8)
	s_waitcnt lgkmcnt(0)
	s_barrier
	s_setprio 1
	s_waitcnt lgkmcnt(0)
	v_mfma_f32_16x16x32_bf16 v[126:129], v[140:143], v[172:175], 0
	v_mfma_f32_16x16x32_bf16 v[122:125], v[148:151], v[172:175], 0
	v_mfma_f32_16x16x32_bf16 v[118:121], v[140:143], v[180:183], 0
	v_mfma_f32_16x16x32_bf16 v[114:117], v[148:151], v[180:183], 0
	v_mfma_f32_16x16x32_bf16 v[106:109], v[140:143], v[188:191], 0
	v_mfma_f32_16x16x32_bf16 v[98:101], v[148:151], v[188:191], 0
	v_mfma_f32_16x16x32_bf16 v[90:93], v[140:143], v[196:199], 0
	v_mfma_f32_16x16x32_bf16 v[82:85], v[148:151], v[196:199], 0
	v_mfma_f32_16x16x32_bf16 v[126:129], v[144:147], v[176:179], v[126:129]
	v_mfma_f32_16x16x32_bf16 v[122:125], v[152:155], v[176:179], v[122:125]
	v_mfma_f32_16x16x32_bf16 v[118:121], v[144:147], v[184:187], v[118:121]
	v_mfma_f32_16x16x32_bf16 v[114:117], v[152:155], v[184:187], v[114:117]
	v_mfma_f32_16x16x32_bf16 v[106:109], v[144:147], v[192:195], v[106:109]
	v_mfma_f32_16x16x32_bf16 v[98:101], v[152:155], v[192:195], v[98:101]
	v_mfma_f32_16x16x32_bf16 v[90:93], v[144:147], v[200:203], v[90:93]
	v_mfma_f32_16x16x32_bf16 v[82:85], v[152:155], v[200:203], v[82:85]
	s_setprio 0
	s_setprio 1
	v_mfma_f32_16x16x32_bf16 v[110:113], v[156:159], v[172:175], 0
	v_mfma_f32_16x16x32_bf16 v[102:105], v[164:167], v[172:175], 0
	v_mfma_f32_16x16x32_bf16 v[94:97], v[156:159], v[180:183], 0
	v_mfma_f32_16x16x32_bf16 v[86:89], v[164:167], v[180:183], 0
	v_mfma_f32_16x16x32_bf16 v[78:81], v[156:159], v[188:191], 0
	v_mfma_f32_16x16x32_bf16 v[74:77], v[164:167], v[188:191], 0
	v_mfma_f32_16x16x32_bf16 v[70:73], v[156:159], v[196:199], 0
	v_mfma_f32_16x16x32_bf16 v[66:69], v[164:167], v[196:199], 0
	v_mfma_f32_16x16x32_bf16 v[110:113], v[160:163], v[176:179], v[110:113]
	v_mfma_f32_16x16x32_bf16 v[102:105], v[168:171], v[176:179], v[102:105]
	v_mfma_f32_16x16x32_bf16 v[94:97], v[160:163], v[184:187], v[94:97]
	v_mfma_f32_16x16x32_bf16 v[86:89], v[168:171], v[184:187], v[86:89]
	v_mfma_f32_16x16x32_bf16 v[78:81], v[160:163], v[192:195], v[78:81]
	v_mfma_f32_16x16x32_bf16 v[74:77], v[168:171], v[192:195], v[74:77]
	v_mfma_f32_16x16x32_bf16 v[70:73], v[160:163], v[200:203], v[70:73]
	v_mfma_f32_16x16x32_bf16 v[66:69], v[168:171], v[200:203], v[66:69]
	s_setprio 0
	s_barrier
	s_mov_b32 m0, s74
	v_lshl_add_u64 v[204:205], s[44:45], 0, v[132:133]
	ds_read_b128 v[172:175], v139 offset:16384
	ds_read_b128 v[176:179], v139 offset:17408
	ds_read_b128 v[180:183], v139 offset:18432
	ds_read_b128 v[184:187], v139 offset:19456
	ds_read_b128 v[188:191], v139 offset:20480
	ds_read_b128 v[192:195], v139 offset:21504
	ds_read_b128 v[196:199], v139 offset:22528
	ds_read_b128 v[200:203], v139 offset:23552
	global_load_lds_dwordx4 v[204:205], off
	v_lshl_add_u64 v[206:207], s[44:45], 0, v[130:131]
	s_mov_b32 m0, s71
	v_lshl_add_u64 v[208:209], s[46:47], 0, v[132:133]
	global_load_lds_dwordx4 v[206:207], off
	s_mov_b32 m0, s73
	v_lshl_add_u64 v[210:211], s[42:43], 0, v[130:131]
	global_load_lds_dwordx4 v[208:209], off
	v_lshl_add_u64 v[208:209], s[46:47], 0, v[130:131]
	s_mov_b32 m0, s72
	s_nop 0
	global_load_lds_dwordx4 v[208:209], off
	v_lshl_add_u64 v[208:209], s[42:43], 0, v[132:133]
	s_mov_b32 m0, s54
	s_nop 0
	global_load_lds_dwordx4 v[208:209], off
	s_mov_b32 m0, s55
	s_nop 0
	global_load_lds_dwordx4 v[210:211], off
	s_waitcnt vmcnt(8)
	s_waitcnt lgkmcnt(0)
	s_barrier
; #define PG8_STAGE(bufoff, gbase, voff) do { _Pragma("unroll") for (int _i = 0; _i < 2; ++_i) \
;         __builtin_amdgcn_global_load_lds((const unsigned*)((const char*)(gbase) + (voff)[_i]), (PG8_LAS unsigned*)(lds + (bufoff) + ldsw + _i * 8192), 16, 0, 0); } while (0)
; #define PG8_LDA(dst, b, h) do { _Pragma("unroll") for (int m = 0; m < 4; ++m) _Pragma("unroll") for (int k = 0; k < 2; ++k) dst[m][k] = *(const PG8_LAS bf16x8*)(lds + PG8_SA(b, h) + aoff + m * 2048 + k * 1024); } while (0)
; #define PG8_LDB(dst, b, h) do { _Pragma("unroll") for (int n = 0; n < 2; ++n) _Pragma("unroll") for (int k = 0; k < 2; ++k) dst[n][k] = *(const PG8_LAS bf16x8*)(lds + PG8_SB(b, h) + boff + n * 2048 + k * 1024); } while (0)
; #define PG8_MMA(ai, bj, At, Bt) do { __builtin_amdgcn_s_setprio(1); _Pragma("unroll") for (int m = 0; m < 4; ++m) _Pragma("unroll") for (int n = 0; n < 2; ++n) _Pragma("unroll") for (int k = 0; k < 2; ++k) \
;         acc[ai][bj][m][n] = __builtin_amdgcn_mfma_f32_16x16x32_bf16(Bt[n][k], At[m][k], acc[ai][bj][m][n], 0, 0, 0); __builtin_amdgcn_s_setprio(0); } while (0)
; #define PG8_WAIT_V(n) asm volatile("s_waitcnt vmcnt(" #n ")" ::: "memory")
; template <class Epi, class Sched, bool ALIGN_EPI = false, bool SP2 = false>
; __device__ __forceinline__ void gemm_phase(PG8_LAS unsigned char* lds, const Gemm g, const Sched& S, const Epi& E) {
;     ...
;             PG8_LDB(B0, 0, 0); PG8_LDB(B1, 0, 1); PG8_SCHED; PG8_LDA(At, 0, 0); PG8_STAGE(PG8_SA(1, 1), a1 + hstep, voffA);
;             PG8_WAIT_V(8); PG8_WAIT_L(0); PG8_BAR; PG8_MMA(0, 0, At, B0); PG8_MMA(0, 1, At, B1); PG8_BAR; PG8_SCHED;
;             PG8_LDA(At, 0, 1); PG8_STAGE(PG8_SB(0, 0), b2, voffB); PG8_STAGE(PG8_SB(0, 1), b2 + hstep, voffB); PG8_STAGE(PG8_SA(0, 0), a2, voffA);
;             PG8_WAIT_V(8); PG8_WAIT_L(0); PG8_BAR; PG8_MMA(1, 0, At, B0); PG8_MMA(1, 1, At, B1); PG8_BAR; PG8_SCHED;
;             PG8_LDB(B0, 1, 0); PG8_LDB(B1, 1, 1); PG8_SCHED; PG8_LDA(At, 1, 0); PG8_STAGE(PG8_SA(0, 1), a2 + hstep, voffA);
;             PG8_WAIT_V(8); PG8_WAIT_L(0); PG8_BAR; PG8_MMA(0, 0, At, B0); PG8_MMA(0, 1, At, B1); PG8_BAR; PG8_SCHED;
;             PG8_LDA(At, 1, 1); PG8_STAGE(PG8_SB(1, 0), b3, voffB); PG8_STAGE(PG8_SB(1, 1), b3 + hstep, voffB); PG8_STAGE(PG8_SA(1, 0), a3, voffA);
;             PG8_WAIT_V(8); PG8_WAIT_L(0); PG8_BAR; PG8_MMA(1, 0, At, B0); PG8_MMA(1, 1, At, B1); PG8_BAR; PG8_SCHED;
	s_setprio 1
	s_waitcnt lgkmcnt(0)
	v_mfma_f32_16x16x32_bf16 v[62:65], v[140:143], v[172:175], 0
	v_mfma_f32_16x16x32_bf16 v[58:61], v[148:151], v[172:175], 0
	v_mfma_f32_16x16x32_bf16 v[54:57], v[140:143], v[180:183], 0
	v_mfma_f32_16x16x32_bf16 v[50:53], v[148:151], v[180:183], 0
	v_mfma_f32_16x16x32_bf16 v[42:45], v[140:143], v[188:191], 0
	v_mfma_f32_16x16x32_bf16 v[34:37], v[148:151], v[188:191], 0
	v_mfma_f32_16x16x32_bf16 v[26:29], v[140:143], v[196:199], 0
	v_mfma_f32_16x16x32_bf16 v[18:21], v[148:151], v[196:199], 0
	v_mfma_f32_16x16x32_bf16 v[62:65], v[144:147], v[176:179], v[62:65]
	v_mfma_f32_16x16x32_bf16 v[58:61], v[152:155], v[176:179], v[58:61]
	v_mfma_f32_16x16x32_bf16 v[54:57], v[144:147], v[184:187], v[54:57]
	v_mfma_f32_16x16x32_bf16 v[50:53], v[152:155], v[184:187], v[50:53]
	v_mfma_f32_16x16x32_bf16 v[42:45], v[144:147], v[192:195], v[42:45]
	v_mfma_f32_16x16x32_bf16 v[34:37], v[152:155], v[192:195], v[34:37]
	v_mfma_f32_16x16x32_bf16 v[26:29], v[144:147], v[200:203], v[26:29]
	v_mfma_f32_16x16x32_bf16 v[18:21], v[152:155], v[200:203], v[18:21]
	s_setprio 0
	s_setprio 1
	v_mfma_f32_16x16x32_bf16 v[46:49], v[156:159], v[172:175], 0
	v_mfma_f32_16x16x32_bf16 v[38:41], v[164:167], v[172:175], 0
	v_mfma_f32_16x16x32_bf16 v[30:33], v[156:159], v[180:183], 0
	v_mfma_f32_16x16x32_bf16 v[22:25], v[164:167], v[180:183], 0
	v_mfma_f32_16x16x32_bf16 v[14:17], v[156:159], v[188:191], 0
	v_mfma_f32_16x16x32_bf16 v[10:13], v[164:167], v[188:191], 0
	v_mfma_f32_16x16x32_bf16 v[6:9], v[156:159], v[196:199], 0
	v_mfma_f32_16x16x32_bf16 v[2:5], v[164:167], v[196:199], 0
	v_mfma_f32_16x16x32_bf16 v[46:49], v[160:163], v[176:179], v[46:49]
	v_mfma_f32_16x16x32_bf16 v[38:41], v[168:171], v[176:179], v[38:41]
	v_mfma_f32_16x16x32_bf16 v[30:33], v[160:163], v[184:187], v[30:33]
	v_mfma_f32_16x16x32_bf16 v[22:25], v[168:171], v[184:187], v[22:25]
	v_mfma_f32_16x16x32_bf16 v[14:17], v[160:163], v[192:195], v[14:17]
	v_mfma_f32_16x16x32_bf16 v[10:13], v[168:171], v[192:195], v[10:13]
	v_mfma_f32_16x16x32_bf16 v[6:9], v[160:163], v[200:203], v[6:9]
	v_mfma_f32_16x16x32_bf16 v[2:5], v[168:171], v[200:203], v[2:5]
	s_setprio 0
	s_barrier
	v_add_u32_e32 v152, s70, v134
	v_add_u32_e32 v168, s27, v134
	ds_read_b128 v[140:143], v152
	ds_read_b128 v[144:147], v152 offset:1024
	ds_read_b128 v[148:151], v152 offset:2048
	ds_read_b128 v[152:155], v152 offset:3072
	ds_read_b128 v[156:159], v168
	ds_read_b128 v[160:163], v168 offset:1024
	ds_read_b128 v[164:167], v168 offset:2048
	ds_read_b128 v[168:171], v168 offset:3072
	s_mov_b32 m0, s56
	v_lshl_add_u64 v[212:213], s[40:41], 0, v[132:133]
	ds_read_b128 v[172:175], v139 offset:32768
	ds_read_b128 v[176:179], v139 offset:33792
	ds_read_b128 v[180:183], v139 offset:34816
	ds_read_b128 v[184:187], v139 offset:35840
	ds_read_b128 v[188:191], v139 offset:36864
	ds_read_b128 v[192:195], v139 offset:37888
	ds_read_b128 v[196:199], v139 offset:38912
	ds_read_b128 v[200:203], v139 offset:39936
	global_load_lds_dwordx4 v[212:213], off
	v_lshl_add_u64 v[212:213], s[40:41], 0, v[130:131]
	s_mov_b32 m0, s57
	s_nop 0
	global_load_lds_dwordx4 v[212:213], off
	s_waitcnt vmcnt(8)
	s_waitcnt lgkmcnt(0)
	s_barrier
	s_setprio 1
	s_waitcnt lgkmcnt(0)
	v_mfma_f32_16x16x32_bf16 v[126:129], v[140:143], v[172:175], v[126:129]
	v_mfma_f32_16x16x32_bf16 v[122:125], v[148:151], v[172:175], v[122:125]
	v_mfma_f32_16x16x32_bf16 v[118:121], v[140:143], v[180:183], v[118:121]
	v_mfma_f32_16x16x32_bf16 v[114:117], v[148:151], v[180:183], v[114:117]
	v_mfma_f32_16x16x32_bf16 v[106:109], v[140:143], v[188:191], v[106:109]
	v_mfma_f32_16x16x32_bf16 v[98:101], v[148:151], v[188:191], v[98:101]
	v_mfma_f32_16x16x32_bf16 v[90:93], v[140:143], v[196:199], v[90:93]
	v_mfma_f32_16x16x32_bf16 v[82:85], v[148:151], v[196:199], v[82:85]
	v_mfma_f32_16x16x32_bf16 v[126:129], v[144:147], v[176:179], v[126:129]
	v_mfma_f32_16x16x32_bf16 v[122:125], v[152:155], v[176:179], v[122:125]
	v_mfma_f32_16x16x32_bf16 v[118:121], v[144:147], v[184:187], v[118:121]
	v_mfma_f32_16x16x32_bf16 v[114:117], v[152:155], v[184:187], v[114:117]
	v_mfma_f32_16x16x32_bf16 v[106:109], v[144:147], v[192:195], v[106:109]
	v_mfma_f32_16x16x32_bf16 v[98:101], v[152:155], v[192:195], v[98:101]
	v_mfma_f32_16x16x32_bf16 v[90:93], v[144:147], v[200:203], v[90:93]
	v_mfma_f32_16x16x32_bf16 v[82:85], v[152:155], v[200:203], v[82:85]
	s_setprio 0
	s_setprio 1
	v_mfma_f32_16x16x32_bf16 v[110:113], v[156:159], v[172:175], v[110:113]
	v_mfma_f32_16x16x32_bf16 v[102:105], v[164:167], v[172:175], v[102:105]
	v_mfma_f32_16x16x32_bf16 v[94:97], v[156:159], v[180:183], v[94:97]
	v_mfma_f32_16x16x32_bf16 v[86:89], v[164:167], v[180:183], v[86:89]
	v_mfma_f32_16x16x32_bf16 v[78:81], v[156:159], v[188:191], v[78:81]
	v_mfma_f32_16x16x32_bf16 v[74:77], v[164:167], v[188:191], v[74:77]
	v_mfma_f32_16x16x32_bf16 v[70:73], v[156:159], v[196:199], v[70:73]
	v_mfma_f32_16x16x32_bf16 v[66:69], v[164:167], v[196:199], v[66:69]
	v_mfma_f32_16x16x32_bf16 v[110:113], v[160:163], v[176:179], v[110:113]
	v_mfma_f32_16x16x32_bf16 v[102:105], v[168:171], v[176:179], v[102:105]
	v_mfma_f32_16x16x32_bf16 v[94:97], v[160:163], v[184:187], v[94:97]
	v_mfma_f32_16x16x32_bf16 v[86:89], v[168:171], v[184:187], v[86:89]
	v_mfma_f32_16x16x32_bf16 v[78:81], v[160:163], v[192:195], v[78:81]
	v_mfma_f32_16x16x32_bf16 v[74:77], v[168:171], v[192:195], v[74:77]
	v_mfma_f32_16x16x32_bf16 v[70:73], v[160:163], v[200:203], v[70:73]
	v_mfma_f32_16x16x32_bf16 v[66:69], v[168:171], v[200:203], v[66:69]
	s_setprio 0
	s_barrier
;     __device__ bool next(int i, Unit& u) const { if (!s.next(i, u)) return false; const int p = u.pn; u.pn = p < 56 ? (p % 7) * 8 + p / 7 : p; return true; }
;     __device__ bool next(int i, Unit& u) const { Unit t; if (!s.next(i >> 1, t)) return false; const int pass = i & 1; u.pm = t.pm + pass * (M / BM); u.pn = t.pn + pass * (D / BM); u.kt0 = 0; return true; }
; #define PG8_STAGE(bufoff, gbase, voff) do { _Pragma("unroll") for (int _i = 0; _i < 2; ++_i) \
;         __builtin_amdgcn_global_load_lds((const unsigned*)((const char*)(gbase) + (voff)[_i]), (PG8_LAS unsigned*)(lds + (bufoff) + ldsw + _i * 8192), 16, 0, 0); } while (0)
; #define PG8_LDA(dst, b, h) do { _Pragma("unroll") for (int m = 0; m < 4; ++m) _Pragma("unroll") for (int k = 0; k < 2; ++k) dst[m][k] = *(const PG8_LAS bf16x8*)(lds + PG8_SA(b, h) + aoff + m * 2048 + k * 1024); } while (0)
; #define PG8_WAIT_V(n) asm volatile("s_waitcnt vmcnt(" #n ")" ::: "memory")
; #define PG8_BAR __builtin_amdgcn_s_barrier()
; template <class Epi, class Sched, bool ALIGN_EPI = false, bool SP2 = false>
; __device__ __forceinline__ void gemm_phase(PG8_LAS unsigned char* lds, const Gemm g, const Sched& S, const Epi& E) {
;     ...
;         const bool has_next = S.next(ui + 1, nxt);
;         const char* nA = has_next ? (const char*)g.A + (size_t)nxt.pm * tstep + (size_t)nxt.kt0 * kstep : cA; const char* nB = has_next ? (const char*)g.Bt + (size_t)nxt.pn * tstep + (size_t)nxt.kt0 * kstep : cB;
;         for (int t = 0; t < nt; t += 2) {
;             if constexpr (Epi::MIDHOOK) { if (t == (nt >> 1)) E.mid(acc, cur, wr, wc, fr, fq); }
;             const bool last = (t == nt - 2);
;             const char* a1 = cA + (size_t)(t + 1) * kstep;
;             const char* a2 = last ? nA : cA + (size_t)(t + 2) * kstep; const char* b2 = last ? nB : cB + (size_t)(t + 2) * kstep;
;             const char* a3 = a2 + kstep; const char* b3 = b2 + kstep;
;             if (last && has_next) S.a_ready(nxt);
;             if constexpr (SP2) {
;             PG8_LDB(B0, 0, 0); PG8_LDB(B1, 0, 1); PG8_SCHED; PG8_LDA(At, 0, 0); PG8_STAGE(PG8_SA(1, 1), a1 + hstep, voffA);
;     ...
;             PG8_LDA(At, 1, 1); PG8_STAGE(PG8_SB(1, 0), b3, voffB); PG8_STAGE(PG8_SB(1, 1), b3 + hstep, voffB); PG8_STAGE(PG8_SA(1, 0), a3, voffA);
;             PG8_WAIT_V(8); PG8_WAIT_L(0); PG8_BAR; PG8_MMA(1, 0, At, B0); PG8_MMA(1, 1, At, B1); PG8_BAR; PG8_SCHED;
	s_mov_b32 m0, s25
	v_lshl_add_u64 v[204:205], v[204:205], 0, s[10:11]
	ds_read_b128 v[172:175], v139 offset:49152
	ds_read_b128 v[176:179], v139 offset:50176
	ds_read_b128 v[180:183], v139 offset:51200
	ds_read_b128 v[184:187], v139 offset:52224
	ds_read_b128 v[188:191], v139 offset:53248
	ds_read_b128 v[192:195], v139 offset:54272
	ds_read_b128 v[196:199], v139 offset:55296
	ds_read_b128 v[200:203], v139 offset:56320
	global_load_lds_dwordx4 v[204:205], off
	v_lshl_add_u64 v[204:205], v[206:207], 0, s[10:11]
	s_mov_b32 m0, s3
	s_nop 0
	global_load_lds_dwordx4 v[204:205], off
	v_lshl_add_u64 v[204:205], s[38:39], 0, v[132:133]
	s_mov_b32 m0, s76
	s_nop 0
	global_load_lds_dwordx4 v[204:205], off
	v_lshl_add_u64 v[204:205], s[38:39], 0, v[130:131]
	s_mov_b32 m0, s75
	s_nop 0
	global_load_lds_dwordx4 v[204:205], off
	v_lshl_add_u64 v[204:205], v[208:209], 0, s[10:11]
	s_mov_b32 m0, s60
	s_nop 0
	global_load_lds_dwordx4 v[204:205], off
	v_lshl_add_u64 v[204:205], v[210:211], 0, s[10:11]
	s_mov_b32 m0, s61
	s_nop 0
	global_load_lds_dwordx4 v[204:205], off
	s_waitcnt vmcnt(8)
	s_waitcnt lgkmcnt(0)
	s_barrier
	s_setprio 1
	s_waitcnt lgkmcnt(0)
	v_mfma_f32_16x16x32_bf16 v[62:65], v[140:143], v[172:175], v[62:65]
	v_mfma_f32_16x16x32_bf16 v[58:61], v[148:151], v[172:175], v[58:61]
	v_mfma_f32_16x16x32_bf16 v[54:57], v[140:143], v[180:183], v[54:57]
	v_mfma_f32_16x16x32_bf16 v[50:53], v[148:151], v[180:183], v[50:53]
	v_mfma_f32_16x16x32_bf16 v[42:45], v[140:143], v[188:191], v[42:45]
	v_mfma_f32_16x16x32_bf16 v[34:37], v[148:151], v[188:191], v[34:37]
	v_mfma_f32_16x16x32_bf16 v[26:29], v[140:143], v[196:199], v[26:29]
	v_mfma_f32_16x16x32_bf16 v[18:21], v[148:151], v[196:199], v[18:21]
	v_mfma_f32_16x16x32_bf16 v[62:65], v[144:147], v[176:179], v[62:65]
	v_mfma_f32_16x16x32_bf16 v[58:61], v[152:155], v[176:179], v[58:61]
	v_mfma_f32_16x16x32_bf16 v[54:57], v[144:147], v[184:187], v[54:57]
	v_mfma_f32_16x16x32_bf16 v[50:53], v[152:155], v[184:187], v[50:53]
	v_mfma_f32_16x16x32_bf16 v[42:45], v[144:147], v[192:195], v[42:45]
	v_mfma_f32_16x16x32_bf16 v[34:37], v[152:155], v[192:195], v[34:37]
	v_mfma_f32_16x16x32_bf16 v[26:29], v[144:147], v[200:203], v[26:29]
	v_mfma_f32_16x16x32_bf16 v[18:21], v[152:155], v[200:203], v[18:21]
	s_setprio 0
	s_setprio 1
	v_mfma_f32_16x16x32_bf16 v[46:49], v[156:159], v[172:175], v[46:49]
	v_mfma_f32_16x16x32_bf16 v[38:41], v[164:167], v[172:175], v[38:41]
	v_mfma_f32_16x16x32_bf16 v[30:33], v[156:159], v[180:183], v[30:33]
	v_mfma_f32_16x16x32_bf16 v[22:25], v[164:167], v[180:183], v[22:25]
	v_mfma_f32_16x16x32_bf16 v[14:17], v[156:159], v[188:191], v[14:17]
	v_mfma_f32_16x16x32_bf16 v[10:13], v[164:167], v[188:191], v[10:13]
	v_mfma_f32_16x16x32_bf16 v[6:9], v[156:159], v[196:199], v[6:9]
	v_mfma_f32_16x16x32_bf16 v[2:5], v[164:167], v[196:199], v[2:5]
	v_mfma_f32_16x16x32_bf16 v[46:49], v[160:163], v[176:179], v[46:49]
	v_mfma_f32_16x16x32_bf16 v[38:41], v[168:171], v[176:179], v[38:41]
	v_mfma_f32_16x16x32_bf16 v[30:33], v[160:163], v[184:187], v[30:33]
	v_mfma_f32_16x16x32_bf16 v[22:25], v[168:171], v[184:187], v[22:25]
	v_mfma_f32_16x16x32_bf16 v[14:17], v[160:163], v[192:195], v[14:17]
	v_mfma_f32_16x16x32_bf16 v[10:13], v[168:171], v[192:195], v[10:13]
	v_mfma_f32_16x16x32_bf16 v[6:9], v[160:163], v[200:203], v[6:9]
	v_mfma_f32_16x16x32_bf16 v[2:5], v[168:171], v[200:203], v[2:5]
	s_setprio 0
	s_barrier
	s_movk_i32 s3, 0x100
	s_andn2_b64 vcc, exec, s[36:37]
	s_mov_b64 s[38:39], -1
	s_mov_b64 s[36:37], 0
	s_cbranch_vccnz .Lkx_1840
.LBB0_1840:
	s_add_u32 s25, s12, s3
	s_addc_u32 s27, s13, 0
	s_add_u32 s42, s25, 0x100
	s_addc_u32 s43, s27, 0
	s_and_b64 s[40:41], s[38:39], exec
	s_cselect_b32 s43, s29, s43
	s_cselect_b32 s42, s28, s42
	s_add_u32 s3, s8, s3
	s_addc_u32 s40, s9, 0
	s_add_u32 s3, s3, 0x100
	s_addc_u32 s40, s40, 0
	s_and_b64 s[38:39], s[38:39], exec
	s_cselect_b32 s45, s31, s40
	s_cselect_b32 s44, s30, s3
	s_add_u32 s48, s25, 0x80080
	ds_read_b128 v[140:143], v137
	ds_read_b128 v[144:147], v137 offset:1024
	ds_read_b128 v[148:151], v137 offset:2048
	ds_read_b128 v[152:155], v137 offset:3072
	ds_read_b128 v[156:159], v138
	ds_read_b128 v[160:163], v138 offset:1024
	ds_read_b128 v[164:167], v138 offset:2048
	ds_read_b128 v[168:171], v138 offset:3072
	s_addc_u32 s49, s27, 0
	s_add_i32 s74, s63, s51
	s_add_i32 m0, s54, 0xc000
	s_add_i32 s77, s54, 0xe000
	s_add_i32 s71, s74, 0x2000
	s_add_u32 s46, s44, 0x80000
	s_addc_u32 s47, s45, 0
	s_add_i32 s73, s64, s51
	s_add_i32 s72, s73, 0x2000
	s_add_i32 s70, 0, 0x18000
	s_add_i32 s27, 0, 0x1c000
	s_add_u32 s40, s42, 0x80000
	s_addc_u32 s41, s43, 0
	s_add_i32 s25, s70, s51
	s_add_i32 s3, s25, 0x2000
	s_add_u32 s38, s44, 0x80080
	s_addc_u32 s39, s45, 0
	s_add_i32 s76, s27, s51
	s_add_i32 s75, s76, 0x2000
	v_lshl_add_u64 v[204:205], s[48:49], 0, v[132:133]
	ds_read_b128 v[172:175], v139
	ds_read_b128 v[176:179], v139 offset:1024
	ds_read_b128 v[180:183], v139 offset:2048
	ds_read_b128 v[184:187], v139 offset:3072
	ds_read_b128 v[188:191], v139 offset:4096
	ds_read_b128 v[192:195], v139 offset:5120
	ds_read_b128 v[196:199], v139 offset:6144
	ds_read_b128 v[200:203], v139 offset:7168
	global_load_lds_dwordx4 v[204:205], off
	v_lshl_add_u64 v[204:205], s[48:49], 0, v[130:131]
	s_mov_b32 m0, s77
	s_nop 0
	global_load_lds_dwordx4 v[204:205], off
	s_waitcnt vmcnt(8)
	s_waitcnt lgkmcnt(0)
	s_barrier
; #define PG8_STAGE(bufoff, gbase, voff) do { _Pragma("unroll") for (int _i = 0; _i < 2; ++_i) \
;         __builtin_amdgcn_global_load_lds((const unsigned*)((const char*)(gbase) + (voff)[_i]), (PG8_LAS unsigned*)(lds + (bufoff) + ldsw + _i * 8192), 16, 0, 0); } while (0)
; #define PG8_LDA(dst, b, h) do { _Pragma("unroll") for (int m = 0; m < 4; ++m) _Pragma("unroll") for (int k = 0; k < 2; ++k) dst[m][k] = *(const PG8_LAS bf16x8*)(lds + PG8_SA(b, h) + aoff + m * 2048 + k * 1024); } while (0)
; #define PG8_LDB(dst, b, h) do { _Pragma("unroll") for (int n = 0; n < 2; ++n) _Pragma("unroll") for (int k = 0; k < 2; ++k) dst[n][k] = *(const PG8_LAS bf16x8*)(lds + PG8_SB(b, h) + boff + n * 2048 + k * 1024); } while (0)
; #define PG8_MMA(ai, bj, At, Bt) do { __builtin_amdgcn_s_setprio(1); _Pragma("unroll") for (int m = 0; m < 4; ++m) _Pragma("unroll") for (int n = 0; n < 2; ++n) _Pragma("unroll") for (int k = 0; k < 2; ++k) \
;         acc[ai][bj][m][n] = __builtin_amdgcn_mfma_f32_16x16x32_bf16(Bt[n][k], At[m][k], acc[ai][bj][m][n], 0, 0, 0); __builtin_amdgcn_s_setprio(0); } while (0)
; #define PG8_WAIT_V(n) asm volatile("s_waitcnt vmcnt(" #n ")" ::: "memory")
; #define PG8_WAIT_L(n) asm volatile("s_waitcnt lgkmcnt(" #n ")" ::: "memory")
; #define PG8_BAR __builtin_amdgcn_s_barrier()
; #define PG8_SCHED __builtin_amdgcn_sched_barrier(0)
; template <class Epi, class Sched, bool ALIGN_EPI = false, bool SP2 = false>
; __device__ __forceinline__ void gemm_phase(PG8_LAS unsigned char* lds, const Gemm g, const Sched& S, const Epi& E) {
;     ...
;             PG8_LDB(B0, 0, 0); PG8_LDB(B1, 0, 1); PG8_SCHED; PG8_LDA(At, 0, 0); PG8_STAGE(PG8_SA(1, 1), a1 + hstep, voffA);
;             PG8_WAIT_V(8); PG8_WAIT_L(0); PG8_BAR; PG8_MMA(0, 0, At, B0); PG8_MMA(0, 1, At, B1); PG8_BAR; PG8_SCHED;
;             PG8_LDA(At, 0, 1); PG8_STAGE(PG8_SB(0, 0), b2, voffB); PG8_STAGE(PG8_SB(0, 1), b2 + hstep, voffB); PG8_STAGE(PG8_SA(0, 0), a2, voffA);
;             PG8_WAIT_V(8); PG8_WAIT_L(0); PG8_BAR; PG8_MMA(1, 0, At, B0); PG8_MMA(1, 1, At, B1); PG8_BAR; PG8_SCHED;
	s_setprio 1
	s_waitcnt lgkmcnt(0)
	v_mfma_f32_16x16x32_bf16 v[126:129], v[140:143], v[172:175], v[126:129]
	v_mfma_f32_16x16x32_bf16 v[122:125], v[148:151], v[172:175], v[122:125]
	v_mfma_f32_16x16x32_bf16 v[118:121], v[140:143], v[180:183], v[118:121]
	v_mfma_f32_16x16x32_bf16 v[114:117], v[148:151], v[180:183], v[114:117]
	v_mfma_f32_16x16x32_bf16 v[106:109], v[140:143], v[188:191], v[106:109]
	v_mfma_f32_16x16x32_bf16 v[98:101], v[148:151], v[188:191], v[98:101]
	v_mfma_f32_16x16x32_bf16 v[90:93], v[140:143], v[196:199], v[90:93]
	v_mfma_f32_16x16x32_bf16 v[82:85], v[148:151], v[196:199], v[82:85]
	v_mfma_f32_16x16x32_bf16 v[126:129], v[144:147], v[176:179], v[126:129]
	v_mfma_f32_16x16x32_bf16 v[122:125], v[152:155], v[176:179], v[122:125]
	v_mfma_f32_16x16x32_bf16 v[118:121], v[144:147], v[184:187], v[118:121]
	v_mfma_f32_16x16x32_bf16 v[114:117], v[152:155], v[184:187], v[114:117]
	v_mfma_f32_16x16x32_bf16 v[106:109], v[144:147], v[192:195], v[106:109]
	v_mfma_f32_16x16x32_bf16 v[98:101], v[152:155], v[192:195], v[98:101]
	v_mfma_f32_16x16x32_bf16 v[90:93], v[144:147], v[200:203], v[90:93]
	v_mfma_f32_16x16x32_bf16 v[82:85], v[152:155], v[200:203], v[82:85]
	s_setprio 0
	s_setprio 1
	v_mfma_f32_16x16x32_bf16 v[110:113], v[156:159], v[172:175], v[110:113]
	v_mfma_f32_16x16x32_bf16 v[102:105], v[164:167], v[172:175], v[102:105]
	v_mfma_f32_16x16x32_bf16 v[94:97], v[156:159], v[180:183], v[94:97]
	v_mfma_f32_16x16x32_bf16 v[86:89], v[164:167], v[180:183], v[86:89]
	v_mfma_f32_16x16x32_bf16 v[78:81], v[156:159], v[188:191], v[78:81]
	v_mfma_f32_16x16x32_bf16 v[74:77], v[164:167], v[188:191], v[74:77]
	v_mfma_f32_16x16x32_bf16 v[70:73], v[156:159], v[196:199], v[70:73]
	v_mfma_f32_16x16x32_bf16 v[66:69], v[164:167], v[196:199], v[66:69]
	v_mfma_f32_16x16x32_bf16 v[110:113], v[160:163], v[176:179], v[110:113]
	v_mfma_f32_16x16x32_bf16 v[102:105], v[168:171], v[176:179], v[102:105]
	v_mfma_f32_16x16x32_bf16 v[94:97], v[160:163], v[184:187], v[94:97]
	v_mfma_f32_16x16x32_bf16 v[86:89], v[168:171], v[184:187], v[86:89]
	v_mfma_f32_16x16x32_bf16 v[78:81], v[160:163], v[192:195], v[78:81]
	v_mfma_f32_16x16x32_bf16 v[74:77], v[168:171], v[192:195], v[74:77]
	v_mfma_f32_16x16x32_bf16 v[70:73], v[160:163], v[200:203], v[70:73]
	v_mfma_f32_16x16x32_bf16 v[66:69], v[168:171], v[200:203], v[66:69]
	s_setprio 0
	s_barrier
	s_mov_b32 m0, s74
	v_lshl_add_u64 v[204:205], s[44:45], 0, v[132:133]
	ds_read_b128 v[172:175], v139 offset:16384
	ds_read_b128 v[176:179], v139 offset:17408
	ds_read_b128 v[180:183], v139 offset:18432
	ds_read_b128 v[184:187], v139 offset:19456
	ds_read_b128 v[188:191], v139 offset:20480
	ds_read_b128 v[192:195], v139 offset:21504
	ds_read_b128 v[196:199], v139 offset:22528
	ds_read_b128 v[200:203], v139 offset:23552
	global_load_lds_dwordx4 v[204:205], off
	v_lshl_add_u64 v[206:207], s[44:45], 0, v[130:131]
	s_mov_b32 m0, s71
	v_lshl_add_u64 v[208:209], s[46:47], 0, v[132:133]
	global_load_lds_dwordx4 v[206:207], off
	s_mov_b32 m0, s73
	v_lshl_add_u64 v[210:211], s[42:43], 0, v[130:131]
	global_load_lds_dwordx4 v[208:209], off
	v_lshl_add_u64 v[208:209], s[46:47], 0, v[130:131]
	s_mov_b32 m0, s72
	s_nop 0
	global_load_lds_dwordx4 v[208:209], off
	v_lshl_add_u64 v[208:209], s[42:43], 0, v[132:133]
	s_mov_b32 m0, s54
	s_nop 0
	global_load_lds_dwordx4 v[208:209], off
	s_mov_b32 m0, s55
	s_nop 0
	global_load_lds_dwordx4 v[210:211], off
	s_waitcnt vmcnt(8)
	s_waitcnt lgkmcnt(0)
	s_barrier
	s_setprio 1
	s_waitcnt lgkmcnt(0)
	v_mfma_f32_16x16x32_bf16 v[62:65], v[140:143], v[172:175], v[62:65]
	v_mfma_f32_16x16x32_bf16 v[58:61], v[148:151], v[172:175], v[58:61]
	v_mfma_f32_16x16x32_bf16 v[54:57], v[140:143], v[180:183], v[54:57]
	v_mfma_f32_16x16x32_bf16 v[50:53], v[148:151], v[180:183], v[50:53]
	v_mfma_f32_16x16x32_bf16 v[42:45], v[140:143], v[188:191], v[42:45]
	v_mfma_f32_16x16x32_bf16 v[34:37], v[148:151], v[188:191], v[34:37]
	v_mfma_f32_16x16x32_bf16 v[26:29], v[140:143], v[196:199], v[26:29]
	v_mfma_f32_16x16x32_bf16 v[18:21], v[148:151], v[196:199], v[18:21]
	v_mfma_f32_16x16x32_bf16 v[62:65], v[144:147], v[176:179], v[62:65]
	v_mfma_f32_16x16x32_bf16 v[58:61], v[152:155], v[176:179], v[58:61]
	v_mfma_f32_16x16x32_bf16 v[54:57], v[144:147], v[184:187], v[54:57]
	v_mfma_f32_16x16x32_bf16 v[50:53], v[152:155], v[184:187], v[50:53]
	v_mfma_f32_16x16x32_bf16 v[42:45], v[144:147], v[192:195], v[42:45]
	v_mfma_f32_16x16x32_bf16 v[34:37], v[152:155], v[192:195], v[34:37]
	v_mfma_f32_16x16x32_bf16 v[26:29], v[144:147], v[200:203], v[26:29]
	v_mfma_f32_16x16x32_bf16 v[18:21], v[152:155], v[200:203], v[18:21]
	s_setprio 0
	s_setprio 1
	v_mfma_f32_16x16x32_bf16 v[46:49], v[156:159], v[172:175], v[46:49]
	v_mfma_f32_16x16x32_bf16 v[38:41], v[164:167], v[172:175], v[38:41]
	v_mfma_f32_16x16x32_bf16 v[30:33], v[156:159], v[180:183], v[30:33]
	v_mfma_f32_16x16x32_bf16 v[22:25], v[164:167], v[180:183], v[22:25]
	v_mfma_f32_16x16x32_bf16 v[14:17], v[156:159], v[188:191], v[14:17]
	v_mfma_f32_16x16x32_bf16 v[10:13], v[164:167], v[188:191], v[10:13]
	v_mfma_f32_16x16x32_bf16 v[6:9], v[156:159], v[196:199], v[6:9]
	v_mfma_f32_16x16x32_bf16 v[2:5], v[164:167], v[196:199], v[2:5]
	v_mfma_f32_16x16x32_bf16 v[46:49], v[160:163], v[176:179], v[46:49]
	v_mfma_f32_16x16x32_bf16 v[38:41], v[168:171], v[176:179], v[38:41]
	v_mfma_f32_16x16x32_bf16 v[30:33], v[160:163], v[184:187], v[30:33]
	v_mfma_f32_16x16x32_bf16 v[22:25], v[168:171], v[184:187], v[22:25]
	v_mfma_f32_16x16x32_bf16 v[14:17], v[160:163], v[192:195], v[14:17]
	v_mfma_f32_16x16x32_bf16 v[10:13], v[168:171], v[192:195], v[10:13]
	v_mfma_f32_16x16x32_bf16 v[6:9], v[160:163], v[200:203], v[6:9]
	v_mfma_f32_16x16x32_bf16 v[2:5], v[168:171], v[200:203], v[2:5]
	s_setprio 0
	s_barrier
; #define PG8_STAGE(bufoff, gbase, voff) do { _Pragma("unroll") for (int _i = 0; _i < 2; ++_i) \
;         __builtin_amdgcn_global_load_lds((const unsigned*)((const char*)(gbase) + (voff)[_i]), (PG8_LAS unsigned*)(lds + (bufoff) + ldsw + _i * 8192), 16, 0, 0); } while (0)
; #define PG8_LDA(dst, b, h) do { _Pragma("unroll") for (int m = 0; m < 4; ++m) _Pragma("unroll") for (int k = 0; k < 2; ++k) dst[m][k] = *(const PG8_LAS bf16x8*)(lds + PG8_SA(b, h) + aoff + m * 2048 + k * 1024); } while (0)
; #define PG8_LDB(dst, b, h) do { _Pragma("unroll") for (int n = 0; n < 2; ++n) _Pragma("unroll") for (int k = 0; k < 2; ++k) dst[n][k] = *(const PG8_LAS bf16x8*)(lds + PG8_SB(b, h) + boff + n * 2048 + k * 1024); } while (0)
; #define PG8_MMA(ai, bj, At, Bt) do { __builtin_amdgcn_s_setprio(1); _Pragma("unroll") for (int m = 0; m < 4; ++m) _Pragma("unroll") for (int n = 0; n < 2; ++n) _Pragma("unroll") for (int k = 0; k < 2; ++k) \
;         acc[ai][bj][m][n] = __builtin_amdgcn_mfma_f32_16x16x32_bf16(Bt[n][k], At[m][k], acc[ai][bj][m][n], 0, 0, 0); __builtin_amdgcn_s_setprio(0); } while (0)
; #define PG8_WAIT_V(n) asm volatile("s_waitcnt vmcnt(" #n ")" ::: "memory")
; #define PG8_WAIT_L(n) asm volatile("s_waitcnt lgkmcnt(" #n ")" ::: "memory")
; #define PG8_BAR __builtin_amdgcn_s_barrier()
; #define PG8_SCHED __builtin_amdgcn_sched_barrier(0)
; template <class Epi, class Sched, bool ALIGN_EPI = false, bool SP2 = false>
; __device__ __forceinline__ void gemm_phase(PG8_LAS unsigned char* lds, const Gemm g, const Sched& S, const Epi& E) {
;     ...
;             PG8_LDB(B0, 1, 0); PG8_LDB(B1, 1, 1); PG8_SCHED; PG8_LDA(At, 1, 0); PG8_STAGE(PG8_SA(0, 1), a2 + hstep, voffA);
;             PG8_WAIT_V(8); PG8_WAIT_L(0); PG8_BAR; PG8_MMA(0, 0, At, B0); PG8_MMA(0, 1, At, B1); PG8_BAR; PG8_SCHED;
;             PG8_LDA(At, 1, 1); PG8_STAGE(PG8_SB(1, 0), b3, voffB); PG8_STAGE(PG8_SB(1, 1), b3 + hstep, voffB); PG8_STAGE(PG8_SA(1, 0), a3, voffA);
;             PG8_WAIT_V(8); PG8_WAIT_L(0); PG8_BAR; PG8_MMA(1, 0, At, B0); PG8_MMA(1, 1, At, B1); PG8_BAR; PG8_SCHED;
	v_add_u32_e32 v152, s70, v134
	v_add_u32_e32 v168, s27, v134
	ds_read_b128 v[140:143], v152
	ds_read_b128 v[144:147], v152 offset:1024
	ds_read_b128 v[148:151], v152 offset:2048
	ds_read_b128 v[152:155], v152 offset:3072
	ds_read_b128 v[156:159], v168
	ds_read_b128 v[160:163], v168 offset:1024
	ds_read_b128 v[164:167], v168 offset:2048
	ds_read_b128 v[168:171], v168 offset:3072
	s_mov_b32 m0, s56
	v_lshl_add_u64 v[212:213], s[40:41], 0, v[132:133]
	ds_read_b128 v[172:175], v139 offset:32768
	ds_read_b128 v[176:179], v139 offset:33792
	ds_read_b128 v[180:183], v139 offset:34816
	ds_read_b128 v[184:187], v139 offset:35840
	ds_read_b128 v[188:191], v139 offset:36864
	ds_read_b128 v[192:195], v139 offset:37888
	ds_read_b128 v[196:199], v139 offset:38912
	ds_read_b128 v[200:203], v139 offset:39936
	global_load_lds_dwordx4 v[212:213], off
	v_lshl_add_u64 v[212:213], s[40:41], 0, v[130:131]
	s_mov_b32 m0, s57
	s_nop 0
	global_load_lds_dwordx4 v[212:213], off
	s_waitcnt vmcnt(8)
	s_waitcnt lgkmcnt(0)
	s_barrier
	s_setprio 1
	s_waitcnt lgkmcnt(0)
	v_mfma_f32_16x16x32_bf16 v[126:129], v[140:143], v[172:175], v[126:129]
	v_mfma_f32_16x16x32_bf16 v[122:125], v[148:151], v[172:175], v[122:125]
	v_mfma_f32_16x16x32_bf16 v[118:121], v[140:143], v[180:183], v[118:121]
	v_mfma_f32_16x16x32_bf16 v[114:117], v[148:151], v[180:183], v[114:117]
	v_mfma_f32_16x16x32_bf16 v[106:109], v[140:143], v[188:191], v[106:109]
	v_mfma_f32_16x16x32_bf16 v[98:101], v[148:151], v[188:191], v[98:101]
	v_mfma_f32_16x16x32_bf16 v[90:93], v[140:143], v[196:199], v[90:93]
	v_mfma_f32_16x16x32_bf16 v[82:85], v[148:151], v[196:199], v[82:85]
	v_mfma_f32_16x16x32_bf16 v[126:129], v[144:147], v[176:179], v[126:129]
	v_mfma_f32_16x16x32_bf16 v[122:125], v[152:155], v[176:179], v[122:125]
	v_mfma_f32_16x16x32_bf16 v[118:121], v[144:147], v[184:187], v[118:121]
	v_mfma_f32_16x16x32_bf16 v[114:117], v[152:155], v[184:187], v[114:117]
	v_mfma_f32_16x16x32_bf16 v[106:109], v[144:147], v[192:195], v[106:109]
	v_mfma_f32_16x16x32_bf16 v[98:101], v[152:155], v[192:195], v[98:101]
	v_mfma_f32_16x16x32_bf16 v[90:93], v[144:147], v[200:203], v[90:93]
	v_mfma_f32_16x16x32_bf16 v[82:85], v[152:155], v[200:203], v[82:85]
	s_setprio 0
	s_setprio 1
	v_mfma_f32_16x16x32_bf16 v[110:113], v[156:159], v[172:175], v[110:113]
	v_mfma_f32_16x16x32_bf16 v[102:105], v[164:167], v[172:175], v[102:105]
	v_mfma_f32_16x16x32_bf16 v[94:97], v[156:159], v[180:183], v[94:97]
	v_mfma_f32_16x16x32_bf16 v[86:89], v[164:167], v[180:183], v[86:89]
	v_mfma_f32_16x16x32_bf16 v[78:81], v[156:159], v[188:191], v[78:81]
	v_mfma_f32_16x16x32_bf16 v[74:77], v[164:167], v[188:191], v[74:77]
	v_mfma_f32_16x16x32_bf16 v[70:73], v[156:159], v[196:199], v[70:73]
	v_mfma_f32_16x16x32_bf16 v[66:69], v[164:167], v[196:199], v[66:69]
	v_mfma_f32_16x16x32_bf16 v[110:113], v[160:163], v[176:179], v[110:113]
	v_mfma_f32_16x16x32_bf16 v[102:105], v[168:171], v[176:179], v[102:105]
	v_mfma_f32_16x16x32_bf16 v[94:97], v[160:163], v[184:187], v[94:97]
	v_mfma_f32_16x16x32_bf16 v[86:89], v[168:171], v[184:187], v[86:89]
	v_mfma_f32_16x16x32_bf16 v[78:81], v[160:163], v[192:195], v[78:81]
	v_mfma_f32_16x16x32_bf16 v[74:77], v[168:171], v[192:195], v[74:77]
	v_mfma_f32_16x16x32_bf16 v[70:73], v[160:163], v[200:203], v[70:73]
	v_mfma_f32_16x16x32_bf16 v[66:69], v[168:171], v[200:203], v[66:69]
	s_setprio 0
	s_barrier
	s_mov_b32 m0, s25
	v_lshl_add_u64 v[204:205], v[204:205], 0, s[10:11]
	ds_read_b128 v[172:175], v139 offset:49152
	ds_read_b128 v[176:179], v139 offset:50176
	ds_read_b128 v[180:183], v139 offset:51200
	ds_read_b128 v[184:187], v139 offset:52224
	ds_read_b128 v[188:191], v139 offset:53248
	ds_read_b128 v[192:195], v139 offset:54272
	ds_read_b128 v[196:199], v139 offset:55296
	ds_read_b128 v[200:203], v139 offset:56320
	global_load_lds_dwordx4 v[204:205], off
	v_lshl_add_u64 v[204:205], v[206:207], 0, s[10:11]
	s_mov_b32 m0, s3
	s_nop 0
	global_load_lds_dwordx4 v[204:205], off
	v_lshl_add_u64 v[204:205], s[38:39], 0, v[132:133]
	s_mov_b32 m0, s76
	s_nop 0
	global_load_lds_dwordx4 v[204:205], off
	v_lshl_add_u64 v[204:205], s[38:39], 0, v[130:131]
	s_mov_b32 m0, s75
	s_nop 0
	global_load_lds_dwordx4 v[204:205], off
	v_lshl_add_u64 v[204:205], v[208:209], 0, s[10:11]
	s_mov_b32 m0, s60
	s_nop 0
	global_load_lds_dwordx4 v[204:205], off
	v_lshl_add_u64 v[204:205], v[210:211], 0, s[10:11]
	s_mov_b32 m0, s61
	s_nop 0
	global_load_lds_dwordx4 v[204:205], off
	s_waitcnt vmcnt(8)
	s_waitcnt lgkmcnt(0)
	s_barrier
	s_setprio 1
	s_waitcnt lgkmcnt(0)
	v_mfma_f32_16x16x32_bf16 v[62:65], v[140:143], v[172:175], v[62:65]
	v_mfma_f32_16x16x32_bf16 v[58:61], v[148:151], v[172:175], v[58:61]
	v_mfma_f32_16x16x32_bf16 v[54:57], v[140:143], v[180:183], v[54:57]
	v_mfma_f32_16x16x32_bf16 v[50:53], v[148:151], v[180:183], v[50:53]
	v_mfma_f32_16x16x32_bf16 v[42:45], v[140:143], v[188:191], v[42:45]
	v_mfma_f32_16x16x32_bf16 v[34:37], v[148:151], v[188:191], v[34:37]
	v_mfma_f32_16x16x32_bf16 v[26:29], v[140:143], v[196:199], v[26:29]
	v_mfma_f32_16x16x32_bf16 v[18:21], v[148:151], v[196:199], v[18:21]
	v_mfma_f32_16x16x32_bf16 v[62:65], v[144:147], v[176:179], v[62:65]
	v_mfma_f32_16x16x32_bf16 v[58:61], v[152:155], v[176:179], v[58:61]
	v_mfma_f32_16x16x32_bf16 v[54:57], v[144:147], v[184:187], v[54:57]
	v_mfma_f32_16x16x32_bf16 v[50:53], v[152:155], v[184:187], v[50:53]
	v_mfma_f32_16x16x32_bf16 v[42:45], v[144:147], v[192:195], v[42:45]
	v_mfma_f32_16x16x32_bf16 v[34:37], v[152:155], v[192:195], v[34:37]
	v_mfma_f32_16x16x32_bf16 v[26:29], v[144:147], v[200:203], v[26:29]
	v_mfma_f32_16x16x32_bf16 v[18:21], v[152:155], v[200:203], v[18:21]
	s_setprio 0
	s_setprio 1
	v_mfma_f32_16x16x32_bf16 v[46:49], v[156:159], v[172:175], v[46:49]
	v_mfma_f32_16x16x32_bf16 v[38:41], v[164:167], v[172:175], v[38:41]
	v_mfma_f32_16x16x32_bf16 v[30:33], v[156:159], v[180:183], v[30:33]
	v_mfma_f32_16x16x32_bf16 v[22:25], v[164:167], v[180:183], v[22:25]
	v_mfma_f32_16x16x32_bf16 v[14:17], v[156:159], v[188:191], v[14:17]
	v_mfma_f32_16x16x32_bf16 v[10:13], v[164:167], v[188:191], v[10:13]
	v_mfma_f32_16x16x32_bf16 v[6:9], v[156:159], v[196:199], v[6:9]
	v_mfma_f32_16x16x32_bf16 v[2:5], v[164:167], v[196:199], v[2:5]
	v_mfma_f32_16x16x32_bf16 v[46:49], v[160:163], v[176:179], v[46:49]
	v_mfma_f32_16x16x32_bf16 v[38:41], v[168:171], v[176:179], v[38:41]
	v_mfma_f32_16x16x32_bf16 v[30:33], v[160:163], v[184:187], v[30:33]
	v_mfma_f32_16x16x32_bf16 v[22:25], v[168:171], v[184:187], v[22:25]
	v_mfma_f32_16x16x32_bf16 v[14:17], v[160:163], v[192:195], v[14:17]
	v_mfma_f32_16x16x32_bf16 v[10:13], v[168:171], v[192:195], v[10:13]
	v_mfma_f32_16x16x32_bf16 v[6:9], v[160:163], v[200:203], v[6:9]
	v_mfma_f32_16x16x32_bf16 v[2:5], v[168:171], v[200:203], v[2:5]
	s_setprio 0
	s_barrier
	s_movk_i32 s3, 0x100
	s_andn2_b64 vcc, exec, s[36:37]
	s_mov_b64 s[38:39], -1
	s_mov_b64 s[36:37], 0
	s_cbranch_vccz .LBB0_1840
